# speedup vs baseline: 1.0059x; 1.0014x over previous
; #define WAIT_V(n) asm volatile("s_waitcnt vmcnt(" #n ")":::"memory")
; #define BAR __builtin_amdgcn_s_barrier()
; DEVINL void gemm8_mainloop(const u16* A, long lda, const u16* Bt, long ldb, int K, int brow, int bcol, f32x4 (&acc)[2][2][4][2], char* smem, int tid) {
;     ...
;   if(wr==1)BAR;
;   WAIT_V(4); BAR;
; DEVINL void compute_rs(const float* part, int m0, float* rs_s, int tid) {
;     ...
;   if (!half) rs_s[row] = rsqrtf(s * (1.f / 2048.f) + EPSN);
;   __syncthreads();
.LBB0_266:
	s_or_b64 exec, exec, s[2:3]
	v_readfirstlane_b32 s44, v167
	s_ashr_i32 s45, s44, 8
	s_cmp_lg_u32 s45, 1
	s_waitcnt lgkmcnt(0)
	s_barrier
	s_cbranch_scc1 .LBB0_268
	s_setprio 1
	s_barrier

; #define STAGE(P,BASE,LD,br,kt) do{long _g=(long)(br)*(LD)+(long)(kt)*BK; \
;     _Pragma("unroll") for(int _i=0;_i<2;++_i){int _b=tid*16+_i*8192;int _r,_c;stage_rc(_b,_r,_c); \
;       __builtin_amdgcn_global_load_lds((const unsigned*)((BASE)+_g+(long)_r*(LD)+_c), \
;         (unsigned*)((char*)(P)+_b),16,0,0);}}while(0)
; #define STAGE(P,BASE,LD,br,kt) do{long _g=(long)(br)*(LD)+(long)(kt)*BK; \
;     _Pragma("unroll") for(int _i=0;_i<2;++_i){int _b=tid*16+_i*8192;int _r,_c;stage_rc(_b,_r,_c); \
;       __builtin_amdgcn_global_load_lds((const unsigned*)((BASE)+_g+(long)_r*(LD)+_c), \
;         (unsigned*)((char*)(P)+_b),16,0,0);}}while(0)
; #define LDA(dst,b,h) _Pragma("unroll") for(int m=0;m<4;++m) _Pragma("unroll") for(int k=0;k<2;++k) \
;     dst[m][k]=*reinterpret_cast<const bf16x8*>((char*)SA(b,h)+lds_byte(wr*64+m*16+fr,k*32+fq*8))
; #define LDB(dst,b,h) _Pragma("unroll") for(int n=0;n<2;++n) _Pragma("unroll") for(int k=0;k<2;++k) \
;     dst[n][k]=*reinterpret_cast<const bf16x8*>((char*)SB(b,h)+lds_byte(wc*32+n*16+fr,k*32+fq*8))
; #define MMA(ai,bj,At_,Bt_) do{__builtin_amdgcn_s_setprio(1); \
;     _Pragma("unroll") for(int m=0;m<4;++m) _Pragma("unroll") for(int n=0;n<2;++n) _Pragma("unroll") for(int k=0;k<2;++k) \
;       acc[ai][bj][m][n]=__builtin_amdgcn_mfma_f32_16x16x32_bf16(Bt_[n][k],At_[m][k],acc[ai][bj][m][n],0,0,0); \
;     __builtin_amdgcn_s_setprio(0);}while(0)
; #define WAIT_L(n) asm volatile("s_waitcnt lgkmcnt(" #n ")":::"memory")
; #define BAR __builtin_amdgcn_s_barrier()
; #define SCHED __builtin_amdgcn_sched_barrier(0)
; DEVINL void gemm8_mainloop(const u16* A, long lda, const u16* Bt, long ldb, int K, int brow, int bcol, f32x4 (&acc)[2][2][4][2], char* smem, int tid) {
;     ...
;     LDB(B0,0,0); SCHED; LDA(At,0,0); STAGE(SA(1,1),A,lda,brow+HALF,t+1);
;     WAIT_L(8); BAR; WAIT_L(0); MMA(0,0,At,B0); BAR; SCHED;
;     LDB(B1,0,1); STAGE(SB(0,0),Bt,ldb,bcol,t+2);
;     BAR; WAIT_L(0); MMA(0,1,At,B1); BAR;
;     LDA(At,0,1); STAGE(SA(0,0),A,lda,brow,t+2);
;     BAR; WAIT_L(0); MMA(1,0,At,B0); BAR; SCHED;
.LBB0_269:
	ds_read_b128 v[170:173], v161
	ds_read_b128 v[180:183], v161 offset:1024
	ds_read_b128 v[184:187], v161 offset:2048
	ds_read_b128 v[188:191], v161 offset:3072
	v_add_u32_e32 v178, 0xc000, v128
	v_lshl_add_u64 v[244:245], s[94:95], 0, v[148:149]
	v_readfirstlane_b32 s3, v178
	v_add_u32_e32 v179, 0xe000, v128
	v_add_u32_e32 v174, s41, v160
	v_add_u32_e32 v175, s45, v160
	v_add_u32_e32 v177, s47, v160
	v_lshl_add_u64 v[162:163], v[244:245], 0, s[12:13]
	s_mov_b32 m0, s3
	v_lshl_add_u64 v[246:247], s[94:95], 0, v[150:151]
	v_readfirstlane_b32 s3, v179
	ds_read_b128 v[192:195], v131
	ds_read_b128 v[196:199], v131 offset:1024
	ds_read_b128 v[200:203], v174
	ds_read_b128 v[204:207], v174 offset:1024
	ds_read_b128 v[208:211], v175
	ds_read_b128 v[212:215], v175 offset:1024
	ds_read_b128 v[216:219], v177
	ds_read_b128 v[220:223], v177 offset:1024
	global_load_lds_dwordx4 v[162:163], off
	v_lshl_add_u64 v[162:163], v[246:247], 0, s[12:13]
	s_mov_b32 m0, s3
	s_nop 0
	global_load_lds_dwordx4 v[162:163], off
	s_waitcnt lgkmcnt(8)
	s_barrier
	s_waitcnt lgkmcnt(0)
	s_nop 0
	v_mfma_f32_16x16x32_bf16 v[124:127], v[170:173], v[192:195], v[124:127]
	v_mfma_f32_16x16x32_bf16 v[120:123], v[184:187], v[192:195], v[120:123]
	v_mfma_f32_16x16x32_bf16 v[116:119], v[170:173], v[200:203], v[116:119]
	v_mfma_f32_16x16x32_bf16 v[112:115], v[184:187], v[200:203], v[112:115]
	v_mfma_f32_16x16x32_bf16 v[108:111], v[170:173], v[208:211], v[108:111]
	v_mfma_f32_16x16x32_bf16 v[104:107], v[184:187], v[208:211], v[104:107]
	v_mfma_f32_16x16x32_bf16 v[100:103], v[170:173], v[216:219], v[100:103]
	v_mfma_f32_16x16x32_bf16 v[96:99], v[184:187], v[216:219], v[96:99]
	v_mfma_f32_16x16x32_bf16 v[124:127], v[180:183], v[196:199], v[124:127]
	v_mfma_f32_16x16x32_bf16 v[120:123], v[188:191], v[196:199], v[120:123]
	v_mfma_f32_16x16x32_bf16 v[116:119], v[180:183], v[204:207], v[116:119]
	v_mfma_f32_16x16x32_bf16 v[112:115], v[188:191], v[204:207], v[112:115]
	v_mfma_f32_16x16x32_bf16 v[108:111], v[180:183], v[212:215], v[108:111]
	v_mfma_f32_16x16x32_bf16 v[104:107], v[188:191], v[212:215], v[104:107]
	v_mfma_f32_16x16x32_bf16 v[100:103], v[180:183], v[220:223], v[100:103]
	v_mfma_f32_16x16x32_bf16 v[96:99], v[188:191], v[220:223], v[96:99]
	s_nop 0
	s_barrier
	v_add_u32_e32 v162, s31, v153
	v_lshl_add_u64 v[248:249], s[94:95], 0, v[144:145]
	v_readfirstlane_b32 s3, v162
	v_add_u32_e32 v163, 0x2000, v162
	v_lshl_add_u64 v[240:241], v[248:249], 0, s[14:15]
	s_mov_b32 m0, s3
	v_lshl_add_u64 v[250:251], s[94:95], 0, v[146:147]
	v_readfirstlane_b32 s3, v163
	ds_read_b128 v[224:227], v158
	ds_read_b128 v[228:231], v158 offset:1024
	ds_read_b128 v[232:235], v158 offset:2048
	ds_read_b128 v[236:239], v158 offset:3072
	global_load_lds_dwordx4 v[240:241], off
	v_lshl_add_u64 v[240:241], v[250:251], 0, s[14:15]
	s_mov_b32 m0, s3
	s_nop 0
	global_load_lds_dwordx4 v[240:241], off
	s_barrier
	s_waitcnt lgkmcnt(0)
	s_nop 0
	v_mfma_f32_16x16x32_bf16 v[92:95], v[224:227], v[192:195], v[92:95]
	v_mfma_f32_16x16x32_bf16 v[88:91], v[232:235], v[192:195], v[88:91]
	v_mfma_f32_16x16x32_bf16 v[84:87], v[224:227], v[200:203], v[84:87]
	v_mfma_f32_16x16x32_bf16 v[80:83], v[232:235], v[200:203], v[80:83]
	v_mfma_f32_16x16x32_bf16 v[76:79], v[224:227], v[208:211], v[76:79]
	v_mfma_f32_16x16x32_bf16 v[72:75], v[232:235], v[208:211], v[72:75]
	v_mfma_f32_16x16x32_bf16 v[68:71], v[224:227], v[216:219], v[68:71]
	v_mfma_f32_16x16x32_bf16 v[64:67], v[232:235], v[216:219], v[64:67]
	v_mfma_f32_16x16x32_bf16 v[92:95], v[228:231], v[196:199], v[92:95]
	v_mfma_f32_16x16x32_bf16 v[88:91], v[236:239], v[196:199], v[88:91]
	v_mfma_f32_16x16x32_bf16 v[84:87], v[228:231], v[204:207], v[84:87]
	v_mfma_f32_16x16x32_bf16 v[80:83], v[236:239], v[204:207], v[80:83]
	v_mfma_f32_16x16x32_bf16 v[76:79], v[228:231], v[212:215], v[76:79]
	v_mfma_f32_16x16x32_bf16 v[72:75], v[236:239], v[212:215], v[72:75]
	v_mfma_f32_16x16x32_bf16 v[68:71], v[228:231], v[220:223], v[68:71]
	v_mfma_f32_16x16x32_bf16 v[64:67], v[236:239], v[220:223], v[64:67]
	s_nop 0
	v_readfirstlane_b32 s3, v128
	v_add_u32_e32 v169, 0x2000, v128
	v_lshl_add_u64 v[240:241], v[244:245], 0, s[16:17]
	s_mov_b32 m0, s3
	v_readfirstlane_b32 s3, v169
	s_barrier
	ds_read_b128 v[192:195], v131 offset:16384
	ds_read_b128 v[196:199], v131 offset:17408
	ds_read_b128 v[200:203], v174 offset:16384
	ds_read_b128 v[204:207], v174 offset:17408
	ds_read_b128 v[208:211], v175 offset:16384
	ds_read_b128 v[212:215], v175 offset:17408
	ds_read_b128 v[216:219], v177 offset:16384
	ds_read_b128 v[220:223], v177 offset:17408
	global_load_lds_dwordx4 v[240:241], off
	v_lshl_add_u64 v[240:241], v[246:247], 0, s[16:17]
	s_mov_b32 m0, s3
	s_nop 0
	global_load_lds_dwordx4 v[240:241], off
	s_barrier
	s_waitcnt lgkmcnt(0)
	s_nop 0
	v_mfma_f32_16x16x32_bf16 v[60:63], v[170:173], v[192:195], v[60:63]
	v_mfma_f32_16x16x32_bf16 v[56:59], v[184:187], v[192:195], v[56:59]
	v_mfma_f32_16x16x32_bf16 v[52:55], v[170:173], v[200:203], v[52:55]
	v_mfma_f32_16x16x32_bf16 v[48:51], v[184:187], v[200:203], v[48:51]
	v_mfma_f32_16x16x32_bf16 v[44:47], v[170:173], v[208:211], v[44:47]
	v_mfma_f32_16x16x32_bf16 v[40:43], v[184:187], v[208:211], v[40:43]
	v_mfma_f32_16x16x32_bf16 v[36:39], v[170:173], v[216:219], v[36:39]
	v_mfma_f32_16x16x32_bf16 v[32:35], v[184:187], v[216:219], v[32:35]
	v_mfma_f32_16x16x32_bf16 v[60:63], v[180:183], v[196:199], v[60:63]
	v_mfma_f32_16x16x32_bf16 v[56:59], v[188:191], v[196:199], v[56:59]
	v_mfma_f32_16x16x32_bf16 v[52:55], v[180:183], v[204:207], v[52:55]
	v_mfma_f32_16x16x32_bf16 v[48:51], v[188:191], v[204:207], v[48:51]
	v_mfma_f32_16x16x32_bf16 v[44:47], v[180:183], v[212:215], v[44:47]
	v_mfma_f32_16x16x32_bf16 v[40:43], v[188:191], v[212:215], v[40:43]
	v_mfma_f32_16x16x32_bf16 v[36:39], v[180:183], v[220:223], v[36:39]
	v_mfma_f32_16x16x32_bf16 v[32:35], v[188:191], v[220:223], v[32:35]
	s_nop 0
	s_barrier
; #define STAGE(P,BASE,LD,br,kt) do{long _g=(long)(br)*(LD)+(long)(kt)*BK; \
;     _Pragma("unroll") for(int _i=0;_i<2;++_i){int _b=tid*16+_i*8192;int _r,_c;stage_rc(_b,_r,_c); \
;       __builtin_amdgcn_global_load_lds((const unsigned*)((BASE)+_g+(long)_r*(LD)+_c), \
;         (unsigned*)((char*)(P)+_b),16,0,0);}}while(0)
; #define STAGE(P,BASE,LD,br,kt) do{long _g=(long)(br)*(LD)+(long)(kt)*BK; \
;     _Pragma("unroll") for(int _i=0;_i<2;++_i){int _b=tid*16+_i*8192;int _r,_c;stage_rc(_b,_r,_c); \
;       __builtin_amdgcn_global_load_lds((const unsigned*)((BASE)+_g+(long)_r*(LD)+_c), \
;         (unsigned*)((char*)(P)+_b),16,0,0);}}while(0)
; #define LDA(dst,b,h) _Pragma("unroll") for(int m=0;m<4;++m) _Pragma("unroll") for(int k=0;k<2;++k) \
;     dst[m][k]=*reinterpret_cast<const bf16x8*>((char*)SA(b,h)+lds_byte(wr*64+m*16+fr,k*32+fq*8))
; #define LDB(dst,b,h) _Pragma("unroll") for(int n=0;n<2;++n) _Pragma("unroll") for(int k=0;k<2;++k) \
;     dst[n][k]=*reinterpret_cast<const bf16x8*>((char*)SB(b,h)+lds_byte(wc*32+n*16+fr,k*32+fq*8))
; #define MMA(ai,bj,At_,Bt_) do{__builtin_amdgcn_s_setprio(1); \
;     _Pragma("unroll") for(int m=0;m<4;++m) _Pragma("unroll") for(int n=0;n<2;++n) _Pragma("unroll") for(int k=0;k<2;++k) \
;       acc[ai][bj][m][n]=__builtin_amdgcn_mfma_f32_16x16x32_bf16(Bt_[n][k],At_[m][k],acc[ai][bj][m][n],0,0,0); \
;     __builtin_amdgcn_s_setprio(0);}while(0)
; #define WAIT_V(n) asm volatile("s_waitcnt vmcnt(" #n ")":::"memory")
; #define WAIT_L(n) asm volatile("s_waitcnt lgkmcnt(" #n ")":::"memory")
; #define BAR __builtin_amdgcn_s_barrier()
; #define SCHED __builtin_amdgcn_sched_barrier(0)
; DEVINL void gemm8_mainloop(const u16* A, long lda, const u16* Bt, long ldb, int K, int brow, int bcol, f32x4 (&acc)[2][2][4][2], char* smem, int tid) {
;     ...
;     STAGE(SB(0,1),Bt,ldb,bcol+HALF,t+2);
;     WAIT_V(6); BAR; MMA(1,1,At,B1); BAR;
;     LDB(B0,1,0); SCHED; LDA(At,1,0); STAGE(SA(0,1),A,lda,brow+HALF,t+2);
;     WAIT_L(8); BAR; WAIT_L(0); MMA(0,0,At,B0); BAR; SCHED;
;     LDB(B1,1,1); STAGE(SB(1,0),Bt,ldb,bcol,t+3);
	v_add_u32_e32 v170, s33, v153
	v_add_u32_e32 v171, 0x2000, v170
	v_readfirstlane_b32 s3, v170
	v_lshl_add_u64 v[172:173], v[248:249], 0, s[18:19]
	s_mov_b32 m0, s3
	v_readfirstlane_b32 s3, v171
	global_load_lds_dwordx4 v[172:173], off
	v_lshl_add_u64 v[172:173], v[250:251], 0, s[18:19]
	s_mov_b32 m0, s3
	s_nop 0
	global_load_lds_dwordx4 v[172:173], off
	s_waitcnt vmcnt(6)
	s_barrier
	s_nop 0
	v_mfma_f32_16x16x32_bf16 v[28:31], v[224:227], v[192:195], v[28:31]
	v_mfma_f32_16x16x32_bf16 v[24:27], v[232:235], v[192:195], v[24:27]
	v_mfma_f32_16x16x32_bf16 v[20:23], v[224:227], v[200:203], v[20:23]
	v_mfma_f32_16x16x32_bf16 v[16:19], v[232:235], v[200:203], v[16:19]
	v_mfma_f32_16x16x32_bf16 v[12:15], v[224:227], v[208:211], v[12:15]
	v_mfma_f32_16x16x32_bf16 v[8:11], v[232:235], v[208:211], v[8:11]
	v_mfma_f32_16x16x32_bf16 v[4:7], v[224:227], v[216:219], v[4:7]
	v_mfma_f32_16x16x32_bf16 v[0:3], v[232:235], v[216:219], v[0:3]
	v_mfma_f32_16x16x32_bf16 v[28:31], v[228:231], v[196:199], v[28:31]
	v_mfma_f32_16x16x32_bf16 v[24:27], v[236:239], v[196:199], v[24:27]
	v_mfma_f32_16x16x32_bf16 v[20:23], v[228:231], v[204:207], v[20:23]
	v_mfma_f32_16x16x32_bf16 v[16:19], v[236:239], v[204:207], v[16:19]
	v_mfma_f32_16x16x32_bf16 v[12:15], v[228:231], v[212:215], v[12:15]
	v_mfma_f32_16x16x32_bf16 v[8:11], v[236:239], v[212:215], v[8:11]
	v_mfma_f32_16x16x32_bf16 v[4:7], v[228:231], v[220:223], v[4:7]
	v_mfma_f32_16x16x32_bf16 v[0:3], v[236:239], v[220:223], v[0:3]
	s_nop 0
	s_barrier
	ds_read_b128 v[180:183], v154
	ds_read_b128 v[184:187], v154 offset:1024
	ds_read_b128 v[188:191], v154 offset:2048
	ds_read_b128 v[192:195], v154 offset:3072
	v_add_u32_e32 v172, 0x4000, v128
	v_add_u32_e32 v173, 0x6000, v128
	v_readfirstlane_b32 s3, v172
	v_lshl_add_u64 v[228:229], v[244:245], 0, s[20:21]
	s_mov_b32 m0, s3
	v_readfirstlane_b32 s3, v173
	ds_read_b128 v[196:199], v131 offset:32768
	ds_read_b128 v[200:203], v131 offset:33792
	ds_read_b128 v[204:207], v174 offset:32768
	ds_read_b128 v[208:211], v174 offset:33792
	ds_read_b128 v[212:215], v175 offset:32768
	ds_read_b128 v[216:219], v175 offset:33792
	ds_read_b128 v[220:223], v177 offset:32768
	ds_read_b128 v[224:227], v177 offset:33792
	global_load_lds_dwordx4 v[228:229], off
	v_lshl_add_u64 v[228:229], v[246:247], 0, s[20:21]
	s_mov_b32 m0, s3
	s_nop 0
	global_load_lds_dwordx4 v[228:229], off
	s_waitcnt lgkmcnt(8)
	s_barrier
	s_waitcnt lgkmcnt(0)
	s_nop 0
	v_mfma_f32_16x16x32_bf16 v[124:127], v[180:183], v[196:199], v[124:127]
	v_mfma_f32_16x16x32_bf16 v[120:123], v[188:191], v[196:199], v[120:123]
	v_mfma_f32_16x16x32_bf16 v[116:119], v[180:183], v[204:207], v[116:119]
	v_mfma_f32_16x16x32_bf16 v[112:115], v[188:191], v[204:207], v[112:115]
	v_mfma_f32_16x16x32_bf16 v[108:111], v[180:183], v[212:215], v[108:111]
	v_mfma_f32_16x16x32_bf16 v[104:107], v[188:191], v[212:215], v[104:107]
	v_mfma_f32_16x16x32_bf16 v[100:103], v[180:183], v[220:223], v[100:103]
	v_mfma_f32_16x16x32_bf16 v[96:99], v[188:191], v[220:223], v[96:99]
	v_mfma_f32_16x16x32_bf16 v[124:127], v[184:187], v[200:203], v[124:127]
	v_mfma_f32_16x16x32_bf16 v[120:123], v[192:195], v[200:203], v[120:123]
	v_mfma_f32_16x16x32_bf16 v[116:119], v[184:187], v[208:211], v[116:119]
	v_mfma_f32_16x16x32_bf16 v[112:115], v[192:195], v[208:211], v[112:115]
	v_mfma_f32_16x16x32_bf16 v[108:111], v[184:187], v[216:219], v[108:111]
	v_mfma_f32_16x16x32_bf16 v[104:107], v[192:195], v[216:219], v[104:107]
	v_mfma_f32_16x16x32_bf16 v[100:103], v[184:187], v[224:227], v[100:103]
	v_mfma_f32_16x16x32_bf16 v[96:99], v[192:195], v[224:227], v[96:99]
	s_nop 0
	s_barrier
	v_readfirstlane_b32 s3, v155
	v_add_u32_e32 v165, 0x2000, v155
	v_lshl_add_u64 v[252:253], v[248:249], 0, s[22:23]
	s_mov_b32 m0, s3
	v_readfirstlane_b32 s3, v165
	ds_read_b128 v[228:231], v152
	ds_read_b128 v[232:235], v152 offset:1024
	ds_read_b128 v[236:239], v152 offset:2048
	ds_read_b128 v[240:243], v152 offset:3072
	global_load_lds_dwordx4 v[252:253], off
	v_lshl_add_u64 v[252:253], v[250:251], 0, s[22:23]
	s_mov_b32 m0, s3
	s_nop 0
	global_load_lds_dwordx4 v[252:253], off
	s_barrier
	s_waitcnt lgkmcnt(0)
	s_nop 0
	v_mfma_f32_16x16x32_bf16 v[92:95], v[228:231], v[196:199], v[92:95]
	v_mfma_f32_16x16x32_bf16 v[88:91], v[236:239], v[196:199], v[88:91]
	v_mfma_f32_16x16x32_bf16 v[84:87], v[228:231], v[204:207], v[84:87]
	v_mfma_f32_16x16x32_bf16 v[80:83], v[236:239], v[204:207], v[80:83]
	v_mfma_f32_16x16x32_bf16 v[76:79], v[228:231], v[212:215], v[76:79]
	v_mfma_f32_16x16x32_bf16 v[72:75], v[236:239], v[212:215], v[72:75]
	v_mfma_f32_16x16x32_bf16 v[68:71], v[228:231], v[220:223], v[68:71]
	v_mfma_f32_16x16x32_bf16 v[64:67], v[236:239], v[220:223], v[64:67]
	v_mfma_f32_16x16x32_bf16 v[92:95], v[232:235], v[200:203], v[92:95]
	v_mfma_f32_16x16x32_bf16 v[88:91], v[240:243], v[200:203], v[88:91]
	v_mfma_f32_16x16x32_bf16 v[84:87], v[232:235], v[208:211], v[84:87]
	v_mfma_f32_16x16x32_bf16 v[80:83], v[240:243], v[208:211], v[80:83]
	v_mfma_f32_16x16x32_bf16 v[76:79], v[232:235], v[216:219], v[76:79]
	v_mfma_f32_16x16x32_bf16 v[72:75], v[240:243], v[216:219], v[72:75]
	v_mfma_f32_16x16x32_bf16 v[68:71], v[232:235], v[224:227], v[68:71]
	v_mfma_f32_16x16x32_bf16 v[64:67], v[240:243], v[224:227], v[64:67]
	s_nop 0
	v_readfirstlane_b32 s3, v156
	v_lshl_add_u64 v[244:245], v[244:245], 0, s[24:25]
	s_mov_b32 m0, s3
	v_readfirstlane_b32 s3, v157
	s_barrier
; #define STAGE(P,BASE,LD,br,kt) do{long _g=(long)(br)*(LD)+(long)(kt)*BK; \
;     _Pragma("unroll") for(int _i=0;_i<2;++_i){int _b=tid*16+_i*8192;int _r,_c;stage_rc(_b,_r,_c); \
;       __builtin_amdgcn_global_load_lds((const unsigned*)((BASE)+_g+(long)_r*(LD)+_c), \
;         (unsigned*)((char*)(P)+_b),16,0,0);}}while(0)
; #define STAGE(P,BASE,LD,br,kt) do{long _g=(long)(br)*(LD)+(long)(kt)*BK; \
;     _Pragma("unroll") for(int _i=0;_i<2;++_i){int _b=tid*16+_i*8192;int _r,_c;stage_rc(_b,_r,_c); \
;       __builtin_amdgcn_global_load_lds((const unsigned*)((BASE)+_g+(long)_r*(LD)+_c), \
;         (unsigned*)((char*)(P)+_b),16,0,0);}}while(0)
; #define LDA(dst,b,h) _Pragma("unroll") for(int m=0;m<4;++m) _Pragma("unroll") for(int k=0;k<2;++k) \
;     dst[m][k]=*reinterpret_cast<const bf16x8*>((char*)SA(b,h)+lds_byte(wr*64+m*16+fr,k*32+fq*8))
; #define LDB(dst,b,h) _Pragma("unroll") for(int n=0;n<2;++n) _Pragma("unroll") for(int k=0;k<2;++k) \
;     dst[n][k]=*reinterpret_cast<const bf16x8*>((char*)SB(b,h)+lds_byte(wc*32+n*16+fr,k*32+fq*8))
; #define MMA(ai,bj,At_,Bt_) do{__builtin_amdgcn_s_setprio(1); \
;     _Pragma("unroll") for(int m=0;m<4;++m) _Pragma("unroll") for(int n=0;n<2;++n) _Pragma("unroll") for(int k=0;k<2;++k) \
;       acc[ai][bj][m][n]=__builtin_amdgcn_mfma_f32_16x16x32_bf16(Bt_[n][k],At_[m][k],acc[ai][bj][m][n],0,0,0); \
;     __builtin_amdgcn_s_setprio(0);}while(0)
; #define WAIT_V(n) asm volatile("s_waitcnt vmcnt(" #n ")":::"memory")
; #define WAIT_L(n) asm volatile("s_waitcnt lgkmcnt(" #n ")":::"memory")
; #define BAR __builtin_amdgcn_s_barrier()
; #define SCHED __builtin_amdgcn_sched_barrier(0)
; DEVINL void gemm8_mainloop(const u16* A, long lda, const u16* Bt, long ldb, int K, int brow, int bcol, f32x4 (&acc)[2][2][4][2], char* smem, int tid) {
;     ...
;     BAR; WAIT_L(0); MMA(0,1,At,B1); BAR;
;     LDA(At,1,1); STAGE(SA(1,0),A,lda,brow,t+3);
;     BAR; WAIT_L(0); MMA(1,0,At,B0); BAR; SCHED;
;     STAGE(SB(1,1),Bt,ldb,bcol+HALF,t+3);
;     WAIT_V(6); BAR; MMA(1,1,At,B1); BAR;
;   }
;   { LDB(B0,0,0); LDA(At,0,0); STAGE(SA(1,1),A,lda,brow+HALF,nt-1);
;     BAR; WAIT_L(0); MMA(0,0,At,B0); BAR;
	ds_read_b128 v[196:199], v131 offset:49152
	ds_read_b128 v[200:203], v131 offset:50176
	ds_read_b128 v[204:207], v174 offset:49152
	ds_read_b128 v[208:211], v174 offset:50176
	ds_read_b128 v[212:215], v175 offset:49152
	ds_read_b128 v[216:219], v175 offset:50176
	ds_read_b128 v[220:223], v177 offset:49152
	ds_read_b128 v[224:227], v177 offset:50176
	global_load_lds_dwordx4 v[244:245], off
	v_lshl_add_u64 v[244:245], v[246:247], 0, s[24:25]
	s_mov_b32 m0, s3
	s_nop 0
	global_load_lds_dwordx4 v[244:245], off
	s_barrier
	s_waitcnt lgkmcnt(0)
	s_nop 0
	v_mfma_f32_16x16x32_bf16 v[60:63], v[180:183], v[196:199], v[60:63]
	v_mfma_f32_16x16x32_bf16 v[56:59], v[188:191], v[196:199], v[56:59]
	v_mfma_f32_16x16x32_bf16 v[52:55], v[180:183], v[204:207], v[52:55]
	v_mfma_f32_16x16x32_bf16 v[48:51], v[188:191], v[204:207], v[48:51]
	v_mfma_f32_16x16x32_bf16 v[44:47], v[180:183], v[212:215], v[44:47]
	v_mfma_f32_16x16x32_bf16 v[40:43], v[188:191], v[212:215], v[40:43]
	v_mfma_f32_16x16x32_bf16 v[36:39], v[180:183], v[220:223], v[36:39]
	v_mfma_f32_16x16x32_bf16 v[32:35], v[188:191], v[220:223], v[32:35]
	v_mfma_f32_16x16x32_bf16 v[60:63], v[184:187], v[200:203], v[60:63]
	v_mfma_f32_16x16x32_bf16 v[56:59], v[192:195], v[200:203], v[56:59]
	v_mfma_f32_16x16x32_bf16 v[52:55], v[184:187], v[208:211], v[52:55]
	v_mfma_f32_16x16x32_bf16 v[48:51], v[192:195], v[208:211], v[48:51]
	v_mfma_f32_16x16x32_bf16 v[44:47], v[184:187], v[216:219], v[44:47]
	v_mfma_f32_16x16x32_bf16 v[40:43], v[192:195], v[216:219], v[40:43]
	v_mfma_f32_16x16x32_bf16 v[36:39], v[184:187], v[224:227], v[36:39]
	v_mfma_f32_16x16x32_bf16 v[32:35], v[192:195], v[224:227], v[32:35]
	s_nop 0
	s_barrier
	v_readfirstlane_b32 s3, v159
	v_add_u32_e32 v165, 0x2000, v159
	v_lshl_add_u64 v[180:181], v[248:249], 0, s[26:27]
	s_mov_b32 m0, s3
	v_readfirstlane_b32 s3, v165
	global_load_lds_dwordx4 v[180:181], off
	v_lshl_add_u64 v[180:181], v[250:251], 0, s[26:27]
	s_mov_b32 m0, s3
	s_nop 0
	global_load_lds_dwordx4 v[180:181], off
	s_waitcnt vmcnt(6)
	s_barrier
	s_nop 0
	v_mfma_f32_16x16x32_bf16 v[28:31], v[228:231], v[196:199], v[28:31]
	v_mfma_f32_16x16x32_bf16 v[24:27], v[236:239], v[196:199], v[24:27]
	v_mfma_f32_16x16x32_bf16 v[20:23], v[228:231], v[204:207], v[20:23]
	v_mfma_f32_16x16x32_bf16 v[16:19], v[236:239], v[204:207], v[16:19]
	v_mfma_f32_16x16x32_bf16 v[12:15], v[228:231], v[212:215], v[12:15]
	v_mfma_f32_16x16x32_bf16 v[8:11], v[236:239], v[212:215], v[8:11]
	v_mfma_f32_16x16x32_bf16 v[4:7], v[228:231], v[220:223], v[4:7]
	v_mfma_f32_16x16x32_bf16 v[0:3], v[236:239], v[220:223], v[0:3]
	v_mfma_f32_16x16x32_bf16 v[28:31], v[232:235], v[200:203], v[28:31]
	v_mfma_f32_16x16x32_bf16 v[24:27], v[240:243], v[200:203], v[24:27]
	v_mfma_f32_16x16x32_bf16 v[20:23], v[232:235], v[208:211], v[20:23]
	v_mfma_f32_16x16x32_bf16 v[16:19], v[240:243], v[208:211], v[16:19]
	v_mfma_f32_16x16x32_bf16 v[12:15], v[232:235], v[216:219], v[12:15]
	v_mfma_f32_16x16x32_bf16 v[8:11], v[240:243], v[216:219], v[8:11]
	v_mfma_f32_16x16x32_bf16 v[4:7], v[232:235], v[224:227], v[4:7]
	v_mfma_f32_16x16x32_bf16 v[0:3], v[240:243], v[224:227], v[0:3]
	s_nop 0
	s_add_i32 s2, s2, 2
	v_lshl_add_u64 v[144:145], v[144:145], 0, s[14:15]
	v_lshl_add_u64 v[146:147], v[146:147], 0, s[14:15]
	v_lshl_add_u64 v[148:149], v[148:149], 0, s[14:15]
	s_cmp_lt_u32 s2, 28
	v_lshl_add_u64 v[150:151], v[150:151], 0, s[14:15]
	s_barrier
	s_cbranch_scc1 .LBB0_269
	s_or_b32 s2, s40, 0x80
	s_ashr_i32 s3, s2, 31
	s_lshl_b64 s[2:3], s[2:3], 12
	s_add_u32 s2, s90, s2
	s_addc_u32 s3, s91, s3
	v_lshl_add_u64 v[156:157], v[136:137], 1, s[2:3]
	v_lshl_add_u64 v[140:141], v[140:141], 1, v[156:157]
	v_readfirstlane_b32 s41, v178
	v_lshl_add_u64 v[140:141], v[140:141], 0, s[28:29]
	s_mov_b32 m0, s41
	ds_read_b128 v[144:147], v161
	ds_read_b128 v[148:151], v161 offset:1024
	ds_read_b128 v[180:183], v161 offset:2048
	ds_read_b128 v[184:187], v161 offset:3072
	ds_read_b128 v[188:191], v131
	ds_read_b128 v[192:195], v131 offset:1024
	ds_read_b128 v[196:199], v174
	ds_read_b128 v[200:203], v174 offset:1024
	ds_read_b128 v[204:207], v175
	ds_read_b128 v[208:211], v175 offset:1024
	ds_read_b128 v[212:215], v177
	ds_read_b128 v[216:219], v177 offset:1024
	global_load_lds_dwordx4 v[140:141], off
	v_lshl_add_u64 v[140:141], v[138:139], 1, s[2:3]
	v_lshl_add_u64 v[140:141], v[142:143], 1, v[140:141]
	v_readfirstlane_b32 s2, v179
	v_lshl_add_u64 v[140:141], v[140:141], 0, s[28:29]
	s_mov_b32 m0, s2
	s_nop 0
	global_load_lds_dwordx4 v[140:141], off
	s_barrier
	s_waitcnt lgkmcnt(0)
	s_nop 0
	v_mfma_f32_16x16x32_bf16 v[124:127], v[144:147], v[188:191], v[124:127]
	v_mfma_f32_16x16x32_bf16 v[120:123], v[180:183], v[188:191], v[120:123]
	v_mfma_f32_16x16x32_bf16 v[108:111], v[144:147], v[204:207], v[108:111]
	v_mfma_f32_16x16x32_bf16 v[104:107], v[180:183], v[204:207], v[104:107]
	v_mfma_f32_16x16x32_bf16 v[124:127], v[148:151], v[192:195], v[124:127]
	v_mfma_f32_16x16x32_bf16 v[120:123], v[184:187], v[192:195], v[120:123]
	v_mfma_f32_16x16x32_bf16 v[116:119], v[144:147], v[196:199], v[116:119]
	v_mfma_f32_16x16x32_bf16 v[112:115], v[180:183], v[196:199], v[112:115]
	v_mfma_f32_16x16x32_bf16 v[108:111], v[148:151], v[208:211], v[108:111]
	v_mfma_f32_16x16x32_bf16 v[104:107], v[184:187], v[208:211], v[104:107]
	v_mfma_f32_16x16x32_bf16 v[100:103], v[144:147], v[212:215], v[100:103]
	v_mfma_f32_16x16x32_bf16 v[96:99], v[180:183], v[212:215], v[96:99]
	v_mfma_f32_16x16x32_bf16 v[140:143], v[148:151], v[200:203], v[116:119]
	v_mfma_f32_16x16x32_bf16 v[220:223], v[184:187], v[200:203], v[112:115]
	v_mfma_f32_16x16x32_bf16 v[224:227], v[148:151], v[216:219], v[100:103]
	v_mfma_f32_16x16x32_bf16 v[228:231], v[184:187], v[216:219], v[96:99]
	s_nop 0
	s_barrier
; #define LDA(dst,b,h) _Pragma("unroll") for(int m=0;m<4;++m) _Pragma("unroll") for(int k=0;k<2;++k) \
;     dst[m][k]=*reinterpret_cast<const bf16x8*>((char*)SA(b,h)+lds_byte(wr*64+m*16+fr,k*32+fq*8))
; #define LDB(dst,b,h) _Pragma("unroll") for(int n=0;n<2;++n) _Pragma("unroll") for(int k=0;k<2;++k) \
;     dst[n][k]=*reinterpret_cast<const bf16x8*>((char*)SB(b,h)+lds_byte(wc*32+n*16+fr,k*32+fq*8))
; #define MMA(ai,bj,At_,Bt_) do{__builtin_amdgcn_s_setprio(1); \
;     _Pragma("unroll") for(int m=0;m<4;++m) _Pragma("unroll") for(int n=0;n<2;++n) _Pragma("unroll") for(int k=0;k<2;++k) \
;       acc[ai][bj][m][n]=__builtin_amdgcn_mfma_f32_16x16x32_bf16(Bt_[n][k],At_[m][k],acc[ai][bj][m][n],0,0,0); \
;     __builtin_amdgcn_s_setprio(0);}while(0)
; #define WAIT_V(n) asm volatile("s_waitcnt vmcnt(" #n ")":::"memory")
; #define WAIT_L(n) asm volatile("s_waitcnt lgkmcnt(" #n ")":::"memory")
; #define BAR __builtin_amdgcn_s_barrier()
; DEVINL void gemm8_mainloop(const u16* A, long lda, const u16* Bt, long ldb, int K, int brow, int bcol, f32x4 (&acc)[2][2][4][2], char* smem, int tid) {
;     ...
;     LDB(B1,0,1); BAR; WAIT_L(0); MMA(0,1,At,B1); BAR;
;     LDA(At,0,1); WAIT_V(4); BAR; WAIT_L(0); MMA(1,0,At,B0); MMA(1,1,At,B1); BAR; }
;   { LDB(B0,1,0); LDA(At,1,0); WAIT_V(2); BAR; WAIT_L(0); MMA(0,0,At,B0); BAR;
;     LDB(B1,1,1); WAIT_V(0); BAR; WAIT_L(0); MMA(0,1,At,B1); BAR;
	s_nop 1
	ds_read_b128 v[96:99], v158
	ds_read_b128 v[100:103], v158 offset:1024
	ds_read_b128 v[112:115], v158 offset:2048
	ds_read_b128 v[116:119], v158 offset:3072
	s_barrier
	s_waitcnt lgkmcnt(0)
	s_nop 0
	v_mfma_f32_16x16x32_bf16 v[92:95], v[96:99], v[188:191], v[92:95]
	v_mfma_f32_16x16x32_bf16 v[88:91], v[112:115], v[188:191], v[88:91]
	v_mfma_f32_16x16x32_bf16 v[76:79], v[96:99], v[204:207], v[76:79]
	v_mfma_f32_16x16x32_bf16 v[72:75], v[112:115], v[204:207], v[72:75]
	v_mfma_f32_16x16x32_bf16 v[92:95], v[100:103], v[192:195], v[92:95]
	v_mfma_f32_16x16x32_bf16 v[88:91], v[116:119], v[192:195], v[88:91]
	v_mfma_f32_16x16x32_bf16 v[84:87], v[96:99], v[196:199], v[84:87]
	v_mfma_f32_16x16x32_bf16 v[80:83], v[112:115], v[196:199], v[80:83]
	v_mfma_f32_16x16x32_bf16 v[76:79], v[100:103], v[208:211], v[76:79]
	v_mfma_f32_16x16x32_bf16 v[72:75], v[116:119], v[208:211], v[72:75]
	v_mfma_f32_16x16x32_bf16 v[68:71], v[96:99], v[212:215], v[68:71]
	v_mfma_f32_16x16x32_bf16 v[64:67], v[112:115], v[212:215], v[64:67]
	v_mfma_f32_16x16x32_bf16 v[156:159], v[100:103], v[200:203], v[84:87]
	v_mfma_f32_16x16x32_bf16 v[188:191], v[116:119], v[200:203], v[80:83]
	v_mfma_f32_16x16x32_bf16 v[192:195], v[100:103], v[216:219], v[68:71]
	v_mfma_f32_16x16x32_bf16 v[196:199], v[116:119], v[216:219], v[64:67]
	s_nop 0
	s_barrier
	s_nop 1
	ds_read_b128 v[64:67], v131 offset:16384
	ds_read_b128 v[68:71], v131 offset:17408
	ds_read_b128 v[80:83], v174 offset:16384
	ds_read_b128 v[84:87], v174 offset:17408
	ds_read_b128 v[200:203], v175 offset:16384
	ds_read_b128 v[204:207], v175 offset:17408
	ds_read_b128 v[208:211], v177 offset:16384
	ds_read_b128 v[212:215], v177 offset:17408
	s_waitcnt vmcnt(4)
	s_barrier
	s_waitcnt lgkmcnt(0)
	s_nop 0
	v_mfma_f32_16x16x32_bf16 v[60:63], v[144:147], v[64:67], v[60:63]
	v_mfma_f32_16x16x32_bf16 v[52:55], v[144:147], v[80:83], v[52:55]
	v_mfma_f32_16x16x32_bf16 v[44:47], v[144:147], v[200:203], v[44:47]
	v_mfma_f32_16x16x32_bf16 v[40:43], v[180:183], v[200:203], v[40:43]
	v_mfma_f32_16x16x32_bf16 v[60:63], v[148:151], v[68:71], v[60:63]
	v_mfma_f32_16x16x32_bf16 v[56:59], v[180:183], v[64:67], v[56:59]
	v_mfma_f32_16x16x32_bf16 v[52:55], v[148:151], v[84:87], v[52:55]
	v_mfma_f32_16x16x32_bf16 v[48:51], v[180:183], v[80:83], v[48:51]
	v_mfma_f32_16x16x32_bf16 v[44:47], v[148:151], v[204:207], v[44:47]
	v_mfma_f32_16x16x32_bf16 v[40:43], v[184:187], v[204:207], v[40:43]
	v_mfma_f32_16x16x32_bf16 v[36:39], v[144:147], v[208:211], v[36:39]
	v_mfma_f32_16x16x32_bf16 v[32:35], v[180:183], v[208:211], v[32:35]
	v_mfma_f32_16x16x32_bf16 v[216:219], v[184:187], v[68:71], v[56:59]
	v_mfma_f32_16x16x32_bf16 v[232:235], v[184:187], v[84:87], v[48:51]
	v_mfma_f32_16x16x32_bf16 v[144:147], v[148:151], v[212:215], v[36:39]
	v_mfma_f32_16x16x32_bf16 v[148:151], v[184:187], v[212:215], v[32:35]
	s_nop 0
	s_nop 0
	v_mfma_f32_16x16x32_bf16 v[28:31], v[96:99], v[64:67], v[28:31]
	v_mfma_f32_16x16x32_bf16 v[20:23], v[96:99], v[80:83], v[20:23]
	v_mfma_f32_16x16x32_bf16 v[12:15], v[96:99], v[200:203], v[12:15]
	v_mfma_f32_16x16x32_bf16 v[4:7], v[96:99], v[208:211], v[4:7]
	v_mfma_f32_16x16x32_bf16 v[28:31], v[100:103], v[68:71], v[28:31]
	v_mfma_f32_16x16x32_bf16 v[24:27], v[112:115], v[64:67], v[24:27]
	v_mfma_f32_16x16x32_bf16 v[20:23], v[100:103], v[84:87], v[20:23]
	v_mfma_f32_16x16x32_bf16 v[16:19], v[112:115], v[80:83], v[16:19]
	v_mfma_f32_16x16x32_bf16 v[12:15], v[100:103], v[204:207], v[12:15]
	v_mfma_f32_16x16x32_bf16 v[8:11], v[112:115], v[200:203], v[8:11]
	v_mfma_f32_16x16x32_bf16 v[4:7], v[100:103], v[212:215], v[4:7]
	v_mfma_f32_16x16x32_bf16 v[0:3], v[112:115], v[208:211], v[0:3]
	v_mfma_f32_16x16x32_bf16 v[178:181], v[116:119], v[68:71], v[24:27]
	v_mfma_f32_16x16x32_bf16 v[182:185], v[116:119], v[84:87], v[16:19]
	v_mfma_f32_16x16x32_bf16 v[200:203], v[116:119], v[204:207], v[8:11]
	v_mfma_f32_16x16x32_bf16 v[204:207], v[116:119], v[212:215], v[0:3]
	s_nop 0
	s_barrier
	s_nop 1
	ds_read_b128 v[0:3], v154
	ds_read_b128 v[8:11], v154 offset:1024
	ds_read_b128 v[208:211], v154 offset:2048
	ds_read_b128 v[212:215], v154 offset:3072
	ds_read_b128 v[16:19], v131 offset:32768
	ds_read_b128 v[24:27], v131 offset:33792
	ds_read_b128 v[32:35], v174 offset:32768
	ds_read_b128 v[36:39], v174 offset:33792
	ds_read_b128 v[48:51], v175 offset:32768
	ds_read_b128 v[56:59], v175 offset:33792
	ds_read_b128 v[236:239], v177 offset:32768
	ds_read_b128 v[240:243], v177 offset:33792
	s_waitcnt vmcnt(2)
	s_barrier
; #define LDA(dst,b,h) _Pragma("unroll") for(int m=0;m<4;++m) _Pragma("unroll") for(int k=0;k<2;++k) \
;     dst[m][k]=*reinterpret_cast<const bf16x8*>((char*)SA(b,h)+lds_byte(wr*64+m*16+fr,k*32+fq*8))
; #define LDB(dst,b,h) _Pragma("unroll") for(int n=0;n<2;++n) _Pragma("unroll") for(int k=0;k<2;++k) \
;     dst[n][k]=*reinterpret_cast<const bf16x8*>((char*)SB(b,h)+lds_byte(wc*32+n*16+fr,k*32+fq*8))
; #define MMA(ai,bj,At_,Bt_) do{__builtin_amdgcn_s_setprio(1); \
;     _Pragma("unroll") for(int m=0;m<4;++m) _Pragma("unroll") for(int n=0;n<2;++n) _Pragma("unroll") for(int k=0;k<2;++k) \
;       acc[ai][bj][m][n]=__builtin_amdgcn_mfma_f32_16x16x32_bf16(Bt_[n][k],At_[m][k],acc[ai][bj][m][n],0,0,0); \
;     __builtin_amdgcn_s_setprio(0);}while(0)
; #define WAIT_V(n) asm volatile("s_waitcnt vmcnt(" #n ")":::"memory")
; #define WAIT_L(n) asm volatile("s_waitcnt lgkmcnt(" #n ")":::"memory")
; #define BAR __builtin_amdgcn_s_barrier()
; DEVINL void gemm8_mainloop(const u16* A, long lda, const u16* Bt, long ldb, int K, int brow, int bcol, f32x4 (&acc)[2][2][4][2], char* smem, int tid) {
;     ...
;   { LDB(B0,1,0); LDA(At,1,0); WAIT_V(2); BAR; WAIT_L(0); MMA(0,0,At,B0); BAR;
;     LDB(B1,1,1); WAIT_V(0); BAR; WAIT_L(0); MMA(0,1,At,B1); BAR;
;     LDA(At,1,1); BAR; WAIT_L(0); MMA(1,0,At,B0); MMA(1,1,At,B1); BAR; }
;   if(wr==0)BAR;
	s_waitcnt lgkmcnt(0)
	s_nop 0
	v_mfma_f32_16x16x32_bf16 v[64:67], v[0:3], v[16:19], v[124:127]
	v_mfma_f32_16x16x32_bf16 v[116:119], v[8:11], v[24:27], v[64:67]
	v_mfma_f32_16x16x32_bf16 v[64:67], v[208:211], v[16:19], v[120:123]
	v_mfma_f32_16x16x32_bf16 v[112:115], v[212:215], v[24:27], v[64:67]
	v_mfma_f32_16x16x32_bf16 v[64:67], v[0:3], v[32:35], v[140:143]
	v_mfma_f32_16x16x32_bf16 v[100:103], v[8:11], v[36:39], v[64:67]
	v_mfma_f32_16x16x32_bf16 v[64:67], v[208:211], v[32:35], v[220:223]
	v_mfma_f32_16x16x32_bf16 v[96:99], v[212:215], v[36:39], v[64:67]
	v_mfma_f32_16x16x32_bf16 v[64:67], v[0:3], v[48:51], v[108:111]
	v_mfma_f32_16x16x32_bf16 v[84:87], v[8:11], v[56:59], v[64:67]
	v_mfma_f32_16x16x32_bf16 v[64:67], v[208:211], v[48:51], v[104:107]
	v_mfma_f32_16x16x32_bf16 v[80:83], v[212:215], v[56:59], v[64:67]
	v_mfma_f32_16x16x32_bf16 v[64:67], v[0:3], v[236:239], v[224:227]
	v_mfma_f32_16x16x32_bf16 v[68:71], v[8:11], v[240:243], v[64:67]
	v_mfma_f32_16x16x32_bf16 v[64:67], v[208:211], v[236:239], v[228:231]
	v_mfma_f32_16x16x32_bf16 v[64:67], v[212:215], v[240:243], v[64:67]
	s_nop 0
	s_barrier
	ds_read_b128 v[140:143], v152
	ds_read_b128 v[220:223], v152 offset:1024
	ds_read_b128 v[224:227], v152 offset:2048
	ds_read_b128 v[152:155], v152 offset:3072
	s_waitcnt vmcnt(0)
	s_barrier
	s_waitcnt lgkmcnt(0)
	s_nop 0
	v_mfma_f32_16x16x32_bf16 v[92:95], v[140:143], v[16:19], v[92:95]
	v_mfma_f32_16x16x32_bf16 v[16:19], v[224:227], v[16:19], v[88:91]
	v_mfma_f32_16x16x32_bf16 v[120:123], v[152:155], v[24:27], v[16:19]
	v_mfma_f32_16x16x32_bf16 v[16:19], v[140:143], v[32:35], v[156:159]
	v_mfma_f32_16x16x32_bf16 v[104:107], v[220:223], v[36:39], v[16:19]
	v_mfma_f32_16x16x32_bf16 v[16:19], v[224:227], v[32:35], v[188:191]
	v_mfma_f32_16x16x32_bf16 v[108:111], v[152:155], v[36:39], v[16:19]
	v_mfma_f32_16x16x32_bf16 v[16:19], v[140:143], v[48:51], v[76:79]
	v_mfma_f32_16x16x32_bf16 v[124:127], v[220:223], v[24:27], v[92:95]
	v_mfma_f32_16x16x32_bf16 v[92:95], v[220:223], v[56:59], v[16:19]
	v_mfma_f32_16x16x32_bf16 v[16:19], v[224:227], v[48:51], v[72:75]
	v_mfma_f32_16x16x32_bf16 v[88:91], v[152:155], v[56:59], v[16:19]
	v_mfma_f32_16x16x32_bf16 v[16:19], v[140:143], v[236:239], v[192:195]
	v_mfma_f32_16x16x32_bf16 v[72:75], v[220:223], v[240:243], v[16:19]
	v_mfma_f32_16x16x32_bf16 v[16:19], v[224:227], v[236:239], v[196:199]
	v_mfma_f32_16x16x32_bf16 v[76:79], v[152:155], v[240:243], v[16:19]
	s_nop 0
	s_barrier
	ds_read_b128 v[156:159], v131 offset:49152
	ds_read_b128 v[186:189], v131 offset:50176
	ds_read_b128 v[190:193], v174 offset:49152
	ds_read_b128 v[194:197], v174 offset:50176
	ds_read_b128 v[228:231], v175 offset:49152
	ds_read_b128 v[236:239], v175 offset:50176
	ds_read_b128 v[240:243], v177 offset:49152
	ds_read_b128 v[244:247], v177 offset:50176
	s_barrier
	s_waitcnt lgkmcnt(0)
	s_nop 0
	v_mfma_f32_16x16x32_bf16 v[16:19], v[0:3], v[156:159], v[60:63]
	v_mfma_f32_16x16x32_bf16 v[56:59], v[8:11], v[186:189], v[16:19]
	v_mfma_f32_16x16x32_bf16 v[16:19], v[208:211], v[156:159], v[216:219]
	v_mfma_f32_16x16x32_bf16 v[48:51], v[212:215], v[186:189], v[16:19]
	v_mfma_f32_16x16x32_bf16 v[16:19], v[0:3], v[190:193], v[52:55]
	v_mfma_f32_16x16x32_bf16 v[36:39], v[8:11], v[194:197], v[16:19]
	v_mfma_f32_16x16x32_bf16 v[16:19], v[208:211], v[190:193], v[232:235]
	v_mfma_f32_16x16x32_bf16 v[32:35], v[212:215], v[194:197], v[16:19]
	v_mfma_f32_16x16x32_bf16 v[16:19], v[0:3], v[228:231], v[44:47]
	v_mfma_f32_16x16x32_bf16 v[0:3], v[0:3], v[240:243], v[144:147]
	v_mfma_f32_16x16x32_bf16 v[24:27], v[8:11], v[236:239], v[16:19]
	v_mfma_f32_16x16x32_bf16 v[16:19], v[208:211], v[228:231], v[40:43]
	v_mfma_f32_16x16x32_bf16 v[8:11], v[8:11], v[244:247], v[0:3]
	v_mfma_f32_16x16x32_bf16 v[0:3], v[208:211], v[240:243], v[148:151]
	v_mfma_f32_16x16x32_bf16 v[16:19], v[212:215], v[236:239], v[16:19]
	v_mfma_f32_16x16x32_bf16 v[0:3], v[212:215], v[244:247], v[0:3]
	s_nop 0
	s_nop 0
	v_mfma_f32_16x16x32_bf16 v[28:31], v[140:143], v[156:159], v[28:31]
	v_mfma_f32_16x16x32_bf16 v[60:63], v[220:223], v[186:189], v[28:31]
	v_mfma_f32_16x16x32_bf16 v[28:31], v[224:227], v[156:159], v[178:181]
	v_mfma_f32_16x16x32_bf16 v[20:23], v[140:143], v[190:193], v[20:23]
	v_mfma_f32_16x16x32_bf16 v[12:15], v[140:143], v[228:231], v[12:15]
	v_mfma_f32_16x16x32_bf16 v[52:55], v[152:155], v[186:189], v[28:31]
	v_mfma_f32_16x16x32_bf16 v[40:43], v[220:223], v[194:197], v[20:23]
	v_mfma_f32_16x16x32_bf16 v[20:23], v[224:227], v[190:193], v[182:185]
	v_mfma_f32_16x16x32_bf16 v[28:31], v[220:223], v[236:239], v[12:15]
	v_mfma_f32_16x16x32_bf16 v[12:15], v[224:227], v[228:231], v[200:203]
	v_mfma_f32_16x16x32_bf16 v[4:7], v[140:143], v[240:243], v[4:7]
	v_mfma_f32_16x16x32_bf16 v[44:47], v[152:155], v[194:197], v[20:23]
	v_mfma_f32_16x16x32_bf16 v[20:23], v[152:155], v[236:239], v[12:15]
	v_mfma_f32_16x16x32_bf16 v[12:15], v[220:223], v[244:247], v[4:7]
	v_mfma_f32_16x16x32_bf16 v[4:7], v[224:227], v[240:243], v[204:207]
	v_mfma_f32_16x16x32_bf16 v[4:7], v[152:155], v[244:247], v[4:7]
	s_setprio 0
	s_cmpk_gt_u32 s44, 0xff
	s_barrier
	s_cbranch_scc1 .LBB0_272
	s_barrier

; #define WAIT_V(n) asm volatile("s_waitcnt vmcnt(" #n ")":::"memory")
; #define BAR __builtin_amdgcn_s_barrier()
; DEVINL void gemm8_mainloop(const u16* A, long lda, const u16* Bt, long ldb, int K, int brow, int bcol, f32x4 (&acc)[2][2][4][2], char* smem, int tid) {
;     ...
;   if(wr==1)BAR;
;   WAIT_V(4); BAR;
.LBB0_846:
	v_mov_b32_e32 v151, v176
	s_nop 0
	v_readfirstlane_b32 s31, v151
	s_ashr_i32 s0, s31, 8
	s_cmp_lg_u32 s0, 1
	s_cbranch_scc1 .LBB0_848
	s_setprio 1
	s_barrier

; #define STAGE(P,BASE,LD,br,kt) do{long _g=(long)(br)*(LD)+(long)(kt)*BK; \
;     _Pragma("unroll") for(int _i=0;_i<2;++_i){int _b=tid*16+_i*8192;int _r,_c;stage_rc(_b,_r,_c); \
;       __builtin_amdgcn_global_load_lds((const unsigned*)((BASE)+_g+(long)_r*(LD)+_c), \
;         (unsigned*)((char*)(P)+_b),16,0,0);}}while(0)
; #define STAGE(P,BASE,LD,br,kt) do{long _g=(long)(br)*(LD)+(long)(kt)*BK; \
;     _Pragma("unroll") for(int _i=0;_i<2;++_i){int _b=tid*16+_i*8192;int _r,_c;stage_rc(_b,_r,_c); \
;       __builtin_amdgcn_global_load_lds((const unsigned*)((BASE)+_g+(long)_r*(LD)+_c), \
;         (unsigned*)((char*)(P)+_b),16,0,0);}}while(0)
; #define LDA(dst,b,h) _Pragma("unroll") for(int m=0;m<4;++m) _Pragma("unroll") for(int k=0;k<2;++k) \
;     dst[m][k]=*reinterpret_cast<const bf16x8*>((char*)SA(b,h)+lds_byte(wr*64+m*16+fr,k*32+fq*8))
; #define LDB(dst,b,h) _Pragma("unroll") for(int n=0;n<2;++n) _Pragma("unroll") for(int k=0;k<2;++k) \
;     dst[n][k]=*reinterpret_cast<const bf16x8*>((char*)SB(b,h)+lds_byte(wc*32+n*16+fr,k*32+fq*8))
; #define MMA(ai,bj,At_,Bt_) do{__builtin_amdgcn_s_setprio(1); \
;     _Pragma("unroll") for(int m=0;m<4;++m) _Pragma("unroll") for(int n=0;n<2;++n) _Pragma("unroll") for(int k=0;k<2;++k) \
;       acc[ai][bj][m][n]=__builtin_amdgcn_mfma_f32_16x16x32_bf16(Bt_[n][k],At_[m][k],acc[ai][bj][m][n],0,0,0); \
;     __builtin_amdgcn_s_setprio(0);}while(0)
; #define WAIT_L(n) asm volatile("s_waitcnt lgkmcnt(" #n ")":::"memory")
; #define BAR __builtin_amdgcn_s_barrier()
; #define SCHED __builtin_amdgcn_sched_barrier(0)
; DEVINL void gemm8_mainloop(const u16* A, long lda, const u16* Bt, long ldb, int K, int brow, int bcol, f32x4 (&acc)[2][2][4][2], char* smem, int tid) {
;     ...
;     LDB(B0,0,0); SCHED; LDA(At,0,0); STAGE(SA(1,1),A,lda,brow+HALF,t+1);
;     WAIT_L(8); BAR; WAIT_L(0); MMA(0,0,At,B0); BAR; SCHED;
;     LDB(B1,0,1); STAGE(SB(0,0),Bt,ldb,bcol,t+2);
;     BAR; WAIT_L(0); MMA(0,1,At,B1); BAR;
;     LDA(At,0,1); STAGE(SA(0,0),A,lda,brow,t+2);
;     BAR; WAIT_L(0); MMA(1,0,At,B0); BAR; SCHED;
.LBB0_849:
	ds_read_b128 v[178:181], v163
	ds_read_b128 v[182:185], v163 offset:1024
	ds_read_b128 v[186:189], v163 offset:2048
	ds_read_b128 v[190:193], v163 offset:3072
	v_add_u32_e32 v174, 0xc000, v152
	v_lshl_add_u64 v[242:243], s[94:95], 0, v[146:147]
	v_readfirstlane_b32 s27, v174
	v_add_u32_e32 v175, 0xe000, v152
	v_add_u32_e32 v171, s0, v162
	v_add_u32_e32 v172, s1, v162
	v_add_u32_e32 v173, s29, v162
	v_lshl_add_u64 v[164:165], v[242:243], 0, s[4:5]
	s_mov_b32 m0, s27
	v_lshl_add_u64 v[244:245], s[94:95], 0, v[148:149]
	v_readfirstlane_b32 s27, v175
	ds_read_b128 v[166:169], v153
	ds_read_b128 v[194:197], v153 offset:1024
	ds_read_b128 v[198:201], v171
	ds_read_b128 v[202:205], v171 offset:1024
	ds_read_b128 v[206:209], v172
	ds_read_b128 v[210:213], v172 offset:1024
	ds_read_b128 v[214:217], v173
	ds_read_b128 v[218:221], v173 offset:1024
	global_load_lds_dwordx4 v[164:165], off
	v_lshl_add_u64 v[164:165], v[244:245], 0, s[4:5]
	s_mov_b32 m0, s27
	s_nop 0
	global_load_lds_dwordx4 v[164:165], off
	s_waitcnt lgkmcnt(8)
	s_barrier
	s_waitcnt lgkmcnt(0)
	s_nop 0
	v_mfma_f32_16x16x32_bf16 v[124:127], v[178:181], v[166:169], v[124:127]
	v_mfma_f32_16x16x32_bf16 v[120:123], v[186:189], v[166:169], v[120:123]
	v_mfma_f32_16x16x32_bf16 v[116:119], v[178:181], v[198:201], v[116:119]
	v_mfma_f32_16x16x32_bf16 v[112:115], v[186:189], v[198:201], v[112:115]
	v_mfma_f32_16x16x32_bf16 v[108:111], v[178:181], v[206:209], v[108:111]
	v_mfma_f32_16x16x32_bf16 v[104:107], v[186:189], v[206:209], v[104:107]
	v_mfma_f32_16x16x32_bf16 v[100:103], v[178:181], v[214:217], v[100:103]
	v_mfma_f32_16x16x32_bf16 v[96:99], v[186:189], v[214:217], v[96:99]
	v_mfma_f32_16x16x32_bf16 v[124:127], v[182:185], v[194:197], v[124:127]
	v_mfma_f32_16x16x32_bf16 v[120:123], v[190:193], v[194:197], v[120:123]
	v_mfma_f32_16x16x32_bf16 v[116:119], v[182:185], v[202:205], v[116:119]
	v_mfma_f32_16x16x32_bf16 v[112:115], v[190:193], v[202:205], v[112:115]
	v_mfma_f32_16x16x32_bf16 v[108:111], v[182:185], v[210:213], v[108:111]
	v_mfma_f32_16x16x32_bf16 v[104:107], v[190:193], v[210:213], v[104:107]
	v_mfma_f32_16x16x32_bf16 v[100:103], v[182:185], v[218:221], v[100:103]
	v_mfma_f32_16x16x32_bf16 v[96:99], v[190:193], v[218:221], v[96:99]
	s_nop 0
	s_barrier
	v_add_u32_e32 v164, s33, v154
	v_lshl_add_u64 v[246:247], s[94:95], 0, v[142:143]
	v_readfirstlane_b32 s27, v164
	v_add_u32_e32 v165, 0x2000, v164
	v_lshl_add_u64 v[238:239], v[246:247], 0, s[6:7]
	s_mov_b32 m0, s27
	v_lshl_add_u64 v[248:249], s[94:95], 0, v[144:145]
	v_readfirstlane_b32 s27, v165
	ds_read_b128 v[222:225], v160
	ds_read_b128 v[226:229], v160 offset:1024
	ds_read_b128 v[230:233], v160 offset:2048
	ds_read_b128 v[234:237], v160 offset:3072
	global_load_lds_dwordx4 v[238:239], off
	v_lshl_add_u64 v[238:239], v[248:249], 0, s[6:7]
	s_mov_b32 m0, s27
	s_nop 0
	global_load_lds_dwordx4 v[238:239], off
	s_barrier
	s_waitcnt lgkmcnt(0)
	s_nop 0
	v_mfma_f32_16x16x32_bf16 v[92:95], v[222:225], v[166:169], v[92:95]
	v_mfma_f32_16x16x32_bf16 v[88:91], v[230:233], v[166:169], v[88:91]
	v_mfma_f32_16x16x32_bf16 v[84:87], v[222:225], v[198:201], v[84:87]
	v_mfma_f32_16x16x32_bf16 v[80:83], v[230:233], v[198:201], v[80:83]
	v_mfma_f32_16x16x32_bf16 v[76:79], v[222:225], v[206:209], v[76:79]
	v_mfma_f32_16x16x32_bf16 v[72:75], v[230:233], v[206:209], v[72:75]
	v_mfma_f32_16x16x32_bf16 v[68:71], v[222:225], v[214:217], v[68:71]
	v_mfma_f32_16x16x32_bf16 v[64:67], v[230:233], v[214:217], v[64:67]
	v_mfma_f32_16x16x32_bf16 v[92:95], v[226:229], v[194:197], v[92:95]
	v_mfma_f32_16x16x32_bf16 v[88:91], v[234:237], v[194:197], v[88:91]
	v_mfma_f32_16x16x32_bf16 v[84:87], v[226:229], v[202:205], v[84:87]
	v_mfma_f32_16x16x32_bf16 v[80:83], v[234:237], v[202:205], v[80:83]
	v_mfma_f32_16x16x32_bf16 v[76:79], v[226:229], v[210:213], v[76:79]
	v_mfma_f32_16x16x32_bf16 v[72:75], v[234:237], v[210:213], v[72:75]
	v_mfma_f32_16x16x32_bf16 v[68:71], v[226:229], v[218:221], v[68:71]
	v_mfma_f32_16x16x32_bf16 v[64:67], v[234:237], v[218:221], v[64:67]
	s_nop 0
	v_readfirstlane_b32 s27, v152
	v_lshl_add_u64 v[166:167], v[242:243], 0, s[8:9]
	s_mov_b32 m0, s27
	s_barrier
	ds_read_b128 v[194:197], v153 offset:16384
	ds_read_b128 v[198:201], v153 offset:17408
	ds_read_b128 v[202:205], v171 offset:16384
	ds_read_b128 v[206:209], v171 offset:17408
	ds_read_b128 v[210:213], v172 offset:16384
	ds_read_b128 v[214:217], v172 offset:17408
	ds_read_b128 v[218:221], v173 offset:16384
	ds_read_b128 v[238:241], v173 offset:17408
	global_load_lds_dwordx4 v[166:167], off
	v_add_u32_e32 v166, 0x2000, v152
	v_lshl_add_u64 v[168:169], v[244:245], 0, s[8:9]
	v_readfirstlane_b32 s27, v166
	s_mov_b32 m0, s27
	s_nop 0
	global_load_lds_dwordx4 v[168:169], off
	s_barrier
	s_waitcnt lgkmcnt(0)
	s_nop 0
	v_mfma_f32_16x16x32_bf16 v[60:63], v[178:181], v[194:197], v[60:63]
	v_mfma_f32_16x16x32_bf16 v[56:59], v[186:189], v[194:197], v[56:59]
	v_mfma_f32_16x16x32_bf16 v[52:55], v[178:181], v[202:205], v[52:55]
	v_mfma_f32_16x16x32_bf16 v[48:51], v[186:189], v[202:205], v[48:51]
	v_mfma_f32_16x16x32_bf16 v[44:47], v[178:181], v[210:213], v[44:47]
	v_mfma_f32_16x16x32_bf16 v[40:43], v[186:189], v[210:213], v[40:43]
	v_mfma_f32_16x16x32_bf16 v[36:39], v[178:181], v[218:221], v[36:39]
	v_mfma_f32_16x16x32_bf16 v[32:35], v[186:189], v[218:221], v[32:35]
	v_mfma_f32_16x16x32_bf16 v[60:63], v[182:185], v[198:201], v[60:63]
	v_mfma_f32_16x16x32_bf16 v[56:59], v[190:193], v[198:201], v[56:59]
	v_mfma_f32_16x16x32_bf16 v[52:55], v[182:185], v[206:209], v[52:55]
	v_mfma_f32_16x16x32_bf16 v[48:51], v[190:193], v[206:209], v[48:51]
	v_mfma_f32_16x16x32_bf16 v[44:47], v[182:185], v[214:217], v[44:47]
	v_mfma_f32_16x16x32_bf16 v[40:43], v[190:193], v[214:217], v[40:43]
	v_mfma_f32_16x16x32_bf16 v[36:39], v[182:185], v[238:241], v[36:39]
	v_mfma_f32_16x16x32_bf16 v[32:35], v[190:193], v[238:241], v[32:35]
	s_nop 0
	s_barrier
; #define STAGE(P,BASE,LD,br,kt) do{long _g=(long)(br)*(LD)+(long)(kt)*BK; \
;     _Pragma("unroll") for(int _i=0;_i<2;++_i){int _b=tid*16+_i*8192;int _r,_c;stage_rc(_b,_r,_c); \
;       __builtin_amdgcn_global_load_lds((const unsigned*)((BASE)+_g+(long)_r*(LD)+_c), \
;         (unsigned*)((char*)(P)+_b),16,0,0);}}while(0)
; #define STAGE(P,BASE,LD,br,kt) do{long _g=(long)(br)*(LD)+(long)(kt)*BK; \
;     _Pragma("unroll") for(int _i=0;_i<2;++_i){int _b=tid*16+_i*8192;int _r,_c;stage_rc(_b,_r,_c); \
;       __builtin_amdgcn_global_load_lds((const unsigned*)((BASE)+_g+(long)_r*(LD)+_c), \
;         (unsigned*)((char*)(P)+_b),16,0,0);}}while(0)
; #define LDA(dst,b,h) _Pragma("unroll") for(int m=0;m<4;++m) _Pragma("unroll") for(int k=0;k<2;++k) \
;     dst[m][k]=*reinterpret_cast<const bf16x8*>((char*)SA(b,h)+lds_byte(wr*64+m*16+fr,k*32+fq*8))
; #define LDB(dst,b,h) _Pragma("unroll") for(int n=0;n<2;++n) _Pragma("unroll") for(int k=0;k<2;++k) \
;     dst[n][k]=*reinterpret_cast<const bf16x8*>((char*)SB(b,h)+lds_byte(wc*32+n*16+fr,k*32+fq*8))
; #define MMA(ai,bj,At_,Bt_) do{__builtin_amdgcn_s_setprio(1); \
;     _Pragma("unroll") for(int m=0;m<4;++m) _Pragma("unroll") for(int n=0;n<2;++n) _Pragma("unroll") for(int k=0;k<2;++k) \
;       acc[ai][bj][m][n]=__builtin_amdgcn_mfma_f32_16x16x32_bf16(Bt_[n][k],At_[m][k],acc[ai][bj][m][n],0,0,0); \
;     __builtin_amdgcn_s_setprio(0);}while(0)
; #define WAIT_V(n) asm volatile("s_waitcnt vmcnt(" #n ")":::"memory")
; #define WAIT_L(n) asm volatile("s_waitcnt lgkmcnt(" #n ")":::"memory")
; #define BAR __builtin_amdgcn_s_barrier()
; #define SCHED __builtin_amdgcn_sched_barrier(0)
; DEVINL void gemm8_mainloop(const u16* A, long lda, const u16* Bt, long ldb, int K, int brow, int bcol, f32x4 (&acc)[2][2][4][2], char* smem, int tid) {
;     ...
;     STAGE(SB(0,1),Bt,ldb,bcol+HALF,t+2);
;     WAIT_V(6); BAR; MMA(1,1,At,B1); BAR;
;     LDB(B0,1,0); SCHED; LDA(At,1,0); STAGE(SA(0,1),A,lda,brow+HALF,t+2);
;     WAIT_L(8); BAR; WAIT_L(0); MMA(0,0,At,B0); BAR; SCHED;
;     LDB(B1,1,1); STAGE(SB(1,0),Bt,ldb,bcol,t+3);
	v_add_u32_e32 v167, s34, v154
	v_lshl_add_u64 v[168:169], v[246:247], 0, s[10:11]
	v_readfirstlane_b32 s27, v167
	s_mov_b32 m0, s27
	v_lshl_add_u64 v[178:179], v[248:249], 0, s[10:11]
	global_load_lds_dwordx4 v[168:169], off
	v_add_u32_e32 v168, 0x2000, v167
	s_nop 0
	v_readfirstlane_b32 s27, v168
	s_mov_b32 m0, s27
	s_nop 0
	global_load_lds_dwordx4 v[178:179], off
	s_waitcnt vmcnt(6)
	s_barrier
	s_nop 0
	v_mfma_f32_16x16x32_bf16 v[28:31], v[222:225], v[194:197], v[28:31]
	v_mfma_f32_16x16x32_bf16 v[24:27], v[230:233], v[194:197], v[24:27]
	v_mfma_f32_16x16x32_bf16 v[20:23], v[222:225], v[202:205], v[20:23]
	v_mfma_f32_16x16x32_bf16 v[16:19], v[230:233], v[202:205], v[16:19]
	v_mfma_f32_16x16x32_bf16 v[12:15], v[222:225], v[210:213], v[12:15]
	v_mfma_f32_16x16x32_bf16 v[8:11], v[230:233], v[210:213], v[8:11]
	v_mfma_f32_16x16x32_bf16 v[4:7], v[222:225], v[218:221], v[4:7]
	v_mfma_f32_16x16x32_bf16 v[0:3], v[230:233], v[218:221], v[0:3]
	v_mfma_f32_16x16x32_bf16 v[28:31], v[226:229], v[198:201], v[28:31]
	v_mfma_f32_16x16x32_bf16 v[24:27], v[234:237], v[198:201], v[24:27]
	v_mfma_f32_16x16x32_bf16 v[20:23], v[226:229], v[206:209], v[20:23]
	v_mfma_f32_16x16x32_bf16 v[16:19], v[234:237], v[206:209], v[16:19]
	v_mfma_f32_16x16x32_bf16 v[12:15], v[226:229], v[214:217], v[12:15]
	v_mfma_f32_16x16x32_bf16 v[8:11], v[234:237], v[214:217], v[8:11]
	v_mfma_f32_16x16x32_bf16 v[4:7], v[226:229], v[238:241], v[4:7]
	v_mfma_f32_16x16x32_bf16 v[0:3], v[234:237], v[238:241], v[0:3]
	s_nop 0
	s_barrier
	ds_read_b128 v[178:181], v157
	ds_read_b128 v[182:185], v157 offset:1024
	ds_read_b128 v[186:189], v157 offset:2048
	ds_read_b128 v[190:193], v157 offset:3072
	v_add_u32_e32 v169, 0x4000, v152
	v_add_u32_e32 v170, 0x6000, v152
	v_readfirstlane_b32 s27, v169
	v_lshl_add_u64 v[226:227], v[242:243], 0, s[12:13]
	s_mov_b32 m0, s27
	v_readfirstlane_b32 s27, v170
	ds_read_b128 v[194:197], v153 offset:32768
	ds_read_b128 v[198:201], v153 offset:33792
	ds_read_b128 v[202:205], v171 offset:32768
	ds_read_b128 v[206:209], v171 offset:33792
	ds_read_b128 v[210:213], v172 offset:32768
	ds_read_b128 v[214:217], v172 offset:33792
	ds_read_b128 v[218:221], v173 offset:32768
	ds_read_b128 v[222:225], v173 offset:33792
	global_load_lds_dwordx4 v[226:227], off
	v_lshl_add_u64 v[226:227], v[244:245], 0, s[12:13]
	s_mov_b32 m0, s27
	s_nop 0
	global_load_lds_dwordx4 v[226:227], off
	s_waitcnt lgkmcnt(8)
	s_barrier
	s_waitcnt lgkmcnt(0)
	s_nop 0
	v_mfma_f32_16x16x32_bf16 v[124:127], v[178:181], v[194:197], v[124:127]
	v_mfma_f32_16x16x32_bf16 v[120:123], v[186:189], v[194:197], v[120:123]
	v_mfma_f32_16x16x32_bf16 v[116:119], v[178:181], v[202:205], v[116:119]
	v_mfma_f32_16x16x32_bf16 v[112:115], v[186:189], v[202:205], v[112:115]
	v_mfma_f32_16x16x32_bf16 v[108:111], v[178:181], v[210:213], v[108:111]
	v_mfma_f32_16x16x32_bf16 v[104:107], v[186:189], v[210:213], v[104:107]
	v_mfma_f32_16x16x32_bf16 v[100:103], v[178:181], v[218:221], v[100:103]
	v_mfma_f32_16x16x32_bf16 v[96:99], v[186:189], v[218:221], v[96:99]
	v_mfma_f32_16x16x32_bf16 v[124:127], v[182:185], v[198:201], v[124:127]
	v_mfma_f32_16x16x32_bf16 v[120:123], v[190:193], v[198:201], v[120:123]
	v_mfma_f32_16x16x32_bf16 v[116:119], v[182:185], v[206:209], v[116:119]
	v_mfma_f32_16x16x32_bf16 v[112:115], v[190:193], v[206:209], v[112:115]
	v_mfma_f32_16x16x32_bf16 v[108:111], v[182:185], v[214:217], v[108:111]
	v_mfma_f32_16x16x32_bf16 v[104:107], v[190:193], v[214:217], v[104:107]
	v_mfma_f32_16x16x32_bf16 v[100:103], v[182:185], v[222:225], v[100:103]
	v_mfma_f32_16x16x32_bf16 v[96:99], v[190:193], v[222:225], v[96:99]
	s_nop 0
	s_barrier
	v_readfirstlane_b32 s27, v156
	v_add_u32_e32 v177, 0x2000, v156
	v_lshl_add_u64 v[250:251], v[246:247], 0, s[14:15]
	s_mov_b32 m0, s27
	v_readfirstlane_b32 s27, v177
	ds_read_b128 v[226:229], v155
	ds_read_b128 v[230:233], v155 offset:1024
	ds_read_b128 v[234:237], v155 offset:2048
	ds_read_b128 v[238:241], v155 offset:3072
	global_load_lds_dwordx4 v[250:251], off
	v_lshl_add_u64 v[250:251], v[248:249], 0, s[14:15]
	s_mov_b32 m0, s27
	s_nop 0
	global_load_lds_dwordx4 v[250:251], off
	s_barrier
	s_waitcnt lgkmcnt(0)
	s_nop 0
	v_mfma_f32_16x16x32_bf16 v[92:95], v[226:229], v[194:197], v[92:95]
	v_mfma_f32_16x16x32_bf16 v[88:91], v[234:237], v[194:197], v[88:91]
	v_mfma_f32_16x16x32_bf16 v[84:87], v[226:229], v[202:205], v[84:87]
	v_mfma_f32_16x16x32_bf16 v[80:83], v[234:237], v[202:205], v[80:83]
	v_mfma_f32_16x16x32_bf16 v[76:79], v[226:229], v[210:213], v[76:79]
	v_mfma_f32_16x16x32_bf16 v[72:75], v[234:237], v[210:213], v[72:75]
	v_mfma_f32_16x16x32_bf16 v[68:71], v[226:229], v[218:221], v[68:71]
	v_mfma_f32_16x16x32_bf16 v[64:67], v[234:237], v[218:221], v[64:67]
	v_mfma_f32_16x16x32_bf16 v[92:95], v[230:233], v[198:201], v[92:95]
	v_mfma_f32_16x16x32_bf16 v[88:91], v[238:241], v[198:201], v[88:91]
	v_mfma_f32_16x16x32_bf16 v[84:87], v[230:233], v[206:209], v[84:87]
	v_mfma_f32_16x16x32_bf16 v[80:83], v[238:241], v[206:209], v[80:83]
	v_mfma_f32_16x16x32_bf16 v[76:79], v[230:233], v[214:217], v[76:79]
	v_mfma_f32_16x16x32_bf16 v[72:75], v[238:241], v[214:217], v[72:75]
	v_mfma_f32_16x16x32_bf16 v[68:71], v[230:233], v[222:225], v[68:71]
	v_mfma_f32_16x16x32_bf16 v[64:67], v[238:241], v[222:225], v[64:67]
	s_nop 0
	v_readfirstlane_b32 s27, v158
	v_lshl_add_u64 v[242:243], v[242:243], 0, s[16:17]
	s_mov_b32 m0, s27
	v_readfirstlane_b32 s27, v159
	s_barrier
; #define STAGE(P,BASE,LD,br,kt) do{long _g=(long)(br)*(LD)+(long)(kt)*BK; \
;     _Pragma("unroll") for(int _i=0;_i<2;++_i){int _b=tid*16+_i*8192;int _r,_c;stage_rc(_b,_r,_c); \
;       __builtin_amdgcn_global_load_lds((const unsigned*)((BASE)+_g+(long)_r*(LD)+_c), \
;         (unsigned*)((char*)(P)+_b),16,0,0);}}while(0)
; #define STAGE(P,BASE,LD,br,kt) do{long _g=(long)(br)*(LD)+(long)(kt)*BK; \
;     _Pragma("unroll") for(int _i=0;_i<2;++_i){int _b=tid*16+_i*8192;int _r,_c;stage_rc(_b,_r,_c); \
;       __builtin_amdgcn_global_load_lds((const unsigned*)((BASE)+_g+(long)_r*(LD)+_c), \
;         (unsigned*)((char*)(P)+_b),16,0,0);}}while(0)
; #define LDA(dst,b,h) _Pragma("unroll") for(int m=0;m<4;++m) _Pragma("unroll") for(int k=0;k<2;++k) \
;     dst[m][k]=*reinterpret_cast<const bf16x8*>((char*)SA(b,h)+lds_byte(wr*64+m*16+fr,k*32+fq*8))
; #define LDB(dst,b,h) _Pragma("unroll") for(int n=0;n<2;++n) _Pragma("unroll") for(int k=0;k<2;++k) \
;     dst[n][k]=*reinterpret_cast<const bf16x8*>((char*)SB(b,h)+lds_byte(wc*32+n*16+fr,k*32+fq*8))
; #define MMA(ai,bj,At_,Bt_) do{__builtin_amdgcn_s_setprio(1); \
;     _Pragma("unroll") for(int m=0;m<4;++m) _Pragma("unroll") for(int n=0;n<2;++n) _Pragma("unroll") for(int k=0;k<2;++k) \
;       acc[ai][bj][m][n]=__builtin_amdgcn_mfma_f32_16x16x32_bf16(Bt_[n][k],At_[m][k],acc[ai][bj][m][n],0,0,0); \
;     __builtin_amdgcn_s_setprio(0);}while(0)
; #define WAIT_V(n) asm volatile("s_waitcnt vmcnt(" #n ")":::"memory")
; #define WAIT_L(n) asm volatile("s_waitcnt lgkmcnt(" #n ")":::"memory")
; #define BAR __builtin_amdgcn_s_barrier()
; #define SCHED __builtin_amdgcn_sched_barrier(0)
; DEVINL void gemm8_mainloop(const u16* A, long lda, const u16* Bt, long ldb, int K, int brow, int bcol, f32x4 (&acc)[2][2][4][2], char* smem, int tid) {
;     ...
;     BAR; WAIT_L(0); MMA(0,1,At,B1); BAR;
;     LDA(At,1,1); STAGE(SA(1,0),A,lda,brow,t+3);
;     BAR; WAIT_L(0); MMA(1,0,At,B0); BAR; SCHED;
;     STAGE(SB(1,1),Bt,ldb,bcol+HALF,t+3);
;     WAIT_V(6); BAR; MMA(1,1,At,B1); BAR;
;   }
;   { LDB(B0,0,0); LDA(At,0,0); STAGE(SA(1,1),A,lda,brow+HALF,nt-1);
;     BAR; WAIT_L(0); MMA(0,0,At,B0); BAR;
	ds_read_b128 v[194:197], v153 offset:49152
	ds_read_b128 v[198:201], v153 offset:50176
	ds_read_b128 v[202:205], v171 offset:49152
	ds_read_b128 v[206:209], v171 offset:50176
	ds_read_b128 v[210:213], v172 offset:49152
	ds_read_b128 v[214:217], v172 offset:50176
	ds_read_b128 v[218:221], v173 offset:49152
	ds_read_b128 v[222:225], v173 offset:50176
	global_load_lds_dwordx4 v[242:243], off
	v_lshl_add_u64 v[242:243], v[244:245], 0, s[16:17]
	s_mov_b32 m0, s27
	s_nop 0
	global_load_lds_dwordx4 v[242:243], off
	s_barrier
	s_waitcnt lgkmcnt(0)
	s_nop 0
	v_mfma_f32_16x16x32_bf16 v[60:63], v[178:181], v[194:197], v[60:63]
	v_mfma_f32_16x16x32_bf16 v[56:59], v[186:189], v[194:197], v[56:59]
	v_mfma_f32_16x16x32_bf16 v[52:55], v[178:181], v[202:205], v[52:55]
	v_mfma_f32_16x16x32_bf16 v[48:51], v[186:189], v[202:205], v[48:51]
	v_mfma_f32_16x16x32_bf16 v[44:47], v[178:181], v[210:213], v[44:47]
	v_mfma_f32_16x16x32_bf16 v[40:43], v[186:189], v[210:213], v[40:43]
	v_mfma_f32_16x16x32_bf16 v[36:39], v[178:181], v[218:221], v[36:39]
	v_mfma_f32_16x16x32_bf16 v[32:35], v[186:189], v[218:221], v[32:35]
	v_mfma_f32_16x16x32_bf16 v[60:63], v[182:185], v[198:201], v[60:63]
	v_mfma_f32_16x16x32_bf16 v[56:59], v[190:193], v[198:201], v[56:59]
	v_mfma_f32_16x16x32_bf16 v[52:55], v[182:185], v[206:209], v[52:55]
	v_mfma_f32_16x16x32_bf16 v[48:51], v[190:193], v[206:209], v[48:51]
	v_mfma_f32_16x16x32_bf16 v[44:47], v[182:185], v[214:217], v[44:47]
	v_mfma_f32_16x16x32_bf16 v[40:43], v[190:193], v[214:217], v[40:43]
	v_mfma_f32_16x16x32_bf16 v[36:39], v[182:185], v[222:225], v[36:39]
	v_mfma_f32_16x16x32_bf16 v[32:35], v[190:193], v[222:225], v[32:35]
	s_nop 0
	s_barrier
	v_readfirstlane_b32 s27, v161
	v_add_u32_e32 v177, 0x2000, v161
	v_lshl_add_u64 v[178:179], v[246:247], 0, s[18:19]
	s_mov_b32 m0, s27
	v_readfirstlane_b32 s27, v177
	global_load_lds_dwordx4 v[178:179], off
	v_lshl_add_u64 v[178:179], v[248:249], 0, s[18:19]
	s_mov_b32 m0, s27
	s_nop 0
	global_load_lds_dwordx4 v[178:179], off
	s_waitcnt vmcnt(6)
	s_barrier
	s_nop 0
	v_mfma_f32_16x16x32_bf16 v[28:31], v[226:229], v[194:197], v[28:31]
	v_mfma_f32_16x16x32_bf16 v[24:27], v[234:237], v[194:197], v[24:27]
	v_mfma_f32_16x16x32_bf16 v[20:23], v[226:229], v[202:205], v[20:23]
	v_mfma_f32_16x16x32_bf16 v[16:19], v[234:237], v[202:205], v[16:19]
	v_mfma_f32_16x16x32_bf16 v[12:15], v[226:229], v[210:213], v[12:15]
	v_mfma_f32_16x16x32_bf16 v[8:11], v[234:237], v[210:213], v[8:11]
	v_mfma_f32_16x16x32_bf16 v[4:7], v[226:229], v[218:221], v[4:7]
	v_mfma_f32_16x16x32_bf16 v[0:3], v[234:237], v[218:221], v[0:3]
	v_mfma_f32_16x16x32_bf16 v[28:31], v[230:233], v[198:201], v[28:31]
	v_mfma_f32_16x16x32_bf16 v[24:27], v[238:241], v[198:201], v[24:27]
	v_mfma_f32_16x16x32_bf16 v[20:23], v[230:233], v[206:209], v[20:23]
	v_mfma_f32_16x16x32_bf16 v[16:19], v[238:241], v[206:209], v[16:19]
	v_mfma_f32_16x16x32_bf16 v[12:15], v[230:233], v[214:217], v[12:15]
	v_mfma_f32_16x16x32_bf16 v[8:11], v[238:241], v[214:217], v[8:11]
	v_mfma_f32_16x16x32_bf16 v[4:7], v[230:233], v[222:225], v[4:7]
	v_mfma_f32_16x16x32_bf16 v[0:3], v[238:241], v[222:225], v[0:3]
	s_nop 0
	s_add_i32 s26, s26, 2
	v_lshl_add_u64 v[142:143], v[142:143], 0, s[20:21]
	v_lshl_add_u64 v[144:145], v[144:145], 0, s[20:21]
	v_lshl_add_u64 v[146:147], v[146:147], 0, s[20:21]
	s_cmp_lt_u32 s26, 28
	v_lshl_add_u64 v[148:149], v[148:149], 0, s[20:21]
	s_barrier
	s_cbranch_scc1 .LBB0_849
	s_or_b32 s0, s28, 0x80
	s_ashr_i32 s1, s0, 31
	s_lshl_b64 s[0:1], s[0:1], 12
	s_add_u32 s0, s58, s0
	s_addc_u32 s1, s59, s1
	v_lshl_add_u64 v[158:159], v[134:135], 1, s[0:1]
	v_lshl_add_u64 v[138:139], v[138:139], 1, v[158:159]
	v_readfirstlane_b32 s26, v174
	v_lshl_add_u64 v[138:139], v[138:139], 0, s[22:23]
	s_mov_b32 m0, s26
	ds_read_b128 v[142:145], v163
	ds_read_b128 v[146:149], v163 offset:1024
	ds_read_b128 v[178:181], v163 offset:2048
	ds_read_b128 v[182:185], v163 offset:3072
	ds_read_b128 v[186:189], v153
	ds_read_b128 v[190:193], v153 offset:1024
	ds_read_b128 v[194:197], v171
	ds_read_b128 v[198:201], v171 offset:1024
	ds_read_b128 v[202:205], v172
	ds_read_b128 v[206:209], v172 offset:1024
	ds_read_b128 v[210:213], v173
	ds_read_b128 v[214:217], v173 offset:1024
	global_load_lds_dwordx4 v[138:139], off
	v_lshl_add_u64 v[138:139], v[136:137], 1, s[0:1]
	v_lshl_add_u64 v[138:139], v[140:141], 1, v[138:139]
	v_readfirstlane_b32 s0, v175
	v_lshl_add_u64 v[138:139], v[138:139], 0, s[22:23]
	s_mov_b32 m0, s0
	s_nop 0
	global_load_lds_dwordx4 v[138:139], off
	s_barrier
	s_waitcnt lgkmcnt(0)
	s_nop 0
	v_mfma_f32_16x16x32_bf16 v[124:127], v[142:145], v[186:189], v[124:127]
	v_mfma_f32_16x16x32_bf16 v[120:123], v[178:181], v[186:189], v[120:123]
	v_mfma_f32_16x16x32_bf16 v[112:115], v[178:181], v[194:197], v[112:115]
	v_mfma_f32_16x16x32_bf16 v[104:107], v[178:181], v[202:205], v[104:107]
	v_mfma_f32_16x16x32_bf16 v[96:99], v[178:181], v[210:213], v[96:99]
	v_mfma_f32_16x16x32_bf16 v[124:127], v[146:149], v[190:193], v[124:127]
	v_mfma_f32_16x16x32_bf16 v[120:123], v[182:185], v[190:193], v[120:123]
	v_mfma_f32_16x16x32_bf16 v[116:119], v[142:145], v[194:197], v[116:119]
	v_mfma_f32_16x16x32_bf16 v[112:115], v[182:185], v[198:201], v[112:115]
	v_mfma_f32_16x16x32_bf16 v[108:111], v[142:145], v[202:205], v[108:111]
	v_mfma_f32_16x16x32_bf16 v[104:107], v[182:185], v[206:209], v[104:107]
	v_mfma_f32_16x16x32_bf16 v[100:103], v[142:145], v[210:213], v[100:103]
	v_mfma_f32_16x16x32_bf16 v[96:99], v[182:185], v[214:217], v[96:99]
	v_mfma_f32_16x16x32_bf16 v[138:141], v[146:149], v[198:201], v[116:119]
	v_mfma_f32_16x16x32_bf16 v[218:221], v[146:149], v[206:209], v[108:111]
	v_mfma_f32_16x16x32_bf16 v[222:225], v[146:149], v[214:217], v[100:103]
	s_nop 0
	s_barrier
; #define LDA(dst,b,h) _Pragma("unroll") for(int m=0;m<4;++m) _Pragma("unroll") for(int k=0;k<2;++k) \
;     dst[m][k]=*reinterpret_cast<const bf16x8*>((char*)SA(b,h)+lds_byte(wr*64+m*16+fr,k*32+fq*8))
; #define LDB(dst,b,h) _Pragma("unroll") for(int n=0;n<2;++n) _Pragma("unroll") for(int k=0;k<2;++k) \
;     dst[n][k]=*reinterpret_cast<const bf16x8*>((char*)SB(b,h)+lds_byte(wc*32+n*16+fr,k*32+fq*8))
; #define MMA(ai,bj,At_,Bt_) do{__builtin_amdgcn_s_setprio(1); \
;     _Pragma("unroll") for(int m=0;m<4;++m) _Pragma("unroll") for(int n=0;n<2;++n) _Pragma("unroll") for(int k=0;k<2;++k) \
;       acc[ai][bj][m][n]=__builtin_amdgcn_mfma_f32_16x16x32_bf16(Bt_[n][k],At_[m][k],acc[ai][bj][m][n],0,0,0); \
;     __builtin_amdgcn_s_setprio(0);}while(0)
; #define WAIT_V(n) asm volatile("s_waitcnt vmcnt(" #n ")":::"memory")
; #define WAIT_L(n) asm volatile("s_waitcnt lgkmcnt(" #n ")":::"memory")
; #define BAR __builtin_amdgcn_s_barrier()
; DEVINL void gemm8_mainloop(const u16* A, long lda, const u16* Bt, long ldb, int K, int brow, int bcol, f32x4 (&acc)[2][2][4][2], char* smem, int tid) {
;     ...
;     LDB(B1,0,1); BAR; WAIT_L(0); MMA(0,1,At,B1); BAR;
;     LDA(At,0,1); WAIT_V(4); BAR; WAIT_L(0); MMA(1,0,At,B0); MMA(1,1,At,B1); BAR; }
;   { LDB(B0,1,0); LDA(At,1,0); WAIT_V(2); BAR; WAIT_L(0); MMA(0,0,At,B0); BAR;
;     LDB(B1,1,1); WAIT_V(0); BAR; WAIT_L(0); MMA(0,1,At,B1); BAR;
	s_nop 1
	ds_read_b128 v[100:103], v160
	ds_read_b128 v[108:111], v160 offset:1024
	ds_read_b128 v[116:119], v160 offset:2048
	ds_read_b128 v[158:161], v160 offset:3072
	s_barrier
	s_waitcnt lgkmcnt(0)
	s_nop 0
	v_mfma_f32_16x16x32_bf16 v[88:91], v[116:119], v[186:189], v[88:91]
	v_mfma_f32_16x16x32_bf16 v[80:83], v[116:119], v[194:197], v[80:83]
	v_mfma_f32_16x16x32_bf16 v[72:75], v[116:119], v[202:205], v[72:75]
	v_mfma_f32_16x16x32_bf16 v[64:67], v[116:119], v[210:213], v[64:67]
	v_mfma_f32_16x16x32_bf16 v[92:95], v[100:103], v[186:189], v[92:95]
	v_mfma_f32_16x16x32_bf16 v[88:91], v[158:161], v[190:193], v[88:91]
	v_mfma_f32_16x16x32_bf16 v[84:87], v[100:103], v[194:197], v[84:87]
	v_mfma_f32_16x16x32_bf16 v[80:83], v[158:161], v[198:201], v[80:83]
	v_mfma_f32_16x16x32_bf16 v[76:79], v[100:103], v[202:205], v[76:79]
	v_mfma_f32_16x16x32_bf16 v[72:75], v[158:161], v[206:209], v[72:75]
	v_mfma_f32_16x16x32_bf16 v[68:71], v[100:103], v[210:213], v[68:71]
	v_mfma_f32_16x16x32_bf16 v[64:67], v[158:161], v[214:217], v[64:67]
	v_mfma_f32_16x16x32_bf16 v[226:229], v[108:111], v[190:193], v[92:95]
	v_mfma_f32_16x16x32_bf16 v[186:189], v[108:111], v[198:201], v[84:87]
	v_mfma_f32_16x16x32_bf16 v[190:193], v[108:111], v[206:209], v[76:79]
	v_mfma_f32_16x16x32_bf16 v[194:197], v[108:111], v[214:217], v[68:71]
	s_nop 0
	s_barrier
	s_nop 0
	ds_read_b128 v[68:71], v153 offset:16384
	ds_read_b128 v[76:79], v153 offset:17408
	ds_read_b128 v[84:87], v171 offset:16384
	ds_read_b128 v[92:95], v171 offset:17408
	ds_read_b128 v[198:201], v172 offset:16384
	ds_read_b128 v[202:205], v172 offset:17408
	ds_read_b128 v[206:209], v173 offset:16384
	ds_read_b128 v[210:213], v173 offset:17408
	s_waitcnt vmcnt(4)
	s_barrier
	s_waitcnt lgkmcnt(0)
	s_nop 0
	v_mfma_f32_16x16x32_bf16 v[60:63], v[142:145], v[68:71], v[60:63]
	v_mfma_f32_16x16x32_bf16 v[56:59], v[178:181], v[68:71], v[56:59]
	v_mfma_f32_16x16x32_bf16 v[52:55], v[142:145], v[84:87], v[52:55]
	v_mfma_f32_16x16x32_bf16 v[48:51], v[178:181], v[84:87], v[48:51]
	v_mfma_f32_16x16x32_bf16 v[36:39], v[142:145], v[206:209], v[36:39]
	v_mfma_f32_16x16x32_bf16 v[32:35], v[178:181], v[206:209], v[32:35]
	v_mfma_f32_16x16x32_bf16 v[60:63], v[146:149], v[76:79], v[60:63]
	v_mfma_f32_16x16x32_bf16 v[56:59], v[182:185], v[76:79], v[56:59]
	v_mfma_f32_16x16x32_bf16 v[52:55], v[146:149], v[92:95], v[52:55]
	v_mfma_f32_16x16x32_bf16 v[48:51], v[182:185], v[92:95], v[48:51]
	v_mfma_f32_16x16x32_bf16 v[44:47], v[142:145], v[198:201], v[44:47]
	v_mfma_f32_16x16x32_bf16 v[40:43], v[178:181], v[198:201], v[40:43]
	v_mfma_f32_16x16x32_bf16 v[36:39], v[146:149], v[210:213], v[36:39]
	v_mfma_f32_16x16x32_bf16 v[32:35], v[182:185], v[210:213], v[32:35]
	v_mfma_f32_16x16x32_bf16 v[214:217], v[146:149], v[202:205], v[44:47]
	v_mfma_f32_16x16x32_bf16 v[230:233], v[182:185], v[202:205], v[40:43]
	s_nop 0
	s_nop 0
	v_mfma_f32_16x16x32_bf16 v[20:23], v[100:103], v[84:87], v[20:23]
	v_mfma_f32_16x16x32_bf16 v[16:19], v[116:119], v[84:87], v[16:19]
	v_mfma_f32_16x16x32_bf16 v[4:7], v[100:103], v[206:209], v[4:7]
	v_mfma_f32_16x16x32_bf16 v[0:3], v[116:119], v[206:209], v[0:3]
	v_mfma_f32_16x16x32_bf16 v[28:31], v[100:103], v[68:71], v[28:31]
	v_mfma_f32_16x16x32_bf16 v[24:27], v[116:119], v[68:71], v[24:27]
	v_mfma_f32_16x16x32_bf16 v[20:23], v[108:111], v[92:95], v[20:23]
	v_mfma_f32_16x16x32_bf16 v[16:19], v[158:161], v[92:95], v[16:19]
	v_mfma_f32_16x16x32_bf16 v[12:15], v[100:103], v[198:201], v[12:15]
	v_mfma_f32_16x16x32_bf16 v[8:11], v[116:119], v[198:201], v[8:11]
	v_mfma_f32_16x16x32_bf16 v[4:7], v[108:111], v[210:213], v[4:7]
	v_mfma_f32_16x16x32_bf16 v[0:3], v[158:161], v[210:213], v[0:3]
	v_mfma_f32_16x16x32_bf16 v[142:145], v[108:111], v[76:79], v[28:31]
	v_mfma_f32_16x16x32_bf16 v[146:149], v[158:161], v[76:79], v[24:27]
	v_mfma_f32_16x16x32_bf16 v[178:181], v[108:111], v[202:205], v[12:15]
	v_mfma_f32_16x16x32_bf16 v[182:185], v[158:161], v[202:205], v[8:11]
	s_nop 0
	s_barrier
	s_nop 0
	ds_read_b128 v[8:11], v157
	ds_read_b128 v[12:15], v157 offset:1024
	ds_read_b128 v[158:161], v157 offset:2048
	ds_read_b128 v[198:201], v157 offset:3072
	ds_read_b128 v[24:27], v153 offset:32768
	ds_read_b128 v[28:31], v153 offset:33792
	ds_read_b128 v[40:43], v171 offset:32768
	ds_read_b128 v[44:47], v171 offset:33792
	ds_read_b128 v[202:205], v172 offset:32768
	ds_read_b128 v[206:209], v172 offset:33792
	ds_read_b128 v[210:213], v173 offset:32768
	ds_read_b128 v[234:237], v173 offset:33792
	s_waitcnt vmcnt(2)
	s_barrier
; #define LDA(dst,b,h) _Pragma("unroll") for(int m=0;m<4;++m) _Pragma("unroll") for(int k=0;k<2;++k) \
;     dst[m][k]=*reinterpret_cast<const bf16x8*>((char*)SA(b,h)+lds_byte(wr*64+m*16+fr,k*32+fq*8))
; #define LDB(dst,b,h) _Pragma("unroll") for(int n=0;n<2;++n) _Pragma("unroll") for(int k=0;k<2;++k) \
;     dst[n][k]=*reinterpret_cast<const bf16x8*>((char*)SB(b,h)+lds_byte(wc*32+n*16+fr,k*32+fq*8))
; #define MMA(ai,bj,At_,Bt_) do{__builtin_amdgcn_s_setprio(1); \
;     _Pragma("unroll") for(int m=0;m<4;++m) _Pragma("unroll") for(int n=0;n<2;++n) _Pragma("unroll") for(int k=0;k<2;++k) \
;       acc[ai][bj][m][n]=__builtin_amdgcn_mfma_f32_16x16x32_bf16(Bt_[n][k],At_[m][k],acc[ai][bj][m][n],0,0,0); \
;     __builtin_amdgcn_s_setprio(0);}while(0)
; #define WAIT_V(n) asm volatile("s_waitcnt vmcnt(" #n ")":::"memory")
; #define WAIT_L(n) asm volatile("s_waitcnt lgkmcnt(" #n ")":::"memory")
; #define BAR __builtin_amdgcn_s_barrier()
; DEVINL void gemm8_mainloop(const u16* A, long lda, const u16* Bt, long ldb, int K, int brow, int bcol, f32x4 (&acc)[2][2][4][2], char* smem, int tid) {
;     ...
;   { LDB(B0,1,0); LDA(At,1,0); WAIT_V(2); BAR; WAIT_L(0); MMA(0,0,At,B0); BAR;
;     LDB(B1,1,1); WAIT_V(0); BAR; WAIT_L(0); MMA(0,1,At,B1); BAR;
;     LDA(At,1,1); BAR; WAIT_L(0); MMA(1,0,At,B0); MMA(1,1,At,B1); BAR; }
;   if(wr==0)BAR;
	s_waitcnt lgkmcnt(0)
	s_nop 0
	v_mfma_f32_16x16x32_bf16 v[68:71], v[8:11], v[24:27], v[124:127]
	v_mfma_f32_16x16x32_bf16 v[124:127], v[12:15], v[28:31], v[68:71]
	v_mfma_f32_16x16x32_bf16 v[68:71], v[158:161], v[24:27], v[120:123]
	v_mfma_f32_16x16x32_bf16 v[116:119], v[198:201], v[28:31], v[68:71]
	v_mfma_f32_16x16x32_bf16 v[68:71], v[8:11], v[40:43], v[138:141]
	v_mfma_f32_16x16x32_bf16 v[108:111], v[12:15], v[44:47], v[68:71]
	v_mfma_f32_16x16x32_bf16 v[68:71], v[158:161], v[40:43], v[112:115]
	v_mfma_f32_16x16x32_bf16 v[100:103], v[198:201], v[44:47], v[68:71]
	v_mfma_f32_16x16x32_bf16 v[68:71], v[8:11], v[202:205], v[218:221]
	v_mfma_f32_16x16x32_bf16 v[92:95], v[12:15], v[206:209], v[68:71]
	v_mfma_f32_16x16x32_bf16 v[68:71], v[158:161], v[202:205], v[104:107]
	v_mfma_f32_16x16x32_bf16 v[84:87], v[198:201], v[206:209], v[68:71]
	v_mfma_f32_16x16x32_bf16 v[68:71], v[8:11], v[210:213], v[222:225]
	v_mfma_f32_16x16x32_bf16 v[76:79], v[12:15], v[234:237], v[68:71]
	v_mfma_f32_16x16x32_bf16 v[68:71], v[158:161], v[210:213], v[96:99]
	v_mfma_f32_16x16x32_bf16 v[68:71], v[198:201], v[234:237], v[68:71]
	s_nop 0
	s_barrier
	ds_read_b128 v[138:141], v155
	ds_read_b128 v[218:221], v155 offset:1024
	ds_read_b128 v[222:225], v155 offset:2048
	ds_read_b128 v[154:157], v155 offset:3072
	s_waitcnt vmcnt(0)
	s_barrier
	s_waitcnt lgkmcnt(0)
	s_nop 0
	v_mfma_f32_16x16x32_bf16 v[96:99], v[138:141], v[24:27], v[226:229]
	v_mfma_f32_16x16x32_bf16 v[24:27], v[222:225], v[24:27], v[88:91]
	v_mfma_f32_16x16x32_bf16 v[112:115], v[154:157], v[28:31], v[24:27]
	v_mfma_f32_16x16x32_bf16 v[24:27], v[138:141], v[40:43], v[186:189]
	v_mfma_f32_16x16x32_bf16 v[104:107], v[218:221], v[44:47], v[24:27]
	v_mfma_f32_16x16x32_bf16 v[24:27], v[222:225], v[40:43], v[80:83]
	v_mfma_f32_16x16x32_bf16 v[120:123], v[218:221], v[28:31], v[96:99]
	v_mfma_f32_16x16x32_bf16 v[96:99], v[154:157], v[44:47], v[24:27]
	v_mfma_f32_16x16x32_bf16 v[24:27], v[138:141], v[202:205], v[190:193]
	v_mfma_f32_16x16x32_bf16 v[88:91], v[218:221], v[206:209], v[24:27]
	v_mfma_f32_16x16x32_bf16 v[24:27], v[222:225], v[202:205], v[72:75]
	v_mfma_f32_16x16x32_bf16 v[80:83], v[154:157], v[206:209], v[24:27]
	v_mfma_f32_16x16x32_bf16 v[24:27], v[138:141], v[210:213], v[194:197]
	v_mfma_f32_16x16x32_bf16 v[72:75], v[218:221], v[234:237], v[24:27]
	v_mfma_f32_16x16x32_bf16 v[24:27], v[222:225], v[210:213], v[64:67]
	v_mfma_f32_16x16x32_bf16 v[64:67], v[154:157], v[234:237], v[24:27]
	s_nop 0
	s_barrier
	ds_read_b128 v[186:189], v153 offset:49152
	ds_read_b128 v[190:193], v153 offset:50176
	ds_read_b128 v[194:197], v171 offset:49152
	ds_read_b128 v[202:205], v171 offset:50176
	ds_read_b128 v[206:209], v172 offset:49152
	ds_read_b128 v[210:213], v172 offset:50176
	ds_read_b128 v[226:229], v173 offset:49152
	ds_read_b128 v[172:175], v173 offset:50176
	s_barrier
	s_waitcnt lgkmcnt(0)
	s_nop 0
	v_mfma_f32_16x16x32_bf16 v[24:27], v[8:11], v[186:189], v[60:63]
	v_mfma_f32_16x16x32_bf16 v[60:63], v[12:15], v[190:193], v[24:27]
	v_mfma_f32_16x16x32_bf16 v[24:27], v[158:161], v[186:189], v[56:59]
	v_mfma_f32_16x16x32_bf16 v[56:59], v[198:201], v[190:193], v[24:27]
	v_mfma_f32_16x16x32_bf16 v[24:27], v[8:11], v[194:197], v[52:55]
	v_mfma_f32_16x16x32_bf16 v[44:47], v[12:15], v[202:205], v[24:27]
	v_mfma_f32_16x16x32_bf16 v[24:27], v[158:161], v[194:197], v[48:51]
	v_mfma_f32_16x16x32_bf16 v[40:43], v[198:201], v[202:205], v[24:27]
	v_mfma_f32_16x16x32_bf16 v[24:27], v[8:11], v[206:209], v[214:217]
	v_mfma_f32_16x16x32_bf16 v[8:11], v[8:11], v[226:229], v[36:39]
	v_mfma_f32_16x16x32_bf16 v[28:31], v[12:15], v[210:213], v[24:27]
	v_mfma_f32_16x16x32_bf16 v[24:27], v[158:161], v[206:209], v[230:233]
	v_mfma_f32_16x16x32_bf16 v[12:15], v[12:15], v[172:175], v[8:11]
	v_mfma_f32_16x16x32_bf16 v[8:11], v[158:161], v[226:229], v[32:35]
	v_mfma_f32_16x16x32_bf16 v[24:27], v[198:201], v[210:213], v[24:27]
	v_mfma_f32_16x16x32_bf16 v[8:11], v[198:201], v[172:175], v[8:11]
	s_nop 0
	s_nop 0
	v_mfma_f32_16x16x32_bf16 v[32:35], v[138:141], v[186:189], v[142:145]
	v_mfma_f32_16x16x32_bf16 v[52:55], v[218:221], v[190:193], v[32:35]
	v_mfma_f32_16x16x32_bf16 v[32:35], v[222:225], v[186:189], v[146:149]
	v_mfma_f32_16x16x32_bf16 v[16:19], v[222:225], v[194:197], v[16:19]
	v_mfma_f32_16x16x32_bf16 v[48:51], v[154:157], v[190:193], v[32:35]
	v_mfma_f32_16x16x32_bf16 v[20:23], v[138:141], v[194:197], v[20:23]
	v_mfma_f32_16x16x32_bf16 v[32:35], v[154:157], v[202:205], v[16:19]
	v_mfma_f32_16x16x32_bf16 v[16:19], v[138:141], v[206:209], v[178:181]
	v_mfma_f32_16x16x32_bf16 v[36:39], v[218:221], v[202:205], v[20:23]
	v_mfma_f32_16x16x32_bf16 v[20:23], v[218:221], v[210:213], v[16:19]
	v_mfma_f32_16x16x32_bf16 v[16:19], v[222:225], v[206:209], v[182:185]
	v_mfma_f32_16x16x32_bf16 v[4:7], v[138:141], v[226:229], v[4:7]
	v_mfma_f32_16x16x32_bf16 v[0:3], v[222:225], v[226:229], v[0:3]
	v_mfma_f32_16x16x32_bf16 v[16:19], v[154:157], v[210:213], v[16:19]
	v_mfma_f32_16x16x32_bf16 v[4:7], v[218:221], v[172:175], v[4:7]
	v_mfma_f32_16x16x32_bf16 v[0:3], v[154:157], v[172:175], v[0:3]
	s_setprio 0
	s_cmpk_gt_u32 s31, 0xff
	s_barrier
	s_cbranch_scc1 .LBB0_852
	s_barrier

; #define WAIT_V(n) asm volatile("s_waitcnt vmcnt(" #n ")":::"memory")
; #define BAR __builtin_amdgcn_s_barrier()
; DEVINL void gemm8_mainloop(const u16* A, long lda, const u16* Bt, long ldb, int K, int brow, int bcol, f32x4 (&acc)[2][2][4][2], char* smem, int tid) {
;     ...
;   if(wr==1)BAR;
;   WAIT_V(4); BAR;
; DEVINL void compute_rs(const float* part, int m0, float* rs_s, int tid) {
;     ...
;   if (!half) rs_s[row] = rsqrtf(s * (1.f / 2048.f) + EPSN);
;   __syncthreads();
.LBB0_913:
	s_or_b64 exec, exec, s[26:27]
	v_readfirstlane_b32 s0, v153
	s_ashr_i32 s1, s0, 8
	s_cmp_lg_u32 s1, 1
	s_waitcnt lgkmcnt(0)
	s_barrier
	s_cbranch_scc1 .LBB0_915
	s_setprio 1
	s_barrier

; #define STAGE(P,BASE,LD,br,kt) do{long _g=(long)(br)*(LD)+(long)(kt)*BK; \
;     _Pragma("unroll") for(int _i=0;_i<2;++_i){int _b=tid*16+_i*8192;int _r,_c;stage_rc(_b,_r,_c); \
;       __builtin_amdgcn_global_load_lds((const unsigned*)((BASE)+_g+(long)_r*(LD)+_c), \
;         (unsigned*)((char*)(P)+_b),16,0,0);}}while(0)
; #define STAGE(P,BASE,LD,br,kt) do{long _g=(long)(br)*(LD)+(long)(kt)*BK; \
;     _Pragma("unroll") for(int _i=0;_i<2;++_i){int _b=tid*16+_i*8192;int _r,_c;stage_rc(_b,_r,_c); \
;       __builtin_amdgcn_global_load_lds((const unsigned*)((BASE)+_g+(long)_r*(LD)+_c), \
;         (unsigned*)((char*)(P)+_b),16,0,0);}}while(0)
; #define LDA(dst,b,h) _Pragma("unroll") for(int m=0;m<4;++m) _Pragma("unroll") for(int k=0;k<2;++k) \
;     dst[m][k]=*reinterpret_cast<const bf16x8*>((char*)SA(b,h)+lds_byte(wr*64+m*16+fr,k*32+fq*8))
; #define LDB(dst,b,h) _Pragma("unroll") for(int n=0;n<2;++n) _Pragma("unroll") for(int k=0;k<2;++k) \
;     dst[n][k]=*reinterpret_cast<const bf16x8*>((char*)SB(b,h)+lds_byte(wc*32+n*16+fr,k*32+fq*8))
; #define MMA(ai,bj,At_,Bt_) do{__builtin_amdgcn_s_setprio(1); \
;     _Pragma("unroll") for(int m=0;m<4;++m) _Pragma("unroll") for(int n=0;n<2;++n) _Pragma("unroll") for(int k=0;k<2;++k) \
;       acc[ai][bj][m][n]=__builtin_amdgcn_mfma_f32_16x16x32_bf16(Bt_[n][k],At_[m][k],acc[ai][bj][m][n],0,0,0); \
;     __builtin_amdgcn_s_setprio(0);}while(0)
; #define WAIT_L(n) asm volatile("s_waitcnt lgkmcnt(" #n ")":::"memory")
; #define BAR __builtin_amdgcn_s_barrier()
; #define SCHED __builtin_amdgcn_sched_barrier(0)
; DEVINL void gemm8_mainloop(const u16* A, long lda, const u16* Bt, long ldb, int K, int brow, int bcol, f32x4 (&acc)[2][2][4][2], char* smem, int tid) {
;     ...
;     LDB(B0,0,0); SCHED; LDA(At,0,0); STAGE(SA(1,1),A,lda,brow+HALF,t+1);
;     WAIT_L(8); BAR; WAIT_L(0); MMA(0,0,At,B0); BAR; SCHED;
;     LDB(B1,0,1); STAGE(SB(0,0),Bt,ldb,bcol,t+2);
;     BAR; WAIT_L(0); MMA(0,1,At,B1); BAR;
;     LDA(At,0,1); STAGE(SA(0,0),A,lda,brow,t+2);
;     BAR; WAIT_L(0); MMA(1,0,At,B0); BAR; SCHED;
.LBB0_916:
	ds_read_b128 v[180:183], v165
	ds_read_b128 v[184:187], v165 offset:1024
	ds_read_b128 v[188:191], v165 offset:2048
	ds_read_b128 v[192:195], v165 offset:3072
	v_add_u32_e32 v177, 0xc000, v154
	v_lshl_add_u64 v[244:245], s[94:95], 0, v[146:147]
	v_readfirstlane_b32 s29, v177
	v_add_u32_e32 v178, 0xe000, v154
	v_add_u32_e32 v173, s1, v164
	v_add_u32_e32 v174, s25, v164
	v_add_u32_e32 v175, s37, v164
	v_lshl_add_u64 v[166:167], v[244:245], 0, s[4:5]
	s_mov_b32 m0, s29
	v_lshl_add_u64 v[246:247], s[94:95], 0, v[148:149]
	v_readfirstlane_b32 s29, v178
	ds_read_b128 v[168:171], v155
	ds_read_b128 v[196:199], v155 offset:1024
	ds_read_b128 v[200:203], v173
	ds_read_b128 v[204:207], v173 offset:1024
	ds_read_b128 v[208:211], v174
	ds_read_b128 v[212:215], v174 offset:1024
	ds_read_b128 v[216:219], v175
	ds_read_b128 v[220:223], v175 offset:1024
	global_load_lds_dwordx4 v[166:167], off
	v_lshl_add_u64 v[166:167], v[246:247], 0, s[4:5]
	s_mov_b32 m0, s29
	s_nop 0
	global_load_lds_dwordx4 v[166:167], off
	s_waitcnt lgkmcnt(8)
	s_barrier
	s_waitcnt lgkmcnt(0)
	s_nop 0
	v_mfma_f32_16x16x32_bf16 v[124:127], v[180:183], v[168:171], v[124:127]
	v_mfma_f32_16x16x32_bf16 v[120:123], v[188:191], v[168:171], v[120:123]
	v_mfma_f32_16x16x32_bf16 v[116:119], v[180:183], v[200:203], v[116:119]
	v_mfma_f32_16x16x32_bf16 v[112:115], v[188:191], v[200:203], v[112:115]
	v_mfma_f32_16x16x32_bf16 v[108:111], v[180:183], v[208:211], v[108:111]
	v_mfma_f32_16x16x32_bf16 v[104:107], v[188:191], v[208:211], v[104:107]
	v_mfma_f32_16x16x32_bf16 v[100:103], v[180:183], v[216:219], v[100:103]
	v_mfma_f32_16x16x32_bf16 v[96:99], v[188:191], v[216:219], v[96:99]
	v_mfma_f32_16x16x32_bf16 v[124:127], v[184:187], v[196:199], v[124:127]
	v_mfma_f32_16x16x32_bf16 v[120:123], v[192:195], v[196:199], v[120:123]
	v_mfma_f32_16x16x32_bf16 v[116:119], v[184:187], v[204:207], v[116:119]
	v_mfma_f32_16x16x32_bf16 v[112:115], v[192:195], v[204:207], v[112:115]
	v_mfma_f32_16x16x32_bf16 v[108:111], v[184:187], v[212:215], v[108:111]
	v_mfma_f32_16x16x32_bf16 v[104:107], v[192:195], v[212:215], v[104:107]
	v_mfma_f32_16x16x32_bf16 v[100:103], v[184:187], v[220:223], v[100:103]
	v_mfma_f32_16x16x32_bf16 v[96:99], v[192:195], v[220:223], v[96:99]
	s_nop 0
	s_barrier
	v_add_u32_e32 v166, s30, v157
	v_lshl_add_u64 v[248:249], s[94:95], 0, v[142:143]
	v_readfirstlane_b32 s29, v166
	v_add_u32_e32 v167, 0x2000, v166
	v_lshl_add_u64 v[240:241], v[248:249], 0, s[6:7]
	s_mov_b32 m0, s29
	v_lshl_add_u64 v[250:251], s[94:95], 0, v[144:145]
	v_readfirstlane_b32 s29, v167
	ds_read_b128 v[224:227], v162
	ds_read_b128 v[228:231], v162 offset:1024
	ds_read_b128 v[232:235], v162 offset:2048
	ds_read_b128 v[236:239], v162 offset:3072
	global_load_lds_dwordx4 v[240:241], off
	v_lshl_add_u64 v[240:241], v[250:251], 0, s[6:7]
	s_mov_b32 m0, s29
	s_nop 0
	global_load_lds_dwordx4 v[240:241], off
	s_barrier
	s_waitcnt lgkmcnt(0)
	s_nop 0
	v_mfma_f32_16x16x32_bf16 v[92:95], v[224:227], v[168:171], v[92:95]
	v_mfma_f32_16x16x32_bf16 v[88:91], v[232:235], v[168:171], v[88:91]
	v_mfma_f32_16x16x32_bf16 v[84:87], v[224:227], v[200:203], v[84:87]
	v_mfma_f32_16x16x32_bf16 v[80:83], v[232:235], v[200:203], v[80:83]
	v_mfma_f32_16x16x32_bf16 v[76:79], v[224:227], v[208:211], v[76:79]
	v_mfma_f32_16x16x32_bf16 v[72:75], v[232:235], v[208:211], v[72:75]
	v_mfma_f32_16x16x32_bf16 v[68:71], v[224:227], v[216:219], v[68:71]
	v_mfma_f32_16x16x32_bf16 v[64:67], v[232:235], v[216:219], v[64:67]
	v_mfma_f32_16x16x32_bf16 v[92:95], v[228:231], v[196:199], v[92:95]
	v_mfma_f32_16x16x32_bf16 v[88:91], v[236:239], v[196:199], v[88:91]
	v_mfma_f32_16x16x32_bf16 v[84:87], v[228:231], v[204:207], v[84:87]
	v_mfma_f32_16x16x32_bf16 v[80:83], v[236:239], v[204:207], v[80:83]
	v_mfma_f32_16x16x32_bf16 v[76:79], v[228:231], v[212:215], v[76:79]
	v_mfma_f32_16x16x32_bf16 v[72:75], v[236:239], v[212:215], v[72:75]
	v_mfma_f32_16x16x32_bf16 v[68:71], v[228:231], v[220:223], v[68:71]
	v_mfma_f32_16x16x32_bf16 v[64:67], v[236:239], v[220:223], v[64:67]
	s_nop 0
	v_readfirstlane_b32 s29, v154
	v_lshl_add_u64 v[168:169], v[244:245], 0, s[8:9]
	s_mov_b32 m0, s29
	s_barrier
	ds_read_b128 v[196:199], v155 offset:16384
	ds_read_b128 v[200:203], v155 offset:17408
	ds_read_b128 v[204:207], v173 offset:16384
	ds_read_b128 v[208:211], v173 offset:17408
	ds_read_b128 v[212:215], v174 offset:16384
	ds_read_b128 v[216:219], v174 offset:17408
	ds_read_b128 v[220:223], v175 offset:16384
	ds_read_b128 v[240:243], v175 offset:17408
	global_load_lds_dwordx4 v[168:169], off
	v_add_u32_e32 v168, 0x2000, v154
	v_lshl_add_u64 v[170:171], v[246:247], 0, s[8:9]
	v_readfirstlane_b32 s29, v168
	s_mov_b32 m0, s29
	s_nop 0
	global_load_lds_dwordx4 v[170:171], off
	s_barrier
	s_waitcnt lgkmcnt(0)
	s_nop 0
	v_mfma_f32_16x16x32_bf16 v[60:63], v[180:183], v[196:199], v[60:63]
	v_mfma_f32_16x16x32_bf16 v[56:59], v[188:191], v[196:199], v[56:59]
	v_mfma_f32_16x16x32_bf16 v[52:55], v[180:183], v[204:207], v[52:55]
	v_mfma_f32_16x16x32_bf16 v[48:51], v[188:191], v[204:207], v[48:51]
	v_mfma_f32_16x16x32_bf16 v[44:47], v[180:183], v[212:215], v[44:47]
	v_mfma_f32_16x16x32_bf16 v[40:43], v[188:191], v[212:215], v[40:43]
	v_mfma_f32_16x16x32_bf16 v[36:39], v[180:183], v[220:223], v[36:39]
	v_mfma_f32_16x16x32_bf16 v[32:35], v[188:191], v[220:223], v[32:35]
	v_mfma_f32_16x16x32_bf16 v[60:63], v[184:187], v[200:203], v[60:63]
	v_mfma_f32_16x16x32_bf16 v[56:59], v[192:195], v[200:203], v[56:59]
	v_mfma_f32_16x16x32_bf16 v[52:55], v[184:187], v[208:211], v[52:55]
	v_mfma_f32_16x16x32_bf16 v[48:51], v[192:195], v[208:211], v[48:51]
	v_mfma_f32_16x16x32_bf16 v[44:47], v[184:187], v[216:219], v[44:47]
	v_mfma_f32_16x16x32_bf16 v[40:43], v[192:195], v[216:219], v[40:43]
	v_mfma_f32_16x16x32_bf16 v[36:39], v[184:187], v[240:243], v[36:39]
	v_mfma_f32_16x16x32_bf16 v[32:35], v[192:195], v[240:243], v[32:35]
	s_nop 0
	s_barrier
; #define STAGE(P,BASE,LD,br,kt) do{long _g=(long)(br)*(LD)+(long)(kt)*BK; \
;     _Pragma("unroll") for(int _i=0;_i<2;++_i){int _b=tid*16+_i*8192;int _r,_c;stage_rc(_b,_r,_c); \
;       __builtin_amdgcn_global_load_lds((const unsigned*)((BASE)+_g+(long)_r*(LD)+_c), \
;         (unsigned*)((char*)(P)+_b),16,0,0);}}while(0)
; #define STAGE(P,BASE,LD,br,kt) do{long _g=(long)(br)*(LD)+(long)(kt)*BK; \
;     _Pragma("unroll") for(int _i=0;_i<2;++_i){int _b=tid*16+_i*8192;int _r,_c;stage_rc(_b,_r,_c); \
;       __builtin_amdgcn_global_load_lds((const unsigned*)((BASE)+_g+(long)_r*(LD)+_c), \
;         (unsigned*)((char*)(P)+_b),16,0,0);}}while(0)
; #define LDA(dst,b,h) _Pragma("unroll") for(int m=0;m<4;++m) _Pragma("unroll") for(int k=0;k<2;++k) \
;     dst[m][k]=*reinterpret_cast<const bf16x8*>((char*)SA(b,h)+lds_byte(wr*64+m*16+fr,k*32+fq*8))
; #define LDB(dst,b,h) _Pragma("unroll") for(int n=0;n<2;++n) _Pragma("unroll") for(int k=0;k<2;++k) \
;     dst[n][k]=*reinterpret_cast<const bf16x8*>((char*)SB(b,h)+lds_byte(wc*32+n*16+fr,k*32+fq*8))
; #define MMA(ai,bj,At_,Bt_) do{__builtin_amdgcn_s_setprio(1); \
;     _Pragma("unroll") for(int m=0;m<4;++m) _Pragma("unroll") for(int n=0;n<2;++n) _Pragma("unroll") for(int k=0;k<2;++k) \
;       acc[ai][bj][m][n]=__builtin_amdgcn_mfma_f32_16x16x32_bf16(Bt_[n][k],At_[m][k],acc[ai][bj][m][n],0,0,0); \
;     __builtin_amdgcn_s_setprio(0);}while(0)
; #define WAIT_V(n) asm volatile("s_waitcnt vmcnt(" #n ")":::"memory")
; #define WAIT_L(n) asm volatile("s_waitcnt lgkmcnt(" #n ")":::"memory")
; #define BAR __builtin_amdgcn_s_barrier()
; #define SCHED __builtin_amdgcn_sched_barrier(0)
; DEVINL void gemm8_mainloop(const u16* A, long lda, const u16* Bt, long ldb, int K, int brow, int bcol, f32x4 (&acc)[2][2][4][2], char* smem, int tid) {
;     ...
;     STAGE(SB(0,1),Bt,ldb,bcol+HALF,t+2);
;     WAIT_V(6); BAR; MMA(1,1,At,B1); BAR;
;     LDB(B0,1,0); SCHED; LDA(At,1,0); STAGE(SA(0,1),A,lda,brow+HALF,t+2);
;     WAIT_L(8); BAR; WAIT_L(0); MMA(0,0,At,B0); BAR; SCHED;
;     LDB(B1,1,1); STAGE(SB(1,0),Bt,ldb,bcol,t+3);
	v_add_u32_e32 v169, s31, v157
	v_lshl_add_u64 v[170:171], v[248:249], 0, s[10:11]
	v_readfirstlane_b32 s29, v169
	s_mov_b32 m0, s29
	v_lshl_add_u64 v[180:181], v[250:251], 0, s[10:11]
	global_load_lds_dwordx4 v[170:171], off
	v_add_u32_e32 v170, 0x2000, v169
	s_nop 0
	v_readfirstlane_b32 s29, v170
	s_mov_b32 m0, s29
	s_nop 0
	global_load_lds_dwordx4 v[180:181], off
	s_waitcnt vmcnt(6)
	s_barrier
	s_nop 0
	v_mfma_f32_16x16x32_bf16 v[28:31], v[224:227], v[196:199], v[28:31]
	v_mfma_f32_16x16x32_bf16 v[24:27], v[232:235], v[196:199], v[24:27]
	v_mfma_f32_16x16x32_bf16 v[20:23], v[224:227], v[204:207], v[20:23]
	v_mfma_f32_16x16x32_bf16 v[16:19], v[232:235], v[204:207], v[16:19]
	v_mfma_f32_16x16x32_bf16 v[12:15], v[224:227], v[212:215], v[12:15]
	v_mfma_f32_16x16x32_bf16 v[8:11], v[232:235], v[212:215], v[8:11]
	v_mfma_f32_16x16x32_bf16 v[4:7], v[224:227], v[220:223], v[4:7]
	v_mfma_f32_16x16x32_bf16 v[0:3], v[232:235], v[220:223], v[0:3]
	v_mfma_f32_16x16x32_bf16 v[28:31], v[228:231], v[200:203], v[28:31]
	v_mfma_f32_16x16x32_bf16 v[24:27], v[236:239], v[200:203], v[24:27]
	v_mfma_f32_16x16x32_bf16 v[20:23], v[228:231], v[208:211], v[20:23]
	v_mfma_f32_16x16x32_bf16 v[16:19], v[236:239], v[208:211], v[16:19]
	v_mfma_f32_16x16x32_bf16 v[12:15], v[228:231], v[216:219], v[12:15]
	v_mfma_f32_16x16x32_bf16 v[8:11], v[236:239], v[216:219], v[8:11]
	v_mfma_f32_16x16x32_bf16 v[4:7], v[228:231], v[240:243], v[4:7]
	v_mfma_f32_16x16x32_bf16 v[0:3], v[236:239], v[240:243], v[0:3]
	s_nop 0
	s_barrier
	ds_read_b128 v[180:183], v158
	ds_read_b128 v[184:187], v158 offset:1024
	ds_read_b128 v[188:191], v158 offset:2048
	ds_read_b128 v[192:195], v158 offset:3072
	v_add_u32_e32 v171, 0x4000, v154
	v_add_u32_e32 v172, 0x6000, v154
	v_readfirstlane_b32 s29, v171
	v_lshl_add_u64 v[228:229], v[244:245], 0, s[12:13]
	s_mov_b32 m0, s29
	v_readfirstlane_b32 s29, v172
	ds_read_b128 v[196:199], v155 offset:32768
	ds_read_b128 v[200:203], v155 offset:33792
	ds_read_b128 v[204:207], v173 offset:32768
	ds_read_b128 v[208:211], v173 offset:33792
	ds_read_b128 v[212:215], v174 offset:32768
	ds_read_b128 v[216:219], v174 offset:33792
	ds_read_b128 v[220:223], v175 offset:32768
	ds_read_b128 v[224:227], v175 offset:33792
	global_load_lds_dwordx4 v[228:229], off
	v_lshl_add_u64 v[228:229], v[246:247], 0, s[12:13]
	s_mov_b32 m0, s29
	s_nop 0
	global_load_lds_dwordx4 v[228:229], off
	s_waitcnt lgkmcnt(8)
	s_barrier
	s_waitcnt lgkmcnt(0)
	s_nop 0
	v_mfma_f32_16x16x32_bf16 v[124:127], v[180:183], v[196:199], v[124:127]
	v_mfma_f32_16x16x32_bf16 v[120:123], v[188:191], v[196:199], v[120:123]
	v_mfma_f32_16x16x32_bf16 v[116:119], v[180:183], v[204:207], v[116:119]
	v_mfma_f32_16x16x32_bf16 v[112:115], v[188:191], v[204:207], v[112:115]
	v_mfma_f32_16x16x32_bf16 v[108:111], v[180:183], v[212:215], v[108:111]
	v_mfma_f32_16x16x32_bf16 v[104:107], v[188:191], v[212:215], v[104:107]
	v_mfma_f32_16x16x32_bf16 v[100:103], v[180:183], v[220:223], v[100:103]
	v_mfma_f32_16x16x32_bf16 v[96:99], v[188:191], v[220:223], v[96:99]
	v_mfma_f32_16x16x32_bf16 v[124:127], v[184:187], v[200:203], v[124:127]
	v_mfma_f32_16x16x32_bf16 v[120:123], v[192:195], v[200:203], v[120:123]
	v_mfma_f32_16x16x32_bf16 v[116:119], v[184:187], v[208:211], v[116:119]
	v_mfma_f32_16x16x32_bf16 v[112:115], v[192:195], v[208:211], v[112:115]
	v_mfma_f32_16x16x32_bf16 v[108:111], v[184:187], v[216:219], v[108:111]
	v_mfma_f32_16x16x32_bf16 v[104:107], v[192:195], v[216:219], v[104:107]
	v_mfma_f32_16x16x32_bf16 v[100:103], v[184:187], v[224:227], v[100:103]
	v_mfma_f32_16x16x32_bf16 v[96:99], v[192:195], v[224:227], v[96:99]
	s_nop 0
	s_barrier
	v_readfirstlane_b32 s29, v159
	v_add_u32_e32 v179, 0x2000, v159
	v_lshl_add_u64 v[252:253], v[248:249], 0, s[14:15]
	s_mov_b32 m0, s29
	v_readfirstlane_b32 s29, v179
	ds_read_b128 v[228:231], v156
	ds_read_b128 v[232:235], v156 offset:1024
	ds_read_b128 v[236:239], v156 offset:2048
	ds_read_b128 v[240:243], v156 offset:3072
	global_load_lds_dwordx4 v[252:253], off
	v_lshl_add_u64 v[252:253], v[250:251], 0, s[14:15]
	s_mov_b32 m0, s29
	s_nop 0
	global_load_lds_dwordx4 v[252:253], off
	s_barrier
	s_waitcnt lgkmcnt(0)
	s_nop 0
	v_mfma_f32_16x16x32_bf16 v[92:95], v[228:231], v[196:199], v[92:95]
	v_mfma_f32_16x16x32_bf16 v[88:91], v[236:239], v[196:199], v[88:91]
	v_mfma_f32_16x16x32_bf16 v[84:87], v[228:231], v[204:207], v[84:87]
	v_mfma_f32_16x16x32_bf16 v[80:83], v[236:239], v[204:207], v[80:83]
	v_mfma_f32_16x16x32_bf16 v[76:79], v[228:231], v[212:215], v[76:79]
	v_mfma_f32_16x16x32_bf16 v[72:75], v[236:239], v[212:215], v[72:75]
	v_mfma_f32_16x16x32_bf16 v[68:71], v[228:231], v[220:223], v[68:71]
	v_mfma_f32_16x16x32_bf16 v[64:67], v[236:239], v[220:223], v[64:67]
	v_mfma_f32_16x16x32_bf16 v[92:95], v[232:235], v[200:203], v[92:95]
	v_mfma_f32_16x16x32_bf16 v[88:91], v[240:243], v[200:203], v[88:91]
	v_mfma_f32_16x16x32_bf16 v[84:87], v[232:235], v[208:211], v[84:87]
	v_mfma_f32_16x16x32_bf16 v[80:83], v[240:243], v[208:211], v[80:83]
	v_mfma_f32_16x16x32_bf16 v[76:79], v[232:235], v[216:219], v[76:79]
	v_mfma_f32_16x16x32_bf16 v[72:75], v[240:243], v[216:219], v[72:75]
	v_mfma_f32_16x16x32_bf16 v[68:71], v[232:235], v[224:227], v[68:71]
	v_mfma_f32_16x16x32_bf16 v[64:67], v[240:243], v[224:227], v[64:67]
	s_nop 0
	v_readfirstlane_b32 s29, v160
	v_lshl_add_u64 v[244:245], v[244:245], 0, s[16:17]
	s_mov_b32 m0, s29
	v_readfirstlane_b32 s29, v161
	s_barrier
; #define STAGE(P,BASE,LD,br,kt) do{long _g=(long)(br)*(LD)+(long)(kt)*BK; \
;     _Pragma("unroll") for(int _i=0;_i<2;++_i){int _b=tid*16+_i*8192;int _r,_c;stage_rc(_b,_r,_c); \
;       __builtin_amdgcn_global_load_lds((const unsigned*)((BASE)+_g+(long)_r*(LD)+_c), \
;         (unsigned*)((char*)(P)+_b),16,0,0);}}while(0)
; #define STAGE(P,BASE,LD,br,kt) do{long _g=(long)(br)*(LD)+(long)(kt)*BK; \
;     _Pragma("unroll") for(int _i=0;_i<2;++_i){int _b=tid*16+_i*8192;int _r,_c;stage_rc(_b,_r,_c); \
;       __builtin_amdgcn_global_load_lds((const unsigned*)((BASE)+_g+(long)_r*(LD)+_c), \
;         (unsigned*)((char*)(P)+_b),16,0,0);}}while(0)
; #define LDA(dst,b,h) _Pragma("unroll") for(int m=0;m<4;++m) _Pragma("unroll") for(int k=0;k<2;++k) \
;     dst[m][k]=*reinterpret_cast<const bf16x8*>((char*)SA(b,h)+lds_byte(wr*64+m*16+fr,k*32+fq*8))
; #define LDB(dst,b,h) _Pragma("unroll") for(int n=0;n<2;++n) _Pragma("unroll") for(int k=0;k<2;++k) \
;     dst[n][k]=*reinterpret_cast<const bf16x8*>((char*)SB(b,h)+lds_byte(wc*32+n*16+fr,k*32+fq*8))
; #define MMA(ai,bj,At_,Bt_) do{__builtin_amdgcn_s_setprio(1); \
;     _Pragma("unroll") for(int m=0;m<4;++m) _Pragma("unroll") for(int n=0;n<2;++n) _Pragma("unroll") for(int k=0;k<2;++k) \
;       acc[ai][bj][m][n]=__builtin_amdgcn_mfma_f32_16x16x32_bf16(Bt_[n][k],At_[m][k],acc[ai][bj][m][n],0,0,0); \
;     __builtin_amdgcn_s_setprio(0);}while(0)
; #define WAIT_V(n) asm volatile("s_waitcnt vmcnt(" #n ")":::"memory")
; #define WAIT_L(n) asm volatile("s_waitcnt lgkmcnt(" #n ")":::"memory")
; #define BAR __builtin_amdgcn_s_barrier()
; #define SCHED __builtin_amdgcn_sched_barrier(0)
; DEVINL void gemm8_mainloop(const u16* A, long lda, const u16* Bt, long ldb, int K, int brow, int bcol, f32x4 (&acc)[2][2][4][2], char* smem, int tid) {
;     ...
;     BAR; WAIT_L(0); MMA(0,1,At,B1); BAR;
;     LDA(At,1,1); STAGE(SA(1,0),A,lda,brow,t+3);
;     BAR; WAIT_L(0); MMA(1,0,At,B0); BAR; SCHED;
;     STAGE(SB(1,1),Bt,ldb,bcol+HALF,t+3);
;     WAIT_V(6); BAR; MMA(1,1,At,B1); BAR;
;   }
;   { LDB(B0,0,0); LDA(At,0,0); STAGE(SA(1,1),A,lda,brow+HALF,nt-1);
;     BAR; WAIT_L(0); MMA(0,0,At,B0); BAR;
	ds_read_b128 v[196:199], v155 offset:49152
	ds_read_b128 v[200:203], v155 offset:50176
	ds_read_b128 v[204:207], v173 offset:49152
	ds_read_b128 v[208:211], v173 offset:50176
	ds_read_b128 v[212:215], v174 offset:49152
	ds_read_b128 v[216:219], v174 offset:50176
	ds_read_b128 v[220:223], v175 offset:49152
	ds_read_b128 v[224:227], v175 offset:50176
	global_load_lds_dwordx4 v[244:245], off
	v_lshl_add_u64 v[244:245], v[246:247], 0, s[16:17]
	s_mov_b32 m0, s29
	s_nop 0
	global_load_lds_dwordx4 v[244:245], off
	s_barrier
	s_waitcnt lgkmcnt(0)
	s_nop 0
	v_mfma_f32_16x16x32_bf16 v[60:63], v[180:183], v[196:199], v[60:63]
	v_mfma_f32_16x16x32_bf16 v[56:59], v[188:191], v[196:199], v[56:59]
	v_mfma_f32_16x16x32_bf16 v[52:55], v[180:183], v[204:207], v[52:55]
	v_mfma_f32_16x16x32_bf16 v[48:51], v[188:191], v[204:207], v[48:51]
	v_mfma_f32_16x16x32_bf16 v[44:47], v[180:183], v[212:215], v[44:47]
	v_mfma_f32_16x16x32_bf16 v[40:43], v[188:191], v[212:215], v[40:43]
	v_mfma_f32_16x16x32_bf16 v[36:39], v[180:183], v[220:223], v[36:39]
	v_mfma_f32_16x16x32_bf16 v[32:35], v[188:191], v[220:223], v[32:35]
	v_mfma_f32_16x16x32_bf16 v[60:63], v[184:187], v[200:203], v[60:63]
	v_mfma_f32_16x16x32_bf16 v[56:59], v[192:195], v[200:203], v[56:59]
	v_mfma_f32_16x16x32_bf16 v[52:55], v[184:187], v[208:211], v[52:55]
	v_mfma_f32_16x16x32_bf16 v[48:51], v[192:195], v[208:211], v[48:51]
	v_mfma_f32_16x16x32_bf16 v[44:47], v[184:187], v[216:219], v[44:47]
	v_mfma_f32_16x16x32_bf16 v[40:43], v[192:195], v[216:219], v[40:43]
	v_mfma_f32_16x16x32_bf16 v[36:39], v[184:187], v[224:227], v[36:39]
	v_mfma_f32_16x16x32_bf16 v[32:35], v[192:195], v[224:227], v[32:35]
	s_nop 0
	s_barrier
	v_readfirstlane_b32 s29, v163
	v_add_u32_e32 v179, 0x2000, v163
	v_lshl_add_u64 v[180:181], v[248:249], 0, s[18:19]
	s_mov_b32 m0, s29
	v_readfirstlane_b32 s29, v179
	global_load_lds_dwordx4 v[180:181], off
	v_lshl_add_u64 v[180:181], v[250:251], 0, s[18:19]
	s_mov_b32 m0, s29
	s_nop 0
	global_load_lds_dwordx4 v[180:181], off
	s_waitcnt vmcnt(6)
	s_barrier
	s_nop 0
	v_mfma_f32_16x16x32_bf16 v[28:31], v[228:231], v[196:199], v[28:31]
	v_mfma_f32_16x16x32_bf16 v[24:27], v[236:239], v[196:199], v[24:27]
	v_mfma_f32_16x16x32_bf16 v[20:23], v[228:231], v[204:207], v[20:23]
	v_mfma_f32_16x16x32_bf16 v[16:19], v[236:239], v[204:207], v[16:19]
	v_mfma_f32_16x16x32_bf16 v[12:15], v[228:231], v[212:215], v[12:15]
	v_mfma_f32_16x16x32_bf16 v[8:11], v[236:239], v[212:215], v[8:11]
	v_mfma_f32_16x16x32_bf16 v[4:7], v[228:231], v[220:223], v[4:7]
	v_mfma_f32_16x16x32_bf16 v[0:3], v[236:239], v[220:223], v[0:3]
	v_mfma_f32_16x16x32_bf16 v[28:31], v[232:235], v[200:203], v[28:31]
	v_mfma_f32_16x16x32_bf16 v[24:27], v[240:243], v[200:203], v[24:27]
	v_mfma_f32_16x16x32_bf16 v[20:23], v[232:235], v[208:211], v[20:23]
	v_mfma_f32_16x16x32_bf16 v[16:19], v[240:243], v[208:211], v[16:19]
	v_mfma_f32_16x16x32_bf16 v[12:15], v[232:235], v[216:219], v[12:15]
	v_mfma_f32_16x16x32_bf16 v[8:11], v[240:243], v[216:219], v[8:11]
	v_mfma_f32_16x16x32_bf16 v[4:7], v[232:235], v[224:227], v[4:7]
	v_mfma_f32_16x16x32_bf16 v[0:3], v[240:243], v[224:227], v[0:3]
	s_nop 0
	s_add_i32 s28, s28, 2
	v_lshl_add_u64 v[142:143], v[142:143], 0, s[20:21]
	v_lshl_add_u64 v[144:145], v[144:145], 0, s[20:21]
	v_lshl_add_u64 v[146:147], v[146:147], 0, s[20:21]
	s_cmp_lt_u32 s28, 28
	v_lshl_add_u64 v[148:149], v[148:149], 0, s[20:21]
	s_barrier
	s_cbranch_scc1 .LBB0_916
	s_or_b32 s28, s24, 0x80
	s_ashr_i32 s29, s28, 31
	s_lshl_b64 s[28:29], s[28:29], 12
	s_add_u32 s28, s90, s28
	s_addc_u32 s29, s91, s29
	v_lshl_add_u64 v[160:161], v[134:135], 1, s[28:29]
	v_lshl_add_u64 v[138:139], v[138:139], 1, v[160:161]
	v_readfirstlane_b32 s1, v177
	v_lshl_add_u64 v[138:139], v[138:139], 0, s[22:23]
	s_mov_b32 m0, s1
	ds_read_b128 v[142:145], v165
	ds_read_b128 v[146:149], v165 offset:1024
	ds_read_b128 v[180:183], v165 offset:2048
	ds_read_b128 v[184:187], v165 offset:3072
	ds_read_b128 v[188:191], v155
	ds_read_b128 v[192:195], v155 offset:1024
	ds_read_b128 v[196:199], v173
	ds_read_b128 v[200:203], v173 offset:1024
	ds_read_b128 v[204:207], v174
	ds_read_b128 v[208:211], v174 offset:1024
	ds_read_b128 v[212:215], v175
	ds_read_b128 v[216:219], v175 offset:1024
	global_load_lds_dwordx4 v[138:139], off
	v_lshl_add_u64 v[138:139], v[136:137], 1, s[28:29]
	v_lshl_add_u64 v[138:139], v[140:141], 1, v[138:139]
	v_readfirstlane_b32 s1, v178
	v_lshl_add_u64 v[138:139], v[138:139], 0, s[22:23]
	s_mov_b32 m0, s1
	s_nop 0
	global_load_lds_dwordx4 v[138:139], off
	s_barrier
	s_waitcnt lgkmcnt(0)
	s_nop 0
	v_mfma_f32_16x16x32_bf16 v[124:127], v[142:145], v[188:191], v[124:127]
	v_mfma_f32_16x16x32_bf16 v[120:123], v[180:183], v[188:191], v[120:123]
	v_mfma_f32_16x16x32_bf16 v[116:119], v[142:145], v[196:199], v[116:119]
	v_mfma_f32_16x16x32_bf16 v[112:115], v[180:183], v[196:199], v[112:115]
	v_mfma_f32_16x16x32_bf16 v[104:107], v[180:183], v[204:207], v[104:107]
	v_mfma_f32_16x16x32_bf16 v[96:99], v[180:183], v[212:215], v[96:99]
	v_mfma_f32_16x16x32_bf16 v[124:127], v[146:149], v[192:195], v[124:127]
	v_mfma_f32_16x16x32_bf16 v[120:123], v[184:187], v[192:195], v[120:123]
	v_mfma_f32_16x16x32_bf16 v[116:119], v[146:149], v[200:203], v[116:119]
	v_mfma_f32_16x16x32_bf16 v[112:115], v[184:187], v[200:203], v[112:115]
	v_mfma_f32_16x16x32_bf16 v[108:111], v[142:145], v[204:207], v[108:111]
	v_mfma_f32_16x16x32_bf16 v[104:107], v[184:187], v[208:211], v[104:107]
	v_mfma_f32_16x16x32_bf16 v[100:103], v[142:145], v[212:215], v[100:103]
	v_mfma_f32_16x16x32_bf16 v[96:99], v[184:187], v[216:219], v[96:99]
	v_mfma_f32_16x16x32_bf16 v[138:141], v[146:149], v[208:211], v[108:111]
	v_mfma_f32_16x16x32_bf16 v[220:223], v[146:149], v[216:219], v[100:103]
	s_nop 0
	s_barrier
; #define LDA(dst,b,h) _Pragma("unroll") for(int m=0;m<4;++m) _Pragma("unroll") for(int k=0;k<2;++k) \
;     dst[m][k]=*reinterpret_cast<const bf16x8*>((char*)SA(b,h)+lds_byte(wr*64+m*16+fr,k*32+fq*8))
; #define LDB(dst,b,h) _Pragma("unroll") for(int n=0;n<2;++n) _Pragma("unroll") for(int k=0;k<2;++k) \
;     dst[n][k]=*reinterpret_cast<const bf16x8*>((char*)SB(b,h)+lds_byte(wc*32+n*16+fr,k*32+fq*8))
; #define MMA(ai,bj,At_,Bt_) do{__builtin_amdgcn_s_setprio(1); \
;     _Pragma("unroll") for(int m=0;m<4;++m) _Pragma("unroll") for(int n=0;n<2;++n) _Pragma("unroll") for(int k=0;k<2;++k) \
;       acc[ai][bj][m][n]=__builtin_amdgcn_mfma_f32_16x16x32_bf16(Bt_[n][k],At_[m][k],acc[ai][bj][m][n],0,0,0); \
;     __builtin_amdgcn_s_setprio(0);}while(0)
; #define WAIT_V(n) asm volatile("s_waitcnt vmcnt(" #n ")":::"memory")
; #define WAIT_L(n) asm volatile("s_waitcnt lgkmcnt(" #n ")":::"memory")
; #define BAR __builtin_amdgcn_s_barrier()
; DEVINL void gemm8_mainloop(const u16* A, long lda, const u16* Bt, long ldb, int K, int brow, int bcol, f32x4 (&acc)[2][2][4][2], char* smem, int tid) {
;     ...
;     LDB(B1,0,1); BAR; WAIT_L(0); MMA(0,1,At,B1); BAR;
;     LDA(At,0,1); WAIT_V(4); BAR; WAIT_L(0); MMA(1,0,At,B0); MMA(1,1,At,B1); BAR; }
;   { LDB(B0,1,0); LDA(At,1,0); WAIT_V(2); BAR; WAIT_L(0); MMA(0,0,At,B0); BAR;
;     LDB(B1,1,1); WAIT_V(0); BAR; WAIT_L(0); MMA(0,1,At,B1); BAR;
	s_nop 2
	ds_read_b128 v[100:103], v162
	ds_read_b128 v[108:111], v162 offset:1024
	ds_read_b128 v[224:227], v162 offset:2048
	ds_read_b128 v[160:163], v162 offset:3072
	s_barrier
	s_waitcnt lgkmcnt(0)
	s_nop 0
	v_mfma_f32_16x16x32_bf16 v[88:91], v[224:227], v[188:191], v[88:91]
	v_mfma_f32_16x16x32_bf16 v[80:83], v[224:227], v[196:199], v[80:83]
	v_mfma_f32_16x16x32_bf16 v[72:75], v[224:227], v[204:207], v[72:75]
	v_mfma_f32_16x16x32_bf16 v[64:67], v[224:227], v[212:215], v[64:67]
	v_mfma_f32_16x16x32_bf16 v[92:95], v[100:103], v[188:191], v[92:95]
	v_mfma_f32_16x16x32_bf16 v[88:91], v[160:163], v[192:195], v[88:91]
	v_mfma_f32_16x16x32_bf16 v[84:87], v[100:103], v[196:199], v[84:87]
	v_mfma_f32_16x16x32_bf16 v[80:83], v[160:163], v[200:203], v[80:83]
	v_mfma_f32_16x16x32_bf16 v[76:79], v[100:103], v[204:207], v[76:79]
	v_mfma_f32_16x16x32_bf16 v[72:75], v[160:163], v[208:211], v[72:75]
	v_mfma_f32_16x16x32_bf16 v[68:71], v[100:103], v[212:215], v[68:71]
	v_mfma_f32_16x16x32_bf16 v[64:67], v[160:163], v[216:219], v[64:67]
	v_mfma_f32_16x16x32_bf16 v[228:231], v[108:111], v[192:195], v[92:95]
	v_mfma_f32_16x16x32_bf16 v[188:191], v[108:111], v[200:203], v[84:87]
	v_mfma_f32_16x16x32_bf16 v[192:195], v[108:111], v[208:211], v[76:79]
	v_mfma_f32_16x16x32_bf16 v[196:199], v[108:111], v[216:219], v[68:71]
	s_nop 0
	s_barrier
	s_nop 0
	ds_read_b128 v[68:71], v155 offset:16384
	ds_read_b128 v[76:79], v155 offset:17408
	ds_read_b128 v[84:87], v173 offset:16384
	ds_read_b128 v[92:95], v173 offset:17408
	ds_read_b128 v[200:203], v174 offset:16384
	ds_read_b128 v[204:207], v174 offset:17408
	ds_read_b128 v[208:211], v175 offset:16384
	ds_read_b128 v[212:215], v175 offset:17408
	s_waitcnt vmcnt(4)
	s_barrier
	s_waitcnt lgkmcnt(0)
	s_nop 0
	v_mfma_f32_16x16x32_bf16 v[60:63], v[142:145], v[68:71], v[60:63]
	v_mfma_f32_16x16x32_bf16 v[56:59], v[180:183], v[68:71], v[56:59]
	v_mfma_f32_16x16x32_bf16 v[48:51], v[180:183], v[84:87], v[48:51]
	v_mfma_f32_16x16x32_bf16 v[40:43], v[180:183], v[200:203], v[40:43]
	v_mfma_f32_16x16x32_bf16 v[32:35], v[180:183], v[208:211], v[32:35]
	v_mfma_f32_16x16x32_bf16 v[60:63], v[146:149], v[76:79], v[60:63]
	v_mfma_f32_16x16x32_bf16 v[56:59], v[184:187], v[76:79], v[56:59]
	v_mfma_f32_16x16x32_bf16 v[52:55], v[142:145], v[84:87], v[52:55]
	v_mfma_f32_16x16x32_bf16 v[48:51], v[184:187], v[92:95], v[48:51]
	v_mfma_f32_16x16x32_bf16 v[44:47], v[142:145], v[200:203], v[44:47]
	v_mfma_f32_16x16x32_bf16 v[40:43], v[184:187], v[204:207], v[40:43]
	v_mfma_f32_16x16x32_bf16 v[36:39], v[142:145], v[208:211], v[36:39]
	v_mfma_f32_16x16x32_bf16 v[32:35], v[184:187], v[212:215], v[32:35]
	v_mfma_f32_16x16x32_bf16 v[216:219], v[146:149], v[92:95], v[52:55]
	v_mfma_f32_16x16x32_bf16 v[232:235], v[146:149], v[204:207], v[44:47]
	v_mfma_f32_16x16x32_bf16 v[142:145], v[146:149], v[212:215], v[36:39]
	s_nop 0
	s_nop 0
	v_mfma_f32_16x16x32_bf16 v[24:27], v[224:227], v[68:71], v[24:27]
	v_mfma_f32_16x16x32_bf16 v[16:19], v[224:227], v[84:87], v[16:19]
	v_mfma_f32_16x16x32_bf16 v[4:7], v[100:103], v[208:211], v[4:7]
	v_mfma_f32_16x16x32_bf16 v[0:3], v[224:227], v[208:211], v[0:3]
	v_mfma_f32_16x16x32_bf16 v[28:31], v[100:103], v[68:71], v[28:31]
	v_mfma_f32_16x16x32_bf16 v[24:27], v[160:163], v[76:79], v[24:27]
	v_mfma_f32_16x16x32_bf16 v[20:23], v[100:103], v[84:87], v[20:23]
	v_mfma_f32_16x16x32_bf16 v[16:19], v[160:163], v[92:95], v[16:19]
	v_mfma_f32_16x16x32_bf16 v[12:15], v[100:103], v[200:203], v[12:15]
	v_mfma_f32_16x16x32_bf16 v[8:11], v[224:227], v[200:203], v[8:11]
	v_mfma_f32_16x16x32_bf16 v[4:7], v[108:111], v[212:215], v[4:7]
	v_mfma_f32_16x16x32_bf16 v[0:3], v[160:163], v[212:215], v[0:3]
	v_mfma_f32_16x16x32_bf16 v[146:149], v[108:111], v[76:79], v[28:31]
	v_mfma_f32_16x16x32_bf16 v[178:181], v[108:111], v[92:95], v[20:23]
	v_mfma_f32_16x16x32_bf16 v[182:185], v[108:111], v[204:207], v[12:15]
	v_mfma_f32_16x16x32_bf16 v[200:203], v[160:163], v[204:207], v[8:11]
	s_nop 0
	s_barrier
	s_nop 0
	ds_read_b128 v[8:11], v158
	ds_read_b128 v[12:15], v158 offset:1024
	ds_read_b128 v[160:163], v158 offset:2048
	ds_read_b128 v[204:207], v158 offset:3072
	ds_read_b128 v[20:23], v155 offset:32768
	ds_read_b128 v[28:31], v155 offset:33792
	ds_read_b128 v[36:39], v173 offset:32768
	ds_read_b128 v[44:47], v173 offset:33792
	ds_read_b128 v[52:55], v174 offset:32768
	ds_read_b128 v[208:211], v174 offset:33792
	ds_read_b128 v[212:215], v175 offset:32768
	ds_read_b128 v[224:227], v175 offset:33792
	s_waitcnt vmcnt(2)
	s_barrier
; #define LDA(dst,b,h) _Pragma("unroll") for(int m=0;m<4;++m) _Pragma("unroll") for(int k=0;k<2;++k) \
;     dst[m][k]=*reinterpret_cast<const bf16x8*>((char*)SA(b,h)+lds_byte(wr*64+m*16+fr,k*32+fq*8))
; #define LDB(dst,b,h) _Pragma("unroll") for(int n=0;n<2;++n) _Pragma("unroll") for(int k=0;k<2;++k) \
;     dst[n][k]=*reinterpret_cast<const bf16x8*>((char*)SB(b,h)+lds_byte(wc*32+n*16+fr,k*32+fq*8))
; #define MMA(ai,bj,At_,Bt_) do{__builtin_amdgcn_s_setprio(1); \
;     _Pragma("unroll") for(int m=0;m<4;++m) _Pragma("unroll") for(int n=0;n<2;++n) _Pragma("unroll") for(int k=0;k<2;++k) \
;       acc[ai][bj][m][n]=__builtin_amdgcn_mfma_f32_16x16x32_bf16(Bt_[n][k],At_[m][k],acc[ai][bj][m][n],0,0,0); \
;     __builtin_amdgcn_s_setprio(0);}while(0)
; #define WAIT_V(n) asm volatile("s_waitcnt vmcnt(" #n ")":::"memory")
; #define WAIT_L(n) asm volatile("s_waitcnt lgkmcnt(" #n ")":::"memory")
; #define BAR __builtin_amdgcn_s_barrier()
; DEVINL void gemm8_mainloop(const u16* A, long lda, const u16* Bt, long ldb, int K, int brow, int bcol, f32x4 (&acc)[2][2][4][2], char* smem, int tid) {
;     ...
;   { LDB(B0,1,0); LDA(At,1,0); WAIT_V(2); BAR; WAIT_L(0); MMA(0,0,At,B0); BAR;
;     LDB(B1,1,1); WAIT_V(0); BAR; WAIT_L(0); MMA(0,1,At,B1); BAR;
;     LDA(At,1,1); BAR; WAIT_L(0); MMA(1,0,At,B0); MMA(1,1,At,B1); BAR; }
;   if(wr==0)BAR;
	s_waitcnt lgkmcnt(0)
	s_nop 0
	v_mfma_f32_16x16x32_bf16 v[68:71], v[8:11], v[20:23], v[124:127]
	v_mfma_f32_16x16x32_bf16 v[124:127], v[12:15], v[28:31], v[68:71]
	v_mfma_f32_16x16x32_bf16 v[68:71], v[160:163], v[20:23], v[120:123]
	v_mfma_f32_16x16x32_bf16 v[120:123], v[204:207], v[28:31], v[68:71]
	v_mfma_f32_16x16x32_bf16 v[68:71], v[8:11], v[36:39], v[116:119]
	v_mfma_f32_16x16x32_bf16 v[108:111], v[12:15], v[44:47], v[68:71]
	v_mfma_f32_16x16x32_bf16 v[68:71], v[160:163], v[36:39], v[112:115]
	v_mfma_f32_16x16x32_bf16 v[100:103], v[204:207], v[44:47], v[68:71]
	v_mfma_f32_16x16x32_bf16 v[68:71], v[8:11], v[52:55], v[138:141]
	v_mfma_f32_16x16x32_bf16 v[92:95], v[12:15], v[208:211], v[68:71]
	v_mfma_f32_16x16x32_bf16 v[68:71], v[160:163], v[52:55], v[104:107]
	v_mfma_f32_16x16x32_bf16 v[84:87], v[204:207], v[208:211], v[68:71]
	v_mfma_f32_16x16x32_bf16 v[68:71], v[8:11], v[212:215], v[220:223]
	v_mfma_f32_16x16x32_bf16 v[76:79], v[12:15], v[224:227], v[68:71]
	v_mfma_f32_16x16x32_bf16 v[68:71], v[160:163], v[212:215], v[96:99]
	v_mfma_f32_16x16x32_bf16 v[68:71], v[204:207], v[224:227], v[68:71]
	s_nop 0
	s_barrier
	ds_read_b128 v[138:141], v156
	ds_read_b128 v[220:223], v156 offset:1024
	ds_read_b128 v[236:239], v156 offset:2048
	ds_read_b128 v[156:159], v156 offset:3072
	s_waitcnt vmcnt(0)
	s_barrier
	s_waitcnt lgkmcnt(0)
	s_nop 0
	v_mfma_f32_16x16x32_bf16 v[96:99], v[138:141], v[20:23], v[228:231]
	v_mfma_f32_16x16x32_bf16 v[20:23], v[236:239], v[20:23], v[88:91]
	v_mfma_f32_16x16x32_bf16 v[112:115], v[156:159], v[28:31], v[20:23]
	v_mfma_f32_16x16x32_bf16 v[20:23], v[138:141], v[36:39], v[188:191]
	v_mfma_f32_16x16x32_bf16 v[104:107], v[220:223], v[44:47], v[20:23]
	v_mfma_f32_16x16x32_bf16 v[20:23], v[236:239], v[36:39], v[80:83]
	v_mfma_f32_16x16x32_bf16 v[116:119], v[220:223], v[28:31], v[96:99]
	v_mfma_f32_16x16x32_bf16 v[96:99], v[156:159], v[44:47], v[20:23]
	v_mfma_f32_16x16x32_bf16 v[20:23], v[138:141], v[52:55], v[192:195]
	v_mfma_f32_16x16x32_bf16 v[88:91], v[220:223], v[208:211], v[20:23]
	v_mfma_f32_16x16x32_bf16 v[20:23], v[236:239], v[52:55], v[72:75]
	v_mfma_f32_16x16x32_bf16 v[80:83], v[156:159], v[208:211], v[20:23]
	v_mfma_f32_16x16x32_bf16 v[20:23], v[138:141], v[212:215], v[196:199]
	v_mfma_f32_16x16x32_bf16 v[72:75], v[220:223], v[224:227], v[20:23]
	v_mfma_f32_16x16x32_bf16 v[20:23], v[236:239], v[212:215], v[64:67]
	v_mfma_f32_16x16x32_bf16 v[64:67], v[156:159], v[224:227], v[20:23]
	s_nop 0
	s_barrier
	ds_read_b128 v[186:189], v155 offset:49152
	ds_read_b128 v[190:193], v155 offset:50176
	ds_read_b128 v[194:197], v173 offset:49152
	ds_read_b128 v[208:211], v173 offset:50176
	ds_read_b128 v[212:215], v174 offset:49152
	ds_read_b128 v[224:227], v174 offset:50176
	ds_read_b128 v[228:231], v175 offset:49152
	ds_read_b128 v[240:243], v175 offset:50176
	s_barrier
	s_waitcnt lgkmcnt(0)
	s_nop 0
	v_mfma_f32_16x16x32_bf16 v[20:23], v[8:11], v[186:189], v[60:63]
	v_mfma_f32_16x16x32_bf16 v[60:63], v[12:15], v[190:193], v[20:23]
	v_mfma_f32_16x16x32_bf16 v[20:23], v[160:163], v[186:189], v[56:59]
	v_mfma_f32_16x16x32_bf16 v[52:55], v[204:207], v[190:193], v[20:23]
	v_mfma_f32_16x16x32_bf16 v[20:23], v[8:11], v[194:197], v[216:219]
	v_mfma_f32_16x16x32_bf16 v[44:47], v[12:15], v[208:211], v[20:23]
	v_mfma_f32_16x16x32_bf16 v[20:23], v[160:163], v[194:197], v[48:51]
	v_mfma_f32_16x16x32_bf16 v[36:39], v[204:207], v[208:211], v[20:23]
	v_mfma_f32_16x16x32_bf16 v[20:23], v[8:11], v[212:215], v[232:235]
	v_mfma_f32_16x16x32_bf16 v[8:11], v[8:11], v[228:231], v[142:145]
	v_mfma_f32_16x16x32_bf16 v[28:31], v[12:15], v[224:227], v[20:23]
	v_mfma_f32_16x16x32_bf16 v[20:23], v[160:163], v[212:215], v[40:43]
	v_mfma_f32_16x16x32_bf16 v[12:15], v[12:15], v[240:243], v[8:11]
	v_mfma_f32_16x16x32_bf16 v[8:11], v[160:163], v[228:231], v[32:35]
	v_mfma_f32_16x16x32_bf16 v[20:23], v[204:207], v[224:227], v[20:23]
	v_mfma_f32_16x16x32_bf16 v[8:11], v[204:207], v[240:243], v[8:11]
	s_nop 0
	s_nop 0
	v_mfma_f32_16x16x32_bf16 v[32:35], v[138:141], v[186:189], v[146:149]
	v_mfma_f32_16x16x32_bf16 v[24:27], v[236:239], v[186:189], v[24:27]
	v_mfma_f32_16x16x32_bf16 v[16:19], v[236:239], v[194:197], v[16:19]
	v_mfma_f32_16x16x32_bf16 v[56:59], v[220:223], v[190:193], v[32:35]
	v_mfma_f32_16x16x32_bf16 v[48:51], v[156:159], v[190:193], v[24:27]
	v_mfma_f32_16x16x32_bf16 v[24:27], v[138:141], v[194:197], v[178:181]
	v_mfma_f32_16x16x32_bf16 v[32:35], v[156:159], v[208:211], v[16:19]
	v_mfma_f32_16x16x32_bf16 v[16:19], v[138:141], v[212:215], v[182:185]
	v_mfma_f32_16x16x32_bf16 v[40:43], v[220:223], v[208:211], v[24:27]
	v_mfma_f32_16x16x32_bf16 v[24:27], v[220:223], v[224:227], v[16:19]
	v_mfma_f32_16x16x32_bf16 v[16:19], v[236:239], v[212:215], v[200:203]
	v_mfma_f32_16x16x32_bf16 v[4:7], v[138:141], v[228:231], v[4:7]
	v_mfma_f32_16x16x32_bf16 v[0:3], v[236:239], v[228:231], v[0:3]
	v_mfma_f32_16x16x32_bf16 v[16:19], v[156:159], v[224:227], v[16:19]
	v_mfma_f32_16x16x32_bf16 v[4:7], v[220:223], v[240:243], v[4:7]
	v_mfma_f32_16x16x32_bf16 v[0:3], v[156:159], v[240:243], v[0:3]
	s_setprio 0
	s_cmpk_gt_u32 s0, 0xff
	s_barrier
	s_cbranch_scc1 .LBB0_919
	s_barrier

; #define WAIT_V(n) asm volatile("s_waitcnt vmcnt(" #n ")":::"memory")
; #define BAR __builtin_amdgcn_s_barrier()
; DEVINL void gemm8_mainloop(const u16* A, long lda, const u16* Bt, long ldb, int K, int brow, int bcol, f32x4 (&acc)[2][2][4][2], char* smem, int tid) {
;     ...
;   if(wr==1)BAR;
;   WAIT_V(4); BAR;
.LBB0_962:
	v_mov_b32_e32 v151, v176
	s_nop 0
	v_readfirstlane_b32 s29, v151
	s_ashr_i32 s0, s29, 8
	s_cmp_lg_u32 s0, 1
	s_cbranch_scc1 .LBB0_964
	s_setprio 1
	s_barrier

; #define STAGE(P,BASE,LD,br,kt) do{long _g=(long)(br)*(LD)+(long)(kt)*BK; \
;     _Pragma("unroll") for(int _i=0;_i<2;++_i){int _b=tid*16+_i*8192;int _r,_c;stage_rc(_b,_r,_c); \
;       __builtin_amdgcn_global_load_lds((const unsigned*)((BASE)+_g+(long)_r*(LD)+_c), \
;         (unsigned*)((char*)(P)+_b),16,0,0);}}while(0)
; #define STAGE(P,BASE,LD,br,kt) do{long _g=(long)(br)*(LD)+(long)(kt)*BK; \
;     _Pragma("unroll") for(int _i=0;_i<2;++_i){int _b=tid*16+_i*8192;int _r,_c;stage_rc(_b,_r,_c); \
;       __builtin_amdgcn_global_load_lds((const unsigned*)((BASE)+_g+(long)_r*(LD)+_c), \
;         (unsigned*)((char*)(P)+_b),16,0,0);}}while(0)
; #define LDA(dst,b,h) _Pragma("unroll") for(int m=0;m<4;++m) _Pragma("unroll") for(int k=0;k<2;++k) \
;     dst[m][k]=*reinterpret_cast<const bf16x8*>((char*)SA(b,h)+lds_byte(wr*64+m*16+fr,k*32+fq*8))
; #define LDB(dst,b,h) _Pragma("unroll") for(int n=0;n<2;++n) _Pragma("unroll") for(int k=0;k<2;++k) \
;     dst[n][k]=*reinterpret_cast<const bf16x8*>((char*)SB(b,h)+lds_byte(wc*32+n*16+fr,k*32+fq*8))
; #define MMA(ai,bj,At_,Bt_) do{__builtin_amdgcn_s_setprio(1); \
;     _Pragma("unroll") for(int m=0;m<4;++m) _Pragma("unroll") for(int n=0;n<2;++n) _Pragma("unroll") for(int k=0;k<2;++k) \
;       acc[ai][bj][m][n]=__builtin_amdgcn_mfma_f32_16x16x32_bf16(Bt_[n][k],At_[m][k],acc[ai][bj][m][n],0,0,0); \
;     __builtin_amdgcn_s_setprio(0);}while(0)
; #define WAIT_L(n) asm volatile("s_waitcnt lgkmcnt(" #n ")":::"memory")
; #define BAR __builtin_amdgcn_s_barrier()
; #define SCHED __builtin_amdgcn_sched_barrier(0)
; DEVINL void gemm8_mainloop(const u16* A, long lda, const u16* Bt, long ldb, int K, int brow, int bcol, f32x4 (&acc)[2][2][4][2], char* smem, int tid) {
;     ...
;     LDB(B0,0,0); SCHED; LDA(At,0,0); STAGE(SA(1,1),A,lda,brow+HALF,t+1);
;     WAIT_L(8); BAR; WAIT_L(0); MMA(0,0,At,B0); BAR; SCHED;
;     LDB(B1,0,1); STAGE(SB(0,0),Bt,ldb,bcol,t+2);
;     BAR; WAIT_L(0); MMA(0,1,At,B1); BAR;
;     LDA(At,0,1); STAGE(SA(0,0),A,lda,brow,t+2);
;     BAR; WAIT_L(0); MMA(1,0,At,B0); BAR; SCHED;
.LBB0_965:
	ds_read_b128 v[178:181], v163
	ds_read_b128 v[182:185], v163 offset:1024
	ds_read_b128 v[186:189], v163 offset:2048
	ds_read_b128 v[190:193], v163 offset:3072
	v_add_u32_e32 v174, 0xc000, v152
	v_lshl_add_u64 v[242:243], s[94:95], 0, v[146:147]
	v_readfirstlane_b32 s25, v174
	v_add_u32_e32 v175, 0xe000, v152
	v_add_u32_e32 v171, s0, v162
	v_add_u32_e32 v172, s1, v162
	v_add_u32_e32 v173, s27, v162
	v_lshl_add_u64 v[164:165], v[242:243], 0, s[4:5]
	s_mov_b32 m0, s25
	v_lshl_add_u64 v[244:245], s[94:95], 0, v[148:149]
	v_readfirstlane_b32 s25, v175
	ds_read_b128 v[166:169], v153
	ds_read_b128 v[194:197], v153 offset:1024
	ds_read_b128 v[198:201], v171
	ds_read_b128 v[202:205], v171 offset:1024
	ds_read_b128 v[206:209], v172
	ds_read_b128 v[210:213], v172 offset:1024
	ds_read_b128 v[214:217], v173
	ds_read_b128 v[218:221], v173 offset:1024
	global_load_lds_dwordx4 v[164:165], off
	v_lshl_add_u64 v[164:165], v[244:245], 0, s[4:5]
	s_mov_b32 m0, s25
	s_nop 0
	global_load_lds_dwordx4 v[164:165], off
	s_waitcnt lgkmcnt(8)
	s_barrier
	s_waitcnt lgkmcnt(0)
	s_nop 0
	v_mfma_f32_16x16x32_bf16 v[124:127], v[178:181], v[166:169], v[124:127]
	v_mfma_f32_16x16x32_bf16 v[120:123], v[186:189], v[166:169], v[120:123]
	v_mfma_f32_16x16x32_bf16 v[116:119], v[178:181], v[198:201], v[116:119]
	v_mfma_f32_16x16x32_bf16 v[112:115], v[186:189], v[198:201], v[112:115]
	v_mfma_f32_16x16x32_bf16 v[108:111], v[178:181], v[206:209], v[108:111]
	v_mfma_f32_16x16x32_bf16 v[104:107], v[186:189], v[206:209], v[104:107]
	v_mfma_f32_16x16x32_bf16 v[100:103], v[178:181], v[214:217], v[100:103]
	v_mfma_f32_16x16x32_bf16 v[96:99], v[186:189], v[214:217], v[96:99]
	v_mfma_f32_16x16x32_bf16 v[124:127], v[182:185], v[194:197], v[124:127]
	v_mfma_f32_16x16x32_bf16 v[120:123], v[190:193], v[194:197], v[120:123]
	v_mfma_f32_16x16x32_bf16 v[116:119], v[182:185], v[202:205], v[116:119]
	v_mfma_f32_16x16x32_bf16 v[112:115], v[190:193], v[202:205], v[112:115]
	v_mfma_f32_16x16x32_bf16 v[108:111], v[182:185], v[210:213], v[108:111]
	v_mfma_f32_16x16x32_bf16 v[104:107], v[190:193], v[210:213], v[104:107]
	v_mfma_f32_16x16x32_bf16 v[100:103], v[182:185], v[218:221], v[100:103]
	v_mfma_f32_16x16x32_bf16 v[96:99], v[190:193], v[218:221], v[96:99]
	s_nop 0
	s_barrier
	v_add_u32_e32 v164, s30, v154
	v_lshl_add_u64 v[246:247], s[94:95], 0, v[142:143]
	v_readfirstlane_b32 s25, v164
	v_add_u32_e32 v165, 0x2000, v164
	v_lshl_add_u64 v[238:239], v[246:247], 0, s[6:7]
	s_mov_b32 m0, s25
	v_lshl_add_u64 v[248:249], s[94:95], 0, v[144:145]
	v_readfirstlane_b32 s25, v165
	ds_read_b128 v[222:225], v160
	ds_read_b128 v[226:229], v160 offset:1024
	ds_read_b128 v[230:233], v160 offset:2048
	ds_read_b128 v[234:237], v160 offset:3072
	global_load_lds_dwordx4 v[238:239], off
	v_lshl_add_u64 v[238:239], v[248:249], 0, s[6:7]
	s_mov_b32 m0, s25
	s_nop 0
	global_load_lds_dwordx4 v[238:239], off
	s_barrier
	s_waitcnt lgkmcnt(0)
	s_nop 0
	v_mfma_f32_16x16x32_bf16 v[92:95], v[222:225], v[166:169], v[92:95]
	v_mfma_f32_16x16x32_bf16 v[88:91], v[230:233], v[166:169], v[88:91]
	v_mfma_f32_16x16x32_bf16 v[84:87], v[222:225], v[198:201], v[84:87]
	v_mfma_f32_16x16x32_bf16 v[80:83], v[230:233], v[198:201], v[80:83]
	v_mfma_f32_16x16x32_bf16 v[76:79], v[222:225], v[206:209], v[76:79]
	v_mfma_f32_16x16x32_bf16 v[72:75], v[230:233], v[206:209], v[72:75]
	v_mfma_f32_16x16x32_bf16 v[68:71], v[222:225], v[214:217], v[68:71]
	v_mfma_f32_16x16x32_bf16 v[64:67], v[230:233], v[214:217], v[64:67]
	v_mfma_f32_16x16x32_bf16 v[92:95], v[226:229], v[194:197], v[92:95]
	v_mfma_f32_16x16x32_bf16 v[88:91], v[234:237], v[194:197], v[88:91]
	v_mfma_f32_16x16x32_bf16 v[84:87], v[226:229], v[202:205], v[84:87]
	v_mfma_f32_16x16x32_bf16 v[80:83], v[234:237], v[202:205], v[80:83]
	v_mfma_f32_16x16x32_bf16 v[76:79], v[226:229], v[210:213], v[76:79]
	v_mfma_f32_16x16x32_bf16 v[72:75], v[234:237], v[210:213], v[72:75]
	v_mfma_f32_16x16x32_bf16 v[68:71], v[226:229], v[218:221], v[68:71]
	v_mfma_f32_16x16x32_bf16 v[64:67], v[234:237], v[218:221], v[64:67]
	s_nop 0
	v_readfirstlane_b32 s25, v152
	v_lshl_add_u64 v[166:167], v[242:243], 0, s[8:9]
	s_mov_b32 m0, s25
	s_barrier
	ds_read_b128 v[194:197], v153 offset:16384
	ds_read_b128 v[198:201], v153 offset:17408
	ds_read_b128 v[202:205], v171 offset:16384
	ds_read_b128 v[206:209], v171 offset:17408
	ds_read_b128 v[210:213], v172 offset:16384
	ds_read_b128 v[214:217], v172 offset:17408
	ds_read_b128 v[218:221], v173 offset:16384
	ds_read_b128 v[238:241], v173 offset:17408
	global_load_lds_dwordx4 v[166:167], off
	v_add_u32_e32 v166, 0x2000, v152
	v_lshl_add_u64 v[168:169], v[244:245], 0, s[8:9]
	v_readfirstlane_b32 s25, v166
	s_mov_b32 m0, s25
	s_nop 0
	global_load_lds_dwordx4 v[168:169], off
	s_barrier
	s_waitcnt lgkmcnt(0)
	s_nop 0
	v_mfma_f32_16x16x32_bf16 v[60:63], v[178:181], v[194:197], v[60:63]
	v_mfma_f32_16x16x32_bf16 v[56:59], v[186:189], v[194:197], v[56:59]
	v_mfma_f32_16x16x32_bf16 v[52:55], v[178:181], v[202:205], v[52:55]
	v_mfma_f32_16x16x32_bf16 v[48:51], v[186:189], v[202:205], v[48:51]
	v_mfma_f32_16x16x32_bf16 v[44:47], v[178:181], v[210:213], v[44:47]
	v_mfma_f32_16x16x32_bf16 v[40:43], v[186:189], v[210:213], v[40:43]
	v_mfma_f32_16x16x32_bf16 v[36:39], v[178:181], v[218:221], v[36:39]
	v_mfma_f32_16x16x32_bf16 v[32:35], v[186:189], v[218:221], v[32:35]
	v_mfma_f32_16x16x32_bf16 v[60:63], v[182:185], v[198:201], v[60:63]
	v_mfma_f32_16x16x32_bf16 v[56:59], v[190:193], v[198:201], v[56:59]
	v_mfma_f32_16x16x32_bf16 v[52:55], v[182:185], v[206:209], v[52:55]
	v_mfma_f32_16x16x32_bf16 v[48:51], v[190:193], v[206:209], v[48:51]
	v_mfma_f32_16x16x32_bf16 v[44:47], v[182:185], v[214:217], v[44:47]
	v_mfma_f32_16x16x32_bf16 v[40:43], v[190:193], v[214:217], v[40:43]
	v_mfma_f32_16x16x32_bf16 v[36:39], v[182:185], v[238:241], v[36:39]
	v_mfma_f32_16x16x32_bf16 v[32:35], v[190:193], v[238:241], v[32:35]
	s_nop 0
	s_barrier
; #define STAGE(P,BASE,LD,br,kt) do{long _g=(long)(br)*(LD)+(long)(kt)*BK; \
;     _Pragma("unroll") for(int _i=0;_i<2;++_i){int _b=tid*16+_i*8192;int _r,_c;stage_rc(_b,_r,_c); \
;       __builtin_amdgcn_global_load_lds((const unsigned*)((BASE)+_g+(long)_r*(LD)+_c), \
;         (unsigned*)((char*)(P)+_b),16,0,0);}}while(0)
; #define STAGE(P,BASE,LD,br,kt) do{long _g=(long)(br)*(LD)+(long)(kt)*BK; \
;     _Pragma("unroll") for(int _i=0;_i<2;++_i){int _b=tid*16+_i*8192;int _r,_c;stage_rc(_b,_r,_c); \
;       __builtin_amdgcn_global_load_lds((const unsigned*)((BASE)+_g+(long)_r*(LD)+_c), \
;         (unsigned*)((char*)(P)+_b),16,0,0);}}while(0)
; #define LDA(dst,b,h) _Pragma("unroll") for(int m=0;m<4;++m) _Pragma("unroll") for(int k=0;k<2;++k) \
;     dst[m][k]=*reinterpret_cast<const bf16x8*>((char*)SA(b,h)+lds_byte(wr*64+m*16+fr,k*32+fq*8))
; #define LDB(dst,b,h) _Pragma("unroll") for(int n=0;n<2;++n) _Pragma("unroll") for(int k=0;k<2;++k) \
;     dst[n][k]=*reinterpret_cast<const bf16x8*>((char*)SB(b,h)+lds_byte(wc*32+n*16+fr,k*32+fq*8))
; #define MMA(ai,bj,At_,Bt_) do{__builtin_amdgcn_s_setprio(1); \
;     _Pragma("unroll") for(int m=0;m<4;++m) _Pragma("unroll") for(int n=0;n<2;++n) _Pragma("unroll") for(int k=0;k<2;++k) \
;       acc[ai][bj][m][n]=__builtin_amdgcn_mfma_f32_16x16x32_bf16(Bt_[n][k],At_[m][k],acc[ai][bj][m][n],0,0,0); \
;     __builtin_amdgcn_s_setprio(0);}while(0)
; #define WAIT_V(n) asm volatile("s_waitcnt vmcnt(" #n ")":::"memory")
; #define WAIT_L(n) asm volatile("s_waitcnt lgkmcnt(" #n ")":::"memory")
; #define BAR __builtin_amdgcn_s_barrier()
; #define SCHED __builtin_amdgcn_sched_barrier(0)
; DEVINL void gemm8_mainloop(const u16* A, long lda, const u16* Bt, long ldb, int K, int brow, int bcol, f32x4 (&acc)[2][2][4][2], char* smem, int tid) {
;     ...
;     STAGE(SB(0,1),Bt,ldb,bcol+HALF,t+2);
;     WAIT_V(6); BAR; MMA(1,1,At,B1); BAR;
;     LDB(B0,1,0); SCHED; LDA(At,1,0); STAGE(SA(0,1),A,lda,brow+HALF,t+2);
;     WAIT_L(8); BAR; WAIT_L(0); MMA(0,0,At,B0); BAR; SCHED;
;     LDB(B1,1,1); STAGE(SB(1,0),Bt,ldb,bcol,t+3);
	v_add_u32_e32 v167, s31, v154
	v_lshl_add_u64 v[168:169], v[246:247], 0, s[10:11]
	v_readfirstlane_b32 s25, v167
	s_mov_b32 m0, s25
	v_lshl_add_u64 v[178:179], v[248:249], 0, s[10:11]
	global_load_lds_dwordx4 v[168:169], off
	v_add_u32_e32 v168, 0x2000, v167
	s_nop 0
	v_readfirstlane_b32 s25, v168
	s_mov_b32 m0, s25
	s_nop 0
	global_load_lds_dwordx4 v[178:179], off
	s_waitcnt vmcnt(6)
	s_barrier
	s_nop 0
	v_mfma_f32_16x16x32_bf16 v[28:31], v[222:225], v[194:197], v[28:31]
	v_mfma_f32_16x16x32_bf16 v[24:27], v[230:233], v[194:197], v[24:27]
	v_mfma_f32_16x16x32_bf16 v[20:23], v[222:225], v[202:205], v[20:23]
	v_mfma_f32_16x16x32_bf16 v[16:19], v[230:233], v[202:205], v[16:19]
	v_mfma_f32_16x16x32_bf16 v[12:15], v[222:225], v[210:213], v[12:15]
	v_mfma_f32_16x16x32_bf16 v[8:11], v[230:233], v[210:213], v[8:11]
	v_mfma_f32_16x16x32_bf16 v[4:7], v[222:225], v[218:221], v[4:7]
	v_mfma_f32_16x16x32_bf16 v[0:3], v[230:233], v[218:221], v[0:3]
	v_mfma_f32_16x16x32_bf16 v[28:31], v[226:229], v[198:201], v[28:31]
	v_mfma_f32_16x16x32_bf16 v[24:27], v[234:237], v[198:201], v[24:27]
	v_mfma_f32_16x16x32_bf16 v[20:23], v[226:229], v[206:209], v[20:23]
	v_mfma_f32_16x16x32_bf16 v[16:19], v[234:237], v[206:209], v[16:19]
	v_mfma_f32_16x16x32_bf16 v[12:15], v[226:229], v[214:217], v[12:15]
	v_mfma_f32_16x16x32_bf16 v[8:11], v[234:237], v[214:217], v[8:11]
	v_mfma_f32_16x16x32_bf16 v[4:7], v[226:229], v[238:241], v[4:7]
	v_mfma_f32_16x16x32_bf16 v[0:3], v[234:237], v[238:241], v[0:3]
	s_nop 0
	s_barrier
	ds_read_b128 v[178:181], v157
	ds_read_b128 v[182:185], v157 offset:1024
	ds_read_b128 v[186:189], v157 offset:2048
	ds_read_b128 v[190:193], v157 offset:3072
	v_add_u32_e32 v169, 0x4000, v152
	v_add_u32_e32 v170, 0x6000, v152
	v_readfirstlane_b32 s25, v169
	v_lshl_add_u64 v[226:227], v[242:243], 0, s[12:13]
	s_mov_b32 m0, s25
	v_readfirstlane_b32 s25, v170
	ds_read_b128 v[194:197], v153 offset:32768
	ds_read_b128 v[198:201], v153 offset:33792
	ds_read_b128 v[202:205], v171 offset:32768
	ds_read_b128 v[206:209], v171 offset:33792
	ds_read_b128 v[210:213], v172 offset:32768
	ds_read_b128 v[214:217], v172 offset:33792
	ds_read_b128 v[218:221], v173 offset:32768
	ds_read_b128 v[222:225], v173 offset:33792
	global_load_lds_dwordx4 v[226:227], off
	v_lshl_add_u64 v[226:227], v[244:245], 0, s[12:13]
	s_mov_b32 m0, s25
	s_nop 0
	global_load_lds_dwordx4 v[226:227], off
	s_waitcnt lgkmcnt(8)
	s_barrier
	s_waitcnt lgkmcnt(0)
	s_nop 0
	v_mfma_f32_16x16x32_bf16 v[124:127], v[178:181], v[194:197], v[124:127]
	v_mfma_f32_16x16x32_bf16 v[120:123], v[186:189], v[194:197], v[120:123]
	v_mfma_f32_16x16x32_bf16 v[116:119], v[178:181], v[202:205], v[116:119]
	v_mfma_f32_16x16x32_bf16 v[112:115], v[186:189], v[202:205], v[112:115]
	v_mfma_f32_16x16x32_bf16 v[108:111], v[178:181], v[210:213], v[108:111]
	v_mfma_f32_16x16x32_bf16 v[104:107], v[186:189], v[210:213], v[104:107]
	v_mfma_f32_16x16x32_bf16 v[100:103], v[178:181], v[218:221], v[100:103]
	v_mfma_f32_16x16x32_bf16 v[96:99], v[186:189], v[218:221], v[96:99]
	v_mfma_f32_16x16x32_bf16 v[124:127], v[182:185], v[198:201], v[124:127]
	v_mfma_f32_16x16x32_bf16 v[120:123], v[190:193], v[198:201], v[120:123]
	v_mfma_f32_16x16x32_bf16 v[116:119], v[182:185], v[206:209], v[116:119]
	v_mfma_f32_16x16x32_bf16 v[112:115], v[190:193], v[206:209], v[112:115]
	v_mfma_f32_16x16x32_bf16 v[108:111], v[182:185], v[214:217], v[108:111]
	v_mfma_f32_16x16x32_bf16 v[104:107], v[190:193], v[214:217], v[104:107]
	v_mfma_f32_16x16x32_bf16 v[100:103], v[182:185], v[222:225], v[100:103]
	v_mfma_f32_16x16x32_bf16 v[96:99], v[190:193], v[222:225], v[96:99]
	s_nop 0
	s_barrier
	v_readfirstlane_b32 s25, v156
	v_add_u32_e32 v177, 0x2000, v156
	v_lshl_add_u64 v[250:251], v[246:247], 0, s[14:15]
	s_mov_b32 m0, s25
	v_readfirstlane_b32 s25, v177
	ds_read_b128 v[226:229], v155
	ds_read_b128 v[230:233], v155 offset:1024
	ds_read_b128 v[234:237], v155 offset:2048
	ds_read_b128 v[238:241], v155 offset:3072
	global_load_lds_dwordx4 v[250:251], off
	v_lshl_add_u64 v[250:251], v[248:249], 0, s[14:15]
	s_mov_b32 m0, s25
	s_nop 0
	global_load_lds_dwordx4 v[250:251], off
	s_barrier
	s_waitcnt lgkmcnt(0)
	s_nop 0
	v_mfma_f32_16x16x32_bf16 v[92:95], v[226:229], v[194:197], v[92:95]
	v_mfma_f32_16x16x32_bf16 v[88:91], v[234:237], v[194:197], v[88:91]
	v_mfma_f32_16x16x32_bf16 v[84:87], v[226:229], v[202:205], v[84:87]
	v_mfma_f32_16x16x32_bf16 v[80:83], v[234:237], v[202:205], v[80:83]
	v_mfma_f32_16x16x32_bf16 v[76:79], v[226:229], v[210:213], v[76:79]
	v_mfma_f32_16x16x32_bf16 v[72:75], v[234:237], v[210:213], v[72:75]
	v_mfma_f32_16x16x32_bf16 v[68:71], v[226:229], v[218:221], v[68:71]
	v_mfma_f32_16x16x32_bf16 v[64:67], v[234:237], v[218:221], v[64:67]
	v_mfma_f32_16x16x32_bf16 v[92:95], v[230:233], v[198:201], v[92:95]
	v_mfma_f32_16x16x32_bf16 v[88:91], v[238:241], v[198:201], v[88:91]
	v_mfma_f32_16x16x32_bf16 v[84:87], v[230:233], v[206:209], v[84:87]
	v_mfma_f32_16x16x32_bf16 v[80:83], v[238:241], v[206:209], v[80:83]
	v_mfma_f32_16x16x32_bf16 v[76:79], v[230:233], v[214:217], v[76:79]
	v_mfma_f32_16x16x32_bf16 v[72:75], v[238:241], v[214:217], v[72:75]
	v_mfma_f32_16x16x32_bf16 v[68:71], v[230:233], v[222:225], v[68:71]
	v_mfma_f32_16x16x32_bf16 v[64:67], v[238:241], v[222:225], v[64:67]
	s_nop 0
	v_readfirstlane_b32 s25, v158
	v_lshl_add_u64 v[242:243], v[242:243], 0, s[16:17]
	s_mov_b32 m0, s25
	v_readfirstlane_b32 s25, v159
	s_barrier
; #define STAGE(P,BASE,LD,br,kt) do{long _g=(long)(br)*(LD)+(long)(kt)*BK; \
;     _Pragma("unroll") for(int _i=0;_i<2;++_i){int _b=tid*16+_i*8192;int _r,_c;stage_rc(_b,_r,_c); \
;       __builtin_amdgcn_global_load_lds((const unsigned*)((BASE)+_g+(long)_r*(LD)+_c), \
;         (unsigned*)((char*)(P)+_b),16,0,0);}}while(0)
; #define STAGE(P,BASE,LD,br,kt) do{long _g=(long)(br)*(LD)+(long)(kt)*BK; \
;     _Pragma("unroll") for(int _i=0;_i<2;++_i){int _b=tid*16+_i*8192;int _r,_c;stage_rc(_b,_r,_c); \
;       __builtin_amdgcn_global_load_lds((const unsigned*)((BASE)+_g+(long)_r*(LD)+_c), \
;         (unsigned*)((char*)(P)+_b),16,0,0);}}while(0)
; #define LDA(dst,b,h) _Pragma("unroll") for(int m=0;m<4;++m) _Pragma("unroll") for(int k=0;k<2;++k) \
;     dst[m][k]=*reinterpret_cast<const bf16x8*>((char*)SA(b,h)+lds_byte(wr*64+m*16+fr,k*32+fq*8))
; #define LDB(dst,b,h) _Pragma("unroll") for(int n=0;n<2;++n) _Pragma("unroll") for(int k=0;k<2;++k) \
;     dst[n][k]=*reinterpret_cast<const bf16x8*>((char*)SB(b,h)+lds_byte(wc*32+n*16+fr,k*32+fq*8))
; #define MMA(ai,bj,At_,Bt_) do{__builtin_amdgcn_s_setprio(1); \
;     _Pragma("unroll") for(int m=0;m<4;++m) _Pragma("unroll") for(int n=0;n<2;++n) _Pragma("unroll") for(int k=0;k<2;++k) \
;       acc[ai][bj][m][n]=__builtin_amdgcn_mfma_f32_16x16x32_bf16(Bt_[n][k],At_[m][k],acc[ai][bj][m][n],0,0,0); \
;     __builtin_amdgcn_s_setprio(0);}while(0)
; #define WAIT_V(n) asm volatile("s_waitcnt vmcnt(" #n ")":::"memory")
; #define WAIT_L(n) asm volatile("s_waitcnt lgkmcnt(" #n ")":::"memory")
; #define BAR __builtin_amdgcn_s_barrier()
; #define SCHED __builtin_amdgcn_sched_barrier(0)
; DEVINL void gemm8_mainloop(const u16* A, long lda, const u16* Bt, long ldb, int K, int brow, int bcol, f32x4 (&acc)[2][2][4][2], char* smem, int tid) {
;     ...
;     BAR; WAIT_L(0); MMA(0,1,At,B1); BAR;
;     LDA(At,1,1); STAGE(SA(1,0),A,lda,brow,t+3);
;     BAR; WAIT_L(0); MMA(1,0,At,B0); BAR; SCHED;
;     STAGE(SB(1,1),Bt,ldb,bcol+HALF,t+3);
;     WAIT_V(6); BAR; MMA(1,1,At,B1); BAR;
;   }
;   { LDB(B0,0,0); LDA(At,0,0); STAGE(SA(1,1),A,lda,brow+HALF,nt-1);
;     BAR; WAIT_L(0); MMA(0,0,At,B0); BAR;
	ds_read_b128 v[194:197], v153 offset:49152
	ds_read_b128 v[198:201], v153 offset:50176
	ds_read_b128 v[202:205], v171 offset:49152
	ds_read_b128 v[206:209], v171 offset:50176
	ds_read_b128 v[210:213], v172 offset:49152
	ds_read_b128 v[214:217], v172 offset:50176
	ds_read_b128 v[218:221], v173 offset:49152
	ds_read_b128 v[222:225], v173 offset:50176
	global_load_lds_dwordx4 v[242:243], off
	v_lshl_add_u64 v[242:243], v[244:245], 0, s[16:17]
	s_mov_b32 m0, s25
	s_nop 0
	global_load_lds_dwordx4 v[242:243], off
	s_barrier
	s_waitcnt lgkmcnt(0)
	s_nop 0
	v_mfma_f32_16x16x32_bf16 v[60:63], v[178:181], v[194:197], v[60:63]
	v_mfma_f32_16x16x32_bf16 v[56:59], v[186:189], v[194:197], v[56:59]
	v_mfma_f32_16x16x32_bf16 v[52:55], v[178:181], v[202:205], v[52:55]
	v_mfma_f32_16x16x32_bf16 v[48:51], v[186:189], v[202:205], v[48:51]
	v_mfma_f32_16x16x32_bf16 v[44:47], v[178:181], v[210:213], v[44:47]
	v_mfma_f32_16x16x32_bf16 v[40:43], v[186:189], v[210:213], v[40:43]
	v_mfma_f32_16x16x32_bf16 v[36:39], v[178:181], v[218:221], v[36:39]
	v_mfma_f32_16x16x32_bf16 v[32:35], v[186:189], v[218:221], v[32:35]
	v_mfma_f32_16x16x32_bf16 v[60:63], v[182:185], v[198:201], v[60:63]
	v_mfma_f32_16x16x32_bf16 v[56:59], v[190:193], v[198:201], v[56:59]
	v_mfma_f32_16x16x32_bf16 v[52:55], v[182:185], v[206:209], v[52:55]
	v_mfma_f32_16x16x32_bf16 v[48:51], v[190:193], v[206:209], v[48:51]
	v_mfma_f32_16x16x32_bf16 v[44:47], v[182:185], v[214:217], v[44:47]
	v_mfma_f32_16x16x32_bf16 v[40:43], v[190:193], v[214:217], v[40:43]
	v_mfma_f32_16x16x32_bf16 v[36:39], v[182:185], v[222:225], v[36:39]
	v_mfma_f32_16x16x32_bf16 v[32:35], v[190:193], v[222:225], v[32:35]
	s_nop 0
	s_barrier
	v_readfirstlane_b32 s25, v161
	v_add_u32_e32 v177, 0x2000, v161
	v_lshl_add_u64 v[178:179], v[246:247], 0, s[18:19]
	s_mov_b32 m0, s25
	v_readfirstlane_b32 s25, v177
	global_load_lds_dwordx4 v[178:179], off
	v_lshl_add_u64 v[178:179], v[248:249], 0, s[18:19]
	s_mov_b32 m0, s25
	s_nop 0
	global_load_lds_dwordx4 v[178:179], off
	s_waitcnt vmcnt(6)
	s_barrier
	s_nop 0
	v_mfma_f32_16x16x32_bf16 v[28:31], v[226:229], v[194:197], v[28:31]
	v_mfma_f32_16x16x32_bf16 v[24:27], v[234:237], v[194:197], v[24:27]
	v_mfma_f32_16x16x32_bf16 v[20:23], v[226:229], v[202:205], v[20:23]
	v_mfma_f32_16x16x32_bf16 v[16:19], v[234:237], v[202:205], v[16:19]
	v_mfma_f32_16x16x32_bf16 v[12:15], v[226:229], v[210:213], v[12:15]
	v_mfma_f32_16x16x32_bf16 v[8:11], v[234:237], v[210:213], v[8:11]
	v_mfma_f32_16x16x32_bf16 v[4:7], v[226:229], v[218:221], v[4:7]
	v_mfma_f32_16x16x32_bf16 v[0:3], v[234:237], v[218:221], v[0:3]
	v_mfma_f32_16x16x32_bf16 v[28:31], v[230:233], v[198:201], v[28:31]
	v_mfma_f32_16x16x32_bf16 v[24:27], v[238:241], v[198:201], v[24:27]
	v_mfma_f32_16x16x32_bf16 v[20:23], v[230:233], v[206:209], v[20:23]
	v_mfma_f32_16x16x32_bf16 v[16:19], v[238:241], v[206:209], v[16:19]
	v_mfma_f32_16x16x32_bf16 v[12:15], v[230:233], v[214:217], v[12:15]
	v_mfma_f32_16x16x32_bf16 v[8:11], v[238:241], v[214:217], v[8:11]
	v_mfma_f32_16x16x32_bf16 v[4:7], v[230:233], v[222:225], v[4:7]
	v_mfma_f32_16x16x32_bf16 v[0:3], v[238:241], v[222:225], v[0:3]
	s_nop 0
	s_add_i32 s24, s24, 2
	v_lshl_add_u64 v[142:143], v[142:143], 0, s[20:21]
	v_lshl_add_u64 v[144:145], v[144:145], 0, s[20:21]
	v_lshl_add_u64 v[146:147], v[146:147], 0, s[20:21]
	s_cmpk_lt_u32 s24, 0x7c
	v_lshl_add_u64 v[148:149], v[148:149], 0, s[20:21]
	s_barrier
	s_cbranch_scc1 .LBB0_965
	s_or_b32 s0, s26, 0x80
	s_ashr_i32 s1, s0, 31
	s_lshl_b64 s[0:1], s[0:1], 14
	s_add_u32 s0, s62, s0
	s_addc_u32 s1, s63, s1
	s_add_u32 s0, s0, 0x3f80
	s_addc_u32 s1, s1, 0
	v_lshl_add_u64 v[158:159], v[134:135], 1, s[0:1]
	v_readfirstlane_b32 s24, v174
	v_lshl_add_u64 v[138:139], v[138:139], 1, v[158:159]
	s_mov_b32 m0, s24
	ds_read_b128 v[142:145], v163
	ds_read_b128 v[146:149], v163 offset:1024
	ds_read_b128 v[178:181], v163 offset:2048
	ds_read_b128 v[182:185], v163 offset:3072
	ds_read_b128 v[186:189], v153
	ds_read_b128 v[190:193], v153 offset:1024
	ds_read_b128 v[194:197], v171
	ds_read_b128 v[198:201], v171 offset:1024
	ds_read_b128 v[202:205], v172
	ds_read_b128 v[206:209], v172 offset:1024
	ds_read_b128 v[210:213], v173
	ds_read_b128 v[214:217], v173 offset:1024
	global_load_lds_dwordx4 v[138:139], off
	v_lshl_add_u64 v[138:139], v[136:137], 1, s[0:1]
	v_readfirstlane_b32 s0, v175
	v_lshl_add_u64 v[138:139], v[140:141], 1, v[138:139]
	s_mov_b32 m0, s0
	s_nop 0
	global_load_lds_dwordx4 v[138:139], off
	s_barrier
	s_waitcnt lgkmcnt(0)
	s_nop 0
	v_mfma_f32_16x16x32_bf16 v[124:127], v[142:145], v[186:189], v[124:127]
	v_mfma_f32_16x16x32_bf16 v[120:123], v[178:181], v[186:189], v[120:123]
	v_mfma_f32_16x16x32_bf16 v[116:119], v[142:145], v[194:197], v[116:119]
	v_mfma_f32_16x16x32_bf16 v[112:115], v[178:181], v[194:197], v[112:115]
	v_mfma_f32_16x16x32_bf16 v[100:103], v[142:145], v[210:213], v[100:103]
	v_mfma_f32_16x16x32_bf16 v[96:99], v[178:181], v[210:213], v[96:99]
	v_mfma_f32_16x16x32_bf16 v[124:127], v[146:149], v[190:193], v[124:127]
	v_mfma_f32_16x16x32_bf16 v[120:123], v[182:185], v[190:193], v[120:123]
	v_mfma_f32_16x16x32_bf16 v[116:119], v[146:149], v[198:201], v[116:119]
	v_mfma_f32_16x16x32_bf16 v[112:115], v[182:185], v[198:201], v[112:115]
	v_mfma_f32_16x16x32_bf16 v[108:111], v[142:145], v[202:205], v[108:111]
	v_mfma_f32_16x16x32_bf16 v[104:107], v[178:181], v[202:205], v[104:107]
	v_mfma_f32_16x16x32_bf16 v[100:103], v[146:149], v[214:217], v[100:103]
	v_mfma_f32_16x16x32_bf16 v[96:99], v[182:185], v[214:217], v[96:99]
	v_mfma_f32_16x16x32_bf16 v[138:141], v[146:149], v[206:209], v[108:111]
	v_mfma_f32_16x16x32_bf16 v[218:221], v[182:185], v[206:209], v[104:107]
	s_nop 0
	s_barrier
; #define LDA(dst,b,h) _Pragma("unroll") for(int m=0;m<4;++m) _Pragma("unroll") for(int k=0;k<2;++k) \
;     dst[m][k]=*reinterpret_cast<const bf16x8*>((char*)SA(b,h)+lds_byte(wr*64+m*16+fr,k*32+fq*8))
; #define LDB(dst,b,h) _Pragma("unroll") for(int n=0;n<2;++n) _Pragma("unroll") for(int k=0;k<2;++k) \
;     dst[n][k]=*reinterpret_cast<const bf16x8*>((char*)SB(b,h)+lds_byte(wc*32+n*16+fr,k*32+fq*8))
; #define MMA(ai,bj,At_,Bt_) do{__builtin_amdgcn_s_setprio(1); \
;     _Pragma("unroll") for(int m=0;m<4;++m) _Pragma("unroll") for(int n=0;n<2;++n) _Pragma("unroll") for(int k=0;k<2;++k) \
;       acc[ai][bj][m][n]=__builtin_amdgcn_mfma_f32_16x16x32_bf16(Bt_[n][k],At_[m][k],acc[ai][bj][m][n],0,0,0); \
;     __builtin_amdgcn_s_setprio(0);}while(0)
; #define WAIT_V(n) asm volatile("s_waitcnt vmcnt(" #n ")":::"memory")
; #define WAIT_L(n) asm volatile("s_waitcnt lgkmcnt(" #n ")":::"memory")
; #define BAR __builtin_amdgcn_s_barrier()
; DEVINL void gemm8_mainloop(const u16* A, long lda, const u16* Bt, long ldb, int K, int brow, int bcol, f32x4 (&acc)[2][2][4][2], char* smem, int tid) {
;     ...
;     LDB(B1,0,1); BAR; WAIT_L(0); MMA(0,1,At,B1); BAR;
;     LDA(At,0,1); WAIT_V(4); BAR; WAIT_L(0); MMA(1,0,At,B0); MMA(1,1,At,B1); BAR; }
;   { LDB(B0,1,0); LDA(At,1,0); WAIT_V(2); BAR; WAIT_L(0); MMA(0,0,At,B0); BAR;
;     LDB(B1,1,1); WAIT_V(0); BAR; WAIT_L(0); MMA(0,1,At,B1); BAR;
	s_nop 1
	ds_read_b128 v[104:107], v160
	ds_read_b128 v[108:111], v160 offset:1024
	ds_read_b128 v[222:225], v160 offset:2048
	ds_read_b128 v[158:161], v160 offset:3072
	s_barrier
	s_waitcnt lgkmcnt(0)
	s_nop 0
	v_mfma_f32_16x16x32_bf16 v[84:87], v[104:107], v[194:197], v[84:87]
	v_mfma_f32_16x16x32_bf16 v[80:83], v[222:225], v[194:197], v[80:83]
	v_mfma_f32_16x16x32_bf16 v[68:71], v[104:107], v[210:213], v[68:71]
	v_mfma_f32_16x16x32_bf16 v[92:95], v[104:107], v[186:189], v[92:95]
	v_mfma_f32_16x16x32_bf16 v[88:91], v[222:225], v[186:189], v[88:91]
	v_mfma_f32_16x16x32_bf16 v[84:87], v[108:111], v[198:201], v[84:87]
	v_mfma_f32_16x16x32_bf16 v[80:83], v[158:161], v[198:201], v[80:83]
	v_mfma_f32_16x16x32_bf16 v[76:79], v[104:107], v[202:205], v[76:79]
	v_mfma_f32_16x16x32_bf16 v[72:75], v[222:225], v[202:205], v[72:75]
	v_mfma_f32_16x16x32_bf16 v[68:71], v[108:111], v[214:217], v[68:71]
	v_mfma_f32_16x16x32_bf16 v[64:67], v[222:225], v[210:213], v[64:67]
	v_mfma_f32_16x16x32_bf16 v[226:229], v[108:111], v[190:193], v[92:95]
	v_mfma_f32_16x16x32_bf16 v[186:189], v[158:161], v[190:193], v[88:91]
	v_mfma_f32_16x16x32_bf16 v[190:193], v[108:111], v[206:209], v[76:79]
	v_mfma_f32_16x16x32_bf16 v[194:197], v[158:161], v[206:209], v[72:75]
	v_mfma_f32_16x16x32_bf16 v[198:201], v[158:161], v[214:217], v[64:67]
	s_nop 0
	s_barrier
	s_nop 0
	ds_read_b128 v[64:67], v153 offset:16384
	ds_read_b128 v[72:75], v153 offset:17408
	ds_read_b128 v[76:79], v171 offset:16384
	ds_read_b128 v[88:91], v171 offset:17408
	ds_read_b128 v[92:95], v172 offset:16384
	ds_read_b128 v[202:205], v172 offset:17408
	ds_read_b128 v[206:209], v173 offset:16384
	ds_read_b128 v[210:213], v173 offset:17408
	s_waitcnt vmcnt(4)
	s_barrier
	s_waitcnt lgkmcnt(0)
	s_nop 0
	v_mfma_f32_16x16x32_bf16 v[60:63], v[142:145], v[64:67], v[60:63]
	v_mfma_f32_16x16x32_bf16 v[56:59], v[178:181], v[64:67], v[56:59]
	v_mfma_f32_16x16x32_bf16 v[52:55], v[142:145], v[76:79], v[52:55]
	v_mfma_f32_16x16x32_bf16 v[48:51], v[178:181], v[76:79], v[48:51]
	v_mfma_f32_16x16x32_bf16 v[36:39], v[142:145], v[206:209], v[36:39]
	v_mfma_f32_16x16x32_bf16 v[32:35], v[178:181], v[206:209], v[32:35]
	v_mfma_f32_16x16x32_bf16 v[60:63], v[146:149], v[72:75], v[60:63]
	v_mfma_f32_16x16x32_bf16 v[56:59], v[182:185], v[72:75], v[56:59]
	v_mfma_f32_16x16x32_bf16 v[52:55], v[146:149], v[88:91], v[52:55]
	v_mfma_f32_16x16x32_bf16 v[48:51], v[182:185], v[88:91], v[48:51]
	v_mfma_f32_16x16x32_bf16 v[44:47], v[142:145], v[92:95], v[44:47]
	v_mfma_f32_16x16x32_bf16 v[40:43], v[178:181], v[92:95], v[40:43]
	v_mfma_f32_16x16x32_bf16 v[36:39], v[146:149], v[210:213], v[36:39]
	v_mfma_f32_16x16x32_bf16 v[32:35], v[182:185], v[210:213], v[32:35]
	v_mfma_f32_16x16x32_bf16 v[214:217], v[146:149], v[202:205], v[44:47]
	v_mfma_f32_16x16x32_bf16 v[230:233], v[182:185], v[202:205], v[40:43]
	s_nop 0
	s_nop 0
	v_mfma_f32_16x16x32_bf16 v[20:23], v[104:107], v[76:79], v[20:23]
	v_mfma_f32_16x16x32_bf16 v[16:19], v[222:225], v[76:79], v[16:19]
	v_mfma_f32_16x16x32_bf16 v[4:7], v[104:107], v[206:209], v[4:7]
	v_mfma_f32_16x16x32_bf16 v[0:3], v[222:225], v[206:209], v[0:3]
	v_mfma_f32_16x16x32_bf16 v[28:31], v[104:107], v[64:67], v[28:31]
	v_mfma_f32_16x16x32_bf16 v[24:27], v[222:225], v[64:67], v[24:27]
	v_mfma_f32_16x16x32_bf16 v[20:23], v[108:111], v[88:91], v[20:23]
	v_mfma_f32_16x16x32_bf16 v[16:19], v[158:161], v[88:91], v[16:19]
	v_mfma_f32_16x16x32_bf16 v[12:15], v[104:107], v[92:95], v[12:15]
	v_mfma_f32_16x16x32_bf16 v[8:11], v[222:225], v[92:95], v[8:11]
	v_mfma_f32_16x16x32_bf16 v[4:7], v[108:111], v[210:213], v[4:7]
	v_mfma_f32_16x16x32_bf16 v[0:3], v[158:161], v[210:213], v[0:3]
	v_mfma_f32_16x16x32_bf16 v[142:145], v[108:111], v[72:75], v[28:31]
	v_mfma_f32_16x16x32_bf16 v[146:149], v[158:161], v[72:75], v[24:27]
	v_mfma_f32_16x16x32_bf16 v[178:181], v[108:111], v[202:205], v[12:15]
	v_mfma_f32_16x16x32_bf16 v[182:185], v[158:161], v[202:205], v[8:11]
	s_nop 0
	s_barrier
	s_nop 0
	ds_read_b128 v[8:11], v157
	ds_read_b128 v[12:15], v157 offset:1024
	ds_read_b128 v[158:161], v157 offset:2048
	ds_read_b128 v[202:205], v157 offset:3072
	ds_read_b128 v[24:27], v153 offset:32768
	ds_read_b128 v[28:31], v153 offset:33792
	ds_read_b128 v[40:43], v171 offset:32768
	ds_read_b128 v[44:47], v171 offset:33792
	ds_read_b128 v[64:67], v172 offset:32768
	ds_read_b128 v[206:209], v172 offset:33792
	ds_read_b128 v[210:213], v173 offset:32768
	ds_read_b128 v[222:225], v173 offset:33792
	s_waitcnt vmcnt(2)
	s_barrier
; #define LDA(dst,b,h) _Pragma("unroll") for(int m=0;m<4;++m) _Pragma("unroll") for(int k=0;k<2;++k) \
;     dst[m][k]=*reinterpret_cast<const bf16x8*>((char*)SA(b,h)+lds_byte(wr*64+m*16+fr,k*32+fq*8))
; #define LDB(dst,b,h) _Pragma("unroll") for(int n=0;n<2;++n) _Pragma("unroll") for(int k=0;k<2;++k) \
;     dst[n][k]=*reinterpret_cast<const bf16x8*>((char*)SB(b,h)+lds_byte(wc*32+n*16+fr,k*32+fq*8))
; #define MMA(ai,bj,At_,Bt_) do{__builtin_amdgcn_s_setprio(1); \
;     _Pragma("unroll") for(int m=0;m<4;++m) _Pragma("unroll") for(int n=0;n<2;++n) _Pragma("unroll") for(int k=0;k<2;++k) \
;       acc[ai][bj][m][n]=__builtin_amdgcn_mfma_f32_16x16x32_bf16(Bt_[n][k],At_[m][k],acc[ai][bj][m][n],0,0,0); \
;     __builtin_amdgcn_s_setprio(0);}while(0)
; #define WAIT_V(n) asm volatile("s_waitcnt vmcnt(" #n ")":::"memory")
; #define WAIT_L(n) asm volatile("s_waitcnt lgkmcnt(" #n ")":::"memory")
; #define BAR __builtin_amdgcn_s_barrier()
; DEVINL void gemm8_mainloop(const u16* A, long lda, const u16* Bt, long ldb, int K, int brow, int bcol, f32x4 (&acc)[2][2][4][2], char* smem, int tid) {
;     ...
;   { LDB(B0,1,0); LDA(At,1,0); WAIT_V(2); BAR; WAIT_L(0); MMA(0,0,At,B0); BAR;
;     LDB(B1,1,1); WAIT_V(0); BAR; WAIT_L(0); MMA(0,1,At,B1); BAR;
;     LDA(At,1,1); BAR; WAIT_L(0); MMA(1,0,At,B0); MMA(1,1,At,B1); BAR; }
;   if(wr==0)BAR;
	s_waitcnt lgkmcnt(0)
	s_nop 0
	v_mfma_f32_16x16x32_bf16 v[72:75], v[8:11], v[24:27], v[124:127]
	v_mfma_f32_16x16x32_bf16 v[124:127], v[12:15], v[28:31], v[72:75]
	v_mfma_f32_16x16x32_bf16 v[72:75], v[158:161], v[24:27], v[120:123]
	v_mfma_f32_16x16x32_bf16 v[120:123], v[202:205], v[28:31], v[72:75]
	v_mfma_f32_16x16x32_bf16 v[72:75], v[8:11], v[40:43], v[116:119]
	v_mfma_f32_16x16x32_bf16 v[108:111], v[12:15], v[44:47], v[72:75]
	v_mfma_f32_16x16x32_bf16 v[72:75], v[158:161], v[40:43], v[112:115]
	v_mfma_f32_16x16x32_bf16 v[104:107], v[202:205], v[44:47], v[72:75]
	v_mfma_f32_16x16x32_bf16 v[72:75], v[8:11], v[64:67], v[138:141]
	v_mfma_f32_16x16x32_bf16 v[92:95], v[12:15], v[206:209], v[72:75]
	v_mfma_f32_16x16x32_bf16 v[72:75], v[158:161], v[64:67], v[218:221]
	v_mfma_f32_16x16x32_bf16 v[88:91], v[202:205], v[206:209], v[72:75]
	v_mfma_f32_16x16x32_bf16 v[72:75], v[8:11], v[210:213], v[100:103]
	v_mfma_f32_16x16x32_bf16 v[76:79], v[12:15], v[222:225], v[72:75]
	v_mfma_f32_16x16x32_bf16 v[72:75], v[158:161], v[210:213], v[96:99]
	v_mfma_f32_16x16x32_bf16 v[72:75], v[202:205], v[222:225], v[72:75]
	s_nop 0
	s_barrier
	ds_read_b128 v[138:141], v155
	ds_read_b128 v[218:221], v155 offset:1024
	ds_read_b128 v[234:237], v155 offset:2048
	ds_read_b128 v[154:157], v155 offset:3072
	s_waitcnt vmcnt(0)
	s_barrier
	s_waitcnt lgkmcnt(0)
	s_nop 0
	v_mfma_f32_16x16x32_bf16 v[96:99], v[138:141], v[24:27], v[226:229]
	v_mfma_f32_16x16x32_bf16 v[24:27], v[234:237], v[24:27], v[186:189]
	v_mfma_f32_16x16x32_bf16 v[116:119], v[154:157], v[28:31], v[24:27]
	v_mfma_f32_16x16x32_bf16 v[24:27], v[138:141], v[40:43], v[84:87]
	v_mfma_f32_16x16x32_bf16 v[112:115], v[218:221], v[28:31], v[96:99]
	v_mfma_f32_16x16x32_bf16 v[96:99], v[218:221], v[44:47], v[24:27]
	v_mfma_f32_16x16x32_bf16 v[24:27], v[234:237], v[40:43], v[80:83]
	v_mfma_f32_16x16x32_bf16 v[100:103], v[154:157], v[44:47], v[24:27]
	v_mfma_f32_16x16x32_bf16 v[24:27], v[138:141], v[64:67], v[190:193]
	v_mfma_f32_16x16x32_bf16 v[80:83], v[218:221], v[206:209], v[24:27]
	v_mfma_f32_16x16x32_bf16 v[24:27], v[234:237], v[64:67], v[194:197]
	v_mfma_f32_16x16x32_bf16 v[84:87], v[154:157], v[206:209], v[24:27]
	v_mfma_f32_16x16x32_bf16 v[24:27], v[138:141], v[210:213], v[68:71]
	v_mfma_f32_16x16x32_bf16 v[64:67], v[218:221], v[222:225], v[24:27]
	v_mfma_f32_16x16x32_bf16 v[24:27], v[234:237], v[210:213], v[198:201]
	v_mfma_f32_16x16x32_bf16 v[68:71], v[154:157], v[222:225], v[24:27]
	s_nop 0
	s_barrier
	ds_read_b128 v[186:189], v153 offset:49152
	ds_read_b128 v[190:193], v153 offset:50176
	ds_read_b128 v[194:197], v171 offset:49152
	ds_read_b128 v[198:201], v171 offset:50176
	ds_read_b128 v[206:209], v172 offset:49152
	ds_read_b128 v[210:213], v172 offset:50176
	ds_read_b128 v[222:225], v173 offset:49152
	ds_read_b128 v[172:175], v173 offset:50176
	s_barrier
	s_waitcnt lgkmcnt(0)
	s_nop 0
	v_mfma_f32_16x16x32_bf16 v[24:27], v[8:11], v[186:189], v[60:63]
	v_mfma_f32_16x16x32_bf16 v[60:63], v[12:15], v[190:193], v[24:27]
	v_mfma_f32_16x16x32_bf16 v[24:27], v[158:161], v[186:189], v[56:59]
	v_mfma_f32_16x16x32_bf16 v[56:59], v[202:205], v[190:193], v[24:27]
	v_mfma_f32_16x16x32_bf16 v[24:27], v[8:11], v[194:197], v[52:55]
	v_mfma_f32_16x16x32_bf16 v[44:47], v[12:15], v[198:201], v[24:27]
	v_mfma_f32_16x16x32_bf16 v[24:27], v[158:161], v[194:197], v[48:51]
	v_mfma_f32_16x16x32_bf16 v[40:43], v[202:205], v[198:201], v[24:27]
	v_mfma_f32_16x16x32_bf16 v[24:27], v[8:11], v[206:209], v[214:217]
	v_mfma_f32_16x16x32_bf16 v[8:11], v[8:11], v[222:225], v[36:39]
	v_mfma_f32_16x16x32_bf16 v[28:31], v[12:15], v[210:213], v[24:27]
	v_mfma_f32_16x16x32_bf16 v[24:27], v[158:161], v[206:209], v[230:233]
	v_mfma_f32_16x16x32_bf16 v[12:15], v[12:15], v[172:175], v[8:11]
	v_mfma_f32_16x16x32_bf16 v[8:11], v[158:161], v[222:225], v[32:35]
	v_mfma_f32_16x16x32_bf16 v[24:27], v[202:205], v[210:213], v[24:27]
	v_mfma_f32_16x16x32_bf16 v[8:11], v[202:205], v[172:175], v[8:11]
	s_nop 0
	s_nop 0
	v_mfma_f32_16x16x32_bf16 v[32:35], v[138:141], v[186:189], v[142:145]
	v_mfma_f32_16x16x32_bf16 v[48:51], v[218:221], v[190:193], v[32:35]
	v_mfma_f32_16x16x32_bf16 v[32:35], v[234:237], v[186:189], v[146:149]
	v_mfma_f32_16x16x32_bf16 v[20:23], v[138:141], v[194:197], v[20:23]
	v_mfma_f32_16x16x32_bf16 v[16:19], v[234:237], v[194:197], v[16:19]
	v_mfma_f32_16x16x32_bf16 v[52:55], v[154:157], v[190:193], v[32:35]
	v_mfma_f32_16x16x32_bf16 v[32:35], v[218:221], v[198:201], v[20:23]
	v_mfma_f32_16x16x32_bf16 v[36:39], v[154:157], v[198:201], v[16:19]
	v_mfma_f32_16x16x32_bf16 v[16:19], v[138:141], v[206:209], v[178:181]
	v_mfma_f32_16x16x32_bf16 v[20:23], v[234:237], v[206:209], v[182:185]
	v_mfma_f32_16x16x32_bf16 v[4:7], v[138:141], v[222:225], v[4:7]
	v_mfma_f32_16x16x32_bf16 v[0:3], v[234:237], v[222:225], v[0:3]
	v_mfma_f32_16x16x32_bf16 v[16:19], v[218:221], v[210:213], v[16:19]
	v_mfma_f32_16x16x32_bf16 v[20:23], v[154:157], v[210:213], v[20:23]
	v_mfma_f32_16x16x32_bf16 v[4:7], v[218:221], v[172:175], v[4:7]
	v_mfma_f32_16x16x32_bf16 v[0:3], v[154:157], v[172:175], v[0:3]
	s_setprio 0
	s_cmpk_gt_u32 s29, 0xff
	s_barrier
	s_cbranch_scc1 .LBB0_968
	s_barrier

; #define WAIT_V(n) asm volatile("s_waitcnt vmcnt(" #n ")":::"memory")
; #define BAR __builtin_amdgcn_s_barrier()
; DEVINL void gemm8_mainloop(const u16* A, long lda, const u16* Bt, long ldb, int K, int brow, int bcol, f32x4 (&acc)[2][2][4][2], char* smem, int tid) {
;     ...
;   if(wr==1)BAR;
;   WAIT_V(4); BAR;
; DEVINL void compute_rs(const float* part, int m0, float* rs_s, int tid) {
;     ...
;   if (!half) rs_s[row] = rsqrtf(s * (1.f / 2048.f) + EPSN);
;   __syncthreads();
.LBB0_1289:
	s_or_b64 exec, exec, s[4:5]
	v_readfirstlane_b32 s0, v167
	s_ashr_i32 s1, s0, 8
	s_cmp_lg_u32 s1, 1
	s_waitcnt lgkmcnt(0)
	s_barrier
	s_cbranch_scc1 .LBB0_1291
	s_setprio 1
	s_barrier

; #define STAGE(P,BASE,LD,br,kt) do{long _g=(long)(br)*(LD)+(long)(kt)*BK; \
;     _Pragma("unroll") for(int _i=0;_i<2;++_i){int _b=tid*16+_i*8192;int _r,_c;stage_rc(_b,_r,_c); \
;       __builtin_amdgcn_global_load_lds((const unsigned*)((BASE)+_g+(long)_r*(LD)+_c), \
;         (unsigned*)((char*)(P)+_b),16,0,0);}}while(0)
; #define STAGE(P,BASE,LD,br,kt) do{long _g=(long)(br)*(LD)+(long)(kt)*BK; \
;     _Pragma("unroll") for(int _i=0;_i<2;++_i){int _b=tid*16+_i*8192;int _r,_c;stage_rc(_b,_r,_c); \
;       __builtin_amdgcn_global_load_lds((const unsigned*)((BASE)+_g+(long)_r*(LD)+_c), \
;         (unsigned*)((char*)(P)+_b),16,0,0);}}while(0)
; #define LDA(dst,b,h) _Pragma("unroll") for(int m=0;m<4;++m) _Pragma("unroll") for(int k=0;k<2;++k) \
;     dst[m][k]=*reinterpret_cast<const bf16x8*>((char*)SA(b,h)+lds_byte(wr*64+m*16+fr,k*32+fq*8))
; #define LDB(dst,b,h) _Pragma("unroll") for(int n=0;n<2;++n) _Pragma("unroll") for(int k=0;k<2;++k) \
;     dst[n][k]=*reinterpret_cast<const bf16x8*>((char*)SB(b,h)+lds_byte(wc*32+n*16+fr,k*32+fq*8))
; #define MMA(ai,bj,At_,Bt_) do{__builtin_amdgcn_s_setprio(1); \
;     _Pragma("unroll") for(int m=0;m<4;++m) _Pragma("unroll") for(int n=0;n<2;++n) _Pragma("unroll") for(int k=0;k<2;++k) \
;       acc[ai][bj][m][n]=__builtin_amdgcn_mfma_f32_16x16x32_bf16(Bt_[n][k],At_[m][k],acc[ai][bj][m][n],0,0,0); \
;     __builtin_amdgcn_s_setprio(0);}while(0)
; #define WAIT_L(n) asm volatile("s_waitcnt lgkmcnt(" #n ")":::"memory")
; #define BAR __builtin_amdgcn_s_barrier()
; #define SCHED __builtin_amdgcn_sched_barrier(0)
; DEVINL void gemm8_mainloop(const u16* A, long lda, const u16* Bt, long ldb, int K, int brow, int bcol, f32x4 (&acc)[2][2][4][2], char* smem, int tid) {
;     ...
;     LDB(B0,0,0); SCHED; LDA(At,0,0); STAGE(SA(1,1),A,lda,brow+HALF,t+1);
;     WAIT_L(8); BAR; WAIT_L(0); MMA(0,0,At,B0); BAR; SCHED;
;     LDB(B1,0,1); STAGE(SB(0,0),Bt,ldb,bcol,t+2);
;     BAR; WAIT_L(0); MMA(0,1,At,B1); BAR;
;     LDA(At,0,1); STAGE(SA(0,0),A,lda,brow,t+2);
;     BAR; WAIT_L(0); MMA(1,0,At,B0); BAR; SCHED;
.LBB0_1292:
	ds_read_b128 v[170:173], v161
	ds_read_b128 v[180:183], v161 offset:1024
	ds_read_b128 v[184:187], v161 offset:2048
	ds_read_b128 v[188:191], v161 offset:3072
	v_add_u32_e32 v178, 0xc000, v128
	v_lshl_add_u64 v[244:245], s[94:95], 0, v[148:149]
	v_readfirstlane_b32 s5, v178
	v_add_u32_e32 v179, 0xe000, v128
	v_add_u32_e32 v174, s1, v160
	v_add_u32_e32 v175, s37, v160
	v_add_u32_e32 v177, s40, v160
	v_lshl_add_u64 v[162:163], v[244:245], 0, s[8:9]
	s_mov_b32 m0, s5
	v_lshl_add_u64 v[246:247], s[94:95], 0, v[150:151]
	v_readfirstlane_b32 s5, v179
	ds_read_b128 v[192:195], v131
	ds_read_b128 v[196:199], v131 offset:1024
	ds_read_b128 v[200:203], v174
	ds_read_b128 v[204:207], v174 offset:1024
	ds_read_b128 v[208:211], v175
	ds_read_b128 v[212:215], v175 offset:1024
	ds_read_b128 v[216:219], v177
	ds_read_b128 v[220:223], v177 offset:1024
	global_load_lds_dwordx4 v[162:163], off
	v_lshl_add_u64 v[162:163], v[246:247], 0, s[8:9]
	s_mov_b32 m0, s5
	s_nop 0
	global_load_lds_dwordx4 v[162:163], off
	s_waitcnt lgkmcnt(8)
	s_barrier
	s_waitcnt lgkmcnt(0)
	s_nop 0
	v_mfma_f32_16x16x32_bf16 v[124:127], v[170:173], v[192:195], v[124:127]
	v_mfma_f32_16x16x32_bf16 v[120:123], v[184:187], v[192:195], v[120:123]
	v_mfma_f32_16x16x32_bf16 v[116:119], v[170:173], v[200:203], v[116:119]
	v_mfma_f32_16x16x32_bf16 v[112:115], v[184:187], v[200:203], v[112:115]
	v_mfma_f32_16x16x32_bf16 v[108:111], v[170:173], v[208:211], v[108:111]
	v_mfma_f32_16x16x32_bf16 v[104:107], v[184:187], v[208:211], v[104:107]
	v_mfma_f32_16x16x32_bf16 v[100:103], v[170:173], v[216:219], v[100:103]
	v_mfma_f32_16x16x32_bf16 v[96:99], v[184:187], v[216:219], v[96:99]
	v_mfma_f32_16x16x32_bf16 v[124:127], v[180:183], v[196:199], v[124:127]
	v_mfma_f32_16x16x32_bf16 v[120:123], v[188:191], v[196:199], v[120:123]
	v_mfma_f32_16x16x32_bf16 v[116:119], v[180:183], v[204:207], v[116:119]
	v_mfma_f32_16x16x32_bf16 v[112:115], v[188:191], v[204:207], v[112:115]
	v_mfma_f32_16x16x32_bf16 v[108:111], v[180:183], v[212:215], v[108:111]
	v_mfma_f32_16x16x32_bf16 v[104:107], v[188:191], v[212:215], v[104:107]
	v_mfma_f32_16x16x32_bf16 v[100:103], v[180:183], v[220:223], v[100:103]
	v_mfma_f32_16x16x32_bf16 v[96:99], v[188:191], v[220:223], v[96:99]
	s_nop 0
	s_barrier
	v_add_u32_e32 v162, s27, v153
	v_lshl_add_u64 v[248:249], s[94:95], 0, v[144:145]
	v_readfirstlane_b32 s5, v162
	v_add_u32_e32 v163, 0x2000, v162
	v_lshl_add_u64 v[240:241], v[248:249], 0, s[10:11]
	s_mov_b32 m0, s5
	v_lshl_add_u64 v[250:251], s[94:95], 0, v[146:147]
	v_readfirstlane_b32 s5, v163
	ds_read_b128 v[224:227], v158
	ds_read_b128 v[228:231], v158 offset:1024
	ds_read_b128 v[232:235], v158 offset:2048
	ds_read_b128 v[236:239], v158 offset:3072
	global_load_lds_dwordx4 v[240:241], off
	v_lshl_add_u64 v[240:241], v[250:251], 0, s[10:11]
	s_mov_b32 m0, s5
	s_nop 0
	global_load_lds_dwordx4 v[240:241], off
	s_barrier
	s_waitcnt lgkmcnt(0)
	s_nop 0
	v_mfma_f32_16x16x32_bf16 v[92:95], v[224:227], v[192:195], v[92:95]
	v_mfma_f32_16x16x32_bf16 v[88:91], v[232:235], v[192:195], v[88:91]
	v_mfma_f32_16x16x32_bf16 v[84:87], v[224:227], v[200:203], v[84:87]
	v_mfma_f32_16x16x32_bf16 v[80:83], v[232:235], v[200:203], v[80:83]
	v_mfma_f32_16x16x32_bf16 v[76:79], v[224:227], v[208:211], v[76:79]
	v_mfma_f32_16x16x32_bf16 v[72:75], v[232:235], v[208:211], v[72:75]
	v_mfma_f32_16x16x32_bf16 v[68:71], v[224:227], v[216:219], v[68:71]
	v_mfma_f32_16x16x32_bf16 v[64:67], v[232:235], v[216:219], v[64:67]
	v_mfma_f32_16x16x32_bf16 v[92:95], v[228:231], v[196:199], v[92:95]
	v_mfma_f32_16x16x32_bf16 v[88:91], v[236:239], v[196:199], v[88:91]
	v_mfma_f32_16x16x32_bf16 v[84:87], v[228:231], v[204:207], v[84:87]
	v_mfma_f32_16x16x32_bf16 v[80:83], v[236:239], v[204:207], v[80:83]
	v_mfma_f32_16x16x32_bf16 v[76:79], v[228:231], v[212:215], v[76:79]
	v_mfma_f32_16x16x32_bf16 v[72:75], v[236:239], v[212:215], v[72:75]
	v_mfma_f32_16x16x32_bf16 v[68:71], v[228:231], v[220:223], v[68:71]
	v_mfma_f32_16x16x32_bf16 v[64:67], v[236:239], v[220:223], v[64:67]
	s_nop 0
	v_readfirstlane_b32 s5, v128
	v_add_u32_e32 v169, 0x2000, v128
	v_lshl_add_u64 v[240:241], v[244:245], 0, s[12:13]
	s_mov_b32 m0, s5
	v_readfirstlane_b32 s5, v169
	s_barrier
	ds_read_b128 v[192:195], v131 offset:16384
	ds_read_b128 v[196:199], v131 offset:17408
	ds_read_b128 v[200:203], v174 offset:16384
	ds_read_b128 v[204:207], v174 offset:17408
	ds_read_b128 v[208:211], v175 offset:16384
	ds_read_b128 v[212:215], v175 offset:17408
	ds_read_b128 v[216:219], v177 offset:16384
	ds_read_b128 v[220:223], v177 offset:17408
	global_load_lds_dwordx4 v[240:241], off
	v_lshl_add_u64 v[240:241], v[246:247], 0, s[12:13]
	s_mov_b32 m0, s5
	s_nop 0
	global_load_lds_dwordx4 v[240:241], off
	s_barrier
	s_waitcnt lgkmcnt(0)
	s_nop 0
	v_mfma_f32_16x16x32_bf16 v[60:63], v[170:173], v[192:195], v[60:63]
	v_mfma_f32_16x16x32_bf16 v[56:59], v[184:187], v[192:195], v[56:59]
	v_mfma_f32_16x16x32_bf16 v[52:55], v[170:173], v[200:203], v[52:55]
	v_mfma_f32_16x16x32_bf16 v[48:51], v[184:187], v[200:203], v[48:51]
	v_mfma_f32_16x16x32_bf16 v[44:47], v[170:173], v[208:211], v[44:47]
	v_mfma_f32_16x16x32_bf16 v[40:43], v[184:187], v[208:211], v[40:43]
	v_mfma_f32_16x16x32_bf16 v[36:39], v[170:173], v[216:219], v[36:39]
	v_mfma_f32_16x16x32_bf16 v[32:35], v[184:187], v[216:219], v[32:35]
	v_mfma_f32_16x16x32_bf16 v[60:63], v[180:183], v[196:199], v[60:63]
	v_mfma_f32_16x16x32_bf16 v[56:59], v[188:191], v[196:199], v[56:59]
	v_mfma_f32_16x16x32_bf16 v[52:55], v[180:183], v[204:207], v[52:55]
	v_mfma_f32_16x16x32_bf16 v[48:51], v[188:191], v[204:207], v[48:51]
	v_mfma_f32_16x16x32_bf16 v[44:47], v[180:183], v[212:215], v[44:47]
	v_mfma_f32_16x16x32_bf16 v[40:43], v[188:191], v[212:215], v[40:43]
	v_mfma_f32_16x16x32_bf16 v[36:39], v[180:183], v[220:223], v[36:39]
	v_mfma_f32_16x16x32_bf16 v[32:35], v[188:191], v[220:223], v[32:35]
	s_nop 0
	s_barrier
; #define STAGE(P,BASE,LD,br,kt) do{long _g=(long)(br)*(LD)+(long)(kt)*BK; \
;     _Pragma("unroll") for(int _i=0;_i<2;++_i){int _b=tid*16+_i*8192;int _r,_c;stage_rc(_b,_r,_c); \
;       __builtin_amdgcn_global_load_lds((const unsigned*)((BASE)+_g+(long)_r*(LD)+_c), \
;         (unsigned*)((char*)(P)+_b),16,0,0);}}while(0)
; #define STAGE(P,BASE,LD,br,kt) do{long _g=(long)(br)*(LD)+(long)(kt)*BK; \
;     _Pragma("unroll") for(int _i=0;_i<2;++_i){int _b=tid*16+_i*8192;int _r,_c;stage_rc(_b,_r,_c); \
;       __builtin_amdgcn_global_load_lds((const unsigned*)((BASE)+_g+(long)_r*(LD)+_c), \
;         (unsigned*)((char*)(P)+_b),16,0,0);}}while(0)
; #define LDA(dst,b,h) _Pragma("unroll") for(int m=0;m<4;++m) _Pragma("unroll") for(int k=0;k<2;++k) \
;     dst[m][k]=*reinterpret_cast<const bf16x8*>((char*)SA(b,h)+lds_byte(wr*64+m*16+fr,k*32+fq*8))
; #define LDB(dst,b,h) _Pragma("unroll") for(int n=0;n<2;++n) _Pragma("unroll") for(int k=0;k<2;++k) \
;     dst[n][k]=*reinterpret_cast<const bf16x8*>((char*)SB(b,h)+lds_byte(wc*32+n*16+fr,k*32+fq*8))
; #define MMA(ai,bj,At_,Bt_) do{__builtin_amdgcn_s_setprio(1); \
;     _Pragma("unroll") for(int m=0;m<4;++m) _Pragma("unroll") for(int n=0;n<2;++n) _Pragma("unroll") for(int k=0;k<2;++k) \
;       acc[ai][bj][m][n]=__builtin_amdgcn_mfma_f32_16x16x32_bf16(Bt_[n][k],At_[m][k],acc[ai][bj][m][n],0,0,0); \
;     __builtin_amdgcn_s_setprio(0);}while(0)
; #define WAIT_V(n) asm volatile("s_waitcnt vmcnt(" #n ")":::"memory")
; #define WAIT_L(n) asm volatile("s_waitcnt lgkmcnt(" #n ")":::"memory")
; #define BAR __builtin_amdgcn_s_barrier()
; #define SCHED __builtin_amdgcn_sched_barrier(0)
; DEVINL void gemm8_mainloop(const u16* A, long lda, const u16* Bt, long ldb, int K, int brow, int bcol, f32x4 (&acc)[2][2][4][2], char* smem, int tid) {
;     ...
;     STAGE(SB(0,1),Bt,ldb,bcol+HALF,t+2);
;     WAIT_V(6); BAR; MMA(1,1,At,B1); BAR;
;     LDB(B0,1,0); SCHED; LDA(At,1,0); STAGE(SA(0,1),A,lda,brow+HALF,t+2);
;     WAIT_L(8); BAR; WAIT_L(0); MMA(0,0,At,B0); BAR; SCHED;
;     LDB(B1,1,1); STAGE(SB(1,0),Bt,ldb,bcol,t+3);
	v_add_u32_e32 v170, s29, v153
	v_add_u32_e32 v171, 0x2000, v170
	v_readfirstlane_b32 s5, v170
	v_lshl_add_u64 v[172:173], v[248:249], 0, s[14:15]
	s_mov_b32 m0, s5
	v_readfirstlane_b32 s5, v171
	global_load_lds_dwordx4 v[172:173], off
	v_lshl_add_u64 v[172:173], v[250:251], 0, s[14:15]
	s_mov_b32 m0, s5
	s_nop 0
	global_load_lds_dwordx4 v[172:173], off
	s_waitcnt vmcnt(6)
	s_barrier
	s_nop 0
	v_mfma_f32_16x16x32_bf16 v[28:31], v[224:227], v[192:195], v[28:31]
	v_mfma_f32_16x16x32_bf16 v[24:27], v[232:235], v[192:195], v[24:27]
	v_mfma_f32_16x16x32_bf16 v[20:23], v[224:227], v[200:203], v[20:23]
	v_mfma_f32_16x16x32_bf16 v[16:19], v[232:235], v[200:203], v[16:19]
	v_mfma_f32_16x16x32_bf16 v[12:15], v[224:227], v[208:211], v[12:15]
	v_mfma_f32_16x16x32_bf16 v[8:11], v[232:235], v[208:211], v[8:11]
	v_mfma_f32_16x16x32_bf16 v[4:7], v[224:227], v[216:219], v[4:7]
	v_mfma_f32_16x16x32_bf16 v[0:3], v[232:235], v[216:219], v[0:3]
	v_mfma_f32_16x16x32_bf16 v[28:31], v[228:231], v[196:199], v[28:31]
	v_mfma_f32_16x16x32_bf16 v[24:27], v[236:239], v[196:199], v[24:27]
	v_mfma_f32_16x16x32_bf16 v[20:23], v[228:231], v[204:207], v[20:23]
	v_mfma_f32_16x16x32_bf16 v[16:19], v[236:239], v[204:207], v[16:19]
	v_mfma_f32_16x16x32_bf16 v[12:15], v[228:231], v[212:215], v[12:15]
	v_mfma_f32_16x16x32_bf16 v[8:11], v[236:239], v[212:215], v[8:11]
	v_mfma_f32_16x16x32_bf16 v[4:7], v[228:231], v[220:223], v[4:7]
	v_mfma_f32_16x16x32_bf16 v[0:3], v[236:239], v[220:223], v[0:3]
	s_nop 0
	s_barrier
	ds_read_b128 v[180:183], v154
	ds_read_b128 v[184:187], v154 offset:1024
	ds_read_b128 v[188:191], v154 offset:2048
	ds_read_b128 v[192:195], v154 offset:3072
	v_add_u32_e32 v172, 0x4000, v128
	v_add_u32_e32 v173, 0x6000, v128
	v_readfirstlane_b32 s5, v172
	v_lshl_add_u64 v[228:229], v[244:245], 0, s[16:17]
	s_mov_b32 m0, s5
	v_readfirstlane_b32 s5, v173
	ds_read_b128 v[196:199], v131 offset:32768
	ds_read_b128 v[200:203], v131 offset:33792
	ds_read_b128 v[204:207], v174 offset:32768
	ds_read_b128 v[208:211], v174 offset:33792
	ds_read_b128 v[212:215], v175 offset:32768
	ds_read_b128 v[216:219], v175 offset:33792
	ds_read_b128 v[220:223], v177 offset:32768
	ds_read_b128 v[224:227], v177 offset:33792
	global_load_lds_dwordx4 v[228:229], off
	v_lshl_add_u64 v[228:229], v[246:247], 0, s[16:17]
	s_mov_b32 m0, s5
	s_nop 0
	global_load_lds_dwordx4 v[228:229], off
	s_waitcnt lgkmcnt(8)
	s_barrier
	s_waitcnt lgkmcnt(0)
	s_nop 0
	v_mfma_f32_16x16x32_bf16 v[124:127], v[180:183], v[196:199], v[124:127]
	v_mfma_f32_16x16x32_bf16 v[120:123], v[188:191], v[196:199], v[120:123]
	v_mfma_f32_16x16x32_bf16 v[116:119], v[180:183], v[204:207], v[116:119]
	v_mfma_f32_16x16x32_bf16 v[112:115], v[188:191], v[204:207], v[112:115]
	v_mfma_f32_16x16x32_bf16 v[108:111], v[180:183], v[212:215], v[108:111]
	v_mfma_f32_16x16x32_bf16 v[104:107], v[188:191], v[212:215], v[104:107]
	v_mfma_f32_16x16x32_bf16 v[100:103], v[180:183], v[220:223], v[100:103]
	v_mfma_f32_16x16x32_bf16 v[96:99], v[188:191], v[220:223], v[96:99]
	v_mfma_f32_16x16x32_bf16 v[124:127], v[184:187], v[200:203], v[124:127]
	v_mfma_f32_16x16x32_bf16 v[120:123], v[192:195], v[200:203], v[120:123]
	v_mfma_f32_16x16x32_bf16 v[116:119], v[184:187], v[208:211], v[116:119]
	v_mfma_f32_16x16x32_bf16 v[112:115], v[192:195], v[208:211], v[112:115]
	v_mfma_f32_16x16x32_bf16 v[108:111], v[184:187], v[216:219], v[108:111]
	v_mfma_f32_16x16x32_bf16 v[104:107], v[192:195], v[216:219], v[104:107]
	v_mfma_f32_16x16x32_bf16 v[100:103], v[184:187], v[224:227], v[100:103]
	v_mfma_f32_16x16x32_bf16 v[96:99], v[192:195], v[224:227], v[96:99]
	s_nop 0
	s_barrier
	v_readfirstlane_b32 s5, v155
	v_add_u32_e32 v165, 0x2000, v155
	v_lshl_add_u64 v[252:253], v[248:249], 0, s[18:19]
	s_mov_b32 m0, s5
	v_readfirstlane_b32 s5, v165
	ds_read_b128 v[228:231], v152
	ds_read_b128 v[232:235], v152 offset:1024
	ds_read_b128 v[236:239], v152 offset:2048
	ds_read_b128 v[240:243], v152 offset:3072
	global_load_lds_dwordx4 v[252:253], off
	v_lshl_add_u64 v[252:253], v[250:251], 0, s[18:19]
	s_mov_b32 m0, s5
	s_nop 0
	global_load_lds_dwordx4 v[252:253], off
	s_barrier
	s_waitcnt lgkmcnt(0)
	s_nop 0
	v_mfma_f32_16x16x32_bf16 v[92:95], v[228:231], v[196:199], v[92:95]
	v_mfma_f32_16x16x32_bf16 v[88:91], v[236:239], v[196:199], v[88:91]
	v_mfma_f32_16x16x32_bf16 v[84:87], v[228:231], v[204:207], v[84:87]
	v_mfma_f32_16x16x32_bf16 v[80:83], v[236:239], v[204:207], v[80:83]
	v_mfma_f32_16x16x32_bf16 v[76:79], v[228:231], v[212:215], v[76:79]
	v_mfma_f32_16x16x32_bf16 v[72:75], v[236:239], v[212:215], v[72:75]
	v_mfma_f32_16x16x32_bf16 v[68:71], v[228:231], v[220:223], v[68:71]
	v_mfma_f32_16x16x32_bf16 v[64:67], v[236:239], v[220:223], v[64:67]
	v_mfma_f32_16x16x32_bf16 v[92:95], v[232:235], v[200:203], v[92:95]
	v_mfma_f32_16x16x32_bf16 v[88:91], v[240:243], v[200:203], v[88:91]
	v_mfma_f32_16x16x32_bf16 v[84:87], v[232:235], v[208:211], v[84:87]
	v_mfma_f32_16x16x32_bf16 v[80:83], v[240:243], v[208:211], v[80:83]
	v_mfma_f32_16x16x32_bf16 v[76:79], v[232:235], v[216:219], v[76:79]
	v_mfma_f32_16x16x32_bf16 v[72:75], v[240:243], v[216:219], v[72:75]
	v_mfma_f32_16x16x32_bf16 v[68:71], v[232:235], v[224:227], v[68:71]
	v_mfma_f32_16x16x32_bf16 v[64:67], v[240:243], v[224:227], v[64:67]
	s_nop 0
	v_readfirstlane_b32 s5, v156
	v_lshl_add_u64 v[244:245], v[244:245], 0, s[20:21]
	s_mov_b32 m0, s5
	v_readfirstlane_b32 s5, v157
	s_barrier
; #define STAGE(P,BASE,LD,br,kt) do{long _g=(long)(br)*(LD)+(long)(kt)*BK; \
;     _Pragma("unroll") for(int _i=0;_i<2;++_i){int _b=tid*16+_i*8192;int _r,_c;stage_rc(_b,_r,_c); \
;       __builtin_amdgcn_global_load_lds((const unsigned*)((BASE)+_g+(long)_r*(LD)+_c), \
;         (unsigned*)((char*)(P)+_b),16,0,0);}}while(0)
; #define STAGE(P,BASE,LD,br,kt) do{long _g=(long)(br)*(LD)+(long)(kt)*BK; \
;     _Pragma("unroll") for(int _i=0;_i<2;++_i){int _b=tid*16+_i*8192;int _r,_c;stage_rc(_b,_r,_c); \
;       __builtin_amdgcn_global_load_lds((const unsigned*)((BASE)+_g+(long)_r*(LD)+_c), \
;         (unsigned*)((char*)(P)+_b),16,0,0);}}while(0)
; #define LDA(dst,b,h) _Pragma("unroll") for(int m=0;m<4;++m) _Pragma("unroll") for(int k=0;k<2;++k) \
;     dst[m][k]=*reinterpret_cast<const bf16x8*>((char*)SA(b,h)+lds_byte(wr*64+m*16+fr,k*32+fq*8))
; #define LDB(dst,b,h) _Pragma("unroll") for(int n=0;n<2;++n) _Pragma("unroll") for(int k=0;k<2;++k) \
;     dst[n][k]=*reinterpret_cast<const bf16x8*>((char*)SB(b,h)+lds_byte(wc*32+n*16+fr,k*32+fq*8))
; #define MMA(ai,bj,At_,Bt_) do{__builtin_amdgcn_s_setprio(1); \
;     _Pragma("unroll") for(int m=0;m<4;++m) _Pragma("unroll") for(int n=0;n<2;++n) _Pragma("unroll") for(int k=0;k<2;++k) \
;       acc[ai][bj][m][n]=__builtin_amdgcn_mfma_f32_16x16x32_bf16(Bt_[n][k],At_[m][k],acc[ai][bj][m][n],0,0,0); \
;     __builtin_amdgcn_s_setprio(0);}while(0)
; #define WAIT_V(n) asm volatile("s_waitcnt vmcnt(" #n ")":::"memory")
; #define WAIT_L(n) asm volatile("s_waitcnt lgkmcnt(" #n ")":::"memory")
; #define BAR __builtin_amdgcn_s_barrier()
; #define SCHED __builtin_amdgcn_sched_barrier(0)
; DEVINL void gemm8_mainloop(const u16* A, long lda, const u16* Bt, long ldb, int K, int brow, int bcol, f32x4 (&acc)[2][2][4][2], char* smem, int tid) {
;     ...
;     LDA(At,1,1); STAGE(SA(1,0),A,lda,brow,t+3);
;     BAR; WAIT_L(0); MMA(1,0,At,B0); BAR; SCHED;
;     STAGE(SB(1,1),Bt,ldb,bcol+HALF,t+3);
;     WAIT_V(6); BAR; MMA(1,1,At,B1); BAR;
;   }
;   { LDB(B0,0,0); LDA(At,0,0); STAGE(SA(1,1),A,lda,brow+HALF,nt-1);
;     BAR; WAIT_L(0); MMA(0,0,At,B0); BAR;
	ds_read_b128 v[196:199], v131 offset:49152
	ds_read_b128 v[200:203], v131 offset:50176
	ds_read_b128 v[204:207], v174 offset:49152
	ds_read_b128 v[208:211], v174 offset:50176
	ds_read_b128 v[212:215], v175 offset:49152
	ds_read_b128 v[216:219], v175 offset:50176
	ds_read_b128 v[220:223], v177 offset:49152
	ds_read_b128 v[224:227], v177 offset:50176
	global_load_lds_dwordx4 v[244:245], off
	v_lshl_add_u64 v[244:245], v[246:247], 0, s[20:21]
	s_mov_b32 m0, s5
	s_nop 0
	global_load_lds_dwordx4 v[244:245], off
	s_barrier
	s_waitcnt lgkmcnt(0)
	s_nop 0
	v_mfma_f32_16x16x32_bf16 v[60:63], v[180:183], v[196:199], v[60:63]
	v_mfma_f32_16x16x32_bf16 v[56:59], v[188:191], v[196:199], v[56:59]
	v_mfma_f32_16x16x32_bf16 v[52:55], v[180:183], v[204:207], v[52:55]
	v_mfma_f32_16x16x32_bf16 v[48:51], v[188:191], v[204:207], v[48:51]
	v_mfma_f32_16x16x32_bf16 v[44:47], v[180:183], v[212:215], v[44:47]
	v_mfma_f32_16x16x32_bf16 v[40:43], v[188:191], v[212:215], v[40:43]
	v_mfma_f32_16x16x32_bf16 v[36:39], v[180:183], v[220:223], v[36:39]
	v_mfma_f32_16x16x32_bf16 v[32:35], v[188:191], v[220:223], v[32:35]
	v_mfma_f32_16x16x32_bf16 v[60:63], v[184:187], v[200:203], v[60:63]
	v_mfma_f32_16x16x32_bf16 v[56:59], v[192:195], v[200:203], v[56:59]
	v_mfma_f32_16x16x32_bf16 v[52:55], v[184:187], v[208:211], v[52:55]
	v_mfma_f32_16x16x32_bf16 v[48:51], v[192:195], v[208:211], v[48:51]
	v_mfma_f32_16x16x32_bf16 v[44:47], v[184:187], v[216:219], v[44:47]
	v_mfma_f32_16x16x32_bf16 v[40:43], v[192:195], v[216:219], v[40:43]
	v_mfma_f32_16x16x32_bf16 v[36:39], v[184:187], v[224:227], v[36:39]
	v_mfma_f32_16x16x32_bf16 v[32:35], v[192:195], v[224:227], v[32:35]
	s_nop 0
	s_barrier
	v_readfirstlane_b32 s5, v159
	v_add_u32_e32 v165, 0x2000, v159
	v_lshl_add_u64 v[180:181], v[248:249], 0, s[22:23]
	s_mov_b32 m0, s5
	v_readfirstlane_b32 s5, v165
	global_load_lds_dwordx4 v[180:181], off
	v_lshl_add_u64 v[180:181], v[250:251], 0, s[22:23]
	s_mov_b32 m0, s5
	s_nop 0
	global_load_lds_dwordx4 v[180:181], off
	s_waitcnt vmcnt(6)
	s_barrier
	s_nop 0
	v_mfma_f32_16x16x32_bf16 v[28:31], v[228:231], v[196:199], v[28:31]
	v_mfma_f32_16x16x32_bf16 v[24:27], v[236:239], v[196:199], v[24:27]
	v_mfma_f32_16x16x32_bf16 v[20:23], v[228:231], v[204:207], v[20:23]
	v_mfma_f32_16x16x32_bf16 v[16:19], v[236:239], v[204:207], v[16:19]
	v_mfma_f32_16x16x32_bf16 v[12:15], v[228:231], v[212:215], v[12:15]
	v_mfma_f32_16x16x32_bf16 v[8:11], v[236:239], v[212:215], v[8:11]
	v_mfma_f32_16x16x32_bf16 v[4:7], v[228:231], v[220:223], v[4:7]
	v_mfma_f32_16x16x32_bf16 v[0:3], v[236:239], v[220:223], v[0:3]
	v_mfma_f32_16x16x32_bf16 v[28:31], v[232:235], v[200:203], v[28:31]
	v_mfma_f32_16x16x32_bf16 v[24:27], v[240:243], v[200:203], v[24:27]
	v_mfma_f32_16x16x32_bf16 v[20:23], v[232:235], v[208:211], v[20:23]
	v_mfma_f32_16x16x32_bf16 v[16:19], v[240:243], v[208:211], v[16:19]
	v_mfma_f32_16x16x32_bf16 v[12:15], v[232:235], v[216:219], v[12:15]
	v_mfma_f32_16x16x32_bf16 v[8:11], v[240:243], v[216:219], v[8:11]
	v_mfma_f32_16x16x32_bf16 v[4:7], v[232:235], v[224:227], v[4:7]
	v_mfma_f32_16x16x32_bf16 v[0:3], v[240:243], v[224:227], v[0:3]
	s_nop 0
	s_add_i32 s4, s4, 2
	v_lshl_add_u64 v[144:145], v[144:145], 0, s[10:11]
	v_lshl_add_u64 v[146:147], v[146:147], 0, s[10:11]
	v_lshl_add_u64 v[148:149], v[148:149], 0, s[10:11]
	s_cmp_lt_u32 s4, 28
	v_lshl_add_u64 v[150:151], v[150:151], 0, s[10:11]
	s_barrier
	s_cbranch_scc1 .LBB0_1292
	s_or_b32 s4, s36, 0x80
	s_ashr_i32 s5, s4, 31
	s_lshl_b64 s[4:5], s[4:5], 12
	s_add_u32 s4, s90, s4
	s_addc_u32 s5, s91, s5
	v_lshl_add_u64 v[156:157], v[136:137], 1, s[4:5]
	v_lshl_add_u64 v[140:141], v[140:141], 1, v[156:157]
	v_readfirstlane_b32 s1, v178
	v_lshl_add_u64 v[140:141], v[140:141], 0, s[24:25]
	s_mov_b32 m0, s1
	ds_read_b128 v[144:147], v161
	ds_read_b128 v[148:151], v161 offset:1024
	ds_read_b128 v[180:183], v161 offset:2048
	ds_read_b128 v[184:187], v161 offset:3072
	ds_read_b128 v[188:191], v131
	ds_read_b128 v[192:195], v131 offset:1024
	ds_read_b128 v[196:199], v174
	ds_read_b128 v[200:203], v174 offset:1024
	ds_read_b128 v[204:207], v175
	ds_read_b128 v[208:211], v175 offset:1024
	ds_read_b128 v[212:215], v177
	ds_read_b128 v[216:219], v177 offset:1024
	global_load_lds_dwordx4 v[140:141], off
	v_lshl_add_u64 v[140:141], v[138:139], 1, s[4:5]
	v_lshl_add_u64 v[140:141], v[142:143], 1, v[140:141]
	v_readfirstlane_b32 s1, v179
	v_lshl_add_u64 v[140:141], v[140:141], 0, s[24:25]
	s_mov_b32 m0, s1
	s_nop 0
	global_load_lds_dwordx4 v[140:141], off
	s_barrier
	s_waitcnt lgkmcnt(0)
	s_nop 0
	v_mfma_f32_16x16x32_bf16 v[124:127], v[144:147], v[188:191], v[124:127]
	v_mfma_f32_16x16x32_bf16 v[120:123], v[180:183], v[188:191], v[120:123]
	v_mfma_f32_16x16x32_bf16 v[108:111], v[144:147], v[204:207], v[108:111]
	v_mfma_f32_16x16x32_bf16 v[104:107], v[180:183], v[204:207], v[104:107]
	v_mfma_f32_16x16x32_bf16 v[124:127], v[148:151], v[192:195], v[124:127]
	v_mfma_f32_16x16x32_bf16 v[120:123], v[184:187], v[192:195], v[120:123]
	v_mfma_f32_16x16x32_bf16 v[116:119], v[144:147], v[196:199], v[116:119]
	v_mfma_f32_16x16x32_bf16 v[112:115], v[180:183], v[196:199], v[112:115]
	v_mfma_f32_16x16x32_bf16 v[108:111], v[148:151], v[208:211], v[108:111]
	v_mfma_f32_16x16x32_bf16 v[104:107], v[184:187], v[208:211], v[104:107]
	v_mfma_f32_16x16x32_bf16 v[100:103], v[144:147], v[212:215], v[100:103]
	v_mfma_f32_16x16x32_bf16 v[96:99], v[180:183], v[212:215], v[96:99]
	v_mfma_f32_16x16x32_bf16 v[140:143], v[148:151], v[200:203], v[116:119]
	v_mfma_f32_16x16x32_bf16 v[220:223], v[184:187], v[200:203], v[112:115]
	v_mfma_f32_16x16x32_bf16 v[224:227], v[148:151], v[216:219], v[100:103]
	v_mfma_f32_16x16x32_bf16 v[228:231], v[184:187], v[216:219], v[96:99]
	s_nop 0
	s_barrier
; #define LDA(dst,b,h) _Pragma("unroll") for(int m=0;m<4;++m) _Pragma("unroll") for(int k=0;k<2;++k) \
;     dst[m][k]=*reinterpret_cast<const bf16x8*>((char*)SA(b,h)+lds_byte(wr*64+m*16+fr,k*32+fq*8))
; #define LDB(dst,b,h) _Pragma("unroll") for(int n=0;n<2;++n) _Pragma("unroll") for(int k=0;k<2;++k) \
;     dst[n][k]=*reinterpret_cast<const bf16x8*>((char*)SB(b,h)+lds_byte(wc*32+n*16+fr,k*32+fq*8))
; #define MMA(ai,bj,At_,Bt_) do{__builtin_amdgcn_s_setprio(1); \
;     _Pragma("unroll") for(int m=0;m<4;++m) _Pragma("unroll") for(int n=0;n<2;++n) _Pragma("unroll") for(int k=0;k<2;++k) \
;       acc[ai][bj][m][n]=__builtin_amdgcn_mfma_f32_16x16x32_bf16(Bt_[n][k],At_[m][k],acc[ai][bj][m][n],0,0,0); \
;     __builtin_amdgcn_s_setprio(0);}while(0)
; #define WAIT_V(n) asm volatile("s_waitcnt vmcnt(" #n ")":::"memory")
; #define WAIT_L(n) asm volatile("s_waitcnt lgkmcnt(" #n ")":::"memory")
; #define BAR __builtin_amdgcn_s_barrier()
; DEVINL void gemm8_mainloop(const u16* A, long lda, const u16* Bt, long ldb, int K, int brow, int bcol, f32x4 (&acc)[2][2][4][2], char* smem, int tid) {
;     ...
;     LDB(B1,0,1); BAR; WAIT_L(0); MMA(0,1,At,B1); BAR;
;     LDA(At,0,1); WAIT_V(4); BAR; WAIT_L(0); MMA(1,0,At,B0); MMA(1,1,At,B1); BAR; }
;   { LDB(B0,1,0); LDA(At,1,0); WAIT_V(2); BAR; WAIT_L(0); MMA(0,0,At,B0); BAR;
	s_nop 1
	ds_read_b128 v[96:99], v158
	ds_read_b128 v[100:103], v158 offset:1024
	ds_read_b128 v[112:115], v158 offset:2048
	ds_read_b128 v[116:119], v158 offset:3072
	s_barrier
	s_waitcnt lgkmcnt(0)
	s_nop 0
	v_mfma_f32_16x16x32_bf16 v[92:95], v[96:99], v[188:191], v[92:95]
	v_mfma_f32_16x16x32_bf16 v[88:91], v[112:115], v[188:191], v[88:91]
	v_mfma_f32_16x16x32_bf16 v[76:79], v[96:99], v[204:207], v[76:79]
	v_mfma_f32_16x16x32_bf16 v[72:75], v[112:115], v[204:207], v[72:75]
	v_mfma_f32_16x16x32_bf16 v[92:95], v[100:103], v[192:195], v[92:95]
	v_mfma_f32_16x16x32_bf16 v[88:91], v[116:119], v[192:195], v[88:91]
	v_mfma_f32_16x16x32_bf16 v[84:87], v[96:99], v[196:199], v[84:87]
	v_mfma_f32_16x16x32_bf16 v[80:83], v[112:115], v[196:199], v[80:83]
	v_mfma_f32_16x16x32_bf16 v[76:79], v[100:103], v[208:211], v[76:79]
	v_mfma_f32_16x16x32_bf16 v[72:75], v[116:119], v[208:211], v[72:75]
	v_mfma_f32_16x16x32_bf16 v[68:71], v[96:99], v[212:215], v[68:71]
	v_mfma_f32_16x16x32_bf16 v[64:67], v[112:115], v[212:215], v[64:67]
	v_mfma_f32_16x16x32_bf16 v[156:159], v[100:103], v[200:203], v[84:87]
	v_mfma_f32_16x16x32_bf16 v[188:191], v[116:119], v[200:203], v[80:83]
	v_mfma_f32_16x16x32_bf16 v[192:195], v[100:103], v[216:219], v[68:71]
	v_mfma_f32_16x16x32_bf16 v[196:199], v[116:119], v[216:219], v[64:67]
	s_nop 0
	s_barrier
	s_nop 1
	ds_read_b128 v[64:67], v131 offset:16384
	ds_read_b128 v[68:71], v131 offset:17408
	ds_read_b128 v[80:83], v174 offset:16384
	ds_read_b128 v[84:87], v174 offset:17408
	ds_read_b128 v[200:203], v175 offset:16384
	ds_read_b128 v[204:207], v175 offset:17408
	ds_read_b128 v[208:211], v177 offset:16384
	ds_read_b128 v[212:215], v177 offset:17408
	s_waitcnt vmcnt(4)
	s_barrier
	s_waitcnt lgkmcnt(0)
	s_nop 0
	v_mfma_f32_16x16x32_bf16 v[60:63], v[144:147], v[64:67], v[60:63]
	v_mfma_f32_16x16x32_bf16 v[52:55], v[144:147], v[80:83], v[52:55]
	v_mfma_f32_16x16x32_bf16 v[44:47], v[144:147], v[200:203], v[44:47]
	v_mfma_f32_16x16x32_bf16 v[40:43], v[180:183], v[200:203], v[40:43]
	v_mfma_f32_16x16x32_bf16 v[60:63], v[148:151], v[68:71], v[60:63]
	v_mfma_f32_16x16x32_bf16 v[56:59], v[180:183], v[64:67], v[56:59]
	v_mfma_f32_16x16x32_bf16 v[52:55], v[148:151], v[84:87], v[52:55]
	v_mfma_f32_16x16x32_bf16 v[48:51], v[180:183], v[80:83], v[48:51]
	v_mfma_f32_16x16x32_bf16 v[44:47], v[148:151], v[204:207], v[44:47]
	v_mfma_f32_16x16x32_bf16 v[40:43], v[184:187], v[204:207], v[40:43]
	v_mfma_f32_16x16x32_bf16 v[36:39], v[144:147], v[208:211], v[36:39]
	v_mfma_f32_16x16x32_bf16 v[32:35], v[180:183], v[208:211], v[32:35]
	v_mfma_f32_16x16x32_bf16 v[216:219], v[184:187], v[68:71], v[56:59]
	v_mfma_f32_16x16x32_bf16 v[232:235], v[184:187], v[84:87], v[48:51]
	v_mfma_f32_16x16x32_bf16 v[144:147], v[148:151], v[212:215], v[36:39]
	v_mfma_f32_16x16x32_bf16 v[148:151], v[184:187], v[212:215], v[32:35]
	s_nop 0
	s_nop 0
	v_mfma_f32_16x16x32_bf16 v[28:31], v[96:99], v[64:67], v[28:31]
	v_mfma_f32_16x16x32_bf16 v[20:23], v[96:99], v[80:83], v[20:23]
	v_mfma_f32_16x16x32_bf16 v[12:15], v[96:99], v[200:203], v[12:15]
	v_mfma_f32_16x16x32_bf16 v[4:7], v[96:99], v[208:211], v[4:7]
	v_mfma_f32_16x16x32_bf16 v[28:31], v[100:103], v[68:71], v[28:31]
	v_mfma_f32_16x16x32_bf16 v[24:27], v[112:115], v[64:67], v[24:27]
	v_mfma_f32_16x16x32_bf16 v[20:23], v[100:103], v[84:87], v[20:23]
	v_mfma_f32_16x16x32_bf16 v[16:19], v[112:115], v[80:83], v[16:19]
	v_mfma_f32_16x16x32_bf16 v[12:15], v[100:103], v[204:207], v[12:15]
	v_mfma_f32_16x16x32_bf16 v[8:11], v[112:115], v[200:203], v[8:11]
	v_mfma_f32_16x16x32_bf16 v[4:7], v[100:103], v[212:215], v[4:7]
	v_mfma_f32_16x16x32_bf16 v[0:3], v[112:115], v[208:211], v[0:3]
	v_mfma_f32_16x16x32_bf16 v[178:181], v[116:119], v[68:71], v[24:27]
	v_mfma_f32_16x16x32_bf16 v[182:185], v[116:119], v[84:87], v[16:19]
	v_mfma_f32_16x16x32_bf16 v[200:203], v[116:119], v[204:207], v[8:11]
	v_mfma_f32_16x16x32_bf16 v[204:207], v[116:119], v[212:215], v[0:3]
	s_nop 0
	s_barrier
	s_nop 1
	ds_read_b128 v[0:3], v154
	ds_read_b128 v[8:11], v154 offset:1024
	ds_read_b128 v[208:211], v154 offset:2048
	ds_read_b128 v[212:215], v154 offset:3072
	ds_read_b128 v[16:19], v131 offset:32768
	ds_read_b128 v[24:27], v131 offset:33792
	ds_read_b128 v[32:35], v174 offset:32768
	ds_read_b128 v[36:39], v174 offset:33792
	ds_read_b128 v[48:51], v175 offset:32768
	ds_read_b128 v[56:59], v175 offset:33792
	ds_read_b128 v[236:239], v177 offset:32768
	ds_read_b128 v[240:243], v177 offset:33792
	s_waitcnt vmcnt(2)
	s_barrier
; #define LDA(dst,b,h) _Pragma("unroll") for(int m=0;m<4;++m) _Pragma("unroll") for(int k=0;k<2;++k) \
;     dst[m][k]=*reinterpret_cast<const bf16x8*>((char*)SA(b,h)+lds_byte(wr*64+m*16+fr,k*32+fq*8))
; #define LDB(dst,b,h) _Pragma("unroll") for(int n=0;n<2;++n) _Pragma("unroll") for(int k=0;k<2;++k) \
;     dst[n][k]=*reinterpret_cast<const bf16x8*>((char*)SB(b,h)+lds_byte(wc*32+n*16+fr,k*32+fq*8))
; #define MMA(ai,bj,At_,Bt_) do{__builtin_amdgcn_s_setprio(1); \
;     _Pragma("unroll") for(int m=0;m<4;++m) _Pragma("unroll") for(int n=0;n<2;++n) _Pragma("unroll") for(int k=0;k<2;++k) \
;       acc[ai][bj][m][n]=__builtin_amdgcn_mfma_f32_16x16x32_bf16(Bt_[n][k],At_[m][k],acc[ai][bj][m][n],0,0,0); \
;     __builtin_amdgcn_s_setprio(0);}while(0)
; #define WAIT_V(n) asm volatile("s_waitcnt vmcnt(" #n ")":::"memory")
; #define WAIT_L(n) asm volatile("s_waitcnt lgkmcnt(" #n ")":::"memory")
; #define BAR __builtin_amdgcn_s_barrier()
; DEVINL void gemm8_mainloop(const u16* A, long lda, const u16* Bt, long ldb, int K, int brow, int bcol, f32x4 (&acc)[2][2][4][2], char* smem, int tid) {
;     ...
;   { LDB(B0,1,0); LDA(At,1,0); WAIT_V(2); BAR; WAIT_L(0); MMA(0,0,At,B0); BAR;
;     LDB(B1,1,1); WAIT_V(0); BAR; WAIT_L(0); MMA(0,1,At,B1); BAR;
;     LDA(At,1,1); BAR; WAIT_L(0); MMA(1,0,At,B0); MMA(1,1,At,B1); BAR; }
;   if(wr==0)BAR;
	s_waitcnt lgkmcnt(0)
	s_nop 0
	v_mfma_f32_16x16x32_bf16 v[64:67], v[0:3], v[16:19], v[124:127]
	v_mfma_f32_16x16x32_bf16 v[116:119], v[8:11], v[24:27], v[64:67]
	v_mfma_f32_16x16x32_bf16 v[64:67], v[208:211], v[16:19], v[120:123]
	v_mfma_f32_16x16x32_bf16 v[112:115], v[212:215], v[24:27], v[64:67]
	v_mfma_f32_16x16x32_bf16 v[64:67], v[0:3], v[32:35], v[140:143]
	v_mfma_f32_16x16x32_bf16 v[100:103], v[8:11], v[36:39], v[64:67]
	v_mfma_f32_16x16x32_bf16 v[64:67], v[208:211], v[32:35], v[220:223]
	v_mfma_f32_16x16x32_bf16 v[96:99], v[212:215], v[36:39], v[64:67]
	v_mfma_f32_16x16x32_bf16 v[64:67], v[0:3], v[48:51], v[108:111]
	v_mfma_f32_16x16x32_bf16 v[84:87], v[8:11], v[56:59], v[64:67]
	v_mfma_f32_16x16x32_bf16 v[64:67], v[208:211], v[48:51], v[104:107]
	v_mfma_f32_16x16x32_bf16 v[80:83], v[212:215], v[56:59], v[64:67]
	v_mfma_f32_16x16x32_bf16 v[64:67], v[0:3], v[236:239], v[224:227]
	v_mfma_f32_16x16x32_bf16 v[68:71], v[8:11], v[240:243], v[64:67]
	v_mfma_f32_16x16x32_bf16 v[64:67], v[208:211], v[236:239], v[228:231]
	v_mfma_f32_16x16x32_bf16 v[64:67], v[212:215], v[240:243], v[64:67]
	s_nop 0
	s_barrier
	ds_read_b128 v[140:143], v152
	ds_read_b128 v[220:223], v152 offset:1024
	ds_read_b128 v[224:227], v152 offset:2048
	ds_read_b128 v[152:155], v152 offset:3072
	s_waitcnt vmcnt(0)
	s_barrier
	s_waitcnt lgkmcnt(0)
	s_nop 0
	v_mfma_f32_16x16x32_bf16 v[92:95], v[140:143], v[16:19], v[92:95]
	v_mfma_f32_16x16x32_bf16 v[16:19], v[224:227], v[16:19], v[88:91]
	v_mfma_f32_16x16x32_bf16 v[120:123], v[152:155], v[24:27], v[16:19]
	v_mfma_f32_16x16x32_bf16 v[16:19], v[140:143], v[32:35], v[156:159]
	v_mfma_f32_16x16x32_bf16 v[104:107], v[220:223], v[36:39], v[16:19]
	v_mfma_f32_16x16x32_bf16 v[16:19], v[224:227], v[32:35], v[188:191]
	v_mfma_f32_16x16x32_bf16 v[108:111], v[152:155], v[36:39], v[16:19]
	v_mfma_f32_16x16x32_bf16 v[16:19], v[140:143], v[48:51], v[76:79]
	v_mfma_f32_16x16x32_bf16 v[124:127], v[220:223], v[24:27], v[92:95]
	v_mfma_f32_16x16x32_bf16 v[92:95], v[220:223], v[56:59], v[16:19]
	v_mfma_f32_16x16x32_bf16 v[16:19], v[224:227], v[48:51], v[72:75]
	v_mfma_f32_16x16x32_bf16 v[88:91], v[152:155], v[56:59], v[16:19]
	v_mfma_f32_16x16x32_bf16 v[16:19], v[140:143], v[236:239], v[192:195]
	v_mfma_f32_16x16x32_bf16 v[72:75], v[220:223], v[240:243], v[16:19]
	v_mfma_f32_16x16x32_bf16 v[16:19], v[224:227], v[236:239], v[196:199]
	v_mfma_f32_16x16x32_bf16 v[76:79], v[152:155], v[240:243], v[16:19]
	s_nop 0
	s_barrier
	ds_read_b128 v[156:159], v131 offset:49152
	ds_read_b128 v[186:189], v131 offset:50176
	ds_read_b128 v[190:193], v174 offset:49152
	ds_read_b128 v[194:197], v174 offset:50176
	ds_read_b128 v[228:231], v175 offset:49152
	ds_read_b128 v[236:239], v175 offset:50176
	ds_read_b128 v[240:243], v177 offset:49152
	ds_read_b128 v[244:247], v177 offset:50176
	s_barrier
	s_waitcnt lgkmcnt(0)
	s_nop 0
	v_mfma_f32_16x16x32_bf16 v[16:19], v[0:3], v[156:159], v[60:63]
	v_mfma_f32_16x16x32_bf16 v[56:59], v[8:11], v[186:189], v[16:19]
	v_mfma_f32_16x16x32_bf16 v[16:19], v[208:211], v[156:159], v[216:219]
	v_mfma_f32_16x16x32_bf16 v[48:51], v[212:215], v[186:189], v[16:19]
	v_mfma_f32_16x16x32_bf16 v[16:19], v[0:3], v[190:193], v[52:55]
	v_mfma_f32_16x16x32_bf16 v[36:39], v[8:11], v[194:197], v[16:19]
	v_mfma_f32_16x16x32_bf16 v[16:19], v[208:211], v[190:193], v[232:235]
	v_mfma_f32_16x16x32_bf16 v[32:35], v[212:215], v[194:197], v[16:19]
	v_mfma_f32_16x16x32_bf16 v[16:19], v[0:3], v[228:231], v[44:47]
	v_mfma_f32_16x16x32_bf16 v[0:3], v[0:3], v[240:243], v[144:147]
	v_mfma_f32_16x16x32_bf16 v[24:27], v[8:11], v[236:239], v[16:19]
	v_mfma_f32_16x16x32_bf16 v[16:19], v[208:211], v[228:231], v[40:43]
	v_mfma_f32_16x16x32_bf16 v[8:11], v[8:11], v[244:247], v[0:3]
	v_mfma_f32_16x16x32_bf16 v[0:3], v[208:211], v[240:243], v[148:151]
	v_mfma_f32_16x16x32_bf16 v[16:19], v[212:215], v[236:239], v[16:19]
	v_mfma_f32_16x16x32_bf16 v[0:3], v[212:215], v[244:247], v[0:3]
	s_nop 0
	s_nop 0
	v_mfma_f32_16x16x32_bf16 v[28:31], v[140:143], v[156:159], v[28:31]
	v_mfma_f32_16x16x32_bf16 v[60:63], v[220:223], v[186:189], v[28:31]
	v_mfma_f32_16x16x32_bf16 v[28:31], v[224:227], v[156:159], v[178:181]
	v_mfma_f32_16x16x32_bf16 v[20:23], v[140:143], v[190:193], v[20:23]
	v_mfma_f32_16x16x32_bf16 v[12:15], v[140:143], v[228:231], v[12:15]
	v_mfma_f32_16x16x32_bf16 v[52:55], v[152:155], v[186:189], v[28:31]
	v_mfma_f32_16x16x32_bf16 v[40:43], v[220:223], v[194:197], v[20:23]
	v_mfma_f32_16x16x32_bf16 v[20:23], v[224:227], v[190:193], v[182:185]
	v_mfma_f32_16x16x32_bf16 v[28:31], v[220:223], v[236:239], v[12:15]
	v_mfma_f32_16x16x32_bf16 v[12:15], v[224:227], v[228:231], v[200:203]
	v_mfma_f32_16x16x32_bf16 v[4:7], v[140:143], v[240:243], v[4:7]
	v_mfma_f32_16x16x32_bf16 v[44:47], v[152:155], v[194:197], v[20:23]
	v_mfma_f32_16x16x32_bf16 v[20:23], v[152:155], v[236:239], v[12:15]
	v_mfma_f32_16x16x32_bf16 v[12:15], v[220:223], v[244:247], v[4:7]
	v_mfma_f32_16x16x32_bf16 v[4:7], v[224:227], v[240:243], v[204:207]
	v_mfma_f32_16x16x32_bf16 v[4:7], v[152:155], v[244:247], v[4:7]
	s_setprio 0
	s_cmpk_gt_u32 s0, 0xff
	s_barrier
	s_cbranch_scc1 .LBB0_1295
	s_barrier

; #define WAIT_V(n) asm volatile("s_waitcnt vmcnt(" #n ")":::"memory")
; #define BAR __builtin_amdgcn_s_barrier()
; DEVINL void gemm8_mainloop(const u16* A, long lda, const u16* Bt, long ldb, int K, int brow, int bcol, f32x4 (&acc)[2][2][4][2], char* smem, int tid) {
;     ...
;   if(wr==1)BAR;
;   WAIT_V(4); BAR;
.LBB0_1868:
	v_mov_b32_e32 v151, v176
	s_nop 0
	v_readfirstlane_b32 s29, v151
	s_ashr_i32 s37, s29, 8
	s_cmp_lg_u32 s37, 1
	s_cbranch_scc1 .LBB0_1870
	s_setprio 1
	s_barrier

; #define STAGE(P,BASE,LD,br,kt) do{long _g=(long)(br)*(LD)+(long)(kt)*BK; \
;     _Pragma("unroll") for(int _i=0;_i<2;++_i){int _b=tid*16+_i*8192;int _r,_c;stage_rc(_b,_r,_c); \
;       __builtin_amdgcn_global_load_lds((const unsigned*)((BASE)+_g+(long)_r*(LD)+_c), \
;         (unsigned*)((char*)(P)+_b),16,0,0);}}while(0)
; #define STAGE(P,BASE,LD,br,kt) do{long _g=(long)(br)*(LD)+(long)(kt)*BK; \
;     _Pragma("unroll") for(int _i=0;_i<2;++_i){int _b=tid*16+_i*8192;int _r,_c;stage_rc(_b,_r,_c); \
;       __builtin_amdgcn_global_load_lds((const unsigned*)((BASE)+_g+(long)_r*(LD)+_c), \
;         (unsigned*)((char*)(P)+_b),16,0,0);}}while(0)
; #define LDA(dst,b,h) _Pragma("unroll") for(int m=0;m<4;++m) _Pragma("unroll") for(int k=0;k<2;++k) \
;     dst[m][k]=*reinterpret_cast<const bf16x8*>((char*)SA(b,h)+lds_byte(wr*64+m*16+fr,k*32+fq*8))
; #define LDB(dst,b,h) _Pragma("unroll") for(int n=0;n<2;++n) _Pragma("unroll") for(int k=0;k<2;++k) \
;     dst[n][k]=*reinterpret_cast<const bf16x8*>((char*)SB(b,h)+lds_byte(wc*32+n*16+fr,k*32+fq*8))
; #define MMA(ai,bj,At_,Bt_) do{__builtin_amdgcn_s_setprio(1); \
;     _Pragma("unroll") for(int m=0;m<4;++m) _Pragma("unroll") for(int n=0;n<2;++n) _Pragma("unroll") for(int k=0;k<2;++k) \
;       acc[ai][bj][m][n]=__builtin_amdgcn_mfma_f32_16x16x32_bf16(Bt_[n][k],At_[m][k],acc[ai][bj][m][n],0,0,0); \
;     __builtin_amdgcn_s_setprio(0);}while(0)
; #define WAIT_L(n) asm volatile("s_waitcnt lgkmcnt(" #n ")":::"memory")
; #define BAR __builtin_amdgcn_s_barrier()
; #define SCHED __builtin_amdgcn_sched_barrier(0)
; DEVINL void gemm8_mainloop(const u16* A, long lda, const u16* Bt, long ldb, int K, int brow, int bcol, f32x4 (&acc)[2][2][4][2], char* smem, int tid) {
;     ...
;   for(int t=0;t<nt-2;t+=2){
;     LDB(B0,0,0); SCHED; LDA(At,0,0); STAGE(SA(1,1),A,lda,brow+HALF,t+1);
;     WAIT_L(8); BAR; WAIT_L(0); MMA(0,0,At,B0); BAR; SCHED;
;     LDB(B1,0,1); STAGE(SB(0,0),Bt,ldb,bcol,t+2);
;     BAR; WAIT_L(0); MMA(0,1,At,B1); BAR;
;     LDA(At,0,1); STAGE(SA(0,0),A,lda,brow,t+2);
;     BAR; WAIT_L(0); MMA(1,0,At,B0); BAR; SCHED;
.LBB0_1871:
	ds_read_b128 v[178:181], v163
	ds_read_b128 v[182:185], v163 offset:1024
	ds_read_b128 v[186:189], v163 offset:2048
	ds_read_b128 v[190:193], v163 offset:3072
	v_add_u32_e32 v174, 0xc000, v152
	v_lshl_add_u64 v[242:243], s[94:95], 0, v[146:147]
	v_readfirstlane_b32 s27, v174
	v_add_u32_e32 v175, 0xe000, v152
	v_add_u32_e32 v171, s25, v162
	v_add_u32_e32 v172, s37, v162
	v_add_u32_e32 v173, s38, v162
	v_lshl_add_u64 v[164:165], v[242:243], 0, s[2:3]
	s_mov_b32 m0, s27
	v_lshl_add_u64 v[244:245], s[94:95], 0, v[148:149]
	v_readfirstlane_b32 s27, v175
	ds_read_b128 v[166:169], v153
	ds_read_b128 v[194:197], v153 offset:1024
	ds_read_b128 v[198:201], v171
	ds_read_b128 v[202:205], v171 offset:1024
	ds_read_b128 v[206:209], v172
	ds_read_b128 v[210:213], v172 offset:1024
	ds_read_b128 v[214:217], v173
	ds_read_b128 v[218:221], v173 offset:1024
	global_load_lds_dwordx4 v[164:165], off
	v_lshl_add_u64 v[164:165], v[244:245], 0, s[2:3]
	s_mov_b32 m0, s27
	s_nop 0
	global_load_lds_dwordx4 v[164:165], off
	s_waitcnt lgkmcnt(8)
	s_barrier
	s_waitcnt lgkmcnt(0)
	s_nop 0
	v_mfma_f32_16x16x32_bf16 v[124:127], v[178:181], v[166:169], v[124:127]
	v_mfma_f32_16x16x32_bf16 v[120:123], v[186:189], v[166:169], v[120:123]
	v_mfma_f32_16x16x32_bf16 v[116:119], v[178:181], v[198:201], v[116:119]
	v_mfma_f32_16x16x32_bf16 v[112:115], v[186:189], v[198:201], v[112:115]
	v_mfma_f32_16x16x32_bf16 v[108:111], v[178:181], v[206:209], v[108:111]
	v_mfma_f32_16x16x32_bf16 v[104:107], v[186:189], v[206:209], v[104:107]
	v_mfma_f32_16x16x32_bf16 v[100:103], v[178:181], v[214:217], v[100:103]
	v_mfma_f32_16x16x32_bf16 v[96:99], v[186:189], v[214:217], v[96:99]
	v_mfma_f32_16x16x32_bf16 v[124:127], v[182:185], v[194:197], v[124:127]
	v_mfma_f32_16x16x32_bf16 v[120:123], v[190:193], v[194:197], v[120:123]
	v_mfma_f32_16x16x32_bf16 v[116:119], v[182:185], v[202:205], v[116:119]
	v_mfma_f32_16x16x32_bf16 v[112:115], v[190:193], v[202:205], v[112:115]
	v_mfma_f32_16x16x32_bf16 v[108:111], v[182:185], v[210:213], v[108:111]
	v_mfma_f32_16x16x32_bf16 v[104:107], v[190:193], v[210:213], v[104:107]
	v_mfma_f32_16x16x32_bf16 v[100:103], v[182:185], v[218:221], v[100:103]
	v_mfma_f32_16x16x32_bf16 v[96:99], v[190:193], v[218:221], v[96:99]
	s_nop 0
	s_barrier
	v_add_u32_e32 v164, s30, v154
	v_lshl_add_u64 v[246:247], s[94:95], 0, v[142:143]
	v_readfirstlane_b32 s27, v164
	v_add_u32_e32 v165, 0x2000, v164
	v_lshl_add_u64 v[238:239], v[246:247], 0, s[4:5]
	s_mov_b32 m0, s27
	v_lshl_add_u64 v[248:249], s[94:95], 0, v[144:145]
	v_readfirstlane_b32 s27, v165
	ds_read_b128 v[222:225], v160
	ds_read_b128 v[226:229], v160 offset:1024
	ds_read_b128 v[230:233], v160 offset:2048
	ds_read_b128 v[234:237], v160 offset:3072
	global_load_lds_dwordx4 v[238:239], off
	v_lshl_add_u64 v[238:239], v[248:249], 0, s[4:5]
	s_mov_b32 m0, s27
	s_nop 0
	global_load_lds_dwordx4 v[238:239], off
	s_barrier
	s_waitcnt lgkmcnt(0)
	s_nop 0
	v_mfma_f32_16x16x32_bf16 v[92:95], v[222:225], v[166:169], v[92:95]
	v_mfma_f32_16x16x32_bf16 v[88:91], v[230:233], v[166:169], v[88:91]
	v_mfma_f32_16x16x32_bf16 v[84:87], v[222:225], v[198:201], v[84:87]
	v_mfma_f32_16x16x32_bf16 v[80:83], v[230:233], v[198:201], v[80:83]
	v_mfma_f32_16x16x32_bf16 v[76:79], v[222:225], v[206:209], v[76:79]
	v_mfma_f32_16x16x32_bf16 v[72:75], v[230:233], v[206:209], v[72:75]
	v_mfma_f32_16x16x32_bf16 v[68:71], v[222:225], v[214:217], v[68:71]
	v_mfma_f32_16x16x32_bf16 v[64:67], v[230:233], v[214:217], v[64:67]
	v_mfma_f32_16x16x32_bf16 v[92:95], v[226:229], v[194:197], v[92:95]
	v_mfma_f32_16x16x32_bf16 v[88:91], v[234:237], v[194:197], v[88:91]
	v_mfma_f32_16x16x32_bf16 v[84:87], v[226:229], v[202:205], v[84:87]
	v_mfma_f32_16x16x32_bf16 v[80:83], v[234:237], v[202:205], v[80:83]
	v_mfma_f32_16x16x32_bf16 v[76:79], v[226:229], v[210:213], v[76:79]
	v_mfma_f32_16x16x32_bf16 v[72:75], v[234:237], v[210:213], v[72:75]
	v_mfma_f32_16x16x32_bf16 v[68:71], v[226:229], v[218:221], v[68:71]
	v_mfma_f32_16x16x32_bf16 v[64:67], v[234:237], v[218:221], v[64:67]
	s_nop 0
	v_readfirstlane_b32 s27, v152
	v_lshl_add_u64 v[166:167], v[242:243], 0, s[6:7]
	s_mov_b32 m0, s27
	s_barrier
	ds_read_b128 v[194:197], v153 offset:16384
	ds_read_b128 v[198:201], v153 offset:17408
	ds_read_b128 v[202:205], v171 offset:16384
	ds_read_b128 v[206:209], v171 offset:17408
	ds_read_b128 v[210:213], v172 offset:16384
	ds_read_b128 v[214:217], v172 offset:17408
	ds_read_b128 v[218:221], v173 offset:16384
	ds_read_b128 v[238:241], v173 offset:17408
	global_load_lds_dwordx4 v[166:167], off
	v_add_u32_e32 v166, 0x2000, v152
	v_lshl_add_u64 v[168:169], v[244:245], 0, s[6:7]
	v_readfirstlane_b32 s27, v166
	s_mov_b32 m0, s27
	s_nop 0
	global_load_lds_dwordx4 v[168:169], off
	s_barrier
	s_waitcnt lgkmcnt(0)
	s_nop 0
	v_mfma_f32_16x16x32_bf16 v[60:63], v[178:181], v[194:197], v[60:63]
	v_mfma_f32_16x16x32_bf16 v[56:59], v[186:189], v[194:197], v[56:59]
	v_mfma_f32_16x16x32_bf16 v[52:55], v[178:181], v[202:205], v[52:55]
	v_mfma_f32_16x16x32_bf16 v[48:51], v[186:189], v[202:205], v[48:51]
	v_mfma_f32_16x16x32_bf16 v[44:47], v[178:181], v[210:213], v[44:47]
	v_mfma_f32_16x16x32_bf16 v[40:43], v[186:189], v[210:213], v[40:43]
	v_mfma_f32_16x16x32_bf16 v[36:39], v[178:181], v[218:221], v[36:39]
	v_mfma_f32_16x16x32_bf16 v[32:35], v[186:189], v[218:221], v[32:35]
	v_mfma_f32_16x16x32_bf16 v[60:63], v[182:185], v[198:201], v[60:63]
	v_mfma_f32_16x16x32_bf16 v[56:59], v[190:193], v[198:201], v[56:59]
	v_mfma_f32_16x16x32_bf16 v[52:55], v[182:185], v[206:209], v[52:55]
	v_mfma_f32_16x16x32_bf16 v[48:51], v[190:193], v[206:209], v[48:51]
	v_mfma_f32_16x16x32_bf16 v[44:47], v[182:185], v[214:217], v[44:47]
	v_mfma_f32_16x16x32_bf16 v[40:43], v[190:193], v[214:217], v[40:43]
	v_mfma_f32_16x16x32_bf16 v[36:39], v[182:185], v[238:241], v[36:39]
	v_mfma_f32_16x16x32_bf16 v[32:35], v[190:193], v[238:241], v[32:35]
	s_nop 0
	s_barrier
; #define STAGE(P,BASE,LD,br,kt) do{long _g=(long)(br)*(LD)+(long)(kt)*BK; \
;     _Pragma("unroll") for(int _i=0;_i<2;++_i){int _b=tid*16+_i*8192;int _r,_c;stage_rc(_b,_r,_c); \
;       __builtin_amdgcn_global_load_lds((const unsigned*)((BASE)+_g+(long)_r*(LD)+_c), \
;         (unsigned*)((char*)(P)+_b),16,0,0);}}while(0)
; #define STAGE(P,BASE,LD,br,kt) do{long _g=(long)(br)*(LD)+(long)(kt)*BK; \
;     _Pragma("unroll") for(int _i=0;_i<2;++_i){int _b=tid*16+_i*8192;int _r,_c;stage_rc(_b,_r,_c); \
;       __builtin_amdgcn_global_load_lds((const unsigned*)((BASE)+_g+(long)_r*(LD)+_c), \
;         (unsigned*)((char*)(P)+_b),16,0,0);}}while(0)
; #define LDA(dst,b,h) _Pragma("unroll") for(int m=0;m<4;++m) _Pragma("unroll") for(int k=0;k<2;++k) \
;     dst[m][k]=*reinterpret_cast<const bf16x8*>((char*)SA(b,h)+lds_byte(wr*64+m*16+fr,k*32+fq*8))
; #define LDB(dst,b,h) _Pragma("unroll") for(int n=0;n<2;++n) _Pragma("unroll") for(int k=0;k<2;++k) \
;     dst[n][k]=*reinterpret_cast<const bf16x8*>((char*)SB(b,h)+lds_byte(wc*32+n*16+fr,k*32+fq*8))
; #define MMA(ai,bj,At_,Bt_) do{__builtin_amdgcn_s_setprio(1); \
;     _Pragma("unroll") for(int m=0;m<4;++m) _Pragma("unroll") for(int n=0;n<2;++n) _Pragma("unroll") for(int k=0;k<2;++k) \
;       acc[ai][bj][m][n]=__builtin_amdgcn_mfma_f32_16x16x32_bf16(Bt_[n][k],At_[m][k],acc[ai][bj][m][n],0,0,0); \
;     __builtin_amdgcn_s_setprio(0);}while(0)
; #define WAIT_V(n) asm volatile("s_waitcnt vmcnt(" #n ")":::"memory")
; #define WAIT_L(n) asm volatile("s_waitcnt lgkmcnt(" #n ")":::"memory")
; #define BAR __builtin_amdgcn_s_barrier()
; #define SCHED __builtin_amdgcn_sched_barrier(0)
; DEVINL void gemm8_mainloop(const u16* A, long lda, const u16* Bt, long ldb, int K, int brow, int bcol, f32x4 (&acc)[2][2][4][2], char* smem, int tid) {
;     ...
;     STAGE(SB(0,1),Bt,ldb,bcol+HALF,t+2);
;     WAIT_V(6); BAR; MMA(1,1,At,B1); BAR;
;     LDB(B0,1,0); SCHED; LDA(At,1,0); STAGE(SA(0,1),A,lda,brow+HALF,t+2);
;     WAIT_L(8); BAR; WAIT_L(0); MMA(0,0,At,B0); BAR; SCHED;
;     LDB(B1,1,1); STAGE(SB(1,0),Bt,ldb,bcol,t+3);
;     BAR; WAIT_L(0); MMA(0,1,At,B1); BAR;
	v_add_u32_e32 v167, s31, v154
	v_lshl_add_u64 v[168:169], v[246:247], 0, s[8:9]
	v_readfirstlane_b32 s27, v167
	s_mov_b32 m0, s27
	v_lshl_add_u64 v[178:179], v[248:249], 0, s[8:9]
	global_load_lds_dwordx4 v[168:169], off
	v_add_u32_e32 v168, 0x2000, v167
	s_nop 0
	v_readfirstlane_b32 s27, v168
	s_mov_b32 m0, s27
	s_nop 0
	global_load_lds_dwordx4 v[178:179], off
	s_waitcnt vmcnt(6)
	s_barrier
	s_nop 0
	v_mfma_f32_16x16x32_bf16 v[28:31], v[222:225], v[194:197], v[28:31]
	v_mfma_f32_16x16x32_bf16 v[24:27], v[230:233], v[194:197], v[24:27]
	v_mfma_f32_16x16x32_bf16 v[20:23], v[222:225], v[202:205], v[20:23]
	v_mfma_f32_16x16x32_bf16 v[16:19], v[230:233], v[202:205], v[16:19]
	v_mfma_f32_16x16x32_bf16 v[12:15], v[222:225], v[210:213], v[12:15]
	v_mfma_f32_16x16x32_bf16 v[8:11], v[230:233], v[210:213], v[8:11]
	v_mfma_f32_16x16x32_bf16 v[4:7], v[222:225], v[218:221], v[4:7]
	v_mfma_f32_16x16x32_bf16 v[0:3], v[230:233], v[218:221], v[0:3]
	v_mfma_f32_16x16x32_bf16 v[28:31], v[226:229], v[198:201], v[28:31]
	v_mfma_f32_16x16x32_bf16 v[24:27], v[234:237], v[198:201], v[24:27]
	v_mfma_f32_16x16x32_bf16 v[20:23], v[226:229], v[206:209], v[20:23]
	v_mfma_f32_16x16x32_bf16 v[16:19], v[234:237], v[206:209], v[16:19]
	v_mfma_f32_16x16x32_bf16 v[12:15], v[226:229], v[214:217], v[12:15]
	v_mfma_f32_16x16x32_bf16 v[8:11], v[234:237], v[214:217], v[8:11]
	v_mfma_f32_16x16x32_bf16 v[4:7], v[226:229], v[238:241], v[4:7]
	v_mfma_f32_16x16x32_bf16 v[0:3], v[234:237], v[238:241], v[0:3]
	s_nop 0
	s_barrier
	ds_read_b128 v[178:181], v156
	ds_read_b128 v[182:185], v156 offset:1024
	ds_read_b128 v[186:189], v156 offset:2048
	ds_read_b128 v[190:193], v156 offset:3072
	v_add_u32_e32 v169, 0x4000, v152
	v_add_u32_e32 v170, 0x6000, v152
	v_readfirstlane_b32 s27, v169
	v_lshl_add_u64 v[226:227], v[242:243], 0, s[10:11]
	s_mov_b32 m0, s27
	v_readfirstlane_b32 s27, v170
	ds_read_b128 v[194:197], v153 offset:32768
	ds_read_b128 v[198:201], v153 offset:33792
	ds_read_b128 v[202:205], v171 offset:32768
	ds_read_b128 v[206:209], v171 offset:33792
	ds_read_b128 v[210:213], v172 offset:32768
	ds_read_b128 v[214:217], v172 offset:33792
	ds_read_b128 v[218:221], v173 offset:32768
	ds_read_b128 v[222:225], v173 offset:33792
	global_load_lds_dwordx4 v[226:227], off
	v_lshl_add_u64 v[226:227], v[244:245], 0, s[10:11]
	s_mov_b32 m0, s27
	s_nop 0
	global_load_lds_dwordx4 v[226:227], off
	s_waitcnt lgkmcnt(8)
	s_barrier
	s_waitcnt lgkmcnt(0)
	s_nop 0
	v_mfma_f32_16x16x32_bf16 v[124:127], v[178:181], v[194:197], v[124:127]
	v_mfma_f32_16x16x32_bf16 v[120:123], v[186:189], v[194:197], v[120:123]
	v_mfma_f32_16x16x32_bf16 v[116:119], v[178:181], v[202:205], v[116:119]
	v_mfma_f32_16x16x32_bf16 v[112:115], v[186:189], v[202:205], v[112:115]
	v_mfma_f32_16x16x32_bf16 v[108:111], v[178:181], v[210:213], v[108:111]
	v_mfma_f32_16x16x32_bf16 v[104:107], v[186:189], v[210:213], v[104:107]
	v_mfma_f32_16x16x32_bf16 v[100:103], v[178:181], v[218:221], v[100:103]
	v_mfma_f32_16x16x32_bf16 v[96:99], v[186:189], v[218:221], v[96:99]
	v_mfma_f32_16x16x32_bf16 v[124:127], v[182:185], v[198:201], v[124:127]
	v_mfma_f32_16x16x32_bf16 v[120:123], v[190:193], v[198:201], v[120:123]
	v_mfma_f32_16x16x32_bf16 v[116:119], v[182:185], v[206:209], v[116:119]
	v_mfma_f32_16x16x32_bf16 v[112:115], v[190:193], v[206:209], v[112:115]
	v_mfma_f32_16x16x32_bf16 v[108:111], v[182:185], v[214:217], v[108:111]
	v_mfma_f32_16x16x32_bf16 v[104:107], v[190:193], v[214:217], v[104:107]
	v_mfma_f32_16x16x32_bf16 v[100:103], v[182:185], v[222:225], v[100:103]
	v_mfma_f32_16x16x32_bf16 v[96:99], v[190:193], v[222:225], v[96:99]
	s_nop 0
	s_barrier
	v_readfirstlane_b32 s27, v157
	v_add_u32_e32 v177, 0x2000, v157
	v_lshl_add_u64 v[250:251], v[246:247], 0, s[12:13]
	s_mov_b32 m0, s27
	v_readfirstlane_b32 s27, v177
	ds_read_b128 v[226:229], v155
	ds_read_b128 v[230:233], v155 offset:1024
	ds_read_b128 v[234:237], v155 offset:2048
	ds_read_b128 v[238:241], v155 offset:3072
	global_load_lds_dwordx4 v[250:251], off
	v_lshl_add_u64 v[250:251], v[248:249], 0, s[12:13]
	s_mov_b32 m0, s27
	s_nop 0
	global_load_lds_dwordx4 v[250:251], off
	s_barrier
	s_waitcnt lgkmcnt(0)
	s_nop 0
	v_mfma_f32_16x16x32_bf16 v[92:95], v[226:229], v[194:197], v[92:95]
	v_mfma_f32_16x16x32_bf16 v[88:91], v[234:237], v[194:197], v[88:91]
	v_mfma_f32_16x16x32_bf16 v[84:87], v[226:229], v[202:205], v[84:87]
	v_mfma_f32_16x16x32_bf16 v[80:83], v[234:237], v[202:205], v[80:83]
	v_mfma_f32_16x16x32_bf16 v[76:79], v[226:229], v[210:213], v[76:79]
	v_mfma_f32_16x16x32_bf16 v[72:75], v[234:237], v[210:213], v[72:75]
	v_mfma_f32_16x16x32_bf16 v[68:71], v[226:229], v[218:221], v[68:71]
	v_mfma_f32_16x16x32_bf16 v[64:67], v[234:237], v[218:221], v[64:67]
	v_mfma_f32_16x16x32_bf16 v[92:95], v[230:233], v[198:201], v[92:95]
	v_mfma_f32_16x16x32_bf16 v[88:91], v[238:241], v[198:201], v[88:91]
	v_mfma_f32_16x16x32_bf16 v[84:87], v[230:233], v[206:209], v[84:87]
	v_mfma_f32_16x16x32_bf16 v[80:83], v[238:241], v[206:209], v[80:83]
	v_mfma_f32_16x16x32_bf16 v[76:79], v[230:233], v[214:217], v[76:79]
	v_mfma_f32_16x16x32_bf16 v[72:75], v[238:241], v[214:217], v[72:75]
	v_mfma_f32_16x16x32_bf16 v[68:71], v[230:233], v[222:225], v[68:71]
	v_mfma_f32_16x16x32_bf16 v[64:67], v[238:241], v[222:225], v[64:67]
	s_nop 0
	v_readfirstlane_b32 s27, v158
	v_lshl_add_u64 v[242:243], v[242:243], 0, s[14:15]
	s_mov_b32 m0, s27
	v_readfirstlane_b32 s27, v159
	s_barrier
; #define STAGE(P,BASE,LD,br,kt) do{long _g=(long)(br)*(LD)+(long)(kt)*BK; \
;     _Pragma("unroll") for(int _i=0;_i<2;++_i){int _b=tid*16+_i*8192;int _r,_c;stage_rc(_b,_r,_c); \
;       __builtin_amdgcn_global_load_lds((const unsigned*)((BASE)+_g+(long)_r*(LD)+_c), \
;         (unsigned*)((char*)(P)+_b),16,0,0);}}while(0)
; #define STAGE(P,BASE,LD,br,kt) do{long _g=(long)(br)*(LD)+(long)(kt)*BK; \
;     _Pragma("unroll") for(int _i=0;_i<2;++_i){int _b=tid*16+_i*8192;int _r,_c;stage_rc(_b,_r,_c); \
;       __builtin_amdgcn_global_load_lds((const unsigned*)((BASE)+_g+(long)_r*(LD)+_c), \
;         (unsigned*)((char*)(P)+_b),16,0,0);}}while(0)
; #define LDA(dst,b,h) _Pragma("unroll") for(int m=0;m<4;++m) _Pragma("unroll") for(int k=0;k<2;++k) \
;     dst[m][k]=*reinterpret_cast<const bf16x8*>((char*)SA(b,h)+lds_byte(wr*64+m*16+fr,k*32+fq*8))
; #define LDB(dst,b,h) _Pragma("unroll") for(int n=0;n<2;++n) _Pragma("unroll") for(int k=0;k<2;++k) \
;     dst[n][k]=*reinterpret_cast<const bf16x8*>((char*)SB(b,h)+lds_byte(wc*32+n*16+fr,k*32+fq*8))
; #define MMA(ai,bj,At_,Bt_) do{__builtin_amdgcn_s_setprio(1); \
;     _Pragma("unroll") for(int m=0;m<4;++m) _Pragma("unroll") for(int n=0;n<2;++n) _Pragma("unroll") for(int k=0;k<2;++k) \
;       acc[ai][bj][m][n]=__builtin_amdgcn_mfma_f32_16x16x32_bf16(Bt_[n][k],At_[m][k],acc[ai][bj][m][n],0,0,0); \
;     __builtin_amdgcn_s_setprio(0);}while(0)
; #define WAIT_V(n) asm volatile("s_waitcnt vmcnt(" #n ")":::"memory")
; #define WAIT_L(n) asm volatile("s_waitcnt lgkmcnt(" #n ")":::"memory")
; #define BAR __builtin_amdgcn_s_barrier()
; #define SCHED __builtin_amdgcn_sched_barrier(0)
; DEVINL void gemm8_mainloop(const u16* A, long lda, const u16* Bt, long ldb, int K, int brow, int bcol, f32x4 (&acc)[2][2][4][2], char* smem, int tid) {
;     ...
;     LDA(At,1,1); STAGE(SA(1,0),A,lda,brow,t+3);
;     BAR; WAIT_L(0); MMA(1,0,At,B0); BAR; SCHED;
;     STAGE(SB(1,1),Bt,ldb,bcol+HALF,t+3);
;     WAIT_V(6); BAR; MMA(1,1,At,B1); BAR;
;   }
;   { LDB(B0,0,0); LDA(At,0,0); STAGE(SA(1,1),A,lda,brow+HALF,nt-1);
;     BAR; WAIT_L(0); MMA(0,0,At,B0); BAR;
	ds_read_b128 v[194:197], v153 offset:49152
	ds_read_b128 v[198:201], v153 offset:50176
	ds_read_b128 v[202:205], v171 offset:49152
	ds_read_b128 v[206:209], v171 offset:50176
	ds_read_b128 v[210:213], v172 offset:49152
	ds_read_b128 v[214:217], v172 offset:50176
	ds_read_b128 v[218:221], v173 offset:49152
	ds_read_b128 v[222:225], v173 offset:50176
	global_load_lds_dwordx4 v[242:243], off
	v_lshl_add_u64 v[242:243], v[244:245], 0, s[14:15]
	s_mov_b32 m0, s27
	s_nop 0
	global_load_lds_dwordx4 v[242:243], off
	s_barrier
	s_waitcnt lgkmcnt(0)
	s_nop 0
	v_mfma_f32_16x16x32_bf16 v[60:63], v[178:181], v[194:197], v[60:63]
	v_mfma_f32_16x16x32_bf16 v[56:59], v[186:189], v[194:197], v[56:59]
	v_mfma_f32_16x16x32_bf16 v[52:55], v[178:181], v[202:205], v[52:55]
	v_mfma_f32_16x16x32_bf16 v[48:51], v[186:189], v[202:205], v[48:51]
	v_mfma_f32_16x16x32_bf16 v[44:47], v[178:181], v[210:213], v[44:47]
	v_mfma_f32_16x16x32_bf16 v[40:43], v[186:189], v[210:213], v[40:43]
	v_mfma_f32_16x16x32_bf16 v[36:39], v[178:181], v[218:221], v[36:39]
	v_mfma_f32_16x16x32_bf16 v[32:35], v[186:189], v[218:221], v[32:35]
	v_mfma_f32_16x16x32_bf16 v[60:63], v[182:185], v[198:201], v[60:63]
	v_mfma_f32_16x16x32_bf16 v[56:59], v[190:193], v[198:201], v[56:59]
	v_mfma_f32_16x16x32_bf16 v[52:55], v[182:185], v[206:209], v[52:55]
	v_mfma_f32_16x16x32_bf16 v[48:51], v[190:193], v[206:209], v[48:51]
	v_mfma_f32_16x16x32_bf16 v[44:47], v[182:185], v[214:217], v[44:47]
	v_mfma_f32_16x16x32_bf16 v[40:43], v[190:193], v[214:217], v[40:43]
	v_mfma_f32_16x16x32_bf16 v[36:39], v[182:185], v[222:225], v[36:39]
	v_mfma_f32_16x16x32_bf16 v[32:35], v[190:193], v[222:225], v[32:35]
	s_nop 0
	s_barrier
	v_readfirstlane_b32 s27, v161
	v_add_u32_e32 v177, 0x2000, v161
	v_lshl_add_u64 v[178:179], v[246:247], 0, s[16:17]
	s_mov_b32 m0, s27
	v_readfirstlane_b32 s27, v177
	global_load_lds_dwordx4 v[178:179], off
	v_lshl_add_u64 v[178:179], v[248:249], 0, s[16:17]
	s_mov_b32 m0, s27
	s_nop 0
	global_load_lds_dwordx4 v[178:179], off
	s_waitcnt vmcnt(6)
	s_barrier
	s_nop 0
	v_mfma_f32_16x16x32_bf16 v[28:31], v[226:229], v[194:197], v[28:31]
	v_mfma_f32_16x16x32_bf16 v[24:27], v[234:237], v[194:197], v[24:27]
	v_mfma_f32_16x16x32_bf16 v[20:23], v[226:229], v[202:205], v[20:23]
	v_mfma_f32_16x16x32_bf16 v[16:19], v[234:237], v[202:205], v[16:19]
	v_mfma_f32_16x16x32_bf16 v[12:15], v[226:229], v[210:213], v[12:15]
	v_mfma_f32_16x16x32_bf16 v[8:11], v[234:237], v[210:213], v[8:11]
	v_mfma_f32_16x16x32_bf16 v[4:7], v[226:229], v[218:221], v[4:7]
	v_mfma_f32_16x16x32_bf16 v[0:3], v[234:237], v[218:221], v[0:3]
	v_mfma_f32_16x16x32_bf16 v[28:31], v[230:233], v[198:201], v[28:31]
	v_mfma_f32_16x16x32_bf16 v[24:27], v[238:241], v[198:201], v[24:27]
	v_mfma_f32_16x16x32_bf16 v[20:23], v[230:233], v[206:209], v[20:23]
	v_mfma_f32_16x16x32_bf16 v[16:19], v[238:241], v[206:209], v[16:19]
	v_mfma_f32_16x16x32_bf16 v[12:15], v[230:233], v[214:217], v[12:15]
	v_mfma_f32_16x16x32_bf16 v[8:11], v[238:241], v[214:217], v[8:11]
	v_mfma_f32_16x16x32_bf16 v[4:7], v[230:233], v[222:225], v[4:7]
	v_mfma_f32_16x16x32_bf16 v[0:3], v[238:241], v[222:225], v[0:3]
	s_nop 0
	s_add_i32 s26, s26, 2
	v_lshl_add_u64 v[142:143], v[142:143], 0, s[18:19]
	v_lshl_add_u64 v[144:145], v[144:145], 0, s[18:19]
	v_lshl_add_u64 v[146:147], v[146:147], 0, s[18:19]
	s_cmp_lt_u32 s26, 28
	v_lshl_add_u64 v[148:149], v[148:149], 0, s[18:19]
	s_barrier
	s_cbranch_scc1 .LBB0_1871
	s_or_b32 s26, s24, 0x80
	s_ashr_i32 s27, s26, 31
	s_lshl_b64 s[26:27], s[26:27], 12
	s_add_u32 s26, s47, s26
	s_addc_u32 s27, s48, s27
	v_lshl_add_u64 v[158:159], v[134:135], 1, s[26:27]
	v_lshl_add_u64 v[138:139], v[138:139], 1, v[158:159]
	v_readfirstlane_b32 s25, v174
	v_lshl_add_u64 v[138:139], v[138:139], 0, s[20:21]
	s_mov_b32 m0, s25
	ds_read_b128 v[142:145], v163
	ds_read_b128 v[146:149], v163 offset:1024
	ds_read_b128 v[178:181], v163 offset:2048
	ds_read_b128 v[182:185], v163 offset:3072
	ds_read_b128 v[186:189], v153
	ds_read_b128 v[190:193], v153 offset:1024
	ds_read_b128 v[194:197], v171
	ds_read_b128 v[198:201], v171 offset:1024
	ds_read_b128 v[202:205], v172
	ds_read_b128 v[206:209], v172 offset:1024
	ds_read_b128 v[210:213], v173
	ds_read_b128 v[214:217], v173 offset:1024
	global_load_lds_dwordx4 v[138:139], off
	v_lshl_add_u64 v[138:139], v[136:137], 1, s[26:27]
	v_lshl_add_u64 v[138:139], v[140:141], 1, v[138:139]
	v_readfirstlane_b32 s25, v175
	v_lshl_add_u64 v[138:139], v[138:139], 0, s[20:21]
	s_mov_b32 m0, s25
	s_nop 0
	global_load_lds_dwordx4 v[138:139], off
	s_barrier
	s_waitcnt lgkmcnt(0)
	s_nop 0
	v_mfma_f32_16x16x32_bf16 v[124:127], v[142:145], v[186:189], v[124:127]
	v_mfma_f32_16x16x32_bf16 v[120:123], v[178:181], v[186:189], v[120:123]
	v_mfma_f32_16x16x32_bf16 v[116:119], v[142:145], v[194:197], v[116:119]
	v_mfma_f32_16x16x32_bf16 v[112:115], v[178:181], v[194:197], v[112:115]
	v_mfma_f32_16x16x32_bf16 v[100:103], v[142:145], v[210:213], v[100:103]
	v_mfma_f32_16x16x32_bf16 v[96:99], v[178:181], v[210:213], v[96:99]
	v_mfma_f32_16x16x32_bf16 v[124:127], v[146:149], v[190:193], v[124:127]
	v_mfma_f32_16x16x32_bf16 v[120:123], v[182:185], v[190:193], v[120:123]
	v_mfma_f32_16x16x32_bf16 v[116:119], v[146:149], v[198:201], v[116:119]
	v_mfma_f32_16x16x32_bf16 v[112:115], v[182:185], v[198:201], v[112:115]
	v_mfma_f32_16x16x32_bf16 v[108:111], v[142:145], v[202:205], v[108:111]
	v_mfma_f32_16x16x32_bf16 v[104:107], v[178:181], v[202:205], v[104:107]
	v_mfma_f32_16x16x32_bf16 v[100:103], v[146:149], v[214:217], v[100:103]
	v_mfma_f32_16x16x32_bf16 v[96:99], v[182:185], v[214:217], v[96:99]
	v_mfma_f32_16x16x32_bf16 v[138:141], v[146:149], v[206:209], v[108:111]
	v_mfma_f32_16x16x32_bf16 v[218:221], v[182:185], v[206:209], v[104:107]
	s_nop 0
	s_barrier
; #define LDA(dst,b,h) _Pragma("unroll") for(int m=0;m<4;++m) _Pragma("unroll") for(int k=0;k<2;++k) \
;     dst[m][k]=*reinterpret_cast<const bf16x8*>((char*)SA(b,h)+lds_byte(wr*64+m*16+fr,k*32+fq*8))
; #define LDB(dst,b,h) _Pragma("unroll") for(int n=0;n<2;++n) _Pragma("unroll") for(int k=0;k<2;++k) \
;     dst[n][k]=*reinterpret_cast<const bf16x8*>((char*)SB(b,h)+lds_byte(wc*32+n*16+fr,k*32+fq*8))
; #define MMA(ai,bj,At_,Bt_) do{__builtin_amdgcn_s_setprio(1); \
;     _Pragma("unroll") for(int m=0;m<4;++m) _Pragma("unroll") for(int n=0;n<2;++n) _Pragma("unroll") for(int k=0;k<2;++k) \
;       acc[ai][bj][m][n]=__builtin_amdgcn_mfma_f32_16x16x32_bf16(Bt_[n][k],At_[m][k],acc[ai][bj][m][n],0,0,0); \
;     __builtin_amdgcn_s_setprio(0);}while(0)
; #define WAIT_V(n) asm volatile("s_waitcnt vmcnt(" #n ")":::"memory")
; #define WAIT_L(n) asm volatile("s_waitcnt lgkmcnt(" #n ")":::"memory")
; #define BAR __builtin_amdgcn_s_barrier()
; DEVINL void gemm8_mainloop(const u16* A, long lda, const u16* Bt, long ldb, int K, int brow, int bcol, f32x4 (&acc)[2][2][4][2], char* smem, int tid) {
;     ...
;     LDB(B1,0,1); BAR; WAIT_L(0); MMA(0,1,At,B1); BAR;
;     LDA(At,0,1); WAIT_V(4); BAR; WAIT_L(0); MMA(1,0,At,B0); MMA(1,1,At,B1); BAR; }
;   { LDB(B0,1,0); LDA(At,1,0); WAIT_V(2); BAR; WAIT_L(0); MMA(0,0,At,B0); BAR;
	s_nop 1
	ds_read_b128 v[104:107], v160
	ds_read_b128 v[108:111], v160 offset:1024
	ds_read_b128 v[222:225], v160 offset:2048
	ds_read_b128 v[158:161], v160 offset:3072
	s_barrier
	s_waitcnt lgkmcnt(0)
	s_nop 0
	v_mfma_f32_16x16x32_bf16 v[84:87], v[104:107], v[194:197], v[84:87]
	v_mfma_f32_16x16x32_bf16 v[80:83], v[222:225], v[194:197], v[80:83]
	v_mfma_f32_16x16x32_bf16 v[68:71], v[104:107], v[210:213], v[68:71]
	v_mfma_f32_16x16x32_bf16 v[92:95], v[104:107], v[186:189], v[92:95]
	v_mfma_f32_16x16x32_bf16 v[88:91], v[222:225], v[186:189], v[88:91]
	v_mfma_f32_16x16x32_bf16 v[84:87], v[108:111], v[198:201], v[84:87]
	v_mfma_f32_16x16x32_bf16 v[80:83], v[158:161], v[198:201], v[80:83]
	v_mfma_f32_16x16x32_bf16 v[76:79], v[104:107], v[202:205], v[76:79]
	v_mfma_f32_16x16x32_bf16 v[72:75], v[222:225], v[202:205], v[72:75]
	v_mfma_f32_16x16x32_bf16 v[68:71], v[108:111], v[214:217], v[68:71]
	v_mfma_f32_16x16x32_bf16 v[64:67], v[222:225], v[210:213], v[64:67]
	v_mfma_f32_16x16x32_bf16 v[226:229], v[108:111], v[190:193], v[92:95]
	v_mfma_f32_16x16x32_bf16 v[186:189], v[158:161], v[190:193], v[88:91]
	v_mfma_f32_16x16x32_bf16 v[190:193], v[108:111], v[206:209], v[76:79]
	v_mfma_f32_16x16x32_bf16 v[194:197], v[158:161], v[206:209], v[72:75]
	v_mfma_f32_16x16x32_bf16 v[198:201], v[158:161], v[214:217], v[64:67]
	s_nop 0
	s_barrier
	s_nop 0
	ds_read_b128 v[64:67], v153 offset:16384
	ds_read_b128 v[72:75], v153 offset:17408
	ds_read_b128 v[76:79], v171 offset:16384
	ds_read_b128 v[88:91], v171 offset:17408
	ds_read_b128 v[92:95], v172 offset:16384
	ds_read_b128 v[202:205], v172 offset:17408
	ds_read_b128 v[206:209], v173 offset:16384
	ds_read_b128 v[210:213], v173 offset:17408
	s_waitcnt vmcnt(4)
	s_barrier
	s_waitcnt lgkmcnt(0)
	s_nop 0
	v_mfma_f32_16x16x32_bf16 v[60:63], v[142:145], v[64:67], v[60:63]
	v_mfma_f32_16x16x32_bf16 v[56:59], v[178:181], v[64:67], v[56:59]
	v_mfma_f32_16x16x32_bf16 v[52:55], v[142:145], v[76:79], v[52:55]
	v_mfma_f32_16x16x32_bf16 v[48:51], v[178:181], v[76:79], v[48:51]
	v_mfma_f32_16x16x32_bf16 v[36:39], v[142:145], v[206:209], v[36:39]
	v_mfma_f32_16x16x32_bf16 v[32:35], v[178:181], v[206:209], v[32:35]
	v_mfma_f32_16x16x32_bf16 v[60:63], v[146:149], v[72:75], v[60:63]
	v_mfma_f32_16x16x32_bf16 v[56:59], v[182:185], v[72:75], v[56:59]
	v_mfma_f32_16x16x32_bf16 v[52:55], v[146:149], v[88:91], v[52:55]
	v_mfma_f32_16x16x32_bf16 v[48:51], v[182:185], v[88:91], v[48:51]
	v_mfma_f32_16x16x32_bf16 v[44:47], v[142:145], v[92:95], v[44:47]
	v_mfma_f32_16x16x32_bf16 v[40:43], v[178:181], v[92:95], v[40:43]
	v_mfma_f32_16x16x32_bf16 v[36:39], v[146:149], v[210:213], v[36:39]
	v_mfma_f32_16x16x32_bf16 v[32:35], v[182:185], v[210:213], v[32:35]
	v_mfma_f32_16x16x32_bf16 v[214:217], v[146:149], v[202:205], v[44:47]
	v_mfma_f32_16x16x32_bf16 v[230:233], v[182:185], v[202:205], v[40:43]
	s_nop 0
	s_nop 0
	v_mfma_f32_16x16x32_bf16 v[20:23], v[104:107], v[76:79], v[20:23]
	v_mfma_f32_16x16x32_bf16 v[16:19], v[222:225], v[76:79], v[16:19]
	v_mfma_f32_16x16x32_bf16 v[4:7], v[104:107], v[206:209], v[4:7]
	v_mfma_f32_16x16x32_bf16 v[28:31], v[104:107], v[64:67], v[28:31]
	v_mfma_f32_16x16x32_bf16 v[24:27], v[222:225], v[64:67], v[24:27]
	v_mfma_f32_16x16x32_bf16 v[20:23], v[108:111], v[88:91], v[20:23]
	v_mfma_f32_16x16x32_bf16 v[16:19], v[158:161], v[88:91], v[16:19]
	v_mfma_f32_16x16x32_bf16 v[12:15], v[104:107], v[92:95], v[12:15]
	v_mfma_f32_16x16x32_bf16 v[8:11], v[222:225], v[92:95], v[8:11]
	v_mfma_f32_16x16x32_bf16 v[4:7], v[108:111], v[210:213], v[4:7]
	v_mfma_f32_16x16x32_bf16 v[0:3], v[222:225], v[206:209], v[0:3]
	v_mfma_f32_16x16x32_bf16 v[142:145], v[108:111], v[72:75], v[28:31]
	v_mfma_f32_16x16x32_bf16 v[146:149], v[158:161], v[72:75], v[24:27]
	v_mfma_f32_16x16x32_bf16 v[178:181], v[108:111], v[202:205], v[12:15]
	v_mfma_f32_16x16x32_bf16 v[182:185], v[158:161], v[202:205], v[8:11]
	v_mfma_f32_16x16x32_bf16 v[158:161], v[158:161], v[210:213], v[0:3]
	s_nop 0
	s_barrier
	s_nop 0
	ds_read_b128 v[0:3], v156
	ds_read_b128 v[8:11], v156 offset:1024
	ds_read_b128 v[202:205], v156 offset:2048
	ds_read_b128 v[206:209], v156 offset:3072
	ds_read_b128 v[12:15], v153 offset:32768
	ds_read_b128 v[24:27], v153 offset:33792
	ds_read_b128 v[28:31], v171 offset:32768
	ds_read_b128 v[40:43], v171 offset:33792
	ds_read_b128 v[44:47], v172 offset:32768
	ds_read_b128 v[64:67], v172 offset:33792
	ds_read_b128 v[210:213], v173 offset:32768
	ds_read_b128 v[222:225], v173 offset:33792
	s_waitcnt vmcnt(2)
	s_barrier
; #define LDA(dst,b,h) _Pragma("unroll") for(int m=0;m<4;++m) _Pragma("unroll") for(int k=0;k<2;++k) \
;     dst[m][k]=*reinterpret_cast<const bf16x8*>((char*)SA(b,h)+lds_byte(wr*64+m*16+fr,k*32+fq*8))
; #define LDB(dst,b,h) _Pragma("unroll") for(int n=0;n<2;++n) _Pragma("unroll") for(int k=0;k<2;++k) \
;     dst[n][k]=*reinterpret_cast<const bf16x8*>((char*)SB(b,h)+lds_byte(wc*32+n*16+fr,k*32+fq*8))
; #define MMA(ai,bj,At_,Bt_) do{__builtin_amdgcn_s_setprio(1); \
;     _Pragma("unroll") for(int m=0;m<4;++m) _Pragma("unroll") for(int n=0;n<2;++n) _Pragma("unroll") for(int k=0;k<2;++k) \
;       acc[ai][bj][m][n]=__builtin_amdgcn_mfma_f32_16x16x32_bf16(Bt_[n][k],At_[m][k],acc[ai][bj][m][n],0,0,0); \
;     __builtin_amdgcn_s_setprio(0);}while(0)
; #define WAIT_V(n) asm volatile("s_waitcnt vmcnt(" #n ")":::"memory")
; #define WAIT_L(n) asm volatile("s_waitcnt lgkmcnt(" #n ")":::"memory")
; #define BAR __builtin_amdgcn_s_barrier()
; DEVINL void gemm8_mainloop(const u16* A, long lda, const u16* Bt, long ldb, int K, int brow, int bcol, f32x4 (&acc)[2][2][4][2], char* smem, int tid) {
;     ...
;   { LDB(B0,1,0); LDA(At,1,0); WAIT_V(2); BAR; WAIT_L(0); MMA(0,0,At,B0); BAR;
;     LDB(B1,1,1); WAIT_V(0); BAR; WAIT_L(0); MMA(0,1,At,B1); BAR;
;     LDA(At,1,1); BAR; WAIT_L(0); MMA(1,0,At,B0); MMA(1,1,At,B1); BAR; }
;   if(wr==0)BAR;
	s_waitcnt lgkmcnt(0)
	s_nop 0
	v_mfma_f32_16x16x32_bf16 v[72:75], v[0:3], v[12:15], v[124:127]
	v_mfma_f32_16x16x32_bf16 v[124:127], v[8:11], v[24:27], v[72:75]
	v_mfma_f32_16x16x32_bf16 v[72:75], v[202:205], v[12:15], v[120:123]
	v_mfma_f32_16x16x32_bf16 v[120:123], v[206:209], v[24:27], v[72:75]
	v_mfma_f32_16x16x32_bf16 v[72:75], v[0:3], v[28:31], v[116:119]
	v_mfma_f32_16x16x32_bf16 v[108:111], v[8:11], v[40:43], v[72:75]
	v_mfma_f32_16x16x32_bf16 v[72:75], v[202:205], v[28:31], v[112:115]
	v_mfma_f32_16x16x32_bf16 v[104:107], v[206:209], v[40:43], v[72:75]
	v_mfma_f32_16x16x32_bf16 v[72:75], v[0:3], v[44:47], v[138:141]
	v_mfma_f32_16x16x32_bf16 v[92:95], v[8:11], v[64:67], v[72:75]
	v_mfma_f32_16x16x32_bf16 v[72:75], v[202:205], v[44:47], v[218:221]
	v_mfma_f32_16x16x32_bf16 v[88:91], v[206:209], v[64:67], v[72:75]
	v_mfma_f32_16x16x32_bf16 v[72:75], v[0:3], v[210:213], v[100:103]
	v_mfma_f32_16x16x32_bf16 v[76:79], v[8:11], v[222:225], v[72:75]
	v_mfma_f32_16x16x32_bf16 v[72:75], v[202:205], v[210:213], v[96:99]
	v_mfma_f32_16x16x32_bf16 v[72:75], v[206:209], v[222:225], v[72:75]
	s_nop 0
	s_barrier
	ds_read_b128 v[138:141], v155
	ds_read_b128 v[218:221], v155 offset:1024
	ds_read_b128 v[234:237], v155 offset:2048
	ds_read_b128 v[154:157], v155 offset:3072
	s_waitcnt vmcnt(0)
	s_barrier
	s_waitcnt lgkmcnt(0)
	s_nop 0
	v_mfma_f32_16x16x32_bf16 v[96:99], v[138:141], v[12:15], v[226:229]
	v_mfma_f32_16x16x32_bf16 v[12:15], v[234:237], v[12:15], v[186:189]
	v_mfma_f32_16x16x32_bf16 v[116:119], v[154:157], v[24:27], v[12:15]
	v_mfma_f32_16x16x32_bf16 v[12:15], v[138:141], v[28:31], v[84:87]
	v_mfma_f32_16x16x32_bf16 v[112:115], v[218:221], v[24:27], v[96:99]
	v_mfma_f32_16x16x32_bf16 v[96:99], v[218:221], v[40:43], v[12:15]
	v_mfma_f32_16x16x32_bf16 v[12:15], v[234:237], v[28:31], v[80:83]
	v_mfma_f32_16x16x32_bf16 v[100:103], v[154:157], v[40:43], v[12:15]
	v_mfma_f32_16x16x32_bf16 v[12:15], v[138:141], v[44:47], v[190:193]
	v_mfma_f32_16x16x32_bf16 v[80:83], v[218:221], v[64:67], v[12:15]
	v_mfma_f32_16x16x32_bf16 v[12:15], v[234:237], v[44:47], v[194:197]
	v_mfma_f32_16x16x32_bf16 v[84:87], v[154:157], v[64:67], v[12:15]
	v_mfma_f32_16x16x32_bf16 v[12:15], v[138:141], v[210:213], v[68:71]
	v_mfma_f32_16x16x32_bf16 v[64:67], v[218:221], v[222:225], v[12:15]
	v_mfma_f32_16x16x32_bf16 v[12:15], v[234:237], v[210:213], v[198:201]
	v_mfma_f32_16x16x32_bf16 v[68:71], v[154:157], v[222:225], v[12:15]
	s_nop 0
	s_barrier
	ds_read_b128 v[186:189], v153 offset:49152
	ds_read_b128 v[190:193], v153 offset:50176
	ds_read_b128 v[194:197], v171 offset:49152
	ds_read_b128 v[198:201], v171 offset:50176
	ds_read_b128 v[210:213], v172 offset:49152
	ds_read_b128 v[222:225], v172 offset:50176
	ds_read_b128 v[226:229], v173 offset:49152
	ds_read_b128 v[172:175], v173 offset:50176
	s_barrier
	s_waitcnt lgkmcnt(0)
	s_nop 0
	v_mfma_f32_16x16x32_bf16 v[12:15], v[0:3], v[186:189], v[60:63]
	v_mfma_f32_16x16x32_bf16 v[60:63], v[8:11], v[190:193], v[12:15]
	v_mfma_f32_16x16x32_bf16 v[12:15], v[202:205], v[186:189], v[56:59]
	v_mfma_f32_16x16x32_bf16 v[56:59], v[206:209], v[190:193], v[12:15]
	v_mfma_f32_16x16x32_bf16 v[12:15], v[0:3], v[194:197], v[52:55]
	v_mfma_f32_16x16x32_bf16 v[44:47], v[8:11], v[198:201], v[12:15]
	v_mfma_f32_16x16x32_bf16 v[12:15], v[202:205], v[194:197], v[48:51]
	v_mfma_f32_16x16x32_bf16 v[40:43], v[206:209], v[198:201], v[12:15]
	v_mfma_f32_16x16x32_bf16 v[12:15], v[0:3], v[210:213], v[214:217]
	v_mfma_f32_16x16x32_bf16 v[28:31], v[8:11], v[222:225], v[12:15]
	v_mfma_f32_16x16x32_bf16 v[12:15], v[202:205], v[210:213], v[230:233]
	v_mfma_f32_16x16x32_bf16 v[0:3], v[0:3], v[226:229], v[36:39]
	v_mfma_f32_16x16x32_bf16 v[24:27], v[206:209], v[222:225], v[12:15]
	v_mfma_f32_16x16x32_bf16 v[12:15], v[8:11], v[172:175], v[0:3]
	v_mfma_f32_16x16x32_bf16 v[0:3], v[202:205], v[226:229], v[32:35]
	v_mfma_f32_16x16x32_bf16 v[8:11], v[206:209], v[172:175], v[0:3]
	s_nop 0
	s_nop 0
	v_mfma_f32_16x16x32_bf16 v[0:3], v[138:141], v[186:189], v[142:145]
	v_mfma_f32_16x16x32_bf16 v[48:51], v[218:221], v[190:193], v[0:3]
	v_mfma_f32_16x16x32_bf16 v[0:3], v[234:237], v[186:189], v[146:149]
	v_mfma_f32_16x16x32_bf16 v[52:55], v[154:157], v[190:193], v[0:3]
	v_mfma_f32_16x16x32_bf16 v[0:3], v[138:141], v[194:197], v[20:23]
	v_mfma_f32_16x16x32_bf16 v[32:35], v[218:221], v[198:201], v[0:3]
	v_mfma_f32_16x16x32_bf16 v[0:3], v[234:237], v[194:197], v[16:19]
	v_mfma_f32_16x16x32_bf16 v[36:39], v[154:157], v[198:201], v[0:3]
	v_mfma_f32_16x16x32_bf16 v[0:3], v[138:141], v[210:213], v[178:181]
	v_mfma_f32_16x16x32_bf16 v[16:19], v[218:221], v[222:225], v[0:3]
	v_mfma_f32_16x16x32_bf16 v[0:3], v[234:237], v[210:213], v[182:185]
	v_mfma_f32_16x16x32_bf16 v[20:23], v[154:157], v[222:225], v[0:3]
	v_mfma_f32_16x16x32_bf16 v[0:3], v[138:141], v[226:229], v[4:7]
	v_mfma_f32_16x16x32_bf16 v[4:7], v[234:237], v[226:229], v[158:161]
	v_mfma_f32_16x16x32_bf16 v[0:3], v[218:221], v[172:175], v[0:3]
	v_mfma_f32_16x16x32_bf16 v[4:7], v[154:157], v[172:175], v[4:7]
	s_setprio 0
	s_cmpk_gt_u32 s29, 0xff
	s_barrier
	s_cbranch_scc1 .LBB0_1874
	s_barrier

; #define WAIT_V(n) asm volatile("s_waitcnt vmcnt(" #n ")":::"memory")
; #define BAR __builtin_amdgcn_s_barrier()
; DEVINL void gemm8_mainloop(const u16* A, long lda, const u16* Bt, long ldb, int K, int brow, int bcol, f32x4 (&acc)[2][2][4][2], char* smem, int tid) {
;     ...
;   if(wr==1)BAR;
;   WAIT_V(4); BAR;
; DEVINL void compute_rs(const float* part, int m0, float* rs_s, int tid) {
;     ...
;   if (!half) rs_s[row] = rsqrtf(s * (1.f / 2048.f) + EPSN);
;   __syncthreads();
.LBB0_1935:
	s_or_b64 exec, exec, s[24:25]
	v_readfirstlane_b32 s37, v153
	s_ashr_i32 s38, s37, 8
	s_cmp_lg_u32 s38, 1
	s_waitcnt lgkmcnt(0)
	s_barrier
	s_cbranch_scc1 .LBB0_1937
	s_setprio 1
	s_barrier

; #define STAGE(P,BASE,LD,br,kt) do{long _g=(long)(br)*(LD)+(long)(kt)*BK; \
;     _Pragma("unroll") for(int _i=0;_i<2;++_i){int _b=tid*16+_i*8192;int _r,_c;stage_rc(_b,_r,_c); \
;       __builtin_amdgcn_global_load_lds((const unsigned*)((BASE)+_g+(long)_r*(LD)+_c), \
;         (unsigned*)((char*)(P)+_b),16,0,0);}}while(0)
; #define STAGE(P,BASE,LD,br,kt) do{long _g=(long)(br)*(LD)+(long)(kt)*BK; \
;     _Pragma("unroll") for(int _i=0;_i<2;++_i){int _b=tid*16+_i*8192;int _r,_c;stage_rc(_b,_r,_c); \
;       __builtin_amdgcn_global_load_lds((const unsigned*)((BASE)+_g+(long)_r*(LD)+_c), \
;         (unsigned*)((char*)(P)+_b),16,0,0);}}while(0)
; #define LDA(dst,b,h) _Pragma("unroll") for(int m=0;m<4;++m) _Pragma("unroll") for(int k=0;k<2;++k) \
;     dst[m][k]=*reinterpret_cast<const bf16x8*>((char*)SA(b,h)+lds_byte(wr*64+m*16+fr,k*32+fq*8))
; #define LDB(dst,b,h) _Pragma("unroll") for(int n=0;n<2;++n) _Pragma("unroll") for(int k=0;k<2;++k) \
;     dst[n][k]=*reinterpret_cast<const bf16x8*>((char*)SB(b,h)+lds_byte(wc*32+n*16+fr,k*32+fq*8))
; #define MMA(ai,bj,At_,Bt_) do{__builtin_amdgcn_s_setprio(1); \
;     _Pragma("unroll") for(int m=0;m<4;++m) _Pragma("unroll") for(int n=0;n<2;++n) _Pragma("unroll") for(int k=0;k<2;++k) \
;       acc[ai][bj][m][n]=__builtin_amdgcn_mfma_f32_16x16x32_bf16(Bt_[n][k],At_[m][k],acc[ai][bj][m][n],0,0,0); \
;     __builtin_amdgcn_s_setprio(0);}while(0)
; #define WAIT_L(n) asm volatile("s_waitcnt lgkmcnt(" #n ")":::"memory")
; #define BAR __builtin_amdgcn_s_barrier()
; #define SCHED __builtin_amdgcn_sched_barrier(0)
; DEVINL void gemm8_mainloop(const u16* A, long lda, const u16* Bt, long ldb, int K, int brow, int bcol, f32x4 (&acc)[2][2][4][2], char* smem, int tid) {
;     ...
;   for(int t=0;t<nt-2;t+=2){
;     LDB(B0,0,0); SCHED; LDA(At,0,0); STAGE(SA(1,1),A,lda,brow+HALF,t+1);
;     WAIT_L(8); BAR; WAIT_L(0); MMA(0,0,At,B0); BAR; SCHED;
;     LDB(B1,0,1); STAGE(SB(0,0),Bt,ldb,bcol,t+2);
;     BAR; WAIT_L(0); MMA(0,1,At,B1); BAR;
;     LDA(At,0,1); STAGE(SA(0,0),A,lda,brow,t+2);
;     BAR; WAIT_L(0); MMA(1,0,At,B0); BAR; SCHED;
.LBB0_1938:
	ds_read_b128 v[180:183], v165
	ds_read_b128 v[184:187], v165 offset:1024
	ds_read_b128 v[188:191], v165 offset:2048
	ds_read_b128 v[192:195], v165 offset:3072
	v_add_u32_e32 v177, 0xc000, v154
	v_lshl_add_u64 v[244:245], s[94:95], 0, v[146:147]
	v_readfirstlane_b32 s27, v177
	v_add_u32_e32 v178, 0xe000, v154
	v_add_u32_e32 v173, s23, v164
	v_add_u32_e32 v174, s38, v164
	v_add_u32_e32 v175, s39, v164
	v_lshl_add_u64 v[166:167], v[244:245], 0, s[2:3]
	s_mov_b32 m0, s27
	v_lshl_add_u64 v[246:247], s[94:95], 0, v[148:149]
	v_readfirstlane_b32 s27, v178
	ds_read_b128 v[168:171], v155
	ds_read_b128 v[196:199], v155 offset:1024
	ds_read_b128 v[200:203], v173
	ds_read_b128 v[204:207], v173 offset:1024
	ds_read_b128 v[208:211], v174
	ds_read_b128 v[212:215], v174 offset:1024
	ds_read_b128 v[216:219], v175
	ds_read_b128 v[220:223], v175 offset:1024
	global_load_lds_dwordx4 v[166:167], off
	v_lshl_add_u64 v[166:167], v[246:247], 0, s[2:3]
	s_mov_b32 m0, s27
	s_nop 0
	global_load_lds_dwordx4 v[166:167], off
	s_waitcnt lgkmcnt(8)
	s_barrier
	s_waitcnt lgkmcnt(0)
	s_nop 0
	v_mfma_f32_16x16x32_bf16 v[124:127], v[180:183], v[168:171], v[124:127]
	v_mfma_f32_16x16x32_bf16 v[120:123], v[188:191], v[168:171], v[120:123]
	v_mfma_f32_16x16x32_bf16 v[116:119], v[180:183], v[200:203], v[116:119]
	v_mfma_f32_16x16x32_bf16 v[112:115], v[188:191], v[200:203], v[112:115]
	v_mfma_f32_16x16x32_bf16 v[108:111], v[180:183], v[208:211], v[108:111]
	v_mfma_f32_16x16x32_bf16 v[104:107], v[188:191], v[208:211], v[104:107]
	v_mfma_f32_16x16x32_bf16 v[100:103], v[180:183], v[216:219], v[100:103]
	v_mfma_f32_16x16x32_bf16 v[96:99], v[188:191], v[216:219], v[96:99]
	v_mfma_f32_16x16x32_bf16 v[124:127], v[184:187], v[196:199], v[124:127]
	v_mfma_f32_16x16x32_bf16 v[120:123], v[192:195], v[196:199], v[120:123]
	v_mfma_f32_16x16x32_bf16 v[116:119], v[184:187], v[204:207], v[116:119]
	v_mfma_f32_16x16x32_bf16 v[112:115], v[192:195], v[204:207], v[112:115]
	v_mfma_f32_16x16x32_bf16 v[108:111], v[184:187], v[212:215], v[108:111]
	v_mfma_f32_16x16x32_bf16 v[104:107], v[192:195], v[212:215], v[104:107]
	v_mfma_f32_16x16x32_bf16 v[100:103], v[184:187], v[220:223], v[100:103]
	v_mfma_f32_16x16x32_bf16 v[96:99], v[192:195], v[220:223], v[96:99]
	s_nop 0
	s_barrier
	v_add_u32_e32 v166, s28, v157
	v_lshl_add_u64 v[248:249], s[94:95], 0, v[142:143]
	v_readfirstlane_b32 s27, v166
	v_add_u32_e32 v167, 0x2000, v166
	v_lshl_add_u64 v[240:241], v[248:249], 0, s[4:5]
	s_mov_b32 m0, s27
	v_lshl_add_u64 v[250:251], s[94:95], 0, v[144:145]
	v_readfirstlane_b32 s27, v167
	ds_read_b128 v[224:227], v161
	ds_read_b128 v[228:231], v161 offset:1024
	ds_read_b128 v[232:235], v161 offset:2048
	ds_read_b128 v[236:239], v161 offset:3072
	global_load_lds_dwordx4 v[240:241], off
	v_lshl_add_u64 v[240:241], v[250:251], 0, s[4:5]
	s_mov_b32 m0, s27
	s_nop 0
	global_load_lds_dwordx4 v[240:241], off
	s_barrier
	s_waitcnt lgkmcnt(0)
	s_nop 0
	v_mfma_f32_16x16x32_bf16 v[92:95], v[224:227], v[168:171], v[92:95]
	v_mfma_f32_16x16x32_bf16 v[88:91], v[232:235], v[168:171], v[88:91]
	v_mfma_f32_16x16x32_bf16 v[84:87], v[224:227], v[200:203], v[84:87]
	v_mfma_f32_16x16x32_bf16 v[80:83], v[232:235], v[200:203], v[80:83]
	v_mfma_f32_16x16x32_bf16 v[76:79], v[224:227], v[208:211], v[76:79]
	v_mfma_f32_16x16x32_bf16 v[72:75], v[232:235], v[208:211], v[72:75]
	v_mfma_f32_16x16x32_bf16 v[68:71], v[224:227], v[216:219], v[68:71]
	v_mfma_f32_16x16x32_bf16 v[64:67], v[232:235], v[216:219], v[64:67]
	v_mfma_f32_16x16x32_bf16 v[92:95], v[228:231], v[196:199], v[92:95]
	v_mfma_f32_16x16x32_bf16 v[88:91], v[236:239], v[196:199], v[88:91]
	v_mfma_f32_16x16x32_bf16 v[84:87], v[228:231], v[204:207], v[84:87]
	v_mfma_f32_16x16x32_bf16 v[80:83], v[236:239], v[204:207], v[80:83]
	v_mfma_f32_16x16x32_bf16 v[76:79], v[228:231], v[212:215], v[76:79]
	v_mfma_f32_16x16x32_bf16 v[72:75], v[236:239], v[212:215], v[72:75]
	v_mfma_f32_16x16x32_bf16 v[68:71], v[228:231], v[220:223], v[68:71]
	v_mfma_f32_16x16x32_bf16 v[64:67], v[236:239], v[220:223], v[64:67]
	s_nop 0
	v_readfirstlane_b32 s27, v154
	v_lshl_add_u64 v[168:169], v[244:245], 0, s[6:7]
	s_mov_b32 m0, s27
	s_barrier
	ds_read_b128 v[196:199], v155 offset:16384
	ds_read_b128 v[200:203], v155 offset:17408
	ds_read_b128 v[204:207], v173 offset:16384
	ds_read_b128 v[208:211], v173 offset:17408
	ds_read_b128 v[212:215], v174 offset:16384
	ds_read_b128 v[216:219], v174 offset:17408
	ds_read_b128 v[220:223], v175 offset:16384
	ds_read_b128 v[240:243], v175 offset:17408
	global_load_lds_dwordx4 v[168:169], off
	v_add_u32_e32 v168, 0x2000, v154
	v_lshl_add_u64 v[170:171], v[246:247], 0, s[6:7]
	v_readfirstlane_b32 s27, v168
	s_mov_b32 m0, s27
	s_nop 0
	global_load_lds_dwordx4 v[170:171], off
	s_barrier
	s_waitcnt lgkmcnt(0)
	s_nop 0
	v_mfma_f32_16x16x32_bf16 v[60:63], v[180:183], v[196:199], v[60:63]
	v_mfma_f32_16x16x32_bf16 v[56:59], v[188:191], v[196:199], v[56:59]
	v_mfma_f32_16x16x32_bf16 v[52:55], v[180:183], v[204:207], v[52:55]
	v_mfma_f32_16x16x32_bf16 v[48:51], v[188:191], v[204:207], v[48:51]
	v_mfma_f32_16x16x32_bf16 v[44:47], v[180:183], v[212:215], v[44:47]
	v_mfma_f32_16x16x32_bf16 v[40:43], v[188:191], v[212:215], v[40:43]
	v_mfma_f32_16x16x32_bf16 v[36:39], v[180:183], v[220:223], v[36:39]
	v_mfma_f32_16x16x32_bf16 v[32:35], v[188:191], v[220:223], v[32:35]
	v_mfma_f32_16x16x32_bf16 v[60:63], v[184:187], v[200:203], v[60:63]
	v_mfma_f32_16x16x32_bf16 v[56:59], v[192:195], v[200:203], v[56:59]
	v_mfma_f32_16x16x32_bf16 v[52:55], v[184:187], v[208:211], v[52:55]
	v_mfma_f32_16x16x32_bf16 v[48:51], v[192:195], v[208:211], v[48:51]
	v_mfma_f32_16x16x32_bf16 v[44:47], v[184:187], v[216:219], v[44:47]
	v_mfma_f32_16x16x32_bf16 v[40:43], v[192:195], v[216:219], v[40:43]
	v_mfma_f32_16x16x32_bf16 v[36:39], v[184:187], v[240:243], v[36:39]
	v_mfma_f32_16x16x32_bf16 v[32:35], v[192:195], v[240:243], v[32:35]
	s_nop 0
	s_barrier
; #define STAGE(P,BASE,LD,br,kt) do{long _g=(long)(br)*(LD)+(long)(kt)*BK; \
;     _Pragma("unroll") for(int _i=0;_i<2;++_i){int _b=tid*16+_i*8192;int _r,_c;stage_rc(_b,_r,_c); \
;       __builtin_amdgcn_global_load_lds((const unsigned*)((BASE)+_g+(long)_r*(LD)+_c), \
;         (unsigned*)((char*)(P)+_b),16,0,0);}}while(0)
; #define STAGE(P,BASE,LD,br,kt) do{long _g=(long)(br)*(LD)+(long)(kt)*BK; \
;     _Pragma("unroll") for(int _i=0;_i<2;++_i){int _b=tid*16+_i*8192;int _r,_c;stage_rc(_b,_r,_c); \
;       __builtin_amdgcn_global_load_lds((const unsigned*)((BASE)+_g+(long)_r*(LD)+_c), \
;         (unsigned*)((char*)(P)+_b),16,0,0);}}while(0)
; #define LDA(dst,b,h) _Pragma("unroll") for(int m=0;m<4;++m) _Pragma("unroll") for(int k=0;k<2;++k) \
;     dst[m][k]=*reinterpret_cast<const bf16x8*>((char*)SA(b,h)+lds_byte(wr*64+m*16+fr,k*32+fq*8))
; #define LDB(dst,b,h) _Pragma("unroll") for(int n=0;n<2;++n) _Pragma("unroll") for(int k=0;k<2;++k) \
;     dst[n][k]=*reinterpret_cast<const bf16x8*>((char*)SB(b,h)+lds_byte(wc*32+n*16+fr,k*32+fq*8))
; #define MMA(ai,bj,At_,Bt_) do{__builtin_amdgcn_s_setprio(1); \
;     _Pragma("unroll") for(int m=0;m<4;++m) _Pragma("unroll") for(int n=0;n<2;++n) _Pragma("unroll") for(int k=0;k<2;++k) \
;       acc[ai][bj][m][n]=__builtin_amdgcn_mfma_f32_16x16x32_bf16(Bt_[n][k],At_[m][k],acc[ai][bj][m][n],0,0,0); \
;     __builtin_amdgcn_s_setprio(0);}while(0)
; #define WAIT_V(n) asm volatile("s_waitcnt vmcnt(" #n ")":::"memory")
; #define WAIT_L(n) asm volatile("s_waitcnt lgkmcnt(" #n ")":::"memory")
; #define BAR __builtin_amdgcn_s_barrier()
; #define SCHED __builtin_amdgcn_sched_barrier(0)
; DEVINL void gemm8_mainloop(const u16* A, long lda, const u16* Bt, long ldb, int K, int brow, int bcol, f32x4 (&acc)[2][2][4][2], char* smem, int tid) {
;     ...
;     STAGE(SB(0,1),Bt,ldb,bcol+HALF,t+2);
;     WAIT_V(6); BAR; MMA(1,1,At,B1); BAR;
;     LDB(B0,1,0); SCHED; LDA(At,1,0); STAGE(SA(0,1),A,lda,brow+HALF,t+2);
;     WAIT_L(8); BAR; WAIT_L(0); MMA(0,0,At,B0); BAR; SCHED;
;     LDB(B1,1,1); STAGE(SB(1,0),Bt,ldb,bcol,t+3);
;     BAR; WAIT_L(0); MMA(0,1,At,B1); BAR;
	v_add_u32_e32 v169, s29, v157
	v_lshl_add_u64 v[170:171], v[248:249], 0, s[8:9]
	v_readfirstlane_b32 s27, v169
	s_mov_b32 m0, s27
	v_lshl_add_u64 v[180:181], v[250:251], 0, s[8:9]
	global_load_lds_dwordx4 v[170:171], off
	v_add_u32_e32 v170, 0x2000, v169
	s_nop 0
	v_readfirstlane_b32 s27, v170
	s_mov_b32 m0, s27
	s_nop 0
	global_load_lds_dwordx4 v[180:181], off
	s_waitcnt vmcnt(6)
	s_barrier
	s_nop 0
	v_mfma_f32_16x16x32_bf16 v[28:31], v[224:227], v[196:199], v[28:31]
	v_mfma_f32_16x16x32_bf16 v[24:27], v[232:235], v[196:199], v[24:27]
	v_mfma_f32_16x16x32_bf16 v[20:23], v[224:227], v[204:207], v[20:23]
	v_mfma_f32_16x16x32_bf16 v[16:19], v[232:235], v[204:207], v[16:19]
	v_mfma_f32_16x16x32_bf16 v[12:15], v[224:227], v[212:215], v[12:15]
	v_mfma_f32_16x16x32_bf16 v[8:11], v[232:235], v[212:215], v[8:11]
	v_mfma_f32_16x16x32_bf16 v[4:7], v[224:227], v[220:223], v[4:7]
	v_mfma_f32_16x16x32_bf16 v[0:3], v[232:235], v[220:223], v[0:3]
	v_mfma_f32_16x16x32_bf16 v[28:31], v[228:231], v[200:203], v[28:31]
	v_mfma_f32_16x16x32_bf16 v[24:27], v[236:239], v[200:203], v[24:27]
	v_mfma_f32_16x16x32_bf16 v[20:23], v[228:231], v[208:211], v[20:23]
	v_mfma_f32_16x16x32_bf16 v[16:19], v[236:239], v[208:211], v[16:19]
	v_mfma_f32_16x16x32_bf16 v[12:15], v[228:231], v[216:219], v[12:15]
	v_mfma_f32_16x16x32_bf16 v[8:11], v[236:239], v[216:219], v[8:11]
	v_mfma_f32_16x16x32_bf16 v[4:7], v[228:231], v[240:243], v[4:7]
	v_mfma_f32_16x16x32_bf16 v[0:3], v[236:239], v[240:243], v[0:3]
	s_nop 0
	s_barrier
	ds_read_b128 v[180:183], v158
	ds_read_b128 v[184:187], v158 offset:1024
	ds_read_b128 v[188:191], v158 offset:2048
	ds_read_b128 v[192:195], v158 offset:3072
	v_add_u32_e32 v171, 0x4000, v154
	v_add_u32_e32 v172, 0x6000, v154
	v_readfirstlane_b32 s27, v171
	v_lshl_add_u64 v[228:229], v[244:245], 0, s[10:11]
	s_mov_b32 m0, s27
	v_readfirstlane_b32 s27, v172
	ds_read_b128 v[196:199], v155 offset:32768
	ds_read_b128 v[200:203], v155 offset:33792
	ds_read_b128 v[204:207], v173 offset:32768
	ds_read_b128 v[208:211], v173 offset:33792
	ds_read_b128 v[212:215], v174 offset:32768
	ds_read_b128 v[216:219], v174 offset:33792
	ds_read_b128 v[220:223], v175 offset:32768
	ds_read_b128 v[224:227], v175 offset:33792
	global_load_lds_dwordx4 v[228:229], off
	v_lshl_add_u64 v[228:229], v[246:247], 0, s[10:11]
	s_mov_b32 m0, s27
	s_nop 0
	global_load_lds_dwordx4 v[228:229], off
	s_waitcnt lgkmcnt(8)
	s_barrier
	s_waitcnt lgkmcnt(0)
	s_nop 0
	v_mfma_f32_16x16x32_bf16 v[124:127], v[180:183], v[196:199], v[124:127]
	v_mfma_f32_16x16x32_bf16 v[120:123], v[188:191], v[196:199], v[120:123]
	v_mfma_f32_16x16x32_bf16 v[116:119], v[180:183], v[204:207], v[116:119]
	v_mfma_f32_16x16x32_bf16 v[112:115], v[188:191], v[204:207], v[112:115]
	v_mfma_f32_16x16x32_bf16 v[108:111], v[180:183], v[212:215], v[108:111]
	v_mfma_f32_16x16x32_bf16 v[104:107], v[188:191], v[212:215], v[104:107]
	v_mfma_f32_16x16x32_bf16 v[100:103], v[180:183], v[220:223], v[100:103]
	v_mfma_f32_16x16x32_bf16 v[96:99], v[188:191], v[220:223], v[96:99]
	v_mfma_f32_16x16x32_bf16 v[124:127], v[184:187], v[200:203], v[124:127]
	v_mfma_f32_16x16x32_bf16 v[120:123], v[192:195], v[200:203], v[120:123]
	v_mfma_f32_16x16x32_bf16 v[116:119], v[184:187], v[208:211], v[116:119]
	v_mfma_f32_16x16x32_bf16 v[112:115], v[192:195], v[208:211], v[112:115]
	v_mfma_f32_16x16x32_bf16 v[108:111], v[184:187], v[216:219], v[108:111]
	v_mfma_f32_16x16x32_bf16 v[104:107], v[192:195], v[216:219], v[104:107]
	v_mfma_f32_16x16x32_bf16 v[100:103], v[184:187], v[224:227], v[100:103]
	v_mfma_f32_16x16x32_bf16 v[96:99], v[192:195], v[224:227], v[96:99]
	s_nop 0
	s_barrier
	v_readfirstlane_b32 s27, v159
	v_add_u32_e32 v179, 0x2000, v159
	v_lshl_add_u64 v[252:253], v[248:249], 0, s[12:13]
	s_mov_b32 m0, s27
	v_readfirstlane_b32 s27, v179
	ds_read_b128 v[228:231], v156
	ds_read_b128 v[232:235], v156 offset:1024
	ds_read_b128 v[236:239], v156 offset:2048
	ds_read_b128 v[240:243], v156 offset:3072
	global_load_lds_dwordx4 v[252:253], off
	v_lshl_add_u64 v[252:253], v[250:251], 0, s[12:13]
	s_mov_b32 m0, s27
	s_nop 0
	global_load_lds_dwordx4 v[252:253], off
	s_barrier
	s_waitcnt lgkmcnt(0)
	s_nop 0
	v_mfma_f32_16x16x32_bf16 v[92:95], v[228:231], v[196:199], v[92:95]
	v_mfma_f32_16x16x32_bf16 v[88:91], v[236:239], v[196:199], v[88:91]
	v_mfma_f32_16x16x32_bf16 v[84:87], v[228:231], v[204:207], v[84:87]
	v_mfma_f32_16x16x32_bf16 v[80:83], v[236:239], v[204:207], v[80:83]
	v_mfma_f32_16x16x32_bf16 v[76:79], v[228:231], v[212:215], v[76:79]
	v_mfma_f32_16x16x32_bf16 v[72:75], v[236:239], v[212:215], v[72:75]
	v_mfma_f32_16x16x32_bf16 v[68:71], v[228:231], v[220:223], v[68:71]
	v_mfma_f32_16x16x32_bf16 v[64:67], v[236:239], v[220:223], v[64:67]
	v_mfma_f32_16x16x32_bf16 v[92:95], v[232:235], v[200:203], v[92:95]
	v_mfma_f32_16x16x32_bf16 v[88:91], v[240:243], v[200:203], v[88:91]
	v_mfma_f32_16x16x32_bf16 v[84:87], v[232:235], v[208:211], v[84:87]
	v_mfma_f32_16x16x32_bf16 v[80:83], v[240:243], v[208:211], v[80:83]
	v_mfma_f32_16x16x32_bf16 v[76:79], v[232:235], v[216:219], v[76:79]
	v_mfma_f32_16x16x32_bf16 v[72:75], v[240:243], v[216:219], v[72:75]
	v_mfma_f32_16x16x32_bf16 v[68:71], v[232:235], v[224:227], v[68:71]
	v_mfma_f32_16x16x32_bf16 v[64:67], v[240:243], v[224:227], v[64:67]
	s_nop 0
	v_readfirstlane_b32 s27, v160
	v_lshl_add_u64 v[244:245], v[244:245], 0, s[14:15]
	s_mov_b32 m0, s27
	v_readfirstlane_b32 s27, v162
	s_barrier
; #define STAGE(P,BASE,LD,br,kt) do{long _g=(long)(br)*(LD)+(long)(kt)*BK; \
;     _Pragma("unroll") for(int _i=0;_i<2;++_i){int _b=tid*16+_i*8192;int _r,_c;stage_rc(_b,_r,_c); \
;       __builtin_amdgcn_global_load_lds((const unsigned*)((BASE)+_g+(long)_r*(LD)+_c), \
;         (unsigned*)((char*)(P)+_b),16,0,0);}}while(0)
; #define STAGE(P,BASE,LD,br,kt) do{long _g=(long)(br)*(LD)+(long)(kt)*BK; \
;     _Pragma("unroll") for(int _i=0;_i<2;++_i){int _b=tid*16+_i*8192;int _r,_c;stage_rc(_b,_r,_c); \
;       __builtin_amdgcn_global_load_lds((const unsigned*)((BASE)+_g+(long)_r*(LD)+_c), \
;         (unsigned*)((char*)(P)+_b),16,0,0);}}while(0)
; #define LDA(dst,b,h) _Pragma("unroll") for(int m=0;m<4;++m) _Pragma("unroll") for(int k=0;k<2;++k) \
;     dst[m][k]=*reinterpret_cast<const bf16x8*>((char*)SA(b,h)+lds_byte(wr*64+m*16+fr,k*32+fq*8))
; #define LDB(dst,b,h) _Pragma("unroll") for(int n=0;n<2;++n) _Pragma("unroll") for(int k=0;k<2;++k) \
;     dst[n][k]=*reinterpret_cast<const bf16x8*>((char*)SB(b,h)+lds_byte(wc*32+n*16+fr,k*32+fq*8))
; #define MMA(ai,bj,At_,Bt_) do{__builtin_amdgcn_s_setprio(1); \
;     _Pragma("unroll") for(int m=0;m<4;++m) _Pragma("unroll") for(int n=0;n<2;++n) _Pragma("unroll") for(int k=0;k<2;++k) \
;       acc[ai][bj][m][n]=__builtin_amdgcn_mfma_f32_16x16x32_bf16(Bt_[n][k],At_[m][k],acc[ai][bj][m][n],0,0,0); \
;     __builtin_amdgcn_s_setprio(0);}while(0)
; #define WAIT_V(n) asm volatile("s_waitcnt vmcnt(" #n ")":::"memory")
; #define WAIT_L(n) asm volatile("s_waitcnt lgkmcnt(" #n ")":::"memory")
; #define BAR __builtin_amdgcn_s_barrier()
; #define SCHED __builtin_amdgcn_sched_barrier(0)
; DEVINL void gemm8_mainloop(const u16* A, long lda, const u16* Bt, long ldb, int K, int brow, int bcol, f32x4 (&acc)[2][2][4][2], char* smem, int tid) {
;     ...
;     LDA(At,1,1); STAGE(SA(1,0),A,lda,brow,t+3);
;     BAR; WAIT_L(0); MMA(1,0,At,B0); BAR; SCHED;
;     STAGE(SB(1,1),Bt,ldb,bcol+HALF,t+3);
;     WAIT_V(6); BAR; MMA(1,1,At,B1); BAR;
;   }
;   { LDB(B0,0,0); LDA(At,0,0); STAGE(SA(1,1),A,lda,brow+HALF,nt-1);
;     BAR; WAIT_L(0); MMA(0,0,At,B0); BAR;
	ds_read_b128 v[196:199], v155 offset:49152
	ds_read_b128 v[200:203], v155 offset:50176
	ds_read_b128 v[204:207], v173 offset:49152
	ds_read_b128 v[208:211], v173 offset:50176
	ds_read_b128 v[212:215], v174 offset:49152
	ds_read_b128 v[216:219], v174 offset:50176
	ds_read_b128 v[220:223], v175 offset:49152
	ds_read_b128 v[224:227], v175 offset:50176
	global_load_lds_dwordx4 v[244:245], off
	v_lshl_add_u64 v[244:245], v[246:247], 0, s[14:15]
	s_mov_b32 m0, s27
	s_nop 0
	global_load_lds_dwordx4 v[244:245], off
	s_barrier
	s_waitcnt lgkmcnt(0)
	s_nop 0
	v_mfma_f32_16x16x32_bf16 v[60:63], v[180:183], v[196:199], v[60:63]
	v_mfma_f32_16x16x32_bf16 v[56:59], v[188:191], v[196:199], v[56:59]
	v_mfma_f32_16x16x32_bf16 v[52:55], v[180:183], v[204:207], v[52:55]
	v_mfma_f32_16x16x32_bf16 v[48:51], v[188:191], v[204:207], v[48:51]
	v_mfma_f32_16x16x32_bf16 v[44:47], v[180:183], v[212:215], v[44:47]
	v_mfma_f32_16x16x32_bf16 v[40:43], v[188:191], v[212:215], v[40:43]
	v_mfma_f32_16x16x32_bf16 v[36:39], v[180:183], v[220:223], v[36:39]
	v_mfma_f32_16x16x32_bf16 v[32:35], v[188:191], v[220:223], v[32:35]
	v_mfma_f32_16x16x32_bf16 v[60:63], v[184:187], v[200:203], v[60:63]
	v_mfma_f32_16x16x32_bf16 v[56:59], v[192:195], v[200:203], v[56:59]
	v_mfma_f32_16x16x32_bf16 v[52:55], v[184:187], v[208:211], v[52:55]
	v_mfma_f32_16x16x32_bf16 v[48:51], v[192:195], v[208:211], v[48:51]
	v_mfma_f32_16x16x32_bf16 v[44:47], v[184:187], v[216:219], v[44:47]
	v_mfma_f32_16x16x32_bf16 v[40:43], v[192:195], v[216:219], v[40:43]
	v_mfma_f32_16x16x32_bf16 v[36:39], v[184:187], v[224:227], v[36:39]
	v_mfma_f32_16x16x32_bf16 v[32:35], v[192:195], v[224:227], v[32:35]
	s_nop 0
	s_barrier
	v_readfirstlane_b32 s27, v163
	v_add_u32_e32 v179, 0x2000, v163
	v_lshl_add_u64 v[180:181], v[248:249], 0, s[16:17]
	s_mov_b32 m0, s27
	v_readfirstlane_b32 s27, v179
	global_load_lds_dwordx4 v[180:181], off
	v_lshl_add_u64 v[180:181], v[250:251], 0, s[16:17]
	s_mov_b32 m0, s27
	s_nop 0
	global_load_lds_dwordx4 v[180:181], off
	s_waitcnt vmcnt(6)
	s_barrier
	s_nop 0
	v_mfma_f32_16x16x32_bf16 v[28:31], v[228:231], v[196:199], v[28:31]
	v_mfma_f32_16x16x32_bf16 v[24:27], v[236:239], v[196:199], v[24:27]
	v_mfma_f32_16x16x32_bf16 v[20:23], v[228:231], v[204:207], v[20:23]
	v_mfma_f32_16x16x32_bf16 v[16:19], v[236:239], v[204:207], v[16:19]
	v_mfma_f32_16x16x32_bf16 v[12:15], v[228:231], v[212:215], v[12:15]
	v_mfma_f32_16x16x32_bf16 v[8:11], v[236:239], v[212:215], v[8:11]
	v_mfma_f32_16x16x32_bf16 v[4:7], v[228:231], v[220:223], v[4:7]
	v_mfma_f32_16x16x32_bf16 v[0:3], v[236:239], v[220:223], v[0:3]
	v_mfma_f32_16x16x32_bf16 v[28:31], v[232:235], v[200:203], v[28:31]
	v_mfma_f32_16x16x32_bf16 v[24:27], v[240:243], v[200:203], v[24:27]
	v_mfma_f32_16x16x32_bf16 v[20:23], v[232:235], v[208:211], v[20:23]
	v_mfma_f32_16x16x32_bf16 v[16:19], v[240:243], v[208:211], v[16:19]
	v_mfma_f32_16x16x32_bf16 v[12:15], v[232:235], v[216:219], v[12:15]
	v_mfma_f32_16x16x32_bf16 v[8:11], v[240:243], v[216:219], v[8:11]
	v_mfma_f32_16x16x32_bf16 v[4:7], v[232:235], v[224:227], v[4:7]
	v_mfma_f32_16x16x32_bf16 v[0:3], v[240:243], v[224:227], v[0:3]
	s_nop 0
	s_add_i32 s26, s26, 2
	v_lshl_add_u64 v[142:143], v[142:143], 0, s[18:19]
	v_lshl_add_u64 v[144:145], v[144:145], 0, s[18:19]
	v_lshl_add_u64 v[146:147], v[146:147], 0, s[18:19]
	s_cmp_lt_u32 s26, 28
	v_lshl_add_u64 v[148:149], v[148:149], 0, s[18:19]
	s_barrier
	s_cbranch_scc1 .LBB0_1938
	s_or_b32 s26, s22, 0x80
	s_ashr_i32 s27, s26, 31
	s_lshl_b64 s[26:27], s[26:27], 12
	s_add_u32 s26, s90, s26
	s_addc_u32 s27, s91, s27
	v_lshl_add_u64 v[216:217], v[134:135], 1, s[26:27]
	v_lshl_add_u64 v[138:139], v[138:139], 1, v[216:217]
	v_readfirstlane_b32 s23, v177
	v_lshl_add_u64 v[138:139], v[138:139], 0, s[20:21]
	s_mov_b32 m0, s23
	ds_read_b128 v[142:145], v165
	ds_read_b128 v[146:149], v165 offset:1024
	ds_read_b128 v[180:183], v165 offset:2048
	ds_read_b128 v[162:165], v165 offset:3072
	ds_read_b128 v[184:187], v155
	ds_read_b128 v[188:191], v155 offset:1024
	ds_read_b128 v[192:195], v173
	ds_read_b128 v[196:199], v173 offset:1024
	ds_read_b128 v[200:203], v174
	ds_read_b128 v[204:207], v174 offset:1024
	ds_read_b128 v[208:211], v175
	ds_read_b128 v[212:215], v175 offset:1024
	global_load_lds_dwordx4 v[138:139], off
	v_lshl_add_u64 v[138:139], v[136:137], 1, s[26:27]
	v_lshl_add_u64 v[138:139], v[140:141], 1, v[138:139]
	v_readfirstlane_b32 s23, v178
	v_lshl_add_u64 v[138:139], v[138:139], 0, s[20:21]
	s_mov_b32 m0, s23
	s_nop 0
	global_load_lds_dwordx4 v[138:139], off
	s_barrier
	s_waitcnt lgkmcnt(0)
	s_nop 0
	v_mfma_f32_16x16x32_bf16 v[124:127], v[142:145], v[184:187], v[124:127]
	v_mfma_f32_16x16x32_bf16 v[120:123], v[180:183], v[184:187], v[120:123]
	v_mfma_f32_16x16x32_bf16 v[116:119], v[142:145], v[192:195], v[116:119]
	v_mfma_f32_16x16x32_bf16 v[112:115], v[180:183], v[192:195], v[112:115]
	v_mfma_f32_16x16x32_bf16 v[104:107], v[180:183], v[200:203], v[104:107]
	v_mfma_f32_16x16x32_bf16 v[96:99], v[180:183], v[208:211], v[96:99]
	v_mfma_f32_16x16x32_bf16 v[124:127], v[146:149], v[188:191], v[124:127]
	v_mfma_f32_16x16x32_bf16 v[120:123], v[162:165], v[188:191], v[120:123]
	v_mfma_f32_16x16x32_bf16 v[116:119], v[146:149], v[196:199], v[116:119]
	v_mfma_f32_16x16x32_bf16 v[112:115], v[162:165], v[196:199], v[112:115]
	v_mfma_f32_16x16x32_bf16 v[108:111], v[142:145], v[200:203], v[108:111]
	v_mfma_f32_16x16x32_bf16 v[104:107], v[162:165], v[204:207], v[104:107]
	v_mfma_f32_16x16x32_bf16 v[100:103], v[142:145], v[208:211], v[100:103]
	v_mfma_f32_16x16x32_bf16 v[96:99], v[162:165], v[212:215], v[96:99]
	v_mfma_f32_16x16x32_bf16 v[138:141], v[146:149], v[204:207], v[108:111]
	v_mfma_f32_16x16x32_bf16 v[216:219], v[146:149], v[212:215], v[100:103]
	s_nop 0
	s_barrier
; #define LDA(dst,b,h) _Pragma("unroll") for(int m=0;m<4;++m) _Pragma("unroll") for(int k=0;k<2;++k) \
;     dst[m][k]=*reinterpret_cast<const bf16x8*>((char*)SA(b,h)+lds_byte(wr*64+m*16+fr,k*32+fq*8))
; #define LDB(dst,b,h) _Pragma("unroll") for(int n=0;n<2;++n) _Pragma("unroll") for(int k=0;k<2;++k) \
;     dst[n][k]=*reinterpret_cast<const bf16x8*>((char*)SB(b,h)+lds_byte(wc*32+n*16+fr,k*32+fq*8))
; #define MMA(ai,bj,At_,Bt_) do{__builtin_amdgcn_s_setprio(1); \
;     _Pragma("unroll") for(int m=0;m<4;++m) _Pragma("unroll") for(int n=0;n<2;++n) _Pragma("unroll") for(int k=0;k<2;++k) \
;       acc[ai][bj][m][n]=__builtin_amdgcn_mfma_f32_16x16x32_bf16(Bt_[n][k],At_[m][k],acc[ai][bj][m][n],0,0,0); \
;     __builtin_amdgcn_s_setprio(0);}while(0)
; #define WAIT_V(n) asm volatile("s_waitcnt vmcnt(" #n ")":::"memory")
; #define WAIT_L(n) asm volatile("s_waitcnt lgkmcnt(" #n ")":::"memory")
; #define BAR __builtin_amdgcn_s_barrier()
; DEVINL void gemm8_mainloop(const u16* A, long lda, const u16* Bt, long ldb, int K, int brow, int bcol, f32x4 (&acc)[2][2][4][2], char* smem, int tid) {
;     ...
;     LDB(B1,0,1); BAR; WAIT_L(0); MMA(0,1,At,B1); BAR;
;     LDA(At,0,1); WAIT_V(4); BAR; WAIT_L(0); MMA(1,0,At,B0); MMA(1,1,At,B1); BAR; }
;   { LDB(B0,1,0); LDA(At,1,0); WAIT_V(2); BAR; WAIT_L(0); MMA(0,0,At,B0); BAR;
	s_nop 2
	ds_read_b128 v[100:103], v161
	ds_read_b128 v[108:111], v161 offset:1024
	ds_read_b128 v[220:223], v161 offset:2048
	ds_read_b128 v[224:227], v161 offset:3072
	s_barrier
	s_waitcnt lgkmcnt(0)
	s_nop 0
	v_mfma_f32_16x16x32_bf16 v[88:91], v[220:223], v[184:187], v[88:91]
	v_mfma_f32_16x16x32_bf16 v[80:83], v[220:223], v[192:195], v[80:83]
	v_mfma_f32_16x16x32_bf16 v[72:75], v[220:223], v[200:203], v[72:75]
	v_mfma_f32_16x16x32_bf16 v[64:67], v[220:223], v[208:211], v[64:67]
	v_mfma_f32_16x16x32_bf16 v[92:95], v[100:103], v[184:187], v[92:95]
	v_mfma_f32_16x16x32_bf16 v[88:91], v[224:227], v[188:191], v[88:91]
	v_mfma_f32_16x16x32_bf16 v[84:87], v[100:103], v[192:195], v[84:87]
	v_mfma_f32_16x16x32_bf16 v[80:83], v[224:227], v[196:199], v[80:83]
	v_mfma_f32_16x16x32_bf16 v[76:79], v[100:103], v[200:203], v[76:79]
	v_mfma_f32_16x16x32_bf16 v[72:75], v[224:227], v[204:207], v[72:75]
	v_mfma_f32_16x16x32_bf16 v[68:71], v[100:103], v[208:211], v[68:71]
	v_mfma_f32_16x16x32_bf16 v[64:67], v[224:227], v[212:215], v[64:67]
	v_mfma_f32_16x16x32_bf16 v[228:231], v[108:111], v[188:191], v[92:95]
	v_mfma_f32_16x16x32_bf16 v[184:187], v[108:111], v[196:199], v[84:87]
	v_mfma_f32_16x16x32_bf16 v[188:191], v[108:111], v[204:207], v[76:79]
	v_mfma_f32_16x16x32_bf16 v[192:195], v[108:111], v[212:215], v[68:71]
	s_nop 0
	s_barrier
	s_nop 0
	ds_read_b128 v[68:71], v155 offset:16384
	ds_read_b128 v[76:79], v155 offset:17408
	ds_read_b128 v[84:87], v173 offset:16384
	ds_read_b128 v[92:95], v173 offset:17408
	ds_read_b128 v[196:199], v174 offset:16384
	ds_read_b128 v[200:203], v174 offset:17408
	ds_read_b128 v[204:207], v175 offset:16384
	ds_read_b128 v[208:211], v175 offset:17408
	s_waitcnt vmcnt(4)
	s_barrier
	s_waitcnt lgkmcnt(0)
	s_nop 0
	v_mfma_f32_16x16x32_bf16 v[60:63], v[142:145], v[68:71], v[60:63]
	v_mfma_f32_16x16x32_bf16 v[56:59], v[180:183], v[68:71], v[56:59]
	v_mfma_f32_16x16x32_bf16 v[48:51], v[180:183], v[84:87], v[48:51]
	v_mfma_f32_16x16x32_bf16 v[40:43], v[180:183], v[196:199], v[40:43]
	v_mfma_f32_16x16x32_bf16 v[32:35], v[180:183], v[204:207], v[32:35]
	v_mfma_f32_16x16x32_bf16 v[60:63], v[146:149], v[76:79], v[60:63]
	v_mfma_f32_16x16x32_bf16 v[56:59], v[162:165], v[76:79], v[56:59]
	v_mfma_f32_16x16x32_bf16 v[52:55], v[142:145], v[84:87], v[52:55]
	v_mfma_f32_16x16x32_bf16 v[48:51], v[162:165], v[92:95], v[48:51]
	v_mfma_f32_16x16x32_bf16 v[44:47], v[142:145], v[196:199], v[44:47]
	v_mfma_f32_16x16x32_bf16 v[40:43], v[162:165], v[200:203], v[40:43]
	v_mfma_f32_16x16x32_bf16 v[36:39], v[142:145], v[204:207], v[36:39]
	v_mfma_f32_16x16x32_bf16 v[32:35], v[162:165], v[208:211], v[32:35]
	v_mfma_f32_16x16x32_bf16 v[212:215], v[146:149], v[92:95], v[52:55]
	v_mfma_f32_16x16x32_bf16 v[232:235], v[146:149], v[200:203], v[44:47]
	v_mfma_f32_16x16x32_bf16 v[142:145], v[146:149], v[208:211], v[36:39]
	s_nop 0
	s_nop 0
	v_mfma_f32_16x16x32_bf16 v[24:27], v[220:223], v[68:71], v[24:27]
	v_mfma_f32_16x16x32_bf16 v[16:19], v[220:223], v[84:87], v[16:19]
	v_mfma_f32_16x16x32_bf16 v[4:7], v[100:103], v[204:207], v[4:7]
	v_mfma_f32_16x16x32_bf16 v[0:3], v[220:223], v[204:207], v[0:3]
	v_mfma_f32_16x16x32_bf16 v[28:31], v[100:103], v[68:71], v[28:31]
	v_mfma_f32_16x16x32_bf16 v[24:27], v[224:227], v[76:79], v[24:27]
	v_mfma_f32_16x16x32_bf16 v[20:23], v[100:103], v[84:87], v[20:23]
	v_mfma_f32_16x16x32_bf16 v[16:19], v[224:227], v[92:95], v[16:19]
	v_mfma_f32_16x16x32_bf16 v[12:15], v[100:103], v[196:199], v[12:15]
	v_mfma_f32_16x16x32_bf16 v[8:11], v[220:223], v[196:199], v[8:11]
	v_mfma_f32_16x16x32_bf16 v[4:7], v[108:111], v[208:211], v[4:7]
	v_mfma_f32_16x16x32_bf16 v[0:3], v[224:227], v[208:211], v[0:3]
	v_mfma_f32_16x16x32_bf16 v[146:149], v[108:111], v[76:79], v[28:31]
	v_mfma_f32_16x16x32_bf16 v[160:163], v[108:111], v[92:95], v[20:23]
	v_mfma_f32_16x16x32_bf16 v[178:181], v[108:111], v[200:203], v[12:15]
	v_mfma_f32_16x16x32_bf16 v[196:199], v[224:227], v[200:203], v[8:11]
	s_nop 0
	s_barrier
	s_nop 0
	ds_read_b128 v[8:11], v158
	ds_read_b128 v[12:15], v158 offset:1024
	ds_read_b128 v[200:203], v158 offset:2048
	ds_read_b128 v[204:207], v158 offset:3072
	ds_read_b128 v[20:23], v155 offset:32768
	ds_read_b128 v[28:31], v155 offset:33792
	ds_read_b128 v[36:39], v173 offset:32768
	ds_read_b128 v[44:47], v173 offset:33792
	ds_read_b128 v[52:55], v174 offset:32768
	ds_read_b128 v[208:211], v174 offset:33792
	ds_read_b128 v[220:223], v175 offset:32768
	ds_read_b128 v[224:227], v175 offset:33792
	s_waitcnt vmcnt(2)
	s_barrier
; #define LDA(dst,b,h) _Pragma("unroll") for(int m=0;m<4;++m) _Pragma("unroll") for(int k=0;k<2;++k) \
;     dst[m][k]=*reinterpret_cast<const bf16x8*>((char*)SA(b,h)+lds_byte(wr*64+m*16+fr,k*32+fq*8))
; #define LDB(dst,b,h) _Pragma("unroll") for(int n=0;n<2;++n) _Pragma("unroll") for(int k=0;k<2;++k) \
;     dst[n][k]=*reinterpret_cast<const bf16x8*>((char*)SB(b,h)+lds_byte(wc*32+n*16+fr,k*32+fq*8))
; #define MMA(ai,bj,At_,Bt_) do{__builtin_amdgcn_s_setprio(1); \
;     _Pragma("unroll") for(int m=0;m<4;++m) _Pragma("unroll") for(int n=0;n<2;++n) _Pragma("unroll") for(int k=0;k<2;++k) \
;       acc[ai][bj][m][n]=__builtin_amdgcn_mfma_f32_16x16x32_bf16(Bt_[n][k],At_[m][k],acc[ai][bj][m][n],0,0,0); \
;     __builtin_amdgcn_s_setprio(0);}while(0)
; #define WAIT_V(n) asm volatile("s_waitcnt vmcnt(" #n ")":::"memory")
; #define WAIT_L(n) asm volatile("s_waitcnt lgkmcnt(" #n ")":::"memory")
; #define BAR __builtin_amdgcn_s_barrier()
; DEVINL void gemm8_mainloop(const u16* A, long lda, const u16* Bt, long ldb, int K, int brow, int bcol, f32x4 (&acc)[2][2][4][2], char* smem, int tid) {
;     ...
;   { LDB(B0,1,0); LDA(At,1,0); WAIT_V(2); BAR; WAIT_L(0); MMA(0,0,At,B0); BAR;
;     LDB(B1,1,1); WAIT_V(0); BAR; WAIT_L(0); MMA(0,1,At,B1); BAR;
;     LDA(At,1,1); BAR; WAIT_L(0); MMA(1,0,At,B0); MMA(1,1,At,B1); BAR; }
;   if(wr==0)BAR;
	s_waitcnt lgkmcnt(0)
	s_nop 0
	v_mfma_f32_16x16x32_bf16 v[68:71], v[8:11], v[20:23], v[124:127]
	v_mfma_f32_16x16x32_bf16 v[124:127], v[12:15], v[28:31], v[68:71]
	v_mfma_f32_16x16x32_bf16 v[68:71], v[200:203], v[20:23], v[120:123]
	v_mfma_f32_16x16x32_bf16 v[120:123], v[204:207], v[28:31], v[68:71]
	v_mfma_f32_16x16x32_bf16 v[68:71], v[8:11], v[36:39], v[116:119]
	v_mfma_f32_16x16x32_bf16 v[108:111], v[12:15], v[44:47], v[68:71]
	v_mfma_f32_16x16x32_bf16 v[68:71], v[200:203], v[36:39], v[112:115]
	v_mfma_f32_16x16x32_bf16 v[100:103], v[204:207], v[44:47], v[68:71]
	v_mfma_f32_16x16x32_bf16 v[68:71], v[8:11], v[52:55], v[138:141]
	v_mfma_f32_16x16x32_bf16 v[92:95], v[12:15], v[208:211], v[68:71]
	v_mfma_f32_16x16x32_bf16 v[68:71], v[200:203], v[52:55], v[104:107]
	v_mfma_f32_16x16x32_bf16 v[84:87], v[204:207], v[208:211], v[68:71]
	v_mfma_f32_16x16x32_bf16 v[68:71], v[8:11], v[220:223], v[216:219]
	v_mfma_f32_16x16x32_bf16 v[76:79], v[12:15], v[224:227], v[68:71]
	v_mfma_f32_16x16x32_bf16 v[68:71], v[200:203], v[220:223], v[96:99]
	v_mfma_f32_16x16x32_bf16 v[68:71], v[204:207], v[224:227], v[68:71]
	s_nop 0
	s_barrier
	ds_read_b128 v[138:141], v156
	ds_read_b128 v[216:219], v156 offset:1024
	ds_read_b128 v[236:239], v156 offset:2048
	ds_read_b128 v[156:159], v156 offset:3072
	s_waitcnt vmcnt(0)
	s_barrier
	s_waitcnt lgkmcnt(0)
	s_nop 0
	v_mfma_f32_16x16x32_bf16 v[96:99], v[138:141], v[20:23], v[228:231]
	v_mfma_f32_16x16x32_bf16 v[20:23], v[236:239], v[20:23], v[88:91]
	v_mfma_f32_16x16x32_bf16 v[112:115], v[156:159], v[28:31], v[20:23]
	v_mfma_f32_16x16x32_bf16 v[20:23], v[138:141], v[36:39], v[184:187]
	v_mfma_f32_16x16x32_bf16 v[104:107], v[216:219], v[44:47], v[20:23]
	v_mfma_f32_16x16x32_bf16 v[20:23], v[236:239], v[36:39], v[80:83]
	v_mfma_f32_16x16x32_bf16 v[116:119], v[216:219], v[28:31], v[96:99]
	v_mfma_f32_16x16x32_bf16 v[96:99], v[156:159], v[44:47], v[20:23]
	v_mfma_f32_16x16x32_bf16 v[20:23], v[138:141], v[52:55], v[188:191]
	v_mfma_f32_16x16x32_bf16 v[88:91], v[216:219], v[208:211], v[20:23]
	v_mfma_f32_16x16x32_bf16 v[20:23], v[236:239], v[52:55], v[72:75]
	v_mfma_f32_16x16x32_bf16 v[80:83], v[156:159], v[208:211], v[20:23]
	v_mfma_f32_16x16x32_bf16 v[20:23], v[138:141], v[220:223], v[192:195]
	v_mfma_f32_16x16x32_bf16 v[72:75], v[216:219], v[224:227], v[20:23]
	v_mfma_f32_16x16x32_bf16 v[20:23], v[236:239], v[220:223], v[64:67]
	v_mfma_f32_16x16x32_bf16 v[64:67], v[156:159], v[224:227], v[20:23]
	s_nop 0
	s_barrier
	ds_read_b128 v[182:185], v155 offset:49152
	ds_read_b128 v[186:189], v155 offset:50176
	ds_read_b128 v[190:193], v173 offset:49152
	ds_read_b128 v[208:211], v173 offset:50176
	ds_read_b128 v[220:223], v174 offset:49152
	ds_read_b128 v[224:227], v174 offset:50176
	ds_read_b128 v[228:231], v175 offset:49152
	ds_read_b128 v[240:243], v175 offset:50176
	s_barrier
	s_waitcnt lgkmcnt(0)
	s_nop 0
	v_mfma_f32_16x16x32_bf16 v[20:23], v[8:11], v[182:185], v[60:63]
	v_mfma_f32_16x16x32_bf16 v[60:63], v[12:15], v[186:189], v[20:23]
	v_mfma_f32_16x16x32_bf16 v[20:23], v[200:203], v[182:185], v[56:59]
	v_mfma_f32_16x16x32_bf16 v[52:55], v[204:207], v[186:189], v[20:23]
	v_mfma_f32_16x16x32_bf16 v[20:23], v[8:11], v[190:193], v[212:215]
	v_mfma_f32_16x16x32_bf16 v[44:47], v[12:15], v[208:211], v[20:23]
	v_mfma_f32_16x16x32_bf16 v[20:23], v[200:203], v[190:193], v[48:51]
	v_mfma_f32_16x16x32_bf16 v[36:39], v[204:207], v[208:211], v[20:23]
	v_mfma_f32_16x16x32_bf16 v[20:23], v[8:11], v[220:223], v[232:235]
	v_mfma_f32_16x16x32_bf16 v[8:11], v[8:11], v[228:231], v[142:145]
	v_mfma_f32_16x16x32_bf16 v[28:31], v[12:15], v[224:227], v[20:23]
	v_mfma_f32_16x16x32_bf16 v[20:23], v[200:203], v[220:223], v[40:43]
	v_mfma_f32_16x16x32_bf16 v[12:15], v[12:15], v[240:243], v[8:11]
	v_mfma_f32_16x16x32_bf16 v[8:11], v[200:203], v[228:231], v[32:35]
	v_mfma_f32_16x16x32_bf16 v[20:23], v[204:207], v[224:227], v[20:23]
	v_mfma_f32_16x16x32_bf16 v[8:11], v[204:207], v[240:243], v[8:11]
	s_nop 0
	s_nop 0
	v_mfma_f32_16x16x32_bf16 v[32:35], v[138:141], v[182:185], v[146:149]
	v_mfma_f32_16x16x32_bf16 v[24:27], v[236:239], v[182:185], v[24:27]
	v_mfma_f32_16x16x32_bf16 v[16:19], v[236:239], v[190:193], v[16:19]
	v_mfma_f32_16x16x32_bf16 v[56:59], v[216:219], v[186:189], v[32:35]
	v_mfma_f32_16x16x32_bf16 v[48:51], v[156:159], v[186:189], v[24:27]
	v_mfma_f32_16x16x32_bf16 v[24:27], v[138:141], v[190:193], v[160:163]
	v_mfma_f32_16x16x32_bf16 v[32:35], v[156:159], v[208:211], v[16:19]
	v_mfma_f32_16x16x32_bf16 v[16:19], v[138:141], v[220:223], v[178:181]
	v_mfma_f32_16x16x32_bf16 v[40:43], v[216:219], v[208:211], v[24:27]
	v_mfma_f32_16x16x32_bf16 v[24:27], v[216:219], v[224:227], v[16:19]
	v_mfma_f32_16x16x32_bf16 v[16:19], v[236:239], v[220:223], v[196:199]
	v_mfma_f32_16x16x32_bf16 v[4:7], v[138:141], v[228:231], v[4:7]
	v_mfma_f32_16x16x32_bf16 v[0:3], v[236:239], v[228:231], v[0:3]
	v_mfma_f32_16x16x32_bf16 v[16:19], v[156:159], v[224:227], v[16:19]
	v_mfma_f32_16x16x32_bf16 v[4:7], v[216:219], v[240:243], v[4:7]
	v_mfma_f32_16x16x32_bf16 v[0:3], v[156:159], v[240:243], v[0:3]
	s_setprio 0
	s_cmpk_gt_u32 s37, 0xff
	s_barrier
	s_cbranch_scc1 .LBB0_1941
	s_barrier

; #define WAIT_V(n) asm volatile("s_waitcnt vmcnt(" #n ")":::"memory")
; #define BAR __builtin_amdgcn_s_barrier()
; DEVINL void gemm8_mainloop(const u16* A, long lda, const u16* Bt, long ldb, int K, int brow, int bcol, f32x4 (&acc)[2][2][4][2], char* smem, int tid) {
;     ...
;   if(wr==1)BAR;
;   WAIT_V(4); BAR;
.LBB0_1984:
	v_mov_b32_e32 v151, v176
	s_nop 0
	v_readfirstlane_b32 s27, v151
	s_ashr_i32 s34, s27, 8
	s_cmp_lg_u32 s34, 1
	s_cbranch_scc1 .LBB0_1986
	s_setprio 1
	s_barrier

; #define STAGE(P,BASE,LD,br,kt) do{long _g=(long)(br)*(LD)+(long)(kt)*BK; \
;     _Pragma("unroll") for(int _i=0;_i<2;++_i){int _b=tid*16+_i*8192;int _r,_c;stage_rc(_b,_r,_c); \
;       __builtin_amdgcn_global_load_lds((const unsigned*)((BASE)+_g+(long)_r*(LD)+_c), \
;         (unsigned*)((char*)(P)+_b),16,0,0);}}while(0)
; #define STAGE(P,BASE,LD,br,kt) do{long _g=(long)(br)*(LD)+(long)(kt)*BK; \
;     _Pragma("unroll") for(int _i=0;_i<2;++_i){int _b=tid*16+_i*8192;int _r,_c;stage_rc(_b,_r,_c); \
;       __builtin_amdgcn_global_load_lds((const unsigned*)((BASE)+_g+(long)_r*(LD)+_c), \
;         (unsigned*)((char*)(P)+_b),16,0,0);}}while(0)
; #define LDA(dst,b,h) _Pragma("unroll") for(int m=0;m<4;++m) _Pragma("unroll") for(int k=0;k<2;++k) \
;     dst[m][k]=*reinterpret_cast<const bf16x8*>((char*)SA(b,h)+lds_byte(wr*64+m*16+fr,k*32+fq*8))
; #define LDB(dst,b,h) _Pragma("unroll") for(int n=0;n<2;++n) _Pragma("unroll") for(int k=0;k<2;++k) \
;     dst[n][k]=*reinterpret_cast<const bf16x8*>((char*)SB(b,h)+lds_byte(wc*32+n*16+fr,k*32+fq*8))
; #define MMA(ai,bj,At_,Bt_) do{__builtin_amdgcn_s_setprio(1); \
;     _Pragma("unroll") for(int m=0;m<4;++m) _Pragma("unroll") for(int n=0;n<2;++n) _Pragma("unroll") for(int k=0;k<2;++k) \
;       acc[ai][bj][m][n]=__builtin_amdgcn_mfma_f32_16x16x32_bf16(Bt_[n][k],At_[m][k],acc[ai][bj][m][n],0,0,0); \
;     __builtin_amdgcn_s_setprio(0);}while(0)
; #define WAIT_L(n) asm volatile("s_waitcnt lgkmcnt(" #n ")":::"memory")
; #define BAR __builtin_amdgcn_s_barrier()
; #define SCHED __builtin_amdgcn_sched_barrier(0)
; DEVINL void gemm8_mainloop(const u16* A, long lda, const u16* Bt, long ldb, int K, int brow, int bcol, f32x4 (&acc)[2][2][4][2], char* smem, int tid) {
;     ...
;   for(int t=0;t<nt-2;t+=2){
;     LDB(B0,0,0); SCHED; LDA(At,0,0); STAGE(SA(1,1),A,lda,brow+HALF,t+1);
;     WAIT_L(8); BAR; WAIT_L(0); MMA(0,0,At,B0); BAR; SCHED;
;     LDB(B1,0,1); STAGE(SB(0,0),Bt,ldb,bcol,t+2);
;     BAR; WAIT_L(0); MMA(0,1,At,B1); BAR;
;     LDA(At,0,1); STAGE(SA(0,0),A,lda,brow,t+2);
;     BAR; WAIT_L(0); MMA(1,0,At,B0); BAR; SCHED;
.LBB0_1987:
	ds_read_b128 v[178:181], v163
	ds_read_b128 v[182:185], v163 offset:1024
	ds_read_b128 v[186:189], v163 offset:2048
	ds_read_b128 v[190:193], v163 offset:3072
	v_add_u32_e32 v174, 0xc000, v152
	v_lshl_add_u64 v[242:243], s[94:95], 0, v[146:147]
	v_readfirstlane_b32 s25, v174
	v_add_u32_e32 v175, 0xe000, v152
	v_add_u32_e32 v171, s23, v162
	v_add_u32_e32 v172, s34, v162
	v_add_u32_e32 v173, s35, v162
	v_lshl_add_u64 v[164:165], v[242:243], 0, s[2:3]
	s_mov_b32 m0, s25
	v_lshl_add_u64 v[244:245], s[94:95], 0, v[148:149]
	v_readfirstlane_b32 s25, v175
	ds_read_b128 v[166:169], v153
	ds_read_b128 v[194:197], v153 offset:1024
	ds_read_b128 v[198:201], v171
	ds_read_b128 v[202:205], v171 offset:1024
	ds_read_b128 v[206:209], v172
	ds_read_b128 v[210:213], v172 offset:1024
	ds_read_b128 v[214:217], v173
	ds_read_b128 v[218:221], v173 offset:1024
	global_load_lds_dwordx4 v[164:165], off
	v_lshl_add_u64 v[164:165], v[244:245], 0, s[2:3]
	s_mov_b32 m0, s25
	s_nop 0
	global_load_lds_dwordx4 v[164:165], off
	s_waitcnt lgkmcnt(8)
	s_barrier
	s_waitcnt lgkmcnt(0)
	s_nop 0
	v_mfma_f32_16x16x32_bf16 v[124:127], v[178:181], v[166:169], v[124:127]
	v_mfma_f32_16x16x32_bf16 v[120:123], v[186:189], v[166:169], v[120:123]
	v_mfma_f32_16x16x32_bf16 v[116:119], v[178:181], v[198:201], v[116:119]
	v_mfma_f32_16x16x32_bf16 v[112:115], v[186:189], v[198:201], v[112:115]
	v_mfma_f32_16x16x32_bf16 v[108:111], v[178:181], v[206:209], v[108:111]
	v_mfma_f32_16x16x32_bf16 v[104:107], v[186:189], v[206:209], v[104:107]
	v_mfma_f32_16x16x32_bf16 v[100:103], v[178:181], v[214:217], v[100:103]
	v_mfma_f32_16x16x32_bf16 v[96:99], v[186:189], v[214:217], v[96:99]
	v_mfma_f32_16x16x32_bf16 v[124:127], v[182:185], v[194:197], v[124:127]
	v_mfma_f32_16x16x32_bf16 v[120:123], v[190:193], v[194:197], v[120:123]
	v_mfma_f32_16x16x32_bf16 v[116:119], v[182:185], v[202:205], v[116:119]
	v_mfma_f32_16x16x32_bf16 v[112:115], v[190:193], v[202:205], v[112:115]
	v_mfma_f32_16x16x32_bf16 v[108:111], v[182:185], v[210:213], v[108:111]
	v_mfma_f32_16x16x32_bf16 v[104:107], v[190:193], v[210:213], v[104:107]
	v_mfma_f32_16x16x32_bf16 v[100:103], v[182:185], v[218:221], v[100:103]
	v_mfma_f32_16x16x32_bf16 v[96:99], v[190:193], v[218:221], v[96:99]
	s_nop 0
	s_barrier
	v_add_u32_e32 v164, s28, v154
	v_lshl_add_u64 v[246:247], s[94:95], 0, v[142:143]
	v_readfirstlane_b32 s25, v164
	v_add_u32_e32 v165, 0x2000, v164
	v_lshl_add_u64 v[238:239], v[246:247], 0, s[4:5]
	s_mov_b32 m0, s25
	v_lshl_add_u64 v[248:249], s[94:95], 0, v[144:145]
	v_readfirstlane_b32 s25, v165
	ds_read_b128 v[222:225], v160
	ds_read_b128 v[226:229], v160 offset:1024
	ds_read_b128 v[230:233], v160 offset:2048
	ds_read_b128 v[234:237], v160 offset:3072
	global_load_lds_dwordx4 v[238:239], off
	v_lshl_add_u64 v[238:239], v[248:249], 0, s[4:5]
	s_mov_b32 m0, s25
	s_nop 0
	global_load_lds_dwordx4 v[238:239], off
	s_barrier
	s_waitcnt lgkmcnt(0)
	s_nop 0
	v_mfma_f32_16x16x32_bf16 v[92:95], v[222:225], v[166:169], v[92:95]
	v_mfma_f32_16x16x32_bf16 v[88:91], v[230:233], v[166:169], v[88:91]
	v_mfma_f32_16x16x32_bf16 v[84:87], v[222:225], v[198:201], v[84:87]
	v_mfma_f32_16x16x32_bf16 v[80:83], v[230:233], v[198:201], v[80:83]
	v_mfma_f32_16x16x32_bf16 v[76:79], v[222:225], v[206:209], v[76:79]
	v_mfma_f32_16x16x32_bf16 v[72:75], v[230:233], v[206:209], v[72:75]
	v_mfma_f32_16x16x32_bf16 v[68:71], v[222:225], v[214:217], v[68:71]
	v_mfma_f32_16x16x32_bf16 v[64:67], v[230:233], v[214:217], v[64:67]
	v_mfma_f32_16x16x32_bf16 v[92:95], v[226:229], v[194:197], v[92:95]
	v_mfma_f32_16x16x32_bf16 v[88:91], v[234:237], v[194:197], v[88:91]
	v_mfma_f32_16x16x32_bf16 v[84:87], v[226:229], v[202:205], v[84:87]
	v_mfma_f32_16x16x32_bf16 v[80:83], v[234:237], v[202:205], v[80:83]
	v_mfma_f32_16x16x32_bf16 v[76:79], v[226:229], v[210:213], v[76:79]
	v_mfma_f32_16x16x32_bf16 v[72:75], v[234:237], v[210:213], v[72:75]
	v_mfma_f32_16x16x32_bf16 v[68:71], v[226:229], v[218:221], v[68:71]
	v_mfma_f32_16x16x32_bf16 v[64:67], v[234:237], v[218:221], v[64:67]
	s_nop 0
	v_readfirstlane_b32 s25, v152
	v_lshl_add_u64 v[166:167], v[242:243], 0, s[6:7]
	s_mov_b32 m0, s25
	s_barrier
	ds_read_b128 v[194:197], v153 offset:16384
	ds_read_b128 v[198:201], v153 offset:17408
	ds_read_b128 v[202:205], v171 offset:16384
	ds_read_b128 v[206:209], v171 offset:17408
	ds_read_b128 v[210:213], v172 offset:16384
	ds_read_b128 v[214:217], v172 offset:17408
	ds_read_b128 v[218:221], v173 offset:16384
	ds_read_b128 v[238:241], v173 offset:17408
	global_load_lds_dwordx4 v[166:167], off
	v_add_u32_e32 v166, 0x2000, v152
	v_lshl_add_u64 v[168:169], v[244:245], 0, s[6:7]
	v_readfirstlane_b32 s25, v166
	s_mov_b32 m0, s25
	s_nop 0
	global_load_lds_dwordx4 v[168:169], off
	s_barrier
	s_waitcnt lgkmcnt(0)
	s_nop 0
	v_mfma_f32_16x16x32_bf16 v[60:63], v[178:181], v[194:197], v[60:63]
	v_mfma_f32_16x16x32_bf16 v[56:59], v[186:189], v[194:197], v[56:59]
	v_mfma_f32_16x16x32_bf16 v[52:55], v[178:181], v[202:205], v[52:55]
	v_mfma_f32_16x16x32_bf16 v[48:51], v[186:189], v[202:205], v[48:51]
	v_mfma_f32_16x16x32_bf16 v[44:47], v[178:181], v[210:213], v[44:47]
	v_mfma_f32_16x16x32_bf16 v[40:43], v[186:189], v[210:213], v[40:43]
	v_mfma_f32_16x16x32_bf16 v[36:39], v[178:181], v[218:221], v[36:39]
	v_mfma_f32_16x16x32_bf16 v[32:35], v[186:189], v[218:221], v[32:35]
	v_mfma_f32_16x16x32_bf16 v[60:63], v[182:185], v[198:201], v[60:63]
	v_mfma_f32_16x16x32_bf16 v[56:59], v[190:193], v[198:201], v[56:59]
	v_mfma_f32_16x16x32_bf16 v[52:55], v[182:185], v[206:209], v[52:55]
	v_mfma_f32_16x16x32_bf16 v[48:51], v[190:193], v[206:209], v[48:51]
	v_mfma_f32_16x16x32_bf16 v[44:47], v[182:185], v[214:217], v[44:47]
	v_mfma_f32_16x16x32_bf16 v[40:43], v[190:193], v[214:217], v[40:43]
	v_mfma_f32_16x16x32_bf16 v[36:39], v[182:185], v[238:241], v[36:39]
	v_mfma_f32_16x16x32_bf16 v[32:35], v[190:193], v[238:241], v[32:35]
	s_nop 0
	s_barrier
; #define STAGE(P,BASE,LD,br,kt) do{long _g=(long)(br)*(LD)+(long)(kt)*BK; \
;     _Pragma("unroll") for(int _i=0;_i<2;++_i){int _b=tid*16+_i*8192;int _r,_c;stage_rc(_b,_r,_c); \
;       __builtin_amdgcn_global_load_lds((const unsigned*)((BASE)+_g+(long)_r*(LD)+_c), \
;         (unsigned*)((char*)(P)+_b),16,0,0);}}while(0)
; #define STAGE(P,BASE,LD,br,kt) do{long _g=(long)(br)*(LD)+(long)(kt)*BK; \
;     _Pragma("unroll") for(int _i=0;_i<2;++_i){int _b=tid*16+_i*8192;int _r,_c;stage_rc(_b,_r,_c); \
;       __builtin_amdgcn_global_load_lds((const unsigned*)((BASE)+_g+(long)_r*(LD)+_c), \
;         (unsigned*)((char*)(P)+_b),16,0,0);}}while(0)
; #define LDA(dst,b,h) _Pragma("unroll") for(int m=0;m<4;++m) _Pragma("unroll") for(int k=0;k<2;++k) \
;     dst[m][k]=*reinterpret_cast<const bf16x8*>((char*)SA(b,h)+lds_byte(wr*64+m*16+fr,k*32+fq*8))
; #define LDB(dst,b,h) _Pragma("unroll") for(int n=0;n<2;++n) _Pragma("unroll") for(int k=0;k<2;++k) \
;     dst[n][k]=*reinterpret_cast<const bf16x8*>((char*)SB(b,h)+lds_byte(wc*32+n*16+fr,k*32+fq*8))
; #define MMA(ai,bj,At_,Bt_) do{__builtin_amdgcn_s_setprio(1); \
;     _Pragma("unroll") for(int m=0;m<4;++m) _Pragma("unroll") for(int n=0;n<2;++n) _Pragma("unroll") for(int k=0;k<2;++k) \
;       acc[ai][bj][m][n]=__builtin_amdgcn_mfma_f32_16x16x32_bf16(Bt_[n][k],At_[m][k],acc[ai][bj][m][n],0,0,0); \
;     __builtin_amdgcn_s_setprio(0);}while(0)
; #define WAIT_V(n) asm volatile("s_waitcnt vmcnt(" #n ")":::"memory")
; #define WAIT_L(n) asm volatile("s_waitcnt lgkmcnt(" #n ")":::"memory")
; #define BAR __builtin_amdgcn_s_barrier()
; #define SCHED __builtin_amdgcn_sched_barrier(0)
; DEVINL void gemm8_mainloop(const u16* A, long lda, const u16* Bt, long ldb, int K, int brow, int bcol, f32x4 (&acc)[2][2][4][2], char* smem, int tid) {
;     ...
;     STAGE(SB(0,1),Bt,ldb,bcol+HALF,t+2);
;     WAIT_V(6); BAR; MMA(1,1,At,B1); BAR;
;     LDB(B0,1,0); SCHED; LDA(At,1,0); STAGE(SA(0,1),A,lda,brow+HALF,t+2);
;     WAIT_L(8); BAR; WAIT_L(0); MMA(0,0,At,B0); BAR; SCHED;
;     LDB(B1,1,1); STAGE(SB(1,0),Bt,ldb,bcol,t+3);
;     BAR; WAIT_L(0); MMA(0,1,At,B1); BAR;
	v_add_u32_e32 v167, s29, v154
	v_lshl_add_u64 v[168:169], v[246:247], 0, s[8:9]
	v_readfirstlane_b32 s25, v167
	s_mov_b32 m0, s25
	v_lshl_add_u64 v[178:179], v[248:249], 0, s[8:9]
	global_load_lds_dwordx4 v[168:169], off
	v_add_u32_e32 v168, 0x2000, v167
	s_nop 0
	v_readfirstlane_b32 s25, v168
	s_mov_b32 m0, s25
	s_nop 0
	global_load_lds_dwordx4 v[178:179], off
	s_waitcnt vmcnt(6)
	s_barrier
	s_nop 0
	v_mfma_f32_16x16x32_bf16 v[28:31], v[222:225], v[194:197], v[28:31]
	v_mfma_f32_16x16x32_bf16 v[24:27], v[230:233], v[194:197], v[24:27]
	v_mfma_f32_16x16x32_bf16 v[20:23], v[222:225], v[202:205], v[20:23]
	v_mfma_f32_16x16x32_bf16 v[16:19], v[230:233], v[202:205], v[16:19]
	v_mfma_f32_16x16x32_bf16 v[12:15], v[222:225], v[210:213], v[12:15]
	v_mfma_f32_16x16x32_bf16 v[8:11], v[230:233], v[210:213], v[8:11]
	v_mfma_f32_16x16x32_bf16 v[4:7], v[222:225], v[218:221], v[4:7]
	v_mfma_f32_16x16x32_bf16 v[0:3], v[230:233], v[218:221], v[0:3]
	v_mfma_f32_16x16x32_bf16 v[28:31], v[226:229], v[198:201], v[28:31]
	v_mfma_f32_16x16x32_bf16 v[24:27], v[234:237], v[198:201], v[24:27]
	v_mfma_f32_16x16x32_bf16 v[20:23], v[226:229], v[206:209], v[20:23]
	v_mfma_f32_16x16x32_bf16 v[16:19], v[234:237], v[206:209], v[16:19]
	v_mfma_f32_16x16x32_bf16 v[12:15], v[226:229], v[214:217], v[12:15]
	v_mfma_f32_16x16x32_bf16 v[8:11], v[234:237], v[214:217], v[8:11]
	v_mfma_f32_16x16x32_bf16 v[4:7], v[226:229], v[238:241], v[4:7]
	v_mfma_f32_16x16x32_bf16 v[0:3], v[234:237], v[238:241], v[0:3]
	s_nop 0
	s_barrier
	ds_read_b128 v[178:181], v156
	ds_read_b128 v[182:185], v156 offset:1024
	ds_read_b128 v[186:189], v156 offset:2048
	ds_read_b128 v[190:193], v156 offset:3072
	v_add_u32_e32 v169, 0x4000, v152
	v_add_u32_e32 v170, 0x6000, v152
	v_readfirstlane_b32 s25, v169
	v_lshl_add_u64 v[226:227], v[242:243], 0, s[10:11]
	s_mov_b32 m0, s25
	v_readfirstlane_b32 s25, v170
	ds_read_b128 v[194:197], v153 offset:32768
	ds_read_b128 v[198:201], v153 offset:33792
	ds_read_b128 v[202:205], v171 offset:32768
	ds_read_b128 v[206:209], v171 offset:33792
	ds_read_b128 v[210:213], v172 offset:32768
	ds_read_b128 v[214:217], v172 offset:33792
	ds_read_b128 v[218:221], v173 offset:32768
	ds_read_b128 v[222:225], v173 offset:33792
	global_load_lds_dwordx4 v[226:227], off
	v_lshl_add_u64 v[226:227], v[244:245], 0, s[10:11]
	s_mov_b32 m0, s25
	s_nop 0
	global_load_lds_dwordx4 v[226:227], off
	s_waitcnt lgkmcnt(8)
	s_barrier
	s_waitcnt lgkmcnt(0)
	s_nop 0
	v_mfma_f32_16x16x32_bf16 v[124:127], v[178:181], v[194:197], v[124:127]
	v_mfma_f32_16x16x32_bf16 v[120:123], v[186:189], v[194:197], v[120:123]
	v_mfma_f32_16x16x32_bf16 v[116:119], v[178:181], v[202:205], v[116:119]
	v_mfma_f32_16x16x32_bf16 v[112:115], v[186:189], v[202:205], v[112:115]
	v_mfma_f32_16x16x32_bf16 v[108:111], v[178:181], v[210:213], v[108:111]
	v_mfma_f32_16x16x32_bf16 v[104:107], v[186:189], v[210:213], v[104:107]
	v_mfma_f32_16x16x32_bf16 v[100:103], v[178:181], v[218:221], v[100:103]
	v_mfma_f32_16x16x32_bf16 v[96:99], v[186:189], v[218:221], v[96:99]
	v_mfma_f32_16x16x32_bf16 v[124:127], v[182:185], v[198:201], v[124:127]
	v_mfma_f32_16x16x32_bf16 v[120:123], v[190:193], v[198:201], v[120:123]
	v_mfma_f32_16x16x32_bf16 v[116:119], v[182:185], v[206:209], v[116:119]
	v_mfma_f32_16x16x32_bf16 v[112:115], v[190:193], v[206:209], v[112:115]
	v_mfma_f32_16x16x32_bf16 v[108:111], v[182:185], v[214:217], v[108:111]
	v_mfma_f32_16x16x32_bf16 v[104:107], v[190:193], v[214:217], v[104:107]
	v_mfma_f32_16x16x32_bf16 v[100:103], v[182:185], v[222:225], v[100:103]
	v_mfma_f32_16x16x32_bf16 v[96:99], v[190:193], v[222:225], v[96:99]
	s_nop 0
	s_barrier
	v_readfirstlane_b32 s25, v157
	v_add_u32_e32 v177, 0x2000, v157
	v_lshl_add_u64 v[250:251], v[246:247], 0, s[12:13]
	s_mov_b32 m0, s25
	v_readfirstlane_b32 s25, v177
	ds_read_b128 v[226:229], v155
	ds_read_b128 v[230:233], v155 offset:1024
	ds_read_b128 v[234:237], v155 offset:2048
	ds_read_b128 v[238:241], v155 offset:3072
	global_load_lds_dwordx4 v[250:251], off
	v_lshl_add_u64 v[250:251], v[248:249], 0, s[12:13]
	s_mov_b32 m0, s25
	s_nop 0
	global_load_lds_dwordx4 v[250:251], off
	s_barrier
	s_waitcnt lgkmcnt(0)
	s_nop 0
	v_mfma_f32_16x16x32_bf16 v[92:95], v[226:229], v[194:197], v[92:95]
	v_mfma_f32_16x16x32_bf16 v[88:91], v[234:237], v[194:197], v[88:91]
	v_mfma_f32_16x16x32_bf16 v[84:87], v[226:229], v[202:205], v[84:87]
	v_mfma_f32_16x16x32_bf16 v[80:83], v[234:237], v[202:205], v[80:83]
	v_mfma_f32_16x16x32_bf16 v[76:79], v[226:229], v[210:213], v[76:79]
	v_mfma_f32_16x16x32_bf16 v[72:75], v[234:237], v[210:213], v[72:75]
	v_mfma_f32_16x16x32_bf16 v[68:71], v[226:229], v[218:221], v[68:71]
	v_mfma_f32_16x16x32_bf16 v[64:67], v[234:237], v[218:221], v[64:67]
	v_mfma_f32_16x16x32_bf16 v[92:95], v[230:233], v[198:201], v[92:95]
	v_mfma_f32_16x16x32_bf16 v[88:91], v[238:241], v[198:201], v[88:91]
	v_mfma_f32_16x16x32_bf16 v[84:87], v[230:233], v[206:209], v[84:87]
	v_mfma_f32_16x16x32_bf16 v[80:83], v[238:241], v[206:209], v[80:83]
	v_mfma_f32_16x16x32_bf16 v[76:79], v[230:233], v[214:217], v[76:79]
	v_mfma_f32_16x16x32_bf16 v[72:75], v[238:241], v[214:217], v[72:75]
	v_mfma_f32_16x16x32_bf16 v[68:71], v[230:233], v[222:225], v[68:71]
	v_mfma_f32_16x16x32_bf16 v[64:67], v[238:241], v[222:225], v[64:67]
	s_nop 0
	v_readfirstlane_b32 s25, v158
	v_lshl_add_u64 v[242:243], v[242:243], 0, s[14:15]
	s_mov_b32 m0, s25
	v_readfirstlane_b32 s25, v159
	s_barrier
; #define STAGE(P,BASE,LD,br,kt) do{long _g=(long)(br)*(LD)+(long)(kt)*BK; \
;     _Pragma("unroll") for(int _i=0;_i<2;++_i){int _b=tid*16+_i*8192;int _r,_c;stage_rc(_b,_r,_c); \
;       __builtin_amdgcn_global_load_lds((const unsigned*)((BASE)+_g+(long)_r*(LD)+_c), \
;         (unsigned*)((char*)(P)+_b),16,0,0);}}while(0)
; #define STAGE(P,BASE,LD,br,kt) do{long _g=(long)(br)*(LD)+(long)(kt)*BK; \
;     _Pragma("unroll") for(int _i=0;_i<2;++_i){int _b=tid*16+_i*8192;int _r,_c;stage_rc(_b,_r,_c); \
;       __builtin_amdgcn_global_load_lds((const unsigned*)((BASE)+_g+(long)_r*(LD)+_c), \
;         (unsigned*)((char*)(P)+_b),16,0,0);}}while(0)
; #define LDA(dst,b,h) _Pragma("unroll") for(int m=0;m<4;++m) _Pragma("unroll") for(int k=0;k<2;++k) \
;     dst[m][k]=*reinterpret_cast<const bf16x8*>((char*)SA(b,h)+lds_byte(wr*64+m*16+fr,k*32+fq*8))
; #define LDB(dst,b,h) _Pragma("unroll") for(int n=0;n<2;++n) _Pragma("unroll") for(int k=0;k<2;++k) \
;     dst[n][k]=*reinterpret_cast<const bf16x8*>((char*)SB(b,h)+lds_byte(wc*32+n*16+fr,k*32+fq*8))
; #define MMA(ai,bj,At_,Bt_) do{__builtin_amdgcn_s_setprio(1); \
;     _Pragma("unroll") for(int m=0;m<4;++m) _Pragma("unroll") for(int n=0;n<2;++n) _Pragma("unroll") for(int k=0;k<2;++k) \
;       acc[ai][bj][m][n]=__builtin_amdgcn_mfma_f32_16x16x32_bf16(Bt_[n][k],At_[m][k],acc[ai][bj][m][n],0,0,0); \
;     __builtin_amdgcn_s_setprio(0);}while(0)
; #define WAIT_V(n) asm volatile("s_waitcnt vmcnt(" #n ")":::"memory")
; #define WAIT_L(n) asm volatile("s_waitcnt lgkmcnt(" #n ")":::"memory")
; #define BAR __builtin_amdgcn_s_barrier()
; #define SCHED __builtin_amdgcn_sched_barrier(0)
; DEVINL void gemm8_mainloop(const u16* A, long lda, const u16* Bt, long ldb, int K, int brow, int bcol, f32x4 (&acc)[2][2][4][2], char* smem, int tid) {
;     ...
;     LDA(At,1,1); STAGE(SA(1,0),A,lda,brow,t+3);
;     BAR; WAIT_L(0); MMA(1,0,At,B0); BAR; SCHED;
;     STAGE(SB(1,1),Bt,ldb,bcol+HALF,t+3);
;     WAIT_V(6); BAR; MMA(1,1,At,B1); BAR;
;   }
;   { LDB(B0,0,0); LDA(At,0,0); STAGE(SA(1,1),A,lda,brow+HALF,nt-1);
;     BAR; WAIT_L(0); MMA(0,0,At,B0); BAR;
	ds_read_b128 v[194:197], v153 offset:49152
	ds_read_b128 v[198:201], v153 offset:50176
	ds_read_b128 v[202:205], v171 offset:49152
	ds_read_b128 v[206:209], v171 offset:50176
	ds_read_b128 v[210:213], v172 offset:49152
	ds_read_b128 v[214:217], v172 offset:50176
	ds_read_b128 v[218:221], v173 offset:49152
	ds_read_b128 v[222:225], v173 offset:50176
	global_load_lds_dwordx4 v[242:243], off
	v_lshl_add_u64 v[242:243], v[244:245], 0, s[14:15]
	s_mov_b32 m0, s25
	s_nop 0
	global_load_lds_dwordx4 v[242:243], off
	s_barrier
	s_waitcnt lgkmcnt(0)
	s_nop 0
	v_mfma_f32_16x16x32_bf16 v[60:63], v[178:181], v[194:197], v[60:63]
	v_mfma_f32_16x16x32_bf16 v[56:59], v[186:189], v[194:197], v[56:59]
	v_mfma_f32_16x16x32_bf16 v[52:55], v[178:181], v[202:205], v[52:55]
	v_mfma_f32_16x16x32_bf16 v[48:51], v[186:189], v[202:205], v[48:51]
	v_mfma_f32_16x16x32_bf16 v[44:47], v[178:181], v[210:213], v[44:47]
	v_mfma_f32_16x16x32_bf16 v[40:43], v[186:189], v[210:213], v[40:43]
	v_mfma_f32_16x16x32_bf16 v[36:39], v[178:181], v[218:221], v[36:39]
	v_mfma_f32_16x16x32_bf16 v[32:35], v[186:189], v[218:221], v[32:35]
	v_mfma_f32_16x16x32_bf16 v[60:63], v[182:185], v[198:201], v[60:63]
	v_mfma_f32_16x16x32_bf16 v[56:59], v[190:193], v[198:201], v[56:59]
	v_mfma_f32_16x16x32_bf16 v[52:55], v[182:185], v[206:209], v[52:55]
	v_mfma_f32_16x16x32_bf16 v[48:51], v[190:193], v[206:209], v[48:51]
	v_mfma_f32_16x16x32_bf16 v[44:47], v[182:185], v[214:217], v[44:47]
	v_mfma_f32_16x16x32_bf16 v[40:43], v[190:193], v[214:217], v[40:43]
	v_mfma_f32_16x16x32_bf16 v[36:39], v[182:185], v[222:225], v[36:39]
	v_mfma_f32_16x16x32_bf16 v[32:35], v[190:193], v[222:225], v[32:35]
	s_nop 0
	s_barrier
	v_readfirstlane_b32 s25, v161
	v_add_u32_e32 v177, 0x2000, v161
	v_lshl_add_u64 v[178:179], v[246:247], 0, s[16:17]
	s_mov_b32 m0, s25
	v_readfirstlane_b32 s25, v177
	global_load_lds_dwordx4 v[178:179], off
	v_lshl_add_u64 v[178:179], v[248:249], 0, s[16:17]
	s_mov_b32 m0, s25
	s_nop 0
	global_load_lds_dwordx4 v[178:179], off
	s_waitcnt vmcnt(6)
	s_barrier
	s_nop 0
	v_mfma_f32_16x16x32_bf16 v[28:31], v[226:229], v[194:197], v[28:31]
	v_mfma_f32_16x16x32_bf16 v[24:27], v[234:237], v[194:197], v[24:27]
	v_mfma_f32_16x16x32_bf16 v[20:23], v[226:229], v[202:205], v[20:23]
	v_mfma_f32_16x16x32_bf16 v[16:19], v[234:237], v[202:205], v[16:19]
	v_mfma_f32_16x16x32_bf16 v[12:15], v[226:229], v[210:213], v[12:15]
	v_mfma_f32_16x16x32_bf16 v[8:11], v[234:237], v[210:213], v[8:11]
	v_mfma_f32_16x16x32_bf16 v[4:7], v[226:229], v[218:221], v[4:7]
	v_mfma_f32_16x16x32_bf16 v[0:3], v[234:237], v[218:221], v[0:3]
	v_mfma_f32_16x16x32_bf16 v[28:31], v[230:233], v[198:201], v[28:31]
	v_mfma_f32_16x16x32_bf16 v[24:27], v[238:241], v[198:201], v[24:27]
	v_mfma_f32_16x16x32_bf16 v[20:23], v[230:233], v[206:209], v[20:23]
	v_mfma_f32_16x16x32_bf16 v[16:19], v[238:241], v[206:209], v[16:19]
	v_mfma_f32_16x16x32_bf16 v[12:15], v[230:233], v[214:217], v[12:15]
	v_mfma_f32_16x16x32_bf16 v[8:11], v[238:241], v[214:217], v[8:11]
	v_mfma_f32_16x16x32_bf16 v[4:7], v[230:233], v[222:225], v[4:7]
	v_mfma_f32_16x16x32_bf16 v[0:3], v[238:241], v[222:225], v[0:3]
	s_nop 0
	s_add_i32 s24, s24, 2
	v_lshl_add_u64 v[142:143], v[142:143], 0, s[18:19]
	v_lshl_add_u64 v[144:145], v[144:145], 0, s[18:19]
	v_lshl_add_u64 v[146:147], v[146:147], 0, s[18:19]
	s_cmpk_lt_u32 s24, 0x7c
	v_lshl_add_u64 v[148:149], v[148:149], 0, s[18:19]
	s_barrier
	s_cbranch_scc1 .LBB0_1987
	s_or_b32 s24, s22, 0x80
	s_ashr_i32 s25, s24, 31
	s_lshl_b64 s[24:25], s[24:25], 14
	s_add_u32 s23, s62, s24
	s_addc_u32 s25, s63, s25
	s_add_u32 s24, s23, 0x3f80
	s_addc_u32 s25, s25, 0
	v_lshl_add_u64 v[158:159], v[134:135], 1, s[24:25]
	v_readfirstlane_b32 s23, v174
	v_lshl_add_u64 v[138:139], v[138:139], 1, v[158:159]
	s_mov_b32 m0, s23
	ds_read_b128 v[142:145], v163
	ds_read_b128 v[146:149], v163 offset:1024
	ds_read_b128 v[178:181], v163 offset:2048
	ds_read_b128 v[182:185], v163 offset:3072
	ds_read_b128 v[186:189], v153
	ds_read_b128 v[190:193], v153 offset:1024
	ds_read_b128 v[194:197], v171
	ds_read_b128 v[198:201], v171 offset:1024
	ds_read_b128 v[202:205], v172
	ds_read_b128 v[206:209], v172 offset:1024
	ds_read_b128 v[210:213], v173
	ds_read_b128 v[214:217], v173 offset:1024
	global_load_lds_dwordx4 v[138:139], off
	v_lshl_add_u64 v[138:139], v[136:137], 1, s[24:25]
	v_readfirstlane_b32 s23, v175
	v_lshl_add_u64 v[138:139], v[140:141], 1, v[138:139]
	s_mov_b32 m0, s23
	s_nop 0
	global_load_lds_dwordx4 v[138:139], off
	s_barrier
	s_waitcnt lgkmcnt(0)
	s_nop 0
	v_mfma_f32_16x16x32_bf16 v[124:127], v[142:145], v[186:189], v[124:127]
	v_mfma_f32_16x16x32_bf16 v[120:123], v[178:181], v[186:189], v[120:123]
	v_mfma_f32_16x16x32_bf16 v[116:119], v[142:145], v[194:197], v[116:119]
	v_mfma_f32_16x16x32_bf16 v[112:115], v[178:181], v[194:197], v[112:115]
	v_mfma_f32_16x16x32_bf16 v[100:103], v[142:145], v[210:213], v[100:103]
	v_mfma_f32_16x16x32_bf16 v[96:99], v[178:181], v[210:213], v[96:99]
	v_mfma_f32_16x16x32_bf16 v[124:127], v[146:149], v[190:193], v[124:127]
	v_mfma_f32_16x16x32_bf16 v[120:123], v[182:185], v[190:193], v[120:123]
	v_mfma_f32_16x16x32_bf16 v[116:119], v[146:149], v[198:201], v[116:119]
	v_mfma_f32_16x16x32_bf16 v[112:115], v[182:185], v[198:201], v[112:115]
	v_mfma_f32_16x16x32_bf16 v[108:111], v[142:145], v[202:205], v[108:111]
	v_mfma_f32_16x16x32_bf16 v[104:107], v[178:181], v[202:205], v[104:107]
	v_mfma_f32_16x16x32_bf16 v[100:103], v[146:149], v[214:217], v[100:103]
	v_mfma_f32_16x16x32_bf16 v[96:99], v[182:185], v[214:217], v[96:99]
	v_mfma_f32_16x16x32_bf16 v[138:141], v[146:149], v[206:209], v[108:111]
	v_mfma_f32_16x16x32_bf16 v[218:221], v[182:185], v[206:209], v[104:107]
	s_nop 0
	s_barrier
; #define LDA(dst,b,h) _Pragma("unroll") for(int m=0;m<4;++m) _Pragma("unroll") for(int k=0;k<2;++k) \
;     dst[m][k]=*reinterpret_cast<const bf16x8*>((char*)SA(b,h)+lds_byte(wr*64+m*16+fr,k*32+fq*8))
; #define LDB(dst,b,h) _Pragma("unroll") for(int n=0;n<2;++n) _Pragma("unroll") for(int k=0;k<2;++k) \
;     dst[n][k]=*reinterpret_cast<const bf16x8*>((char*)SB(b,h)+lds_byte(wc*32+n*16+fr,k*32+fq*8))
; #define MMA(ai,bj,At_,Bt_) do{__builtin_amdgcn_s_setprio(1); \
;     _Pragma("unroll") for(int m=0;m<4;++m) _Pragma("unroll") for(int n=0;n<2;++n) _Pragma("unroll") for(int k=0;k<2;++k) \
;       acc[ai][bj][m][n]=__builtin_amdgcn_mfma_f32_16x16x32_bf16(Bt_[n][k],At_[m][k],acc[ai][bj][m][n],0,0,0); \
;     __builtin_amdgcn_s_setprio(0);}while(0)
; #define WAIT_V(n) asm volatile("s_waitcnt vmcnt(" #n ")":::"memory")
; #define WAIT_L(n) asm volatile("s_waitcnt lgkmcnt(" #n ")":::"memory")
; #define BAR __builtin_amdgcn_s_barrier()
; DEVINL void gemm8_mainloop(const u16* A, long lda, const u16* Bt, long ldb, int K, int brow, int bcol, f32x4 (&acc)[2][2][4][2], char* smem, int tid) {
;     ...
;     LDB(B1,0,1); BAR; WAIT_L(0); MMA(0,1,At,B1); BAR;
;     LDA(At,0,1); WAIT_V(4); BAR; WAIT_L(0); MMA(1,0,At,B0); MMA(1,1,At,B1); BAR; }
;   { LDB(B0,1,0); LDA(At,1,0); WAIT_V(2); BAR; WAIT_L(0); MMA(0,0,At,B0); BAR;
	s_nop 1
	ds_read_b128 v[104:107], v160
	ds_read_b128 v[108:111], v160 offset:1024
	ds_read_b128 v[222:225], v160 offset:2048
	ds_read_b128 v[158:161], v160 offset:3072
	s_barrier
	s_waitcnt lgkmcnt(0)
	s_nop 0
	v_mfma_f32_16x16x32_bf16 v[84:87], v[104:107], v[194:197], v[84:87]
	v_mfma_f32_16x16x32_bf16 v[80:83], v[222:225], v[194:197], v[80:83]
	v_mfma_f32_16x16x32_bf16 v[68:71], v[104:107], v[210:213], v[68:71]
	v_mfma_f32_16x16x32_bf16 v[92:95], v[104:107], v[186:189], v[92:95]
	v_mfma_f32_16x16x32_bf16 v[88:91], v[222:225], v[186:189], v[88:91]
	v_mfma_f32_16x16x32_bf16 v[84:87], v[108:111], v[198:201], v[84:87]
	v_mfma_f32_16x16x32_bf16 v[80:83], v[158:161], v[198:201], v[80:83]
	v_mfma_f32_16x16x32_bf16 v[76:79], v[104:107], v[202:205], v[76:79]
	v_mfma_f32_16x16x32_bf16 v[72:75], v[222:225], v[202:205], v[72:75]
	v_mfma_f32_16x16x32_bf16 v[68:71], v[108:111], v[214:217], v[68:71]
	v_mfma_f32_16x16x32_bf16 v[64:67], v[222:225], v[210:213], v[64:67]
	v_mfma_f32_16x16x32_bf16 v[226:229], v[108:111], v[190:193], v[92:95]
	v_mfma_f32_16x16x32_bf16 v[186:189], v[158:161], v[190:193], v[88:91]
	v_mfma_f32_16x16x32_bf16 v[190:193], v[108:111], v[206:209], v[76:79]
	v_mfma_f32_16x16x32_bf16 v[194:197], v[158:161], v[206:209], v[72:75]
	v_mfma_f32_16x16x32_bf16 v[198:201], v[158:161], v[214:217], v[64:67]
	s_nop 0
	s_barrier
	s_nop 0
	ds_read_b128 v[64:67], v153 offset:16384
	ds_read_b128 v[72:75], v153 offset:17408
	ds_read_b128 v[76:79], v171 offset:16384
	ds_read_b128 v[88:91], v171 offset:17408
	ds_read_b128 v[92:95], v172 offset:16384
	ds_read_b128 v[202:205], v172 offset:17408
	ds_read_b128 v[206:209], v173 offset:16384
	ds_read_b128 v[210:213], v173 offset:17408
	s_waitcnt vmcnt(4)
	s_barrier
	s_waitcnt lgkmcnt(0)
	s_nop 0
	v_mfma_f32_16x16x32_bf16 v[60:63], v[142:145], v[64:67], v[60:63]
	v_mfma_f32_16x16x32_bf16 v[56:59], v[178:181], v[64:67], v[56:59]
	v_mfma_f32_16x16x32_bf16 v[52:55], v[142:145], v[76:79], v[52:55]
	v_mfma_f32_16x16x32_bf16 v[48:51], v[178:181], v[76:79], v[48:51]
	v_mfma_f32_16x16x32_bf16 v[36:39], v[142:145], v[206:209], v[36:39]
	v_mfma_f32_16x16x32_bf16 v[32:35], v[178:181], v[206:209], v[32:35]
	v_mfma_f32_16x16x32_bf16 v[60:63], v[146:149], v[72:75], v[60:63]
	v_mfma_f32_16x16x32_bf16 v[56:59], v[182:185], v[72:75], v[56:59]
	v_mfma_f32_16x16x32_bf16 v[52:55], v[146:149], v[88:91], v[52:55]
	v_mfma_f32_16x16x32_bf16 v[48:51], v[182:185], v[88:91], v[48:51]
	v_mfma_f32_16x16x32_bf16 v[44:47], v[142:145], v[92:95], v[44:47]
	v_mfma_f32_16x16x32_bf16 v[40:43], v[178:181], v[92:95], v[40:43]
	v_mfma_f32_16x16x32_bf16 v[36:39], v[146:149], v[210:213], v[36:39]
	v_mfma_f32_16x16x32_bf16 v[32:35], v[182:185], v[210:213], v[32:35]
	v_mfma_f32_16x16x32_bf16 v[214:217], v[146:149], v[202:205], v[44:47]
	v_mfma_f32_16x16x32_bf16 v[230:233], v[182:185], v[202:205], v[40:43]
	s_nop 0
	s_nop 0
	v_mfma_f32_16x16x32_bf16 v[20:23], v[104:107], v[76:79], v[20:23]
	v_mfma_f32_16x16x32_bf16 v[16:19], v[222:225], v[76:79], v[16:19]
	v_mfma_f32_16x16x32_bf16 v[4:7], v[104:107], v[206:209], v[4:7]
	v_mfma_f32_16x16x32_bf16 v[28:31], v[104:107], v[64:67], v[28:31]
	v_mfma_f32_16x16x32_bf16 v[24:27], v[222:225], v[64:67], v[24:27]
	v_mfma_f32_16x16x32_bf16 v[20:23], v[108:111], v[88:91], v[20:23]
	v_mfma_f32_16x16x32_bf16 v[16:19], v[158:161], v[88:91], v[16:19]
	v_mfma_f32_16x16x32_bf16 v[12:15], v[104:107], v[92:95], v[12:15]
	v_mfma_f32_16x16x32_bf16 v[8:11], v[222:225], v[92:95], v[8:11]
	v_mfma_f32_16x16x32_bf16 v[4:7], v[108:111], v[210:213], v[4:7]
	v_mfma_f32_16x16x32_bf16 v[0:3], v[222:225], v[206:209], v[0:3]
	v_mfma_f32_16x16x32_bf16 v[142:145], v[108:111], v[72:75], v[28:31]
	v_mfma_f32_16x16x32_bf16 v[146:149], v[158:161], v[72:75], v[24:27]
	v_mfma_f32_16x16x32_bf16 v[178:181], v[108:111], v[202:205], v[12:15]
	v_mfma_f32_16x16x32_bf16 v[182:185], v[158:161], v[202:205], v[8:11]
	v_mfma_f32_16x16x32_bf16 v[158:161], v[158:161], v[210:213], v[0:3]
	s_nop 0
	s_barrier
	s_nop 0
	ds_read_b128 v[0:3], v156
	ds_read_b128 v[8:11], v156 offset:1024
	ds_read_b128 v[202:205], v156 offset:2048
	ds_read_b128 v[206:209], v156 offset:3072
	ds_read_b128 v[12:15], v153 offset:32768
	ds_read_b128 v[24:27], v153 offset:33792
	ds_read_b128 v[28:31], v171 offset:32768
	ds_read_b128 v[40:43], v171 offset:33792
	ds_read_b128 v[44:47], v172 offset:32768
	ds_read_b128 v[64:67], v172 offset:33792
	ds_read_b128 v[210:213], v173 offset:32768
	ds_read_b128 v[222:225], v173 offset:33792
	s_waitcnt vmcnt(2)
	s_barrier
; #define LDA(dst,b,h) _Pragma("unroll") for(int m=0;m<4;++m) _Pragma("unroll") for(int k=0;k<2;++k) \
;     dst[m][k]=*reinterpret_cast<const bf16x8*>((char*)SA(b,h)+lds_byte(wr*64+m*16+fr,k*32+fq*8))
; #define LDB(dst,b,h) _Pragma("unroll") for(int n=0;n<2;++n) _Pragma("unroll") for(int k=0;k<2;++k) \
;     dst[n][k]=*reinterpret_cast<const bf16x8*>((char*)SB(b,h)+lds_byte(wc*32+n*16+fr,k*32+fq*8))
; #define MMA(ai,bj,At_,Bt_) do{__builtin_amdgcn_s_setprio(1); \
;     _Pragma("unroll") for(int m=0;m<4;++m) _Pragma("unroll") for(int n=0;n<2;++n) _Pragma("unroll") for(int k=0;k<2;++k) \
;       acc[ai][bj][m][n]=__builtin_amdgcn_mfma_f32_16x16x32_bf16(Bt_[n][k],At_[m][k],acc[ai][bj][m][n],0,0,0); \
;     __builtin_amdgcn_s_setprio(0);}while(0)
; #define WAIT_V(n) asm volatile("s_waitcnt vmcnt(" #n ")":::"memory")
; #define WAIT_L(n) asm volatile("s_waitcnt lgkmcnt(" #n ")":::"memory")
; #define BAR __builtin_amdgcn_s_barrier()
; DEVINL void gemm8_mainloop(const u16* A, long lda, const u16* Bt, long ldb, int K, int brow, int bcol, f32x4 (&acc)[2][2][4][2], char* smem, int tid) {
;     ...
;   { LDB(B0,1,0); LDA(At,1,0); WAIT_V(2); BAR; WAIT_L(0); MMA(0,0,At,B0); BAR;
;     LDB(B1,1,1); WAIT_V(0); BAR; WAIT_L(0); MMA(0,1,At,B1); BAR;
;     LDA(At,1,1); BAR; WAIT_L(0); MMA(1,0,At,B0); MMA(1,1,At,B1); BAR; }
;   if(wr==0)BAR;
	s_waitcnt lgkmcnt(0)
	s_nop 0
	v_mfma_f32_16x16x32_bf16 v[72:75], v[0:3], v[12:15], v[124:127]
	v_mfma_f32_16x16x32_bf16 v[124:127], v[8:11], v[24:27], v[72:75]
	v_mfma_f32_16x16x32_bf16 v[72:75], v[202:205], v[12:15], v[120:123]
	v_mfma_f32_16x16x32_bf16 v[120:123], v[206:209], v[24:27], v[72:75]
	v_mfma_f32_16x16x32_bf16 v[72:75], v[0:3], v[28:31], v[116:119]
	v_mfma_f32_16x16x32_bf16 v[108:111], v[8:11], v[40:43], v[72:75]
	v_mfma_f32_16x16x32_bf16 v[72:75], v[202:205], v[28:31], v[112:115]
	v_mfma_f32_16x16x32_bf16 v[104:107], v[206:209], v[40:43], v[72:75]
	v_mfma_f32_16x16x32_bf16 v[72:75], v[0:3], v[44:47], v[138:141]
	v_mfma_f32_16x16x32_bf16 v[92:95], v[8:11], v[64:67], v[72:75]
	v_mfma_f32_16x16x32_bf16 v[72:75], v[202:205], v[44:47], v[218:221]
	v_mfma_f32_16x16x32_bf16 v[88:91], v[206:209], v[64:67], v[72:75]
	v_mfma_f32_16x16x32_bf16 v[72:75], v[0:3], v[210:213], v[100:103]
	v_mfma_f32_16x16x32_bf16 v[76:79], v[8:11], v[222:225], v[72:75]
	v_mfma_f32_16x16x32_bf16 v[72:75], v[202:205], v[210:213], v[96:99]
	v_mfma_f32_16x16x32_bf16 v[72:75], v[206:209], v[222:225], v[72:75]
	s_nop 0
	s_barrier
	ds_read_b128 v[138:141], v155
	ds_read_b128 v[218:221], v155 offset:1024
	ds_read_b128 v[234:237], v155 offset:2048
	ds_read_b128 v[154:157], v155 offset:3072
	s_waitcnt vmcnt(0)
	s_barrier
	s_waitcnt lgkmcnt(0)
	s_nop 0
	v_mfma_f32_16x16x32_bf16 v[96:99], v[138:141], v[12:15], v[226:229]
	v_mfma_f32_16x16x32_bf16 v[12:15], v[234:237], v[12:15], v[186:189]
	v_mfma_f32_16x16x32_bf16 v[116:119], v[154:157], v[24:27], v[12:15]
	v_mfma_f32_16x16x32_bf16 v[12:15], v[138:141], v[28:31], v[84:87]
	v_mfma_f32_16x16x32_bf16 v[112:115], v[218:221], v[24:27], v[96:99]
	v_mfma_f32_16x16x32_bf16 v[96:99], v[218:221], v[40:43], v[12:15]
	v_mfma_f32_16x16x32_bf16 v[12:15], v[234:237], v[28:31], v[80:83]
	v_mfma_f32_16x16x32_bf16 v[100:103], v[154:157], v[40:43], v[12:15]
	v_mfma_f32_16x16x32_bf16 v[12:15], v[138:141], v[44:47], v[190:193]
	v_mfma_f32_16x16x32_bf16 v[80:83], v[218:221], v[64:67], v[12:15]
	v_mfma_f32_16x16x32_bf16 v[12:15], v[234:237], v[44:47], v[194:197]
	v_mfma_f32_16x16x32_bf16 v[84:87], v[154:157], v[64:67], v[12:15]
	v_mfma_f32_16x16x32_bf16 v[12:15], v[138:141], v[210:213], v[68:71]
	v_mfma_f32_16x16x32_bf16 v[64:67], v[218:221], v[222:225], v[12:15]
	v_mfma_f32_16x16x32_bf16 v[12:15], v[234:237], v[210:213], v[198:201]
	v_mfma_f32_16x16x32_bf16 v[68:71], v[154:157], v[222:225], v[12:15]
	s_nop 0
	s_barrier
	ds_read_b128 v[186:189], v153 offset:49152
	ds_read_b128 v[190:193], v153 offset:50176
	ds_read_b128 v[194:197], v171 offset:49152
	ds_read_b128 v[198:201], v171 offset:50176
	ds_read_b128 v[210:213], v172 offset:49152
	ds_read_b128 v[222:225], v172 offset:50176
	ds_read_b128 v[226:229], v173 offset:49152
	ds_read_b128 v[172:175], v173 offset:50176
	s_barrier
	s_waitcnt lgkmcnt(0)
	s_nop 0
	v_mfma_f32_16x16x32_bf16 v[12:15], v[0:3], v[186:189], v[60:63]
	v_mfma_f32_16x16x32_bf16 v[60:63], v[8:11], v[190:193], v[12:15]
	v_mfma_f32_16x16x32_bf16 v[12:15], v[202:205], v[186:189], v[56:59]
	v_mfma_f32_16x16x32_bf16 v[56:59], v[206:209], v[190:193], v[12:15]
	v_mfma_f32_16x16x32_bf16 v[12:15], v[0:3], v[194:197], v[52:55]
	v_mfma_f32_16x16x32_bf16 v[44:47], v[8:11], v[198:201], v[12:15]
	v_mfma_f32_16x16x32_bf16 v[12:15], v[202:205], v[194:197], v[48:51]
	v_mfma_f32_16x16x32_bf16 v[40:43], v[206:209], v[198:201], v[12:15]
	v_mfma_f32_16x16x32_bf16 v[12:15], v[0:3], v[210:213], v[214:217]
	v_mfma_f32_16x16x32_bf16 v[28:31], v[8:11], v[222:225], v[12:15]
	v_mfma_f32_16x16x32_bf16 v[12:15], v[202:205], v[210:213], v[230:233]
	v_mfma_f32_16x16x32_bf16 v[0:3], v[0:3], v[226:229], v[36:39]
	v_mfma_f32_16x16x32_bf16 v[24:27], v[206:209], v[222:225], v[12:15]
	v_mfma_f32_16x16x32_bf16 v[12:15], v[8:11], v[172:175], v[0:3]
	v_mfma_f32_16x16x32_bf16 v[0:3], v[202:205], v[226:229], v[32:35]
	v_mfma_f32_16x16x32_bf16 v[8:11], v[206:209], v[172:175], v[0:3]
	s_nop 0
	s_nop 0
	v_mfma_f32_16x16x32_bf16 v[0:3], v[138:141], v[186:189], v[142:145]
	v_mfma_f32_16x16x32_bf16 v[48:51], v[218:221], v[190:193], v[0:3]
	v_mfma_f32_16x16x32_bf16 v[0:3], v[234:237], v[186:189], v[146:149]
	v_mfma_f32_16x16x32_bf16 v[52:55], v[154:157], v[190:193], v[0:3]
	v_mfma_f32_16x16x32_bf16 v[0:3], v[138:141], v[194:197], v[20:23]
	v_mfma_f32_16x16x32_bf16 v[32:35], v[218:221], v[198:201], v[0:3]
	v_mfma_f32_16x16x32_bf16 v[0:3], v[234:237], v[194:197], v[16:19]
	v_mfma_f32_16x16x32_bf16 v[36:39], v[154:157], v[198:201], v[0:3]
	v_mfma_f32_16x16x32_bf16 v[0:3], v[138:141], v[210:213], v[178:181]
	v_mfma_f32_16x16x32_bf16 v[16:19], v[218:221], v[222:225], v[0:3]
	v_mfma_f32_16x16x32_bf16 v[0:3], v[234:237], v[210:213], v[182:185]
	v_mfma_f32_16x16x32_bf16 v[20:23], v[154:157], v[222:225], v[0:3]
	v_mfma_f32_16x16x32_bf16 v[0:3], v[138:141], v[226:229], v[4:7]
	v_mfma_f32_16x16x32_bf16 v[4:7], v[234:237], v[226:229], v[158:161]
	v_mfma_f32_16x16x32_bf16 v[0:3], v[218:221], v[172:175], v[0:3]
	v_mfma_f32_16x16x32_bf16 v[4:7], v[154:157], v[172:175], v[4:7]
	s_setprio 0
	s_cmpk_gt_u32 s27, 0xff
	s_barrier
	s_cbranch_scc1 .LBB0_1990
	s_barrier
